# the already-satisfied s_waitcnt lgkmcnt(0) right after each pre-MFMA barrier removed (120 sites: 15 K-loops and their peeled iterations); on top of norm-loop consolidation
# baseline (speedup 1.0000x reference)
; #define PG8_WAIT_V(n) asm volatile("s_waitcnt vmcnt(" #n ")" ::: "memory")
; template <class Epi, class Sched, bool ALIGN_EPI = true, bool SP2 = true, bool FULLLINE = false, bool NOSTAGE = false, bool FP8 = false>
; __device__ __forceinline__ void gemm_phase(PG8_LAS unsigned char* lds, const Gemm g, const Sched& S, const Epi& E) {
;     ...
;         static_assert(SP2, "only the SP2 loop is kept");
;         { const int t = 0; if constexpr (Epi::NST == 16) PG8_ITER(PG8_WAIT_V(24)); else if constexpr (Epi::NST == 8) PG8_ITER(PG8_WAIT_V(16)); else PG8_ITER(PG8_WAIT_V(8)); }
.LBB0_261:
	s_ashr_i32 s75, s74, 31
	s_lshl_b64 s[40:41], s[74:75], 20
	s_add_u32 s76, s58, s40
	ds_read_b128 v[2:5], v156
	ds_read_b128 v[6:9], v156 offset:1024
	ds_read_b128 v[10:13], v156 offset:2048
	ds_read_b128 v[14:17], v156 offset:3072
	ds_read_b128 v[18:21], v157
	ds_read_b128 v[22:25], v157 offset:1024
	ds_read_b128 v[26:29], v157 offset:2048
	ds_read_b128 v[30:33], v157 offset:3072
	s_addc_u32 s77, s59, s41
	s_ashr_i32 s73, s72, 31
	s_lshl_b64 s[40:41], s[72:73], 20
	s_add_u32 s78, s84, s40
	s_addc_u32 s79, s85, s41
	s_and_b64 s[40:41], s[8:9], exec
	s_cselect_b32 s3, s77, s83
	s_cselect_b32 s11, s76, s82
	s_cselect_b32 s13, s79, s81
	s_cselect_b32 s42, s78, s80
	v_lshl_add_u64 v[138:139], s[82:83], 0, v[140:141]
	s_mov_b32 m0, s89
	v_lshl_add_u64 v[66:67], v[138:139], 0, s[20:21]
	ds_read_b128 v[34:37], v158
	ds_read_b128 v[38:41], v158 offset:1024
	ds_read_b128 v[42:45], v158 offset:2048
	ds_read_b128 v[46:49], v158 offset:3072
	ds_read_b128 v[50:53], v158 offset:4096
	ds_read_b128 v[54:57], v158 offset:5120
	ds_read_b128 v[58:61], v158 offset:6144
	ds_read_b128 v[62:65], v158 offset:7168
	global_load_lds_dwordx4 v[66:67], off
	v_lshl_add_u64 v[66:67], v[138:139], 0, s[22:23]
	s_mov_b32 m0, s45
	s_nop 0
	global_load_lds_dwordx4 v[66:67], off
	s_waitcnt vmcnt(24)
	s_waitcnt lgkmcnt(0)
	s_barrier
	v_mfma_f32_16x16x32_bf16 v[86:89], v[10:13], v[50:53], 0
	v_mfma_f32_16x16x32_bf16 v[90:93], v[14:17], v[54:57], v[86:89]
	v_mfma_f32_16x16x32_bf16 v[86:89], v[2:5], v[58:61], 0
	v_mfma_f32_16x16x32_bf16 v[66:69], v[2:5], v[34:37], 0
	v_mfma_f32_16x16x32_bf16 v[70:73], v[10:13], v[34:37], 0
	v_mfma_f32_16x16x32_bf16 v[74:77], v[2:5], v[42:45], 0
	v_mfma_f32_16x16x32_bf16 v[78:81], v[10:13], v[42:45], 0
	v_mfma_f32_16x16x32_bf16 v[82:85], v[2:5], v[50:53], 0
	v_mfma_f32_16x16x32_bf16 v[94:97], v[6:9], v[62:65], v[86:89]
	v_mfma_f32_16x16x32_bf16 v[86:89], v[10:13], v[58:61], 0
	v_mfma_f32_16x16x32_bf16 v[66:69], v[6:9], v[38:41], v[66:69]
	v_mfma_f32_16x16x32_bf16 v[70:73], v[14:17], v[38:41], v[70:73]
	v_mfma_f32_16x16x32_bf16 v[74:77], v[6:9], v[46:49], v[74:77]
	v_mfma_f32_16x16x32_bf16 v[78:81], v[14:17], v[46:49], v[78:81]
	v_mfma_f32_16x16x32_bf16 v[82:85], v[6:9], v[54:57], v[82:85]
	v_mfma_f32_16x16x32_bf16 v[106:109], v[14:17], v[62:65], v[86:89]
	v_mfma_f32_16x16x32_bf16 v[86:89], v[18:21], v[34:37], 0
	v_mfma_f32_16x16x32_bf16 v[34:37], v[26:29], v[34:37], 0
	v_mfma_f32_16x16x32_bf16 v[110:113], v[22:25], v[38:41], v[86:89]
	v_mfma_f32_16x16x32_bf16 v[34:37], v[30:33], v[38:41], v[34:37]
	v_mfma_f32_16x16x32_bf16 v[38:41], v[18:21], v[42:45], 0
	v_mfma_f32_16x16x32_bf16 v[42:45], v[26:29], v[42:45], 0
	v_mfma_f32_16x16x32_bf16 v[38:41], v[22:25], v[46:49], v[38:41]
	v_mfma_f32_16x16x32_bf16 v[42:45], v[30:33], v[46:49], v[42:45]
	v_mfma_f32_16x16x32_bf16 v[46:49], v[18:21], v[50:53], 0
	v_mfma_f32_16x16x32_bf16 v[50:53], v[26:29], v[50:53], 0
	v_mfma_f32_16x16x32_bf16 v[46:49], v[22:25], v[54:57], v[46:49]
	v_mfma_f32_16x16x32_bf16 v[50:53], v[30:33], v[54:57], v[50:53]
	v_mfma_f32_16x16x32_bf16 v[54:57], v[18:21], v[58:61], 0
	v_mfma_f32_16x16x32_bf16 v[58:61], v[26:29], v[58:61], 0
	v_mfma_f32_16x16x32_bf16 v[54:57], v[22:25], v[62:65], v[54:57]
	v_mfma_f32_16x16x32_bf16 v[58:61], v[30:33], v[62:65], v[58:61]
	s_barrier
	v_lshl_add_u64 v[154:155], s[80:81], 0, v[142:143]
	s_add_i32 s43, s62, s88
	v_lshl_add_u64 v[130:131], v[154:155], 0, s[24:25]
	s_mov_b32 m0, s43
	s_add_i32 s53, s43, 0x2000
	ds_read_b128 v[62:65], v158 offset:16384
	ds_read_b128 v[86:89], v158 offset:17408
	ds_read_b128 v[98:101], v158 offset:18432
	ds_read_b128 v[102:105], v158 offset:19456
	ds_read_b128 v[114:117], v158 offset:20480
	ds_read_b128 v[118:121], v158 offset:21504
	ds_read_b128 v[122:125], v158 offset:22528
	ds_read_b128 v[126:129], v158 offset:23552
	global_load_lds_dwordx4 v[130:131], off
	v_lshl_add_u64 v[130:131], v[154:155], 0, s[26:27]
	s_mov_b32 m0, s53
	s_add_i32 s73, s63, s88
	global_load_lds_dwordx4 v[130:131], off
	v_lshl_add_u64 v[130:131], v[154:155], 0, s[28:29]
	s_mov_b32 m0, s73
	s_add_i32 s40, s73, 0x2000
	global_load_lds_dwordx4 v[130:131], off
	v_lshl_add_u64 v[130:131], v[154:155], 0, s[30:31]
	s_mov_b32 m0, s40
	s_nop 0
	global_load_lds_dwordx4 v[130:131], off
	v_lshl_add_u64 v[130:131], v[138:139], 0, s[24:25]
	s_mov_b32 m0, s44
	s_nop 0
	global_load_lds_dwordx4 v[130:131], off
	v_lshl_add_u64 v[130:131], v[138:139], 0, s[26:27]
	s_mov_b32 m0, s90
	s_nop 0
	global_load_lds_dwordx4 v[130:131], off
	s_waitcnt vmcnt(24)
	s_waitcnt lgkmcnt(0)
	s_barrier
	v_mfma_f32_16x16x32_bf16 v[130:133], v[2:5], v[62:65], 0
	v_mfma_f32_16x16x32_bf16 v[150:153], v[2:5], v[98:101], 0
	v_mfma_f32_16x16x32_bf16 v[170:173], v[2:5], v[114:117], 0
	v_mfma_f32_16x16x32_bf16 v[2:5], v[2:5], v[122:125], 0
	v_mfma_f32_16x16x32_bf16 v[130:133], v[6:9], v[86:89], v[130:133]
	v_mfma_f32_16x16x32_bf16 v[150:153], v[6:9], v[102:105], v[150:153]
	v_mfma_f32_16x16x32_bf16 v[170:173], v[6:9], v[118:121], v[170:173]
	v_mfma_f32_16x16x32_bf16 v[2:5], v[6:9], v[126:129], v[2:5]
	v_mfma_f32_16x16x32_bf16 v[6:9], v[10:13], v[122:125], 0
	v_mfma_f32_16x16x32_bf16 v[134:137], v[10:13], v[62:65], 0
	v_mfma_f32_16x16x32_bf16 v[166:169], v[10:13], v[98:101], 0
	v_mfma_f32_16x16x32_bf16 v[174:177], v[10:13], v[114:117], 0
	v_mfma_f32_16x16x32_bf16 v[6:9], v[14:17], v[126:129], v[6:9]
	v_mfma_f32_16x16x32_bf16 v[134:137], v[14:17], v[86:89], v[134:137]
	v_mfma_f32_16x16x32_bf16 v[166:169], v[14:17], v[102:105], v[166:169]
	v_mfma_f32_16x16x32_bf16 v[174:177], v[14:17], v[118:121], v[174:177]
	v_mfma_f32_16x16x32_bf16 v[10:13], v[18:21], v[62:65], 0
	v_mfma_f32_16x16x32_bf16 v[14:17], v[26:29], v[62:65], 0
	v_mfma_f32_16x16x32_bf16 v[62:65], v[18:21], v[98:101], 0
	v_mfma_f32_16x16x32_bf16 v[178:181], v[22:25], v[102:105], v[62:65]
	v_mfma_f32_16x16x32_bf16 v[62:65], v[26:29], v[98:101], 0
	v_mfma_f32_16x16x32_bf16 v[182:185], v[30:33], v[102:105], v[62:65]
	v_mfma_f32_16x16x32_bf16 v[62:65], v[18:21], v[114:117], 0
	v_mfma_f32_16x16x32_bf16 v[18:21], v[18:21], v[122:125], 0
	v_mfma_f32_16x16x32_bf16 v[10:13], v[22:25], v[86:89], v[10:13]
	v_mfma_f32_16x16x32_bf16 v[14:17], v[30:33], v[86:89], v[14:17]
	v_mfma_f32_16x16x32_bf16 v[186:189], v[22:25], v[118:121], v[62:65]
	v_mfma_f32_16x16x32_bf16 v[62:65], v[26:29], v[114:117], 0
	v_mfma_f32_16x16x32_bf16 v[194:197], v[22:25], v[126:129], v[18:21]
	v_mfma_f32_16x16x32_bf16 v[18:21], v[26:29], v[122:125], 0
	v_mfma_f32_16x16x32_bf16 v[190:193], v[30:33], v[118:121], v[62:65]
	v_mfma_f32_16x16x32_bf16 v[198:201], v[30:33], v[126:129], v[18:21]
	s_barrier
; #define PG8_WAIT_V(n) asm volatile("s_waitcnt vmcnt(" #n ")" ::: "memory")
; template <class Epi, class Sched, bool ALIGN_EPI = true, bool SP2 = true, bool FULLLINE = false, bool NOSTAGE = false, bool FP8 = false>
; __device__ __forceinline__ void gemm_phase(PG8_LAS unsigned char* lds, const Gemm g, const Sched& S, const Epi& E) {
;     ...
;         static_assert(SP2, "only the SP2 loop is kept");
;         { const int t = 0; if constexpr (Epi::NST == 16) PG8_ITER(PG8_WAIT_V(24)); else if constexpr (Epi::NST == 8) PG8_ITER(PG8_WAIT_V(16)); else PG8_ITER(PG8_WAIT_V(8)); }
	ds_read_b128 v[26:29], v159
	ds_read_b128 v[30:33], v159 offset:1024
	s_nop 0
	ds_read_b128 v[62:65], v159 offset:2048
	ds_read_b128 v[202:205], v159 offset:3072
	ds_read_b128 v[206:209], v160
	ds_read_b128 v[210:213], v160 offset:1024
	ds_read_b128 v[214:217], v160 offset:2048
	ds_read_b128 v[218:221], v160 offset:3072
	s_mov_b32 m0, s91
	v_lshl_add_u64 v[86:87], v[138:139], 0, s[28:29]
	ds_read_b128 v[18:21], v158 offset:32768
	ds_read_b128 v[22:25], v158 offset:33792
	ds_read_b128 v[222:225], v158 offset:34816
	ds_read_b128 v[226:229], v158 offset:35840
	ds_read_b128 v[230:233], v158 offset:36864
	ds_read_b128 v[234:237], v158 offset:37888
	ds_read_b128 v[238:241], v158 offset:38912
	ds_read_b128 v[242:245], v158 offset:39936
	global_load_lds_dwordx4 v[86:87], off
	v_lshl_add_u64 v[86:87], v[138:139], 0, s[30:31]
	s_mov_b32 m0, s92
	s_nop 0
	global_load_lds_dwordx4 v[86:87], off
	s_waitcnt vmcnt(8)
	s_waitcnt lgkmcnt(0)
	s_barrier
	v_mfma_f32_16x16x32_bf16 v[66:69], v[26:29], v[18:21], v[66:69]
	v_mfma_f32_16x16x32_bf16 v[118:121], v[30:33], v[22:25], v[66:69]
	v_mfma_f32_16x16x32_bf16 v[66:69], v[62:65], v[18:21], v[70:73]
	v_mfma_f32_16x16x32_bf16 v[114:117], v[202:205], v[22:25], v[66:69]
	v_mfma_f32_16x16x32_bf16 v[66:69], v[26:29], v[222:225], v[74:77]
	v_mfma_f32_16x16x32_bf16 v[102:105], v[30:33], v[226:229], v[66:69]
	v_mfma_f32_16x16x32_bf16 v[66:69], v[62:65], v[222:225], v[78:81]
	v_mfma_f32_16x16x32_bf16 v[98:101], v[202:205], v[226:229], v[66:69]
	v_mfma_f32_16x16x32_bf16 v[66:69], v[26:29], v[230:233], v[82:85]
	v_mfma_f32_16x16x32_bf16 v[86:89], v[30:33], v[234:237], v[66:69]
	v_mfma_f32_16x16x32_bf16 v[66:69], v[62:65], v[230:233], v[90:93]
	v_mfma_f32_16x16x32_bf16 v[82:85], v[202:205], v[234:237], v[66:69]
	v_mfma_f32_16x16x32_bf16 v[66:69], v[26:29], v[238:241], v[94:97]
	v_mfma_f32_16x16x32_bf16 v[70:73], v[62:65], v[238:241], v[106:109]
	v_mfma_f32_16x16x32_bf16 v[66:69], v[30:33], v[242:245], v[66:69]
	v_mfma_f32_16x16x32_bf16 v[70:73], v[202:205], v[242:245], v[70:73]
	v_mfma_f32_16x16x32_bf16 v[74:77], v[206:209], v[18:21], v[110:113]
	v_mfma_f32_16x16x32_bf16 v[18:21], v[214:217], v[18:21], v[34:37]
	v_mfma_f32_16x16x32_bf16 v[122:125], v[218:221], v[22:25], v[18:21]
	v_mfma_f32_16x16x32_bf16 v[18:21], v[206:209], v[222:225], v[38:41]
	v_mfma_f32_16x16x32_bf16 v[110:113], v[210:213], v[226:229], v[18:21]
	v_mfma_f32_16x16x32_bf16 v[18:21], v[214:217], v[222:225], v[42:45]
	v_mfma_f32_16x16x32_bf16 v[106:109], v[218:221], v[226:229], v[18:21]
	v_mfma_f32_16x16x32_bf16 v[18:21], v[206:209], v[230:233], v[46:49]
	v_mfma_f32_16x16x32_bf16 v[94:97], v[210:213], v[234:237], v[18:21]
	v_mfma_f32_16x16x32_bf16 v[18:21], v[214:217], v[230:233], v[50:53]
	v_mfma_f32_16x16x32_bf16 v[90:93], v[218:221], v[234:237], v[18:21]
	v_mfma_f32_16x16x32_bf16 v[18:21], v[206:209], v[238:241], v[54:57]
	v_mfma_f32_16x16x32_bf16 v[126:129], v[210:213], v[22:25], v[74:77]
	v_mfma_f32_16x16x32_bf16 v[74:77], v[210:213], v[242:245], v[18:21]
	v_mfma_f32_16x16x32_bf16 v[18:21], v[214:217], v[238:241], v[58:61]
	v_mfma_f32_16x16x32_bf16 v[78:81], v[218:221], v[242:245], v[18:21]
	s_barrier
	s_add_i32 s41, s46, s88
	s_nop 4
	v_lshl_add_u64 v[18:19], v[154:155], 0, s[34:35]
	s_mov_b32 m0, s41
	s_add_i32 s50, s41, 0x2000
	ds_read_b128 v[42:45], v158 offset:49152
	ds_read_b128 v[46:49], v158 offset:50176
	ds_read_b128 v[222:225], v158 offset:51200
	ds_read_b128 v[226:229], v158 offset:52224
	ds_read_b128 v[230:233], v158 offset:53248
	ds_read_b128 v[234:237], v158 offset:54272
	ds_read_b128 v[238:241], v158 offset:55296
	ds_read_b128 v[242:245], v158 offset:56320
	global_load_lds_dwordx4 v[18:19], off
	v_lshl_add_u64 v[18:19], v[154:155], 0, s[36:37]
	s_mov_b32 m0, s50
	s_mov_b64 s[56:57], 0x80180
	s_add_i32 s51, s47, s88
	global_load_lds_dwordx4 v[18:19], off
	v_lshl_add_u64 v[18:19], v[154:155], 0, s[56:57]
	s_mov_b32 m0, s51
	s_mov_b64 s[56:57], 0xc0180
	s_add_i32 s33, s51, 0x2000
	global_load_lds_dwordx4 v[18:19], off
	v_lshl_add_u64 v[18:19], v[154:155], 0, s[56:57]
	s_mov_b32 m0, s33
	s_nop 0
	global_load_lds_dwordx4 v[18:19], off
	v_lshl_add_u64 v[18:19], v[138:139], 0, s[34:35]
	s_mov_b32 m0, s93
	s_nop 0
	global_load_lds_dwordx4 v[18:19], off
	v_lshl_add_u64 v[18:19], v[138:139], 0, s[36:37]
	s_mov_b32 m0, s94
	s_nop 0
	global_load_lds_dwordx4 v[18:19], off
	s_waitcnt vmcnt(8)
	s_waitcnt lgkmcnt(0)
	s_barrier
	v_mfma_f32_16x16x32_bf16 v[18:21], v[26:29], v[42:45], v[130:133]
	v_mfma_f32_16x16x32_bf16 v[50:53], v[30:33], v[46:49], v[18:21]
	v_mfma_f32_16x16x32_bf16 v[18:21], v[62:65], v[42:45], v[134:137]
	v_mfma_f32_16x16x32_bf16 v[54:57], v[202:205], v[46:49], v[18:21]
	v_mfma_f32_16x16x32_bf16 v[18:21], v[26:29], v[222:225], v[150:153]
	v_mfma_f32_16x16x32_bf16 v[34:37], v[30:33], v[226:229], v[18:21]
	v_mfma_f32_16x16x32_bf16 v[18:21], v[62:65], v[222:225], v[166:169]
	v_mfma_f32_16x16x32_bf16 v[38:41], v[202:205], v[226:229], v[18:21]
	v_mfma_f32_16x16x32_bf16 v[18:21], v[26:29], v[230:233], v[170:173]
	v_mfma_f32_16x16x32_bf16 v[22:25], v[62:65], v[230:233], v[174:177]
	v_mfma_f32_16x16x32_bf16 v[2:5], v[26:29], v[238:241], v[2:5]
	v_mfma_f32_16x16x32_bf16 v[6:9], v[62:65], v[238:241], v[6:9]
	v_mfma_f32_16x16x32_bf16 v[18:21], v[30:33], v[234:237], v[18:21]
	v_mfma_f32_16x16x32_bf16 v[22:25], v[202:205], v[234:237], v[22:25]
	v_mfma_f32_16x16x32_bf16 v[2:5], v[30:33], v[242:245], v[2:5]
	v_mfma_f32_16x16x32_bf16 v[6:9], v[202:205], v[242:245], v[6:9]
	v_mfma_f32_16x16x32_bf16 v[10:13], v[206:209], v[42:45], v[10:13]
	v_mfma_f32_16x16x32_bf16 v[58:61], v[210:213], v[46:49], v[10:13]
	v_mfma_f32_16x16x32_bf16 v[10:13], v[214:217], v[42:45], v[14:17]
	v_mfma_f32_16x16x32_bf16 v[62:65], v[218:221], v[46:49], v[10:13]
	v_mfma_f32_16x16x32_bf16 v[10:13], v[206:209], v[222:225], v[178:181]
	v_mfma_f32_16x16x32_bf16 v[42:45], v[210:213], v[226:229], v[10:13]
	v_mfma_f32_16x16x32_bf16 v[10:13], v[214:217], v[222:225], v[182:185]
	v_mfma_f32_16x16x32_bf16 v[46:49], v[218:221], v[226:229], v[10:13]
	v_mfma_f32_16x16x32_bf16 v[10:13], v[206:209], v[230:233], v[186:189]
	v_mfma_f32_16x16x32_bf16 v[26:29], v[210:213], v[234:237], v[10:13]
	v_mfma_f32_16x16x32_bf16 v[10:13], v[214:217], v[230:233], v[190:193]
	v_mfma_f32_16x16x32_bf16 v[30:33], v[218:221], v[234:237], v[10:13]
	v_mfma_f32_16x16x32_bf16 v[10:13], v[206:209], v[238:241], v[194:197]
	v_mfma_f32_16x16x32_bf16 v[14:17], v[214:217], v[238:241], v[198:201]
	v_mfma_f32_16x16x32_bf16 v[10:13], v[210:213], v[242:245], v[10:13]
	v_mfma_f32_16x16x32_bf16 v[14:17], v[218:221], v[242:245], v[14:17]
	s_barrier
	s_add_u32 s82, s82, 0x80180
	s_addc_u32 s83, s83, 0
	s_add_u32 s56, s80, 0x200
	s_addc_u32 s57, s81, 0
	s_mov_b32 s75, 0
.LBB0_262:
	ds_read_b128 v[130:133], v156
	ds_read_b128 v[134:137], v156 offset:1024
	ds_read_b128 v[150:153], v156 offset:2048
	ds_read_b128 v[166:169], v156 offset:3072
	ds_read_b128 v[170:173], v157
	ds_read_b128 v[174:177], v157 offset:1024
	ds_read_b128 v[178:181], v157 offset:2048
	ds_read_b128 v[182:185], v157 offset:3072
	s_add_u32 s0, s82, 0xfff80080
	s_addc_u32 s1, s83, -1
	s_cmp_eq_u32 s75, 28
	s_cselect_b32 s81, s3, s1
	s_cselect_b32 s80, s11, s0
	s_cselect_b32 vcc_hi, s13, s57
	s_cselect_b32 vcc_lo, s42, s56
	s_mov_b32 m0, s89
	v_lshl_add_u64 v[138:139], s[82:83], 0, v[144:145]
	ds_read_b128 v[186:189], v158
	ds_read_b128 v[190:193], v158 offset:1024
	ds_read_b128 v[194:197], v158 offset:2048
	ds_read_b128 v[198:201], v158 offset:3072
	ds_read_b128 v[202:205], v158 offset:4096
	ds_read_b128 v[206:209], v158 offset:5120
	ds_read_b128 v[210:213], v158 offset:6144
	ds_read_b128 v[214:217], v158 offset:7168
	global_load_lds_dwordx4 v[138:139], off
	v_lshl_add_u64 v[138:139], v[138:139], 0, s[38:39]
	s_mov_b32 m0, s45
	s_nop 0
	global_load_lds_dwordx4 v[138:139], off
	s_waitcnt vmcnt(8)
	s_waitcnt lgkmcnt(0)
	s_barrier
	v_mfma_f32_16x16x32_bf16 v[118:121], v[130:133], v[186:189], v[118:121]
	v_mfma_f32_16x16x32_bf16 v[114:117], v[150:153], v[186:189], v[114:117]
	v_mfma_f32_16x16x32_bf16 v[102:105], v[130:133], v[194:197], v[102:105]
	v_mfma_f32_16x16x32_bf16 v[98:101], v[150:153], v[194:197], v[98:101]
	v_mfma_f32_16x16x32_bf16 v[86:89], v[130:133], v[202:205], v[86:89]
	v_mfma_f32_16x16x32_bf16 v[82:85], v[150:153], v[202:205], v[82:85]
	v_mfma_f32_16x16x32_bf16 v[66:69], v[130:133], v[210:213], v[66:69]
	v_mfma_f32_16x16x32_bf16 v[70:73], v[150:153], v[210:213], v[70:73]
	v_mfma_f32_16x16x32_bf16 v[118:121], v[134:137], v[190:193], v[118:121]
	v_mfma_f32_16x16x32_bf16 v[114:117], v[166:169], v[190:193], v[114:117]
	v_mfma_f32_16x16x32_bf16 v[102:105], v[134:137], v[198:201], v[102:105]
	v_mfma_f32_16x16x32_bf16 v[98:101], v[166:169], v[198:201], v[98:101]
	v_mfma_f32_16x16x32_bf16 v[86:89], v[134:137], v[206:209], v[86:89]
	v_mfma_f32_16x16x32_bf16 v[82:85], v[166:169], v[206:209], v[82:85]
	v_mfma_f32_16x16x32_bf16 v[66:69], v[134:137], v[214:217], v[66:69]
	v_mfma_f32_16x16x32_bf16 v[70:73], v[166:169], v[214:217], v[70:73]
	v_mfma_f32_16x16x32_bf16 v[126:129], v[170:173], v[186:189], v[126:129]
	v_mfma_f32_16x16x32_bf16 v[122:125], v[178:181], v[186:189], v[122:125]
	v_mfma_f32_16x16x32_bf16 v[110:113], v[170:173], v[194:197], v[110:113]
	v_mfma_f32_16x16x32_bf16 v[106:109], v[178:181], v[194:197], v[106:109]
	v_mfma_f32_16x16x32_bf16 v[94:97], v[170:173], v[202:205], v[94:97]
	v_mfma_f32_16x16x32_bf16 v[90:93], v[178:181], v[202:205], v[90:93]
	v_mfma_f32_16x16x32_bf16 v[74:77], v[170:173], v[210:213], v[74:77]
	v_mfma_f32_16x16x32_bf16 v[78:81], v[178:181], v[210:213], v[78:81]
	v_mfma_f32_16x16x32_bf16 v[126:129], v[174:177], v[190:193], v[126:129]
	v_mfma_f32_16x16x32_bf16 v[122:125], v[182:185], v[190:193], v[122:125]
	v_mfma_f32_16x16x32_bf16 v[110:113], v[174:177], v[198:201], v[110:113]
	v_mfma_f32_16x16x32_bf16 v[106:109], v[182:185], v[198:201], v[106:109]
	v_mfma_f32_16x16x32_bf16 v[94:97], v[174:177], v[206:209], v[94:97]
	v_mfma_f32_16x16x32_bf16 v[90:93], v[182:185], v[206:209], v[90:93]
	v_mfma_f32_16x16x32_bf16 v[74:77], v[174:177], v[214:217], v[74:77]
	v_mfma_f32_16x16x32_bf16 v[78:81], v[182:185], v[214:217], v[78:81]
	s_barrier
	s_mov_b32 m0, s43
	v_lshl_add_u64 v[138:139], vcc, 0, v[142:143]
	ds_read_b128 v[186:189], v158 offset:16384
	ds_read_b128 v[190:193], v158 offset:17408
	ds_read_b128 v[194:197], v158 offset:18432
	ds_read_b128 v[198:201], v158 offset:19456
	ds_read_b128 v[202:205], v158 offset:20480
	ds_read_b128 v[206:209], v158 offset:21504
	ds_read_b128 v[210:213], v158 offset:22528
	ds_read_b128 v[214:217], v158 offset:23552
	global_load_lds_dwordx4 v[138:139], off
	v_lshl_add_u64 v[154:155], v[138:139], 0, s[38:39]
	s_mov_b32 m0, s53
	s_nop 0
	global_load_lds_dwordx4 v[154:155], off
	v_lshl_add_u64 v[154:155], v[138:139], 0, s[60:61]
	s_mov_b32 m0, s73
	s_nop 0
	global_load_lds_dwordx4 v[154:155], off
	v_lshl_add_u64 v[154:155], v[138:139], 0, s[66:67]
	s_mov_b32 m0, s40
	s_nop 0
	global_load_lds_dwordx4 v[154:155], off
	v_lshl_add_u64 v[154:155], s[80:81], 0, v[140:141]
	s_mov_b32 m0, s44
	v_lshl_add_u64 v[218:219], v[154:155], 0, s[38:39]
	global_load_lds_dwordx4 v[154:155], off
	s_mov_b32 m0, s90
	s_nop 0
	global_load_lds_dwordx4 v[218:219], off
	s_waitcnt vmcnt(8)
	s_waitcnt lgkmcnt(0)
	s_barrier
	v_mfma_f32_16x16x32_bf16 v[50:53], v[130:133], v[186:189], v[50:53]
	v_mfma_f32_16x16x32_bf16 v[54:57], v[150:153], v[186:189], v[54:57]
	v_mfma_f32_16x16x32_bf16 v[34:37], v[130:133], v[194:197], v[34:37]
	v_mfma_f32_16x16x32_bf16 v[38:41], v[150:153], v[194:197], v[38:41]
	v_mfma_f32_16x16x32_bf16 v[18:21], v[130:133], v[202:205], v[18:21]
	v_mfma_f32_16x16x32_bf16 v[22:25], v[150:153], v[202:205], v[22:25]
	v_mfma_f32_16x16x32_bf16 v[2:5], v[130:133], v[210:213], v[2:5]
	v_mfma_f32_16x16x32_bf16 v[6:9], v[150:153], v[210:213], v[6:9]
	v_mfma_f32_16x16x32_bf16 v[50:53], v[134:137], v[190:193], v[50:53]
	v_mfma_f32_16x16x32_bf16 v[54:57], v[166:169], v[190:193], v[54:57]
	v_mfma_f32_16x16x32_bf16 v[34:37], v[134:137], v[198:201], v[34:37]
	v_mfma_f32_16x16x32_bf16 v[38:41], v[166:169], v[198:201], v[38:41]
	v_mfma_f32_16x16x32_bf16 v[18:21], v[134:137], v[206:209], v[18:21]
	v_mfma_f32_16x16x32_bf16 v[22:25], v[166:169], v[206:209], v[22:25]
	v_mfma_f32_16x16x32_bf16 v[2:5], v[134:137], v[214:217], v[2:5]
	v_mfma_f32_16x16x32_bf16 v[6:9], v[166:169], v[214:217], v[6:9]
	v_mfma_f32_16x16x32_bf16 v[58:61], v[170:173], v[186:189], v[58:61]
	v_mfma_f32_16x16x32_bf16 v[62:65], v[178:181], v[186:189], v[62:65]
	v_mfma_f32_16x16x32_bf16 v[42:45], v[170:173], v[194:197], v[42:45]
	v_mfma_f32_16x16x32_bf16 v[46:49], v[178:181], v[194:197], v[46:49]
	v_mfma_f32_16x16x32_bf16 v[26:29], v[170:173], v[202:205], v[26:29]
	v_mfma_f32_16x16x32_bf16 v[30:33], v[178:181], v[202:205], v[30:33]
	v_mfma_f32_16x16x32_bf16 v[10:13], v[170:173], v[210:213], v[10:13]
	v_mfma_f32_16x16x32_bf16 v[14:17], v[178:181], v[210:213], v[14:17]
	v_mfma_f32_16x16x32_bf16 v[58:61], v[174:177], v[190:193], v[58:61]
	v_mfma_f32_16x16x32_bf16 v[62:65], v[182:185], v[190:193], v[62:65]
	v_mfma_f32_16x16x32_bf16 v[42:45], v[174:177], v[198:201], v[42:45]
	v_mfma_f32_16x16x32_bf16 v[46:49], v[182:185], v[198:201], v[46:49]
	v_mfma_f32_16x16x32_bf16 v[26:29], v[174:177], v[206:209], v[26:29]
	v_mfma_f32_16x16x32_bf16 v[30:33], v[182:185], v[206:209], v[30:33]
	v_mfma_f32_16x16x32_bf16 v[10:13], v[174:177], v[214:217], v[10:13]
	v_mfma_f32_16x16x32_bf16 v[14:17], v[182:185], v[214:217], v[14:17]
	s_barrier
; #define PG8_WAIT_V(n) asm volatile("s_waitcnt vmcnt(" #n ")" ::: "memory")
; template <class Epi, class Sched, bool ALIGN_EPI = true, bool SP2 = true, bool FULLLINE = false, bool NOSTAGE = false, bool FP8 = false>
; __device__ __forceinline__ void gemm_phase(PG8_LAS unsigned char* lds, const Gemm g, const Sched& S, const Epi& E) {
;     ...
;         static_assert(SP2, "only the SP2 loop is kept");
;         { const int t = 0; if constexpr (Epi::NST == 16) PG8_ITER(PG8_WAIT_V(24)); else if constexpr (Epi::NST == 8) PG8_ITER(PG8_WAIT_V(16)); else PG8_ITER(PG8_WAIT_V(8)); }
;         for (int t = 2; t < nt; t += 2) PG8_ITER(PG8_WAIT_V(8));
	ds_read_b128 v[130:133], v159
	ds_read_b128 v[134:137], v159 offset:1024
	ds_read_b128 v[150:153], v159 offset:2048
	ds_read_b128 v[166:169], v159 offset:3072
	ds_read_b128 v[170:173], v160
	ds_read_b128 v[174:177], v160 offset:1024
	ds_read_b128 v[178:181], v160 offset:2048
	ds_read_b128 v[182:185], v160 offset:3072
	s_mov_b32 m0, s91
	v_lshl_add_u64 v[218:219], v[154:155], 0, s[60:61]
	ds_read_b128 v[186:189], v158 offset:32768
	ds_read_b128 v[190:193], v158 offset:33792
	ds_read_b128 v[194:197], v158 offset:34816
	ds_read_b128 v[198:201], v158 offset:35840
	ds_read_b128 v[202:205], v158 offset:36864
	ds_read_b128 v[206:209], v158 offset:37888
	ds_read_b128 v[210:213], v158 offset:38912
	ds_read_b128 v[214:217], v158 offset:39936
	global_load_lds_dwordx4 v[218:219], off
	v_lshl_add_u64 v[218:219], v[154:155], 0, s[66:67]
	s_mov_b32 m0, s92
	s_nop 0
	global_load_lds_dwordx4 v[218:219], off
	s_waitcnt vmcnt(8)
	s_waitcnt lgkmcnt(0)
	s_barrier
	v_mfma_f32_16x16x32_bf16 v[118:121], v[130:133], v[186:189], v[118:121]
	v_mfma_f32_16x16x32_bf16 v[114:117], v[150:153], v[186:189], v[114:117]
	v_mfma_f32_16x16x32_bf16 v[102:105], v[130:133], v[194:197], v[102:105]
	v_mfma_f32_16x16x32_bf16 v[98:101], v[150:153], v[194:197], v[98:101]
	v_mfma_f32_16x16x32_bf16 v[86:89], v[130:133], v[202:205], v[86:89]
	v_mfma_f32_16x16x32_bf16 v[82:85], v[150:153], v[202:205], v[82:85]
	v_mfma_f32_16x16x32_bf16 v[66:69], v[130:133], v[210:213], v[66:69]
	v_mfma_f32_16x16x32_bf16 v[70:73], v[150:153], v[210:213], v[70:73]
	v_mfma_f32_16x16x32_bf16 v[118:121], v[134:137], v[190:193], v[118:121]
	v_mfma_f32_16x16x32_bf16 v[114:117], v[166:169], v[190:193], v[114:117]
	v_mfma_f32_16x16x32_bf16 v[102:105], v[134:137], v[198:201], v[102:105]
	v_mfma_f32_16x16x32_bf16 v[98:101], v[166:169], v[198:201], v[98:101]
	v_mfma_f32_16x16x32_bf16 v[86:89], v[134:137], v[206:209], v[86:89]
	v_mfma_f32_16x16x32_bf16 v[82:85], v[166:169], v[206:209], v[82:85]
	v_mfma_f32_16x16x32_bf16 v[66:69], v[134:137], v[214:217], v[66:69]
	v_mfma_f32_16x16x32_bf16 v[70:73], v[166:169], v[214:217], v[70:73]
	v_mfma_f32_16x16x32_bf16 v[126:129], v[170:173], v[186:189], v[126:129]
	v_mfma_f32_16x16x32_bf16 v[122:125], v[178:181], v[186:189], v[122:125]
	v_mfma_f32_16x16x32_bf16 v[110:113], v[170:173], v[194:197], v[110:113]
	v_mfma_f32_16x16x32_bf16 v[106:109], v[178:181], v[194:197], v[106:109]
	v_mfma_f32_16x16x32_bf16 v[94:97], v[170:173], v[202:205], v[94:97]
	v_mfma_f32_16x16x32_bf16 v[90:93], v[178:181], v[202:205], v[90:93]
	v_mfma_f32_16x16x32_bf16 v[74:77], v[170:173], v[210:213], v[74:77]
	v_mfma_f32_16x16x32_bf16 v[78:81], v[178:181], v[210:213], v[78:81]
	v_mfma_f32_16x16x32_bf16 v[126:129], v[174:177], v[190:193], v[126:129]
	v_mfma_f32_16x16x32_bf16 v[122:125], v[182:185], v[190:193], v[122:125]
	v_mfma_f32_16x16x32_bf16 v[110:113], v[174:177], v[198:201], v[110:113]
	v_mfma_f32_16x16x32_bf16 v[106:109], v[182:185], v[198:201], v[106:109]
	v_mfma_f32_16x16x32_bf16 v[94:97], v[174:177], v[206:209], v[94:97]
	v_mfma_f32_16x16x32_bf16 v[90:93], v[182:185], v[206:209], v[90:93]
	v_mfma_f32_16x16x32_bf16 v[74:77], v[174:177], v[214:217], v[74:77]
	v_mfma_f32_16x16x32_bf16 v[78:81], v[182:185], v[214:217], v[78:81]
	s_barrier
	s_mov_b32 m0, s41
	v_lshl_add_u64 v[218:219], v[138:139], 0, s[68:69]
	ds_read_b128 v[186:189], v158 offset:49152
	ds_read_b128 v[190:193], v158 offset:50176
	ds_read_b128 v[194:197], v158 offset:51200
	ds_read_b128 v[198:201], v158 offset:52224
	ds_read_b128 v[202:205], v158 offset:53248
	ds_read_b128 v[206:209], v158 offset:54272
	ds_read_b128 v[210:213], v158 offset:55296
	ds_read_b128 v[214:217], v158 offset:56320
	global_load_lds_dwordx4 v[218:219], off
	v_lshl_add_u64 v[218:219], v[138:139], 0, s[70:71]
	s_mov_b32 m0, s50
	s_nop 0
	global_load_lds_dwordx4 v[218:219], off
	v_lshl_add_u64 v[218:219], v[138:139], 0, s[20:21]
	s_mov_b32 m0, s51
	v_lshl_add_u64 v[138:139], v[138:139], 0, s[22:23]
	global_load_lds_dwordx4 v[218:219], off
	s_mov_b32 m0, s33
	s_nop 0
	global_load_lds_dwordx4 v[138:139], off
	v_lshl_add_u64 v[138:139], v[154:155], 0, s[68:69]
	s_mov_b32 m0, s93
	s_nop 0
	global_load_lds_dwordx4 v[138:139], off
	v_lshl_add_u64 v[138:139], v[154:155], 0, s[70:71]
	s_mov_b32 m0, s94
	s_nop 0
	global_load_lds_dwordx4 v[138:139], off
	s_waitcnt vmcnt(8)
	s_waitcnt lgkmcnt(0)
	s_barrier
	v_mfma_f32_16x16x32_bf16 v[50:53], v[130:133], v[186:189], v[50:53]
	v_mfma_f32_16x16x32_bf16 v[54:57], v[150:153], v[186:189], v[54:57]
	v_mfma_f32_16x16x32_bf16 v[34:37], v[130:133], v[194:197], v[34:37]
	v_mfma_f32_16x16x32_bf16 v[38:41], v[150:153], v[194:197], v[38:41]
	v_mfma_f32_16x16x32_bf16 v[18:21], v[130:133], v[202:205], v[18:21]
	v_mfma_f32_16x16x32_bf16 v[22:25], v[150:153], v[202:205], v[22:25]
	v_mfma_f32_16x16x32_bf16 v[2:5], v[130:133], v[210:213], v[2:5]
	v_mfma_f32_16x16x32_bf16 v[6:9], v[150:153], v[210:213], v[6:9]
	v_mfma_f32_16x16x32_bf16 v[50:53], v[134:137], v[190:193], v[50:53]
	v_mfma_f32_16x16x32_bf16 v[54:57], v[166:169], v[190:193], v[54:57]
	v_mfma_f32_16x16x32_bf16 v[34:37], v[134:137], v[198:201], v[34:37]
	v_mfma_f32_16x16x32_bf16 v[38:41], v[166:169], v[198:201], v[38:41]
	v_mfma_f32_16x16x32_bf16 v[18:21], v[134:137], v[206:209], v[18:21]
	v_mfma_f32_16x16x32_bf16 v[22:25], v[166:169], v[206:209], v[22:25]
	v_mfma_f32_16x16x32_bf16 v[2:5], v[134:137], v[214:217], v[2:5]
	v_mfma_f32_16x16x32_bf16 v[6:9], v[166:169], v[214:217], v[6:9]
	v_mfma_f32_16x16x32_bf16 v[58:61], v[170:173], v[186:189], v[58:61]
	v_mfma_f32_16x16x32_bf16 v[62:65], v[178:181], v[186:189], v[62:65]
	v_mfma_f32_16x16x32_bf16 v[42:45], v[170:173], v[194:197], v[42:45]
	v_mfma_f32_16x16x32_bf16 v[46:49], v[178:181], v[194:197], v[46:49]
	v_mfma_f32_16x16x32_bf16 v[26:29], v[170:173], v[202:205], v[26:29]
	v_mfma_f32_16x16x32_bf16 v[30:33], v[178:181], v[202:205], v[30:33]
	v_mfma_f32_16x16x32_bf16 v[10:13], v[170:173], v[210:213], v[10:13]
	v_mfma_f32_16x16x32_bf16 v[14:17], v[178:181], v[210:213], v[14:17]
	v_mfma_f32_16x16x32_bf16 v[58:61], v[174:177], v[190:193], v[58:61]
	v_mfma_f32_16x16x32_bf16 v[62:65], v[182:185], v[190:193], v[62:65]
	v_mfma_f32_16x16x32_bf16 v[42:45], v[174:177], v[198:201], v[42:45]
	v_mfma_f32_16x16x32_bf16 v[46:49], v[182:185], v[198:201], v[46:49]
	v_mfma_f32_16x16x32_bf16 v[26:29], v[174:177], v[206:209], v[26:29]
	v_mfma_f32_16x16x32_bf16 v[30:33], v[182:185], v[206:209], v[30:33]
	v_mfma_f32_16x16x32_bf16 v[10:13], v[174:177], v[214:217], v[10:13]
	v_mfma_f32_16x16x32_bf16 v[14:17], v[182:185], v[214:217], v[14:17]
	s_barrier
	s_add_i32 s75, s75, 2
	s_add_u32 s82, s82, 0x100
	s_addc_u32 s83, s83, 0
	s_add_u32 s56, s56, 0x100
	s_addc_u32 s57, s57, 0
	s_cmp_gt_u32 s75, 29
	s_cbranch_scc0 .LBB0_262
	s_and_b64 vcc, exec, s[18:19]
	s_cbranch_vccz .LBB0_265
	s_barrier

; template <class Epi, class Sched, bool ALIGN_EPI = true, bool SP2 = true, bool FULLLINE = false, bool NOSTAGE = false, bool FP8 = false>
; __device__ __forceinline__ void gemm_phase(PG8_LAS unsigned char* lds, const Gemm g, const Sched& S, const Epi& E) {
;     ...
;         const bool has_next = S.next(ui + 1, nxt);
;         const char* nA = has_next ? PG8_ABASE(nxt) : cA; const char* nB = has_next ? PG8_BBASE(nxt) : cB;
.LBB0_593:
	s_ashr_i32 s69, s68, 31
	s_lshl_b64 s[40:41], s[68:69], 21
	s_add_u32 s70, s42, s40
	ds_read_b128 v[2:5], v160
	ds_read_b128 v[6:9], v160 offset:1024
	ds_read_b128 v[10:13], v160 offset:2048
	ds_read_b128 v[14:17], v160 offset:3072
	ds_read_b128 v[18:21], v161
	ds_read_b128 v[22:25], v161 offset:1024
	ds_read_b128 v[26:29], v161 offset:2048
	ds_read_b128 v[30:33], v161 offset:3072
	s_addc_u32 s71, s43, s41
	s_ashr_i32 s67, s66, 31
	s_lshl_b64 s[40:41], s[66:67], 21
	s_add_u32 s72, s44, s40
	s_addc_u32 s73, s45, s41
	s_and_b64 s[40:41], s[8:9], exec
	s_cselect_b32 s67, s71, s79
	s_cselect_b32 s69, s70, s78
	s_cselect_b32 s92, s73, s77
	s_cselect_b32 s93, s72, s76
	v_lshl_add_u64 v[246:247], s[78:79], 0, v[146:147]
	s_mov_b32 m0, s88
	v_lshl_add_u64 v[66:67], v[246:247], 0, s[12:13]
	ds_read_b128 v[34:37], v162
	ds_read_b128 v[38:41], v162 offset:1024
	ds_read_b128 v[42:45], v162 offset:2048
	ds_read_b128 v[46:49], v162 offset:3072
	ds_read_b128 v[50:53], v162 offset:4096
	ds_read_b128 v[54:57], v162 offset:5120
	ds_read_b128 v[58:61], v162 offset:6144
	ds_read_b128 v[62:65], v162 offset:7168
	global_load_lds_dwordx4 v[66:67], off
	v_lshl_add_u64 v[66:67], v[246:247], 0, s[14:15]
	s_mov_b32 m0, s89
	s_nop 0
	global_load_lds_dwordx4 v[66:67], off
	s_waitcnt vmcnt(24)
	s_waitcnt lgkmcnt(0)
	s_barrier
	v_mfma_f32_16x16x32_bf16 v[66:69], v[2:5], v[34:37], 0
	v_mfma_f32_16x16x32_bf16 v[70:73], v[10:13], v[34:37], 0
	v_mfma_f32_16x16x32_bf16 v[74:77], v[2:5], v[42:45], 0
	v_mfma_f32_16x16x32_bf16 v[78:81], v[10:13], v[42:45], 0
	v_mfma_f32_16x16x32_bf16 v[82:85], v[2:5], v[50:53], 0
	v_mfma_f32_16x16x32_bf16 v[86:89], v[10:13], v[50:53], 0
	v_mfma_f32_16x16x32_bf16 v[90:93], v[2:5], v[58:61], 0
	v_mfma_f32_16x16x32_bf16 v[94:97], v[10:13], v[58:61], 0
	v_mfma_f32_16x16x32_bf16 v[66:69], v[6:9], v[38:41], v[66:69]
	v_mfma_f32_16x16x32_bf16 v[70:73], v[14:17], v[38:41], v[70:73]
	v_mfma_f32_16x16x32_bf16 v[74:77], v[6:9], v[46:49], v[74:77]
	v_mfma_f32_16x16x32_bf16 v[78:81], v[14:17], v[46:49], v[78:81]
	v_mfma_f32_16x16x32_bf16 v[82:85], v[6:9], v[54:57], v[82:85]
	v_mfma_f32_16x16x32_bf16 v[86:89], v[14:17], v[54:57], v[86:89]
	v_mfma_f32_16x16x32_bf16 v[90:93], v[6:9], v[62:65], v[90:93]
	v_mfma_f32_16x16x32_bf16 v[94:97], v[14:17], v[62:65], v[94:97]
	v_mfma_f32_16x16x32_bf16 v[98:101], v[18:21], v[34:37], 0
	v_mfma_f32_16x16x32_bf16 v[34:37], v[26:29], v[34:37], 0
	v_mfma_f32_16x16x32_bf16 v[106:109], v[22:25], v[38:41], v[98:101]
	v_mfma_f32_16x16x32_bf16 v[34:37], v[30:33], v[38:41], v[34:37]
	v_mfma_f32_16x16x32_bf16 v[38:41], v[18:21], v[42:45], 0
	v_mfma_f32_16x16x32_bf16 v[42:45], v[26:29], v[42:45], 0
	v_mfma_f32_16x16x32_bf16 v[38:41], v[22:25], v[46:49], v[38:41]
	v_mfma_f32_16x16x32_bf16 v[42:45], v[30:33], v[46:49], v[42:45]
	v_mfma_f32_16x16x32_bf16 v[46:49], v[18:21], v[50:53], 0
	v_mfma_f32_16x16x32_bf16 v[50:53], v[26:29], v[50:53], 0
	v_mfma_f32_16x16x32_bf16 v[46:49], v[22:25], v[54:57], v[46:49]
	v_mfma_f32_16x16x32_bf16 v[50:53], v[30:33], v[54:57], v[50:53]
	v_mfma_f32_16x16x32_bf16 v[54:57], v[18:21], v[58:61], 0
	v_mfma_f32_16x16x32_bf16 v[58:61], v[26:29], v[58:61], 0
	v_mfma_f32_16x16x32_bf16 v[54:57], v[22:25], v[62:65], v[54:57]
	v_mfma_f32_16x16x32_bf16 v[58:61], v[30:33], v[62:65], v[58:61]
	s_barrier
	v_lshl_add_u64 v[248:249], s[76:77], 0, v[148:149]
	s_add_i32 s94, s85, s46
	v_lshl_add_u64 v[130:131], v[248:249], 0, s[16:17]
	s_mov_b32 m0, s94
	s_add_i32 s95, s94, 0x2000
	ds_read_b128 v[62:65], v162 offset:16384
	ds_read_b128 v[98:101], v162 offset:17408
	ds_read_b128 v[102:105], v162 offset:18432
	ds_read_b128 v[110:113], v162 offset:19456
	ds_read_b128 v[114:117], v162 offset:20480
	ds_read_b128 v[118:121], v162 offset:21504
	ds_read_b128 v[122:125], v162 offset:22528
	ds_read_b128 v[126:129], v162 offset:23552
	global_load_lds_dwordx4 v[130:131], off
	v_lshl_add_u64 v[130:131], v[248:249], 0, s[18:19]
	s_mov_b32 m0, s95
	s_add_i32 s96, s87, s46
	global_load_lds_dwordx4 v[130:131], off
	v_lshl_add_u64 v[130:131], v[248:249], 0, s[20:21]
	s_mov_b32 m0, s96
	s_add_i32 s40, s96, 0x2000
	global_load_lds_dwordx4 v[130:131], off
	v_lshl_add_u64 v[130:131], v[248:249], 0, s[22:23]
	s_mov_b32 m0, s40
	s_nop 0
	global_load_lds_dwordx4 v[130:131], off
	v_lshl_add_u64 v[130:131], v[246:247], 0, s[16:17]
	s_mov_b32 m0, s47
	s_nop 0
	global_load_lds_dwordx4 v[130:131], off
	v_lshl_add_u64 v[130:131], v[246:247], 0, s[18:19]
	s_mov_b32 m0, s52
	s_nop 0
	global_load_lds_dwordx4 v[130:131], off
	s_waitcnt vmcnt(24)
	s_waitcnt lgkmcnt(0)
	s_barrier
	v_mfma_f32_16x16x32_bf16 v[130:133], v[2:5], v[62:65], 0
	v_mfma_f32_16x16x32_bf16 v[156:159], v[6:9], v[98:101], v[130:133]
	v_mfma_f32_16x16x32_bf16 v[130:133], v[10:13], v[62:65], 0
	v_mfma_f32_16x16x32_bf16 v[166:169], v[14:17], v[98:101], v[130:133]
	v_mfma_f32_16x16x32_bf16 v[130:133], v[2:5], v[102:105], 0
	v_mfma_f32_16x16x32_bf16 v[170:173], v[6:9], v[110:113], v[130:133]
	v_mfma_f32_16x16x32_bf16 v[130:133], v[10:13], v[102:105], 0
	v_mfma_f32_16x16x32_bf16 v[174:177], v[14:17], v[110:113], v[130:133]
	v_mfma_f32_16x16x32_bf16 v[130:133], v[2:5], v[114:117], 0
	v_mfma_f32_16x16x32_bf16 v[2:5], v[2:5], v[122:125], 0
	v_mfma_f32_16x16x32_bf16 v[178:181], v[6:9], v[118:121], v[130:133]
	v_mfma_f32_16x16x32_bf16 v[2:5], v[6:9], v[126:129], v[2:5]
	v_mfma_f32_16x16x32_bf16 v[6:9], v[10:13], v[122:125], 0
	v_mfma_f32_16x16x32_bf16 v[130:133], v[10:13], v[114:117], 0
	v_mfma_f32_16x16x32_bf16 v[6:9], v[14:17], v[126:129], v[6:9]
	v_mfma_f32_16x16x32_bf16 v[182:185], v[14:17], v[118:121], v[130:133]
	v_mfma_f32_16x16x32_bf16 v[10:13], v[18:21], v[62:65], 0
	v_mfma_f32_16x16x32_bf16 v[186:189], v[22:25], v[98:101], v[10:13]
	v_mfma_f32_16x16x32_bf16 v[10:13], v[26:29], v[62:65], 0
	v_mfma_f32_16x16x32_bf16 v[62:65], v[30:33], v[98:101], v[10:13]
	v_mfma_f32_16x16x32_bf16 v[10:13], v[18:21], v[102:105], 0
	v_mfma_f32_16x16x32_bf16 v[190:193], v[22:25], v[110:113], v[10:13]
	v_mfma_f32_16x16x32_bf16 v[10:13], v[26:29], v[102:105], 0
	v_mfma_f32_16x16x32_bf16 v[194:197], v[30:33], v[110:113], v[10:13]
	v_mfma_f32_16x16x32_bf16 v[10:13], v[18:21], v[114:117], 0
	v_mfma_f32_16x16x32_bf16 v[198:201], v[22:25], v[118:121], v[10:13]
	v_mfma_f32_16x16x32_bf16 v[10:13], v[26:29], v[114:117], 0
	v_mfma_f32_16x16x32_bf16 v[202:205], v[30:33], v[118:121], v[10:13]
	v_mfma_f32_16x16x32_bf16 v[10:13], v[18:21], v[122:125], 0
	v_mfma_f32_16x16x32_bf16 v[206:209], v[22:25], v[126:129], v[10:13]
	v_mfma_f32_16x16x32_bf16 v[10:13], v[26:29], v[122:125], 0
	v_mfma_f32_16x16x32_bf16 v[210:213], v[30:33], v[126:129], v[10:13]
	s_barrier
; #define PG8_WAIT_V(n) asm volatile("s_waitcnt vmcnt(" #n ")" ::: "memory")
; template <class Epi, class Sched, bool ALIGN_EPI = true, bool SP2 = true, bool FULLLINE = false, bool NOSTAGE = false, bool FP8 = false>
; __device__ __forceinline__ void gemm_phase(PG8_LAS unsigned char* lds, const Gemm g, const Sched& S, const Epi& E) {
;     ...
;         static_assert(SP2, "only the SP2 loop is kept");
;         { const int t = 0; if constexpr (Epi::NST == 16) PG8_ITER(PG8_WAIT_V(24)); else if constexpr (Epi::NST == 8) PG8_ITER(PG8_WAIT_V(16)); else PG8_ITER(PG8_WAIT_V(8)); }
;         for (int t = 2; t < nt; t += 2) PG8_ITER(PG8_WAIT_V(8));
	s_nop 5
	ds_read_b128 v[10:13], v163
	ds_read_b128 v[14:17], v163 offset:1024
	ds_read_b128 v[26:29], v163 offset:2048
	ds_read_b128 v[30:33], v163 offset:3072
	ds_read_b128 v[214:217], v164
	ds_read_b128 v[218:221], v164 offset:1024
	ds_read_b128 v[222:225], v164 offset:2048
	ds_read_b128 v[226:229], v164 offset:3072
	s_mov_b32 m0, s53
	v_lshl_add_u64 v[98:99], v[246:247], 0, s[20:21]
	ds_read_b128 v[18:21], v162 offset:32768
	ds_read_b128 v[22:25], v162 offset:33792
	ds_read_b128 v[110:113], v162 offset:34816
	ds_read_b128 v[122:125], v162 offset:35840
	ds_read_b128 v[230:233], v162 offset:36864
	ds_read_b128 v[234:237], v162 offset:37888
	ds_read_b128 v[238:241], v162 offset:38912
	ds_read_b128 v[242:245], v162 offset:39936
	global_load_lds_dwordx4 v[98:99], off
	v_lshl_add_u64 v[98:99], v[246:247], 0, s[22:23]
	s_mov_b32 m0, s54
	s_nop 0
	global_load_lds_dwordx4 v[98:99], off
	s_waitcnt vmcnt(8)
	s_waitcnt lgkmcnt(0)
	s_barrier
	v_mfma_f32_16x16x32_bf16 v[66:69], v[10:13], v[18:21], v[66:69]
	v_mfma_f32_16x16x32_bf16 v[142:145], v[14:17], v[22:25], v[66:69]
	v_mfma_f32_16x16x32_bf16 v[66:69], v[26:29], v[18:21], v[70:73]
	v_mfma_f32_16x16x32_bf16 v[138:141], v[30:33], v[22:25], v[66:69]
	v_mfma_f32_16x16x32_bf16 v[66:69], v[10:13], v[110:113], v[74:77]
	v_mfma_f32_16x16x32_bf16 v[118:121], v[14:17], v[122:125], v[66:69]
	v_mfma_f32_16x16x32_bf16 v[66:69], v[26:29], v[110:113], v[78:81]
	v_mfma_f32_16x16x32_bf16 v[114:117], v[30:33], v[122:125], v[66:69]
	v_mfma_f32_16x16x32_bf16 v[66:69], v[10:13], v[230:233], v[82:85]
	v_mfma_f32_16x16x32_bf16 v[102:105], v[14:17], v[234:237], v[66:69]
	v_mfma_f32_16x16x32_bf16 v[66:69], v[26:29], v[230:233], v[86:89]
	v_mfma_f32_16x16x32_bf16 v[98:101], v[30:33], v[234:237], v[66:69]
	v_mfma_f32_16x16x32_bf16 v[66:69], v[10:13], v[238:241], v[90:93]
	v_mfma_f32_16x16x32_bf16 v[86:89], v[14:17], v[242:245], v[66:69]
	v_mfma_f32_16x16x32_bf16 v[66:69], v[26:29], v[238:241], v[94:97]
	v_mfma_f32_16x16x32_bf16 v[82:85], v[30:33], v[242:245], v[66:69]
	v_mfma_f32_16x16x32_bf16 v[66:69], v[214:217], v[18:21], v[106:109]
	v_mfma_f32_16x16x32_bf16 v[18:21], v[222:225], v[18:21], v[34:37]
	v_mfma_f32_16x16x32_bf16 v[130:133], v[226:229], v[22:25], v[18:21]
	v_mfma_f32_16x16x32_bf16 v[18:21], v[214:217], v[110:113], v[38:41]
	v_mfma_f32_16x16x32_bf16 v[126:129], v[218:221], v[122:125], v[18:21]
	v_mfma_f32_16x16x32_bf16 v[18:21], v[222:225], v[110:113], v[42:45]
	v_mfma_f32_16x16x32_bf16 v[122:125], v[226:229], v[122:125], v[18:21]
	v_mfma_f32_16x16x32_bf16 v[18:21], v[214:217], v[230:233], v[46:49]
	v_mfma_f32_16x16x32_bf16 v[110:113], v[218:221], v[234:237], v[18:21]
	v_mfma_f32_16x16x32_bf16 v[18:21], v[222:225], v[230:233], v[50:53]
	v_mfma_f32_16x16x32_bf16 v[106:109], v[226:229], v[234:237], v[18:21]
	v_mfma_f32_16x16x32_bf16 v[18:21], v[214:217], v[238:241], v[54:57]
	v_mfma_f32_16x16x32_bf16 v[94:97], v[218:221], v[242:245], v[18:21]
	v_mfma_f32_16x16x32_bf16 v[18:21], v[222:225], v[238:241], v[58:61]
	v_mfma_f32_16x16x32_bf16 v[134:137], v[218:221], v[22:25], v[66:69]
	v_mfma_f32_16x16x32_bf16 v[90:93], v[226:229], v[242:245], v[18:21]
	s_barrier
	s_add_i32 s41, s90, s46
	s_nop 3
	v_lshl_add_u64 v[18:19], v[248:249], 0, s[24:25]
	s_mov_b32 m0, s41
	s_add_i32 s50, s41, 0x2000
	ds_read_b128 v[34:37], v162 offset:49152
	ds_read_b128 v[38:41], v162 offset:50176
	ds_read_b128 v[42:45], v162 offset:51200
	ds_read_b128 v[46:49], v162 offset:52224
	ds_read_b128 v[230:233], v162 offset:53248
	ds_read_b128 v[234:237], v162 offset:54272
	ds_read_b128 v[238:241], v162 offset:55296
	ds_read_b128 v[242:245], v162 offset:56320
	global_load_lds_dwordx4 v[18:19], off
	v_lshl_add_u64 v[18:19], v[248:249], 0, s[26:27]
	s_mov_b32 m0, s50
	s_mov_b64 s[56:57], 0x100180
	s_add_i32 s51, s91, s46
	global_load_lds_dwordx4 v[18:19], off
	v_lshl_add_u64 v[18:19], v[248:249], 0, s[56:57]
	s_mov_b32 m0, s51
	s_mov_b64 s[56:57], 0x180180
	s_add_i32 s33, s51, 0x2000
	global_load_lds_dwordx4 v[18:19], off
	v_lshl_add_u64 v[18:19], v[248:249], 0, s[56:57]
	s_mov_b32 m0, s33
	s_nop 0
	global_load_lds_dwordx4 v[18:19], off
	v_lshl_add_u64 v[18:19], v[246:247], 0, s[24:25]
	s_mov_b32 m0, s55
	s_nop 0
	global_load_lds_dwordx4 v[18:19], off
	v_lshl_add_u64 v[18:19], v[246:247], 0, s[26:27]
	s_mov_b32 m0, s62
	s_nop 0
	global_load_lds_dwordx4 v[18:19], off
	s_waitcnt vmcnt(8)
	s_waitcnt lgkmcnt(0)
	s_barrier
	v_mfma_f32_16x16x32_bf16 v[18:21], v[10:13], v[34:37], v[156:159]
	v_mfma_f32_16x16x32_bf16 v[70:73], v[14:17], v[38:41], v[18:21]
	v_mfma_f32_16x16x32_bf16 v[18:21], v[26:29], v[34:37], v[166:169]
	v_mfma_f32_16x16x32_bf16 v[66:69], v[30:33], v[38:41], v[18:21]
	v_mfma_f32_16x16x32_bf16 v[18:21], v[10:13], v[42:45], v[170:173]
	v_mfma_f32_16x16x32_bf16 v[54:57], v[14:17], v[46:49], v[18:21]
	v_mfma_f32_16x16x32_bf16 v[18:21], v[26:29], v[42:45], v[174:177]
	v_mfma_f32_16x16x32_bf16 v[50:53], v[30:33], v[46:49], v[18:21]
	v_mfma_f32_16x16x32_bf16 v[18:21], v[10:13], v[230:233], v[178:181]
	v_mfma_f32_16x16x32_bf16 v[2:5], v[10:13], v[238:241], v[2:5]
	v_mfma_f32_16x16x32_bf16 v[22:25], v[14:17], v[234:237], v[18:21]
	v_mfma_f32_16x16x32_bf16 v[18:21], v[26:29], v[230:233], v[182:185]
	v_mfma_f32_16x16x32_bf16 v[14:17], v[14:17], v[242:245], v[2:5]
	v_mfma_f32_16x16x32_bf16 v[2:5], v[26:29], v[238:241], v[6:9]
	v_mfma_f32_16x16x32_bf16 v[18:21], v[30:33], v[234:237], v[18:21]
	v_mfma_f32_16x16x32_bf16 v[10:13], v[30:33], v[242:245], v[2:5]
	v_mfma_f32_16x16x32_bf16 v[2:5], v[214:217], v[34:37], v[186:189]
	v_mfma_f32_16x16x32_bf16 v[78:81], v[218:221], v[38:41], v[2:5]
	v_mfma_f32_16x16x32_bf16 v[2:5], v[222:225], v[34:37], v[62:65]
	v_mfma_f32_16x16x32_bf16 v[74:77], v[226:229], v[38:41], v[2:5]
	v_mfma_f32_16x16x32_bf16 v[2:5], v[214:217], v[42:45], v[190:193]
	v_mfma_f32_16x16x32_bf16 v[62:65], v[218:221], v[46:49], v[2:5]
	v_mfma_f32_16x16x32_bf16 v[2:5], v[222:225], v[42:45], v[194:197]
	v_mfma_f32_16x16x32_bf16 v[58:61], v[226:229], v[46:49], v[2:5]
	v_mfma_f32_16x16x32_bf16 v[2:5], v[214:217], v[230:233], v[198:201]
	v_mfma_f32_16x16x32_bf16 v[30:33], v[218:221], v[234:237], v[2:5]
	v_mfma_f32_16x16x32_bf16 v[2:5], v[222:225], v[230:233], v[202:205]
	v_mfma_f32_16x16x32_bf16 v[26:29], v[226:229], v[234:237], v[2:5]
	v_mfma_f32_16x16x32_bf16 v[2:5], v[214:217], v[238:241], v[206:209]
	v_mfma_f32_16x16x32_bf16 v[6:9], v[218:221], v[242:245], v[2:5]
	v_mfma_f32_16x16x32_bf16 v[2:5], v[222:225], v[238:241], v[210:213]
	v_mfma_f32_16x16x32_bf16 v[2:5], v[226:229], v[242:245], v[2:5]
	s_barrier
	s_add_u32 s78, s78, 0x100180
	s_addc_u32 s79, s79, 0
	s_add_u32 s56, s76, 0x200
	s_addc_u32 s57, s77, 0
	s_mov_b32 s76, 0
.LBB0_594:
	ds_read_b128 v[34:37], v160
	ds_read_b128 v[38:41], v160 offset:1024
	ds_read_b128 v[42:45], v160 offset:2048
	ds_read_b128 v[46:49], v160 offset:3072
	ds_read_b128 v[156:159], v161
	ds_read_b128 v[166:169], v161 offset:1024
	ds_read_b128 v[170:173], v161 offset:2048
	ds_read_b128 v[174:177], v161 offset:3072
	s_add_u32 s0, s78, 0xfff00080
	s_addc_u32 s1, s79, -1
	s_cmp_eq_u32 s76, 60
	s_cselect_b32 vcc_hi, s67, s1
	s_cselect_b32 vcc_lo, s69, s0
	s_cselect_b32 s65, s92, s57
	s_cselect_b32 s64, s93, s56
	s_mov_b32 m0, s88
	v_lshl_add_u64 v[210:211], s[78:79], 0, v[150:151]
	ds_read_b128 v[178:181], v162
	ds_read_b128 v[182:185], v162 offset:1024
	ds_read_b128 v[186:189], v162 offset:2048
	ds_read_b128 v[190:193], v162 offset:3072
	ds_read_b128 v[194:197], v162 offset:4096
	ds_read_b128 v[198:201], v162 offset:5120
	ds_read_b128 v[202:205], v162 offset:6144
	ds_read_b128 v[206:209], v162 offset:7168
	global_load_lds_dwordx4 v[210:211], off
	v_lshl_add_u64 v[210:211], v[210:211], 0, s[28:29]
	s_mov_b32 m0, s89
	s_nop 0
	global_load_lds_dwordx4 v[210:211], off
	s_waitcnt vmcnt(8)
	s_waitcnt lgkmcnt(0)
	s_barrier
	v_mfma_f32_16x16x32_bf16 v[142:145], v[34:37], v[178:181], v[142:145]
	v_mfma_f32_16x16x32_bf16 v[138:141], v[42:45], v[178:181], v[138:141]
	v_mfma_f32_16x16x32_bf16 v[118:121], v[34:37], v[186:189], v[118:121]
	v_mfma_f32_16x16x32_bf16 v[114:117], v[42:45], v[186:189], v[114:117]
	v_mfma_f32_16x16x32_bf16 v[102:105], v[34:37], v[194:197], v[102:105]
	v_mfma_f32_16x16x32_bf16 v[98:101], v[42:45], v[194:197], v[98:101]
	v_mfma_f32_16x16x32_bf16 v[86:89], v[34:37], v[202:205], v[86:89]
	v_mfma_f32_16x16x32_bf16 v[82:85], v[42:45], v[202:205], v[82:85]
	v_mfma_f32_16x16x32_bf16 v[142:145], v[38:41], v[182:185], v[142:145]
	v_mfma_f32_16x16x32_bf16 v[138:141], v[46:49], v[182:185], v[138:141]
	v_mfma_f32_16x16x32_bf16 v[118:121], v[38:41], v[190:193], v[118:121]
	v_mfma_f32_16x16x32_bf16 v[114:117], v[46:49], v[190:193], v[114:117]
	v_mfma_f32_16x16x32_bf16 v[102:105], v[38:41], v[198:201], v[102:105]
	v_mfma_f32_16x16x32_bf16 v[98:101], v[46:49], v[198:201], v[98:101]
	v_mfma_f32_16x16x32_bf16 v[86:89], v[38:41], v[206:209], v[86:89]
	v_mfma_f32_16x16x32_bf16 v[82:85], v[46:49], v[206:209], v[82:85]
	v_mfma_f32_16x16x32_bf16 v[134:137], v[156:159], v[178:181], v[134:137]
	v_mfma_f32_16x16x32_bf16 v[130:133], v[170:173], v[178:181], v[130:133]
	v_mfma_f32_16x16x32_bf16 v[126:129], v[156:159], v[186:189], v[126:129]
	v_mfma_f32_16x16x32_bf16 v[122:125], v[170:173], v[186:189], v[122:125]
	v_mfma_f32_16x16x32_bf16 v[110:113], v[156:159], v[194:197], v[110:113]
	v_mfma_f32_16x16x32_bf16 v[106:109], v[170:173], v[194:197], v[106:109]
	v_mfma_f32_16x16x32_bf16 v[94:97], v[156:159], v[202:205], v[94:97]
	v_mfma_f32_16x16x32_bf16 v[90:93], v[170:173], v[202:205], v[90:93]
	v_mfma_f32_16x16x32_bf16 v[134:137], v[166:169], v[182:185], v[134:137]
	v_mfma_f32_16x16x32_bf16 v[130:133], v[174:177], v[182:185], v[130:133]
	v_mfma_f32_16x16x32_bf16 v[126:129], v[166:169], v[190:193], v[126:129]
	v_mfma_f32_16x16x32_bf16 v[122:125], v[174:177], v[190:193], v[122:125]
	v_mfma_f32_16x16x32_bf16 v[110:113], v[166:169], v[198:201], v[110:113]
	v_mfma_f32_16x16x32_bf16 v[106:109], v[174:177], v[198:201], v[106:109]
	v_mfma_f32_16x16x32_bf16 v[94:97], v[166:169], v[206:209], v[94:97]
	v_mfma_f32_16x16x32_bf16 v[90:93], v[174:177], v[206:209], v[90:93]
	s_barrier
	s_mov_b32 m0, s94
	v_lshl_add_u64 v[210:211], s[64:65], 0, v[148:149]
	ds_read_b128 v[178:181], v162 offset:16384
	ds_read_b128 v[182:185], v162 offset:17408
	ds_read_b128 v[186:189], v162 offset:18432
	ds_read_b128 v[190:193], v162 offset:19456
	ds_read_b128 v[194:197], v162 offset:20480
	ds_read_b128 v[198:201], v162 offset:21504
	ds_read_b128 v[202:205], v162 offset:22528
	ds_read_b128 v[206:209], v162 offset:23552
	global_load_lds_dwordx4 v[210:211], off
	v_lshl_add_u64 v[212:213], v[210:211], 0, s[28:29]
	s_mov_b32 m0, s95
	s_nop 0
	global_load_lds_dwordx4 v[212:213], off
	v_lshl_add_u64 v[212:213], v[210:211], 0, s[30:31]
	s_mov_b32 m0, s96
	s_nop 0
	global_load_lds_dwordx4 v[212:213], off
	v_lshl_add_u64 v[212:213], v[210:211], 0, s[34:35]
	s_mov_b32 m0, s40
	s_nop 0
	global_load_lds_dwordx4 v[212:213], off
	v_lshl_add_u64 v[212:213], vcc, 0, v[146:147]
	s_mov_b32 m0, s47
	v_lshl_add_u64 v[214:215], v[212:213], 0, s[28:29]
	global_load_lds_dwordx4 v[212:213], off
	s_mov_b32 m0, s52
	s_nop 0
	global_load_lds_dwordx4 v[214:215], off
	s_waitcnt vmcnt(8)
	s_waitcnt lgkmcnt(0)
	s_barrier
	v_mfma_f32_16x16x32_bf16 v[70:73], v[34:37], v[178:181], v[70:73]
	v_mfma_f32_16x16x32_bf16 v[66:69], v[42:45], v[178:181], v[66:69]
	v_mfma_f32_16x16x32_bf16 v[54:57], v[34:37], v[186:189], v[54:57]
	v_mfma_f32_16x16x32_bf16 v[50:53], v[42:45], v[186:189], v[50:53]
	v_mfma_f32_16x16x32_bf16 v[22:25], v[34:37], v[194:197], v[22:25]
	v_mfma_f32_16x16x32_bf16 v[18:21], v[42:45], v[194:197], v[18:21]
	v_mfma_f32_16x16x32_bf16 v[14:17], v[34:37], v[202:205], v[14:17]
	v_mfma_f32_16x16x32_bf16 v[10:13], v[42:45], v[202:205], v[10:13]
	v_mfma_f32_16x16x32_bf16 v[70:73], v[38:41], v[182:185], v[70:73]
	v_mfma_f32_16x16x32_bf16 v[66:69], v[46:49], v[182:185], v[66:69]
	v_mfma_f32_16x16x32_bf16 v[54:57], v[38:41], v[190:193], v[54:57]
	v_mfma_f32_16x16x32_bf16 v[50:53], v[46:49], v[190:193], v[50:53]
	v_mfma_f32_16x16x32_bf16 v[22:25], v[38:41], v[198:201], v[22:25]
	v_mfma_f32_16x16x32_bf16 v[18:21], v[46:49], v[198:201], v[18:21]
	v_mfma_f32_16x16x32_bf16 v[14:17], v[38:41], v[206:209], v[14:17]
	v_mfma_f32_16x16x32_bf16 v[10:13], v[46:49], v[206:209], v[10:13]
	v_mfma_f32_16x16x32_bf16 v[30:33], v[156:159], v[194:197], v[30:33]
	v_mfma_f32_16x16x32_bf16 v[26:29], v[170:173], v[194:197], v[26:29]
	v_mfma_f32_16x16x32_bf16 v[6:9], v[156:159], v[202:205], v[6:9]
	v_mfma_f32_16x16x32_bf16 v[2:5], v[170:173], v[202:205], v[2:5]
	v_mfma_f32_16x16x32_bf16 v[34:37], v[156:159], v[178:181], v[78:81]
	v_mfma_f32_16x16x32_bf16 v[38:41], v[170:173], v[178:181], v[74:77]
	v_mfma_f32_16x16x32_bf16 v[42:45], v[156:159], v[186:189], v[62:65]
	v_mfma_f32_16x16x32_bf16 v[46:49], v[170:173], v[186:189], v[58:61]
	v_mfma_f32_16x16x32_bf16 v[30:33], v[166:169], v[198:201], v[30:33]
	v_mfma_f32_16x16x32_bf16 v[26:29], v[174:177], v[198:201], v[26:29]
	v_mfma_f32_16x16x32_bf16 v[6:9], v[166:169], v[206:209], v[6:9]
	v_mfma_f32_16x16x32_bf16 v[2:5], v[174:177], v[206:209], v[2:5]
	v_mfma_f32_16x16x32_bf16 v[34:37], v[166:169], v[182:185], v[34:37]
	v_mfma_f32_16x16x32_bf16 v[38:41], v[174:177], v[182:185], v[38:41]
	v_mfma_f32_16x16x32_bf16 v[42:45], v[166:169], v[190:193], v[42:45]
	v_mfma_f32_16x16x32_bf16 v[46:49], v[174:177], v[190:193], v[46:49]
	s_barrier
; #define PG8_WAIT_V(n) asm volatile("s_waitcnt vmcnt(" #n ")" ::: "memory")
; template <class Epi, class Sched, bool ALIGN_EPI = true, bool SP2 = true, bool FULLLINE = false, bool NOSTAGE = false, bool FP8 = false>
; __device__ __forceinline__ void gemm_phase(PG8_LAS unsigned char* lds, const Gemm g, const Sched& S, const Epi& E) {
;     ...
;         static_assert(SP2, "only the SP2 loop is kept");
;         { const int t = 0; if constexpr (Epi::NST == 16) PG8_ITER(PG8_WAIT_V(24)); else if constexpr (Epi::NST == 8) PG8_ITER(PG8_WAIT_V(16)); else PG8_ITER(PG8_WAIT_V(8)); }
;         for (int t = 2; t < nt; t += 2) PG8_ITER(PG8_WAIT_V(8));
	ds_read_b128 v[58:61], v163
	ds_read_b128 v[62:65], v163 offset:1024
	ds_read_b128 v[74:77], v163 offset:2048
	ds_read_b128 v[78:81], v163 offset:3072
	ds_read_b128 v[156:159], v164
	ds_read_b128 v[166:169], v164 offset:1024
	ds_read_b128 v[170:173], v164 offset:2048
	ds_read_b128 v[174:177], v164 offset:3072
	s_mov_b32 m0, s53
	v_lshl_add_u64 v[214:215], v[212:213], 0, s[30:31]
	ds_read_b128 v[178:181], v162 offset:32768
	ds_read_b128 v[182:185], v162 offset:33792
	ds_read_b128 v[186:189], v162 offset:34816
	ds_read_b128 v[190:193], v162 offset:35840
	ds_read_b128 v[194:197], v162 offset:36864
	ds_read_b128 v[198:201], v162 offset:37888
	ds_read_b128 v[202:205], v162 offset:38912
	ds_read_b128 v[206:209], v162 offset:39936
	global_load_lds_dwordx4 v[214:215], off
	v_lshl_add_u64 v[214:215], v[212:213], 0, s[34:35]
	s_mov_b32 m0, s54
	s_nop 0
	global_load_lds_dwordx4 v[214:215], off
	s_waitcnt vmcnt(8)
	s_waitcnt lgkmcnt(0)
	s_barrier
	v_mfma_f32_16x16x32_bf16 v[142:145], v[58:61], v[178:181], v[142:145]
	v_mfma_f32_16x16x32_bf16 v[138:141], v[74:77], v[178:181], v[138:141]
	v_mfma_f32_16x16x32_bf16 v[118:121], v[58:61], v[186:189], v[118:121]
	v_mfma_f32_16x16x32_bf16 v[114:117], v[74:77], v[186:189], v[114:117]
	v_mfma_f32_16x16x32_bf16 v[102:105], v[58:61], v[194:197], v[102:105]
	v_mfma_f32_16x16x32_bf16 v[98:101], v[74:77], v[194:197], v[98:101]
	v_mfma_f32_16x16x32_bf16 v[86:89], v[58:61], v[202:205], v[86:89]
	v_mfma_f32_16x16x32_bf16 v[82:85], v[74:77], v[202:205], v[82:85]
	v_mfma_f32_16x16x32_bf16 v[142:145], v[62:65], v[182:185], v[142:145]
	v_mfma_f32_16x16x32_bf16 v[138:141], v[78:81], v[182:185], v[138:141]
	v_mfma_f32_16x16x32_bf16 v[118:121], v[62:65], v[190:193], v[118:121]
	v_mfma_f32_16x16x32_bf16 v[114:117], v[78:81], v[190:193], v[114:117]
	v_mfma_f32_16x16x32_bf16 v[102:105], v[62:65], v[198:201], v[102:105]
	v_mfma_f32_16x16x32_bf16 v[98:101], v[78:81], v[198:201], v[98:101]
	v_mfma_f32_16x16x32_bf16 v[86:89], v[62:65], v[206:209], v[86:89]
	v_mfma_f32_16x16x32_bf16 v[82:85], v[78:81], v[206:209], v[82:85]
	v_mfma_f32_16x16x32_bf16 v[134:137], v[156:159], v[178:181], v[134:137]
	v_mfma_f32_16x16x32_bf16 v[130:133], v[170:173], v[178:181], v[130:133]
	v_mfma_f32_16x16x32_bf16 v[126:129], v[156:159], v[186:189], v[126:129]
	v_mfma_f32_16x16x32_bf16 v[122:125], v[170:173], v[186:189], v[122:125]
	v_mfma_f32_16x16x32_bf16 v[110:113], v[156:159], v[194:197], v[110:113]
	v_mfma_f32_16x16x32_bf16 v[106:109], v[170:173], v[194:197], v[106:109]
	v_mfma_f32_16x16x32_bf16 v[94:97], v[156:159], v[202:205], v[94:97]
	v_mfma_f32_16x16x32_bf16 v[90:93], v[170:173], v[202:205], v[90:93]
	v_mfma_f32_16x16x32_bf16 v[134:137], v[166:169], v[182:185], v[134:137]
	v_mfma_f32_16x16x32_bf16 v[130:133], v[174:177], v[182:185], v[130:133]
	v_mfma_f32_16x16x32_bf16 v[126:129], v[166:169], v[190:193], v[126:129]
	v_mfma_f32_16x16x32_bf16 v[122:125], v[174:177], v[190:193], v[122:125]
	v_mfma_f32_16x16x32_bf16 v[110:113], v[166:169], v[198:201], v[110:113]
	v_mfma_f32_16x16x32_bf16 v[106:109], v[174:177], v[198:201], v[106:109]
	v_mfma_f32_16x16x32_bf16 v[94:97], v[166:169], v[206:209], v[94:97]
	v_mfma_f32_16x16x32_bf16 v[90:93], v[174:177], v[206:209], v[90:93]
	s_barrier
	s_mov_b32 m0, s41
	v_lshl_add_u64 v[214:215], v[210:211], 0, s[36:37]
	ds_read_b128 v[178:181], v162 offset:49152
	ds_read_b128 v[182:185], v162 offset:50176
	ds_read_b128 v[186:189], v162 offset:51200
	ds_read_b128 v[190:193], v162 offset:52224
	ds_read_b128 v[194:197], v162 offset:53248
	ds_read_b128 v[198:201], v162 offset:54272
	ds_read_b128 v[202:205], v162 offset:55296
	ds_read_b128 v[206:209], v162 offset:56320
	global_load_lds_dwordx4 v[214:215], off
	v_lshl_add_u64 v[214:215], v[210:211], 0, s[38:39]
	s_mov_b32 m0, s50
	s_nop 0
	global_load_lds_dwordx4 v[214:215], off
	v_lshl_add_u64 v[214:215], v[210:211], 0, s[12:13]
	s_mov_b32 m0, s51
	v_lshl_add_u64 v[210:211], v[210:211], 0, s[14:15]
	global_load_lds_dwordx4 v[214:215], off
	s_mov_b32 m0, s33
	s_nop 0
	global_load_lds_dwordx4 v[210:211], off
	v_lshl_add_u64 v[210:211], v[212:213], 0, s[36:37]
	s_mov_b32 m0, s55
	s_nop 0
	global_load_lds_dwordx4 v[210:211], off
	v_lshl_add_u64 v[210:211], v[212:213], 0, s[38:39]
	s_mov_b32 m0, s62
	s_nop 0
	global_load_lds_dwordx4 v[210:211], off
	s_waitcnt vmcnt(8)
	s_waitcnt lgkmcnt(0)
	s_barrier
	v_mfma_f32_16x16x32_bf16 v[70:73], v[58:61], v[178:181], v[70:73]
	v_mfma_f32_16x16x32_bf16 v[66:69], v[74:77], v[178:181], v[66:69]
	v_mfma_f32_16x16x32_bf16 v[54:57], v[58:61], v[186:189], v[54:57]
	v_mfma_f32_16x16x32_bf16 v[50:53], v[74:77], v[186:189], v[50:53]
	v_mfma_f32_16x16x32_bf16 v[22:25], v[58:61], v[194:197], v[22:25]
	v_mfma_f32_16x16x32_bf16 v[18:21], v[74:77], v[194:197], v[18:21]
	v_mfma_f32_16x16x32_bf16 v[14:17], v[58:61], v[202:205], v[14:17]
	v_mfma_f32_16x16x32_bf16 v[10:13], v[74:77], v[202:205], v[10:13]
	v_mfma_f32_16x16x32_bf16 v[70:73], v[62:65], v[182:185], v[70:73]
	v_mfma_f32_16x16x32_bf16 v[66:69], v[78:81], v[182:185], v[66:69]
	v_mfma_f32_16x16x32_bf16 v[54:57], v[62:65], v[190:193], v[54:57]
	v_mfma_f32_16x16x32_bf16 v[50:53], v[78:81], v[190:193], v[50:53]
	v_mfma_f32_16x16x32_bf16 v[22:25], v[62:65], v[198:201], v[22:25]
	v_mfma_f32_16x16x32_bf16 v[18:21], v[78:81], v[198:201], v[18:21]
	v_mfma_f32_16x16x32_bf16 v[14:17], v[62:65], v[206:209], v[14:17]
	v_mfma_f32_16x16x32_bf16 v[10:13], v[78:81], v[206:209], v[10:13]
	v_mfma_f32_16x16x32_bf16 v[34:37], v[156:159], v[178:181], v[34:37]
	v_mfma_f32_16x16x32_bf16 v[78:81], v[166:169], v[182:185], v[34:37]
	v_mfma_f32_16x16x32_bf16 v[34:37], v[170:173], v[178:181], v[38:41]
	v_mfma_f32_16x16x32_bf16 v[74:77], v[174:177], v[182:185], v[34:37]
	v_mfma_f32_16x16x32_bf16 v[34:37], v[156:159], v[186:189], v[42:45]
	v_mfma_f32_16x16x32_bf16 v[62:65], v[166:169], v[190:193], v[34:37]
	v_mfma_f32_16x16x32_bf16 v[34:37], v[170:173], v[186:189], v[46:49]
	v_mfma_f32_16x16x32_bf16 v[30:33], v[156:159], v[194:197], v[30:33]
	v_mfma_f32_16x16x32_bf16 v[26:29], v[170:173], v[194:197], v[26:29]
	v_mfma_f32_16x16x32_bf16 v[6:9], v[156:159], v[202:205], v[6:9]
	v_mfma_f32_16x16x32_bf16 v[2:5], v[170:173], v[202:205], v[2:5]
	v_mfma_f32_16x16x32_bf16 v[58:61], v[174:177], v[190:193], v[34:37]
	v_mfma_f32_16x16x32_bf16 v[30:33], v[166:169], v[198:201], v[30:33]
	v_mfma_f32_16x16x32_bf16 v[26:29], v[174:177], v[198:201], v[26:29]
	v_mfma_f32_16x16x32_bf16 v[6:9], v[166:169], v[206:209], v[6:9]
	v_mfma_f32_16x16x32_bf16 v[2:5], v[174:177], v[206:209], v[2:5]
	s_barrier
	s_add_i32 s76, s76, 2
	s_add_u32 s78, s78, 0x100
	s_addc_u32 s79, s79, 0
	s_add_u32 s56, s56, 0x100
	s_addc_u32 s57, s57, 0
	s_cmp_gt_u32 s76, 61
	s_cbranch_scc0 .LBB0_594
	s_and_b64 vcc, exec, s[10:11]
	s_cbranch_vccz .LBB0_597
	s_barrier

; template <class Epi, class Sched, bool ALIGN_EPI = true, bool SP2 = true, bool FULLLINE = false, bool NOSTAGE = false, bool FP8 = false>
; __device__ __forceinline__ void gemm_phase(PG8_LAS unsigned char* lds, const Gemm g, const Sched& S, const Epi& E) {
;     ...
;         const bool has_next = S.next(ui + 1, nxt);
;         const char* nA = has_next ? PG8_ABASE(nxt) : cA; const char* nB = has_next ? PG8_BBASE(nxt) : cB;
.LBB0_766:
	s_ashr_i32 s69, s68, 31
	s_lshl_b64 s[40:41], s[68:69], 20
	s_add_u32 s70, s58, s40
	ds_read_b128 v[2:5], v1
	ds_read_b128 v[6:9], v1 offset:1024
	ds_read_b128 v[10:13], v1 offset:2048
	ds_read_b128 v[14:17], v1 offset:3072
	ds_read_b128 v[18:21], v142
	ds_read_b128 v[22:25], v142 offset:1024
	ds_read_b128 v[26:29], v142 offset:2048
	ds_read_b128 v[30:33], v142 offset:3072
	s_addc_u32 s71, s59, s41
	s_ashr_i32 s67, s66, 31
	s_lshl_b64 s[40:41], s[66:67], 20
	s_add_u32 s72, s3, s40
	s_addc_u32 s73, s42, s41
	s_and_b64 s[40:41], s[8:9], exec
	s_cselect_b32 s67, s71, s79
	s_cselect_b32 s69, s70, s78
	s_cselect_b32 s89, s73, s77
	s_cselect_b32 s90, s72, s76
	v_lshl_add_u64 v[140:141], s[78:79], 0, v[132:133]
	s_mov_b32 m0, s81
	v_lshl_add_u64 v[66:67], v[140:141], 0, s[12:13]
	ds_read_b128 v[34:37], v143
	ds_read_b128 v[38:41], v143 offset:1024
	ds_read_b128 v[42:45], v143 offset:2048
	ds_read_b128 v[46:49], v143 offset:3072
	ds_read_b128 v[50:53], v143 offset:4096
	ds_read_b128 v[54:57], v143 offset:5120
	ds_read_b128 v[58:61], v143 offset:6144
	ds_read_b128 v[62:65], v143 offset:7168
	global_load_lds_dwordx4 v[66:67], off
	v_lshl_add_u64 v[66:67], v[140:141], 0, s[14:15]
	s_mov_b32 m0, s82
	s_nop 0
	global_load_lds_dwordx4 v[66:67], off
	s_waitcnt vmcnt(16)
	s_waitcnt lgkmcnt(0)
	s_barrier
	v_mfma_f32_16x16x32_bf16 v[86:89], v[10:13], v[50:53], 0
	v_mfma_f32_16x16x32_bf16 v[90:93], v[14:17], v[54:57], v[86:89]
	v_mfma_f32_16x16x32_bf16 v[86:89], v[2:5], v[58:61], 0
	v_mfma_f32_16x16x32_bf16 v[66:69], v[2:5], v[34:37], 0
	v_mfma_f32_16x16x32_bf16 v[70:73], v[10:13], v[34:37], 0
	v_mfma_f32_16x16x32_bf16 v[74:77], v[2:5], v[42:45], 0
	v_mfma_f32_16x16x32_bf16 v[78:81], v[10:13], v[42:45], 0
	v_mfma_f32_16x16x32_bf16 v[82:85], v[2:5], v[50:53], 0
	v_mfma_f32_16x16x32_bf16 v[94:97], v[6:9], v[62:65], v[86:89]
	v_mfma_f32_16x16x32_bf16 v[86:89], v[10:13], v[58:61], 0
	v_mfma_f32_16x16x32_bf16 v[66:69], v[6:9], v[38:41], v[66:69]
	v_mfma_f32_16x16x32_bf16 v[70:73], v[14:17], v[38:41], v[70:73]
	v_mfma_f32_16x16x32_bf16 v[74:77], v[6:9], v[46:49], v[74:77]
	v_mfma_f32_16x16x32_bf16 v[78:81], v[14:17], v[46:49], v[78:81]
	v_mfma_f32_16x16x32_bf16 v[82:85], v[6:9], v[54:57], v[82:85]
	v_mfma_f32_16x16x32_bf16 v[106:109], v[14:17], v[62:65], v[86:89]
	v_mfma_f32_16x16x32_bf16 v[86:89], v[18:21], v[34:37], 0
	v_mfma_f32_16x16x32_bf16 v[34:37], v[26:29], v[34:37], 0
	v_mfma_f32_16x16x32_bf16 v[110:113], v[22:25], v[38:41], v[86:89]
	v_mfma_f32_16x16x32_bf16 v[34:37], v[30:33], v[38:41], v[34:37]
	v_mfma_f32_16x16x32_bf16 v[38:41], v[18:21], v[42:45], 0
	v_mfma_f32_16x16x32_bf16 v[42:45], v[26:29], v[42:45], 0
	v_mfma_f32_16x16x32_bf16 v[38:41], v[22:25], v[46:49], v[38:41]
	v_mfma_f32_16x16x32_bf16 v[42:45], v[30:33], v[46:49], v[42:45]
	v_mfma_f32_16x16x32_bf16 v[46:49], v[18:21], v[50:53], 0
	v_mfma_f32_16x16x32_bf16 v[50:53], v[26:29], v[50:53], 0
	v_mfma_f32_16x16x32_bf16 v[46:49], v[22:25], v[54:57], v[46:49]
	v_mfma_f32_16x16x32_bf16 v[50:53], v[30:33], v[54:57], v[50:53]
	v_mfma_f32_16x16x32_bf16 v[54:57], v[18:21], v[58:61], 0
	v_mfma_f32_16x16x32_bf16 v[58:61], v[26:29], v[58:61], 0
	v_mfma_f32_16x16x32_bf16 v[54:57], v[22:25], v[62:65], v[54:57]
	v_mfma_f32_16x16x32_bf16 v[58:61], v[30:33], v[62:65], v[58:61]
	s_barrier
	v_lshl_add_u64 v[238:239], s[76:77], 0, v[130:131]
	s_mov_b32 m0, s83
	v_lshl_add_u64 v[146:147], v[238:239], 0, s[16:17]
	s_add_i32 s91, s83, 0x2000
	ds_read_b128 v[62:65], v143 offset:16384
	ds_read_b128 v[86:89], v143 offset:17408
	ds_read_b128 v[98:101], v143 offset:18432
	ds_read_b128 v[102:105], v143 offset:19456
	ds_read_b128 v[114:117], v143 offset:20480
	ds_read_b128 v[118:121], v143 offset:21504
	ds_read_b128 v[122:125], v143 offset:22528
	ds_read_b128 v[126:129], v143 offset:23552
	global_load_lds_dwordx4 v[146:147], off
	v_lshl_add_u64 v[146:147], v[238:239], 0, s[18:19]
	s_mov_b32 m0, s91
	s_add_i32 s92, s80, s43
	global_load_lds_dwordx4 v[146:147], off
	v_lshl_add_u64 v[146:147], v[238:239], 0, s[20:21]
	s_mov_b32 m0, s92
	s_add_i32 s40, s92, 0x2000
	global_load_lds_dwordx4 v[146:147], off
	v_lshl_add_u64 v[146:147], v[238:239], 0, s[22:23]
	s_mov_b32 m0, s40
	s_nop 0
	global_load_lds_dwordx4 v[146:147], off
	v_lshl_add_u64 v[146:147], v[140:141], 0, s[16:17]
	s_mov_b32 m0, s45
	s_nop 0
	global_load_lds_dwordx4 v[146:147], off
	v_lshl_add_u64 v[146:147], v[140:141], 0, s[18:19]
	s_mov_b32 m0, s46
	s_nop 0
	global_load_lds_dwordx4 v[146:147], off
	s_waitcnt vmcnt(16)
	s_waitcnt lgkmcnt(0)
	s_barrier
	v_mfma_f32_16x16x32_bf16 v[146:149], v[2:5], v[62:65], 0
	v_mfma_f32_16x16x32_bf16 v[154:157], v[2:5], v[98:101], 0
	v_mfma_f32_16x16x32_bf16 v[162:165], v[2:5], v[114:117], 0
	v_mfma_f32_16x16x32_bf16 v[2:5], v[2:5], v[122:125], 0
	v_mfma_f32_16x16x32_bf16 v[146:149], v[6:9], v[86:89], v[146:149]
	v_mfma_f32_16x16x32_bf16 v[154:157], v[6:9], v[102:105], v[154:157]
	v_mfma_f32_16x16x32_bf16 v[162:165], v[6:9], v[118:121], v[162:165]
	v_mfma_f32_16x16x32_bf16 v[2:5], v[6:9], v[126:129], v[2:5]
	v_mfma_f32_16x16x32_bf16 v[6:9], v[10:13], v[122:125], 0
	v_mfma_f32_16x16x32_bf16 v[150:153], v[10:13], v[62:65], 0
	v_mfma_f32_16x16x32_bf16 v[158:161], v[10:13], v[98:101], 0
	v_mfma_f32_16x16x32_bf16 v[166:169], v[10:13], v[114:117], 0
	v_mfma_f32_16x16x32_bf16 v[10:13], v[14:17], v[126:129], v[6:9]
	v_mfma_f32_16x16x32_bf16 v[150:153], v[14:17], v[86:89], v[150:153]
	v_mfma_f32_16x16x32_bf16 v[158:161], v[14:17], v[102:105], v[158:161]
	v_mfma_f32_16x16x32_bf16 v[166:169], v[14:17], v[118:121], v[166:169]
	v_mfma_f32_16x16x32_bf16 v[6:9], v[18:21], v[62:65], 0
	v_mfma_f32_16x16x32_bf16 v[14:17], v[22:25], v[86:89], v[6:9]
	v_mfma_f32_16x16x32_bf16 v[6:9], v[26:29], v[62:65], 0
	v_mfma_f32_16x16x32_bf16 v[170:173], v[30:33], v[86:89], v[6:9]
	v_mfma_f32_16x16x32_bf16 v[6:9], v[18:21], v[98:101], 0
	v_mfma_f32_16x16x32_bf16 v[174:177], v[22:25], v[102:105], v[6:9]
	v_mfma_f32_16x16x32_bf16 v[6:9], v[26:29], v[98:101], 0
	v_mfma_f32_16x16x32_bf16 v[178:181], v[30:33], v[102:105], v[6:9]
	v_mfma_f32_16x16x32_bf16 v[6:9], v[18:21], v[114:117], 0
	v_mfma_f32_16x16x32_bf16 v[182:185], v[22:25], v[118:121], v[6:9]
	v_mfma_f32_16x16x32_bf16 v[6:9], v[26:29], v[114:117], 0
	v_mfma_f32_16x16x32_bf16 v[186:189], v[30:33], v[118:121], v[6:9]
	v_mfma_f32_16x16x32_bf16 v[6:9], v[18:21], v[122:125], 0
	v_mfma_f32_16x16x32_bf16 v[190:193], v[22:25], v[126:129], v[6:9]
	v_mfma_f32_16x16x32_bf16 v[6:9], v[26:29], v[122:125], 0
	v_mfma_f32_16x16x32_bf16 v[194:197], v[30:33], v[126:129], v[6:9]
	s_barrier
; #define PG8_WAIT_V(n) asm volatile("s_waitcnt vmcnt(" #n ")" ::: "memory")
; template <class Epi, class Sched, bool ALIGN_EPI = true, bool SP2 = true, bool FULLLINE = false, bool NOSTAGE = false, bool FP8 = false>
; __device__ __forceinline__ void gemm_phase(PG8_LAS unsigned char* lds, const Gemm g, const Sched& S, const Epi& E) {
;     ...
;         static_assert(SP2, "only the SP2 loop is kept");
;         { const int t = 0; if constexpr (Epi::NST == 16) PG8_ITER(PG8_WAIT_V(24)); else if constexpr (Epi::NST == 8) PG8_ITER(PG8_WAIT_V(16)); else PG8_ITER(PG8_WAIT_V(8)); }
;         for (int t = 2; t < nt; t += 2) PG8_ITER(PG8_WAIT_V(8));
	s_nop 5
	ds_read_b128 v[6:9], v144
	ds_read_b128 v[26:29], v144 offset:1024
	ds_read_b128 v[30:33], v144 offset:2048
	ds_read_b128 v[62:65], v144 offset:3072
	ds_read_b128 v[198:201], v145
	ds_read_b128 v[202:205], v145 offset:1024
	ds_read_b128 v[206:209], v145 offset:2048
	ds_read_b128 v[210:213], v145 offset:3072
	s_mov_b32 m0, s47
	v_lshl_add_u64 v[86:87], v[140:141], 0, s[20:21]
	ds_read_b128 v[18:21], v143 offset:32768
	ds_read_b128 v[22:25], v143 offset:33792
	ds_read_b128 v[214:217], v143 offset:34816
	ds_read_b128 v[218:221], v143 offset:35840
	ds_read_b128 v[222:225], v143 offset:36864
	ds_read_b128 v[226:229], v143 offset:37888
	ds_read_b128 v[230:233], v143 offset:38912
	ds_read_b128 v[234:237], v143 offset:39936
	global_load_lds_dwordx4 v[86:87], off
	v_lshl_add_u64 v[86:87], v[140:141], 0, s[22:23]
	s_mov_b32 m0, s52
	s_nop 0
	global_load_lds_dwordx4 v[86:87], off
	s_waitcnt vmcnt(8)
	s_waitcnt lgkmcnt(0)
	s_barrier
	v_mfma_f32_16x16x32_bf16 v[66:69], v[6:9], v[18:21], v[66:69]
	v_mfma_f32_16x16x32_bf16 v[118:121], v[26:29], v[22:25], v[66:69]
	v_mfma_f32_16x16x32_bf16 v[66:69], v[30:33], v[18:21], v[70:73]
	v_mfma_f32_16x16x32_bf16 v[114:117], v[62:65], v[22:25], v[66:69]
	v_mfma_f32_16x16x32_bf16 v[66:69], v[6:9], v[214:217], v[74:77]
	v_mfma_f32_16x16x32_bf16 v[102:105], v[26:29], v[218:221], v[66:69]
	v_mfma_f32_16x16x32_bf16 v[66:69], v[30:33], v[214:217], v[78:81]
	v_mfma_f32_16x16x32_bf16 v[98:101], v[62:65], v[218:221], v[66:69]
	v_mfma_f32_16x16x32_bf16 v[66:69], v[6:9], v[222:225], v[82:85]
	v_mfma_f32_16x16x32_bf16 v[86:89], v[26:29], v[226:229], v[66:69]
	v_mfma_f32_16x16x32_bf16 v[66:69], v[30:33], v[222:225], v[90:93]
	v_mfma_f32_16x16x32_bf16 v[82:85], v[62:65], v[226:229], v[66:69]
	v_mfma_f32_16x16x32_bf16 v[66:69], v[6:9], v[230:233], v[94:97]
	v_mfma_f32_16x16x32_bf16 v[70:73], v[26:29], v[234:237], v[66:69]
	v_mfma_f32_16x16x32_bf16 v[66:69], v[30:33], v[230:233], v[106:109]
	v_mfma_f32_16x16x32_bf16 v[66:69], v[62:65], v[234:237], v[66:69]
	v_mfma_f32_16x16x32_bf16 v[74:77], v[198:201], v[18:21], v[110:113]
	v_mfma_f32_16x16x32_bf16 v[18:21], v[206:209], v[18:21], v[34:37]
	v_mfma_f32_16x16x32_bf16 v[122:125], v[210:213], v[22:25], v[18:21]
	v_mfma_f32_16x16x32_bf16 v[18:21], v[198:201], v[214:217], v[38:41]
	v_mfma_f32_16x16x32_bf16 v[110:113], v[202:205], v[218:221], v[18:21]
	v_mfma_f32_16x16x32_bf16 v[18:21], v[206:209], v[214:217], v[42:45]
	v_mfma_f32_16x16x32_bf16 v[106:109], v[210:213], v[218:221], v[18:21]
	v_mfma_f32_16x16x32_bf16 v[18:21], v[198:201], v[222:225], v[46:49]
	v_mfma_f32_16x16x32_bf16 v[94:97], v[202:205], v[226:229], v[18:21]
	v_mfma_f32_16x16x32_bf16 v[18:21], v[206:209], v[222:225], v[50:53]
	v_mfma_f32_16x16x32_bf16 v[90:93], v[210:213], v[226:229], v[18:21]
	v_mfma_f32_16x16x32_bf16 v[18:21], v[198:201], v[230:233], v[54:57]
	v_mfma_f32_16x16x32_bf16 v[78:81], v[202:205], v[234:237], v[18:21]
	v_mfma_f32_16x16x32_bf16 v[18:21], v[206:209], v[230:233], v[58:61]
	v_mfma_f32_16x16x32_bf16 v[126:129], v[202:205], v[22:25], v[74:77]
	v_mfma_f32_16x16x32_bf16 v[74:77], v[210:213], v[234:237], v[18:21]
	s_barrier
	s_add_i32 s41, s84, s43
	s_nop 3
	v_lshl_add_u64 v[18:19], v[238:239], 0, s[24:25]
	s_mov_b32 m0, s41
	s_add_i32 s50, s41, 0x2000
	ds_read_b128 v[42:45], v143 offset:49152
	ds_read_b128 v[46:49], v143 offset:50176
	ds_read_b128 v[214:217], v143 offset:51200
	ds_read_b128 v[218:221], v143 offset:52224
	ds_read_b128 v[222:225], v143 offset:53248
	ds_read_b128 v[226:229], v143 offset:54272
	ds_read_b128 v[230:233], v143 offset:55296
	ds_read_b128 v[234:237], v143 offset:56320
	global_load_lds_dwordx4 v[18:19], off
	v_lshl_add_u64 v[18:19], v[238:239], 0, s[26:27]
	s_mov_b32 m0, s50
	s_mov_b64 s[56:57], 0x80180
	s_add_i32 s51, s85, s43
	global_load_lds_dwordx4 v[18:19], off
	v_lshl_add_u64 v[18:19], v[238:239], 0, s[56:57]
	s_mov_b32 m0, s51
	s_mov_b64 s[56:57], 0xc0180
	s_add_i32 s33, s51, 0x2000
	global_load_lds_dwordx4 v[18:19], off
	v_lshl_add_u64 v[18:19], v[238:239], 0, s[56:57]
	s_mov_b32 m0, s33
	s_nop 0
	global_load_lds_dwordx4 v[18:19], off
	v_lshl_add_u64 v[18:19], v[140:141], 0, s[24:25]
	s_mov_b32 m0, s53
	s_nop 0
	global_load_lds_dwordx4 v[18:19], off
	v_lshl_add_u64 v[18:19], v[140:141], 0, s[26:27]
	s_mov_b32 m0, s54
	s_nop 0
	global_load_lds_dwordx4 v[18:19], off
	s_waitcnt vmcnt(8)
	s_waitcnt lgkmcnt(0)
	s_barrier
	v_mfma_f32_16x16x32_bf16 v[18:21], v[6:9], v[42:45], v[146:149]
	v_mfma_f32_16x16x32_bf16 v[54:57], v[26:29], v[46:49], v[18:21]
	v_mfma_f32_16x16x32_bf16 v[18:21], v[30:33], v[42:45], v[150:153]
	v_mfma_f32_16x16x32_bf16 v[50:53], v[62:65], v[46:49], v[18:21]
	v_mfma_f32_16x16x32_bf16 v[18:21], v[6:9], v[214:217], v[154:157]
	v_mfma_f32_16x16x32_bf16 v[38:41], v[26:29], v[218:221], v[18:21]
	v_mfma_f32_16x16x32_bf16 v[18:21], v[30:33], v[214:217], v[158:161]
	v_mfma_f32_16x16x32_bf16 v[34:37], v[62:65], v[218:221], v[18:21]
	v_mfma_f32_16x16x32_bf16 v[18:21], v[6:9], v[222:225], v[162:165]
	v_mfma_f32_16x16x32_bf16 v[2:5], v[6:9], v[230:233], v[2:5]
	v_mfma_f32_16x16x32_bf16 v[22:25], v[26:29], v[226:229], v[18:21]
	v_mfma_f32_16x16x32_bf16 v[18:21], v[30:33], v[222:225], v[166:169]
	v_mfma_f32_16x16x32_bf16 v[6:9], v[26:29], v[234:237], v[2:5]
	v_mfma_f32_16x16x32_bf16 v[2:5], v[30:33], v[230:233], v[10:13]
	v_mfma_f32_16x16x32_bf16 v[18:21], v[62:65], v[226:229], v[18:21]
	v_mfma_f32_16x16x32_bf16 v[2:5], v[62:65], v[234:237], v[2:5]
	v_mfma_f32_16x16x32_bf16 v[10:13], v[198:201], v[42:45], v[14:17]
	v_mfma_f32_16x16x32_bf16 v[62:65], v[202:205], v[46:49], v[10:13]
	v_mfma_f32_16x16x32_bf16 v[10:13], v[206:209], v[42:45], v[170:173]
	v_mfma_f32_16x16x32_bf16 v[58:61], v[210:213], v[46:49], v[10:13]
	v_mfma_f32_16x16x32_bf16 v[10:13], v[198:201], v[214:217], v[174:177]
	v_mfma_f32_16x16x32_bf16 v[46:49], v[202:205], v[218:221], v[10:13]
	v_mfma_f32_16x16x32_bf16 v[10:13], v[206:209], v[214:217], v[178:181]
	v_mfma_f32_16x16x32_bf16 v[42:45], v[210:213], v[218:221], v[10:13]
	v_mfma_f32_16x16x32_bf16 v[10:13], v[198:201], v[222:225], v[182:185]
	v_mfma_f32_16x16x32_bf16 v[30:33], v[202:205], v[226:229], v[10:13]
	v_mfma_f32_16x16x32_bf16 v[10:13], v[206:209], v[222:225], v[186:189]
	v_mfma_f32_16x16x32_bf16 v[26:29], v[210:213], v[226:229], v[10:13]
	v_mfma_f32_16x16x32_bf16 v[10:13], v[198:201], v[230:233], v[190:193]
	v_mfma_f32_16x16x32_bf16 v[14:17], v[202:205], v[234:237], v[10:13]
	v_mfma_f32_16x16x32_bf16 v[10:13], v[206:209], v[230:233], v[194:197]
	v_mfma_f32_16x16x32_bf16 v[10:13], v[210:213], v[234:237], v[10:13]
	s_barrier
	s_add_u32 s78, s78, 0x80180
	s_addc_u32 s79, s79, 0
	s_add_u32 s56, s76, 0x200
	s_addc_u32 s57, s77, 0
	s_mov_b32 s76, 0
.LBB0_767:
	ds_read_b128 v[146:149], v1
	ds_read_b128 v[150:153], v1 offset:1024
	ds_read_b128 v[154:157], v1 offset:2048
	ds_read_b128 v[158:161], v1 offset:3072
	ds_read_b128 v[162:165], v142
	ds_read_b128 v[166:169], v142 offset:1024
	ds_read_b128 v[170:173], v142 offset:2048
	ds_read_b128 v[174:177], v142 offset:3072
	s_add_u32 s0, s78, 0xfff80080
	s_addc_u32 s1, s79, -1
	s_cmp_eq_u32 s76, 28
	s_cselect_b32 s95, s67, s1
	s_cselect_b32 s94, s69, s0
	s_cselect_b32 s97, s89, s57
	s_cselect_b32 s96, s90, s56
	s_mov_b32 m0, s81
	v_lshl_add_u64 v[140:141], s[78:79], 0, v[134:135]
	ds_read_b128 v[178:181], v143
	ds_read_b128 v[182:185], v143 offset:1024
	ds_read_b128 v[186:189], v143 offset:2048
	ds_read_b128 v[190:193], v143 offset:3072
	ds_read_b128 v[194:197], v143 offset:4096
	ds_read_b128 v[198:201], v143 offset:5120
	ds_read_b128 v[202:205], v143 offset:6144
	ds_read_b128 v[206:209], v143 offset:7168
	global_load_lds_dwordx4 v[140:141], off
	v_lshl_add_u64 v[140:141], v[140:141], 0, s[28:29]
	s_mov_b32 m0, s82
	s_nop 0
	global_load_lds_dwordx4 v[140:141], off
	s_waitcnt vmcnt(8)
	s_waitcnt lgkmcnt(0)
	s_barrier
	v_mfma_f32_16x16x32_bf16 v[118:121], v[146:149], v[178:181], v[118:121]
	v_mfma_f32_16x16x32_bf16 v[114:117], v[154:157], v[178:181], v[114:117]
	v_mfma_f32_16x16x32_bf16 v[102:105], v[146:149], v[186:189], v[102:105]
	v_mfma_f32_16x16x32_bf16 v[98:101], v[154:157], v[186:189], v[98:101]
	v_mfma_f32_16x16x32_bf16 v[86:89], v[146:149], v[194:197], v[86:89]
	v_mfma_f32_16x16x32_bf16 v[82:85], v[154:157], v[194:197], v[82:85]
	v_mfma_f32_16x16x32_bf16 v[70:73], v[146:149], v[202:205], v[70:73]
	v_mfma_f32_16x16x32_bf16 v[66:69], v[154:157], v[202:205], v[66:69]
	v_mfma_f32_16x16x32_bf16 v[118:121], v[150:153], v[182:185], v[118:121]
	v_mfma_f32_16x16x32_bf16 v[114:117], v[158:161], v[182:185], v[114:117]
	v_mfma_f32_16x16x32_bf16 v[102:105], v[150:153], v[190:193], v[102:105]
	v_mfma_f32_16x16x32_bf16 v[98:101], v[158:161], v[190:193], v[98:101]
	v_mfma_f32_16x16x32_bf16 v[86:89], v[150:153], v[198:201], v[86:89]
	v_mfma_f32_16x16x32_bf16 v[82:85], v[158:161], v[198:201], v[82:85]
	v_mfma_f32_16x16x32_bf16 v[70:73], v[150:153], v[206:209], v[70:73]
	v_mfma_f32_16x16x32_bf16 v[66:69], v[158:161], v[206:209], v[66:69]
	v_mfma_f32_16x16x32_bf16 v[126:129], v[162:165], v[178:181], v[126:129]
	v_mfma_f32_16x16x32_bf16 v[122:125], v[170:173], v[178:181], v[122:125]
	v_mfma_f32_16x16x32_bf16 v[110:113], v[162:165], v[186:189], v[110:113]
	v_mfma_f32_16x16x32_bf16 v[106:109], v[170:173], v[186:189], v[106:109]
	v_mfma_f32_16x16x32_bf16 v[94:97], v[162:165], v[194:197], v[94:97]
	v_mfma_f32_16x16x32_bf16 v[90:93], v[170:173], v[194:197], v[90:93]
	v_mfma_f32_16x16x32_bf16 v[78:81], v[162:165], v[202:205], v[78:81]
	v_mfma_f32_16x16x32_bf16 v[74:77], v[170:173], v[202:205], v[74:77]
	v_mfma_f32_16x16x32_bf16 v[126:129], v[166:169], v[182:185], v[126:129]
	v_mfma_f32_16x16x32_bf16 v[122:125], v[174:177], v[182:185], v[122:125]
	v_mfma_f32_16x16x32_bf16 v[110:113], v[166:169], v[190:193], v[110:113]
	v_mfma_f32_16x16x32_bf16 v[106:109], v[174:177], v[190:193], v[106:109]
	v_mfma_f32_16x16x32_bf16 v[94:97], v[166:169], v[198:201], v[94:97]
	v_mfma_f32_16x16x32_bf16 v[90:93], v[174:177], v[198:201], v[90:93]
	v_mfma_f32_16x16x32_bf16 v[78:81], v[166:169], v[206:209], v[78:81]
	v_mfma_f32_16x16x32_bf16 v[74:77], v[174:177], v[206:209], v[74:77]
	s_barrier
	s_mov_b32 m0, s83
	v_lshl_add_u64 v[140:141], s[96:97], 0, v[130:131]
	ds_read_b128 v[178:181], v143 offset:16384
	ds_read_b128 v[182:185], v143 offset:17408
	ds_read_b128 v[186:189], v143 offset:18432
	ds_read_b128 v[190:193], v143 offset:19456
	ds_read_b128 v[194:197], v143 offset:20480
	ds_read_b128 v[198:201], v143 offset:21504
	ds_read_b128 v[202:205], v143 offset:22528
	ds_read_b128 v[206:209], v143 offset:23552
	global_load_lds_dwordx4 v[140:141], off
	v_lshl_add_u64 v[210:211], v[140:141], 0, s[28:29]
	s_mov_b32 m0, s91
	s_nop 0
	global_load_lds_dwordx4 v[210:211], off
	v_lshl_add_u64 v[210:211], v[140:141], 0, s[30:31]
	s_mov_b32 m0, s92
	s_nop 0
	global_load_lds_dwordx4 v[210:211], off
	v_lshl_add_u64 v[210:211], v[140:141], 0, s[34:35]
	s_mov_b32 m0, s40
	s_nop 0
	global_load_lds_dwordx4 v[210:211], off
	v_lshl_add_u64 v[210:211], s[94:95], 0, v[132:133]
	s_mov_b32 m0, s45
	v_lshl_add_u64 v[212:213], v[210:211], 0, s[28:29]
	global_load_lds_dwordx4 v[210:211], off
	s_mov_b32 m0, s46
	s_nop 0
	global_load_lds_dwordx4 v[212:213], off
	s_waitcnt vmcnt(8)
	s_waitcnt lgkmcnt(0)
	s_barrier
	v_mfma_f32_16x16x32_bf16 v[54:57], v[146:149], v[178:181], v[54:57]
	v_mfma_f32_16x16x32_bf16 v[50:53], v[154:157], v[178:181], v[50:53]
	v_mfma_f32_16x16x32_bf16 v[38:41], v[146:149], v[186:189], v[38:41]
	v_mfma_f32_16x16x32_bf16 v[34:37], v[154:157], v[186:189], v[34:37]
	v_mfma_f32_16x16x32_bf16 v[22:25], v[146:149], v[194:197], v[22:25]
	v_mfma_f32_16x16x32_bf16 v[18:21], v[154:157], v[194:197], v[18:21]
	v_mfma_f32_16x16x32_bf16 v[6:9], v[146:149], v[202:205], v[6:9]
	v_mfma_f32_16x16x32_bf16 v[2:5], v[154:157], v[202:205], v[2:5]
	v_mfma_f32_16x16x32_bf16 v[54:57], v[150:153], v[182:185], v[54:57]
	v_mfma_f32_16x16x32_bf16 v[50:53], v[158:161], v[182:185], v[50:53]
	v_mfma_f32_16x16x32_bf16 v[38:41], v[150:153], v[190:193], v[38:41]
	v_mfma_f32_16x16x32_bf16 v[34:37], v[158:161], v[190:193], v[34:37]
	v_mfma_f32_16x16x32_bf16 v[22:25], v[150:153], v[198:201], v[22:25]
	v_mfma_f32_16x16x32_bf16 v[18:21], v[158:161], v[198:201], v[18:21]
	v_mfma_f32_16x16x32_bf16 v[6:9], v[150:153], v[206:209], v[6:9]
	v_mfma_f32_16x16x32_bf16 v[2:5], v[158:161], v[206:209], v[2:5]
	v_mfma_f32_16x16x32_bf16 v[62:65], v[162:165], v[178:181], v[62:65]
	v_mfma_f32_16x16x32_bf16 v[58:61], v[170:173], v[178:181], v[58:61]
	v_mfma_f32_16x16x32_bf16 v[46:49], v[162:165], v[186:189], v[46:49]
	v_mfma_f32_16x16x32_bf16 v[42:45], v[170:173], v[186:189], v[42:45]
	v_mfma_f32_16x16x32_bf16 v[30:33], v[162:165], v[194:197], v[30:33]
	v_mfma_f32_16x16x32_bf16 v[26:29], v[170:173], v[194:197], v[26:29]
	v_mfma_f32_16x16x32_bf16 v[14:17], v[162:165], v[202:205], v[14:17]
	v_mfma_f32_16x16x32_bf16 v[10:13], v[170:173], v[202:205], v[10:13]
	v_mfma_f32_16x16x32_bf16 v[62:65], v[166:169], v[182:185], v[62:65]
	v_mfma_f32_16x16x32_bf16 v[58:61], v[174:177], v[182:185], v[58:61]
	v_mfma_f32_16x16x32_bf16 v[46:49], v[166:169], v[190:193], v[46:49]
	v_mfma_f32_16x16x32_bf16 v[42:45], v[174:177], v[190:193], v[42:45]
	v_mfma_f32_16x16x32_bf16 v[30:33], v[166:169], v[198:201], v[30:33]
	v_mfma_f32_16x16x32_bf16 v[26:29], v[174:177], v[198:201], v[26:29]
	v_mfma_f32_16x16x32_bf16 v[14:17], v[166:169], v[206:209], v[14:17]
	v_mfma_f32_16x16x32_bf16 v[10:13], v[174:177], v[206:209], v[10:13]
	s_barrier
; #define PG8_WAIT_V(n) asm volatile("s_waitcnt vmcnt(" #n ")" ::: "memory")
; template <class Epi, class Sched, bool ALIGN_EPI = true, bool SP2 = true, bool FULLLINE = false, bool NOSTAGE = false, bool FP8 = false>
; __device__ __forceinline__ void gemm_phase(PG8_LAS unsigned char* lds, const Gemm g, const Sched& S, const Epi& E) {
;     ...
;         static_assert(SP2, "only the SP2 loop is kept");
;         { const int t = 0; if constexpr (Epi::NST == 16) PG8_ITER(PG8_WAIT_V(24)); else if constexpr (Epi::NST == 8) PG8_ITER(PG8_WAIT_V(16)); else PG8_ITER(PG8_WAIT_V(8)); }
;         for (int t = 2; t < nt; t += 2) PG8_ITER(PG8_WAIT_V(8));
	ds_read_b128 v[146:149], v144
	ds_read_b128 v[150:153], v144 offset:1024
	ds_read_b128 v[154:157], v144 offset:2048
	ds_read_b128 v[158:161], v144 offset:3072
	ds_read_b128 v[162:165], v145
	ds_read_b128 v[166:169], v145 offset:1024
	ds_read_b128 v[170:173], v145 offset:2048
	ds_read_b128 v[174:177], v145 offset:3072
	s_mov_b32 m0, s47
	v_lshl_add_u64 v[212:213], v[210:211], 0, s[30:31]
	ds_read_b128 v[178:181], v143 offset:32768
	ds_read_b128 v[182:185], v143 offset:33792
	ds_read_b128 v[186:189], v143 offset:34816
	ds_read_b128 v[190:193], v143 offset:35840
	ds_read_b128 v[194:197], v143 offset:36864
	ds_read_b128 v[198:201], v143 offset:37888
	ds_read_b128 v[202:205], v143 offset:38912
	ds_read_b128 v[206:209], v143 offset:39936
	global_load_lds_dwordx4 v[212:213], off
	v_lshl_add_u64 v[212:213], v[210:211], 0, s[34:35]
	s_mov_b32 m0, s52
	s_nop 0
	global_load_lds_dwordx4 v[212:213], off
	s_waitcnt vmcnt(8)
	s_waitcnt lgkmcnt(0)
	s_barrier
	v_mfma_f32_16x16x32_bf16 v[118:121], v[146:149], v[178:181], v[118:121]
	v_mfma_f32_16x16x32_bf16 v[114:117], v[154:157], v[178:181], v[114:117]
	v_mfma_f32_16x16x32_bf16 v[102:105], v[146:149], v[186:189], v[102:105]
	v_mfma_f32_16x16x32_bf16 v[98:101], v[154:157], v[186:189], v[98:101]
	v_mfma_f32_16x16x32_bf16 v[86:89], v[146:149], v[194:197], v[86:89]
	v_mfma_f32_16x16x32_bf16 v[82:85], v[154:157], v[194:197], v[82:85]
	v_mfma_f32_16x16x32_bf16 v[70:73], v[146:149], v[202:205], v[70:73]
	v_mfma_f32_16x16x32_bf16 v[66:69], v[154:157], v[202:205], v[66:69]
	v_mfma_f32_16x16x32_bf16 v[118:121], v[150:153], v[182:185], v[118:121]
	v_mfma_f32_16x16x32_bf16 v[114:117], v[158:161], v[182:185], v[114:117]
	v_mfma_f32_16x16x32_bf16 v[102:105], v[150:153], v[190:193], v[102:105]
	v_mfma_f32_16x16x32_bf16 v[98:101], v[158:161], v[190:193], v[98:101]
	v_mfma_f32_16x16x32_bf16 v[86:89], v[150:153], v[198:201], v[86:89]
	v_mfma_f32_16x16x32_bf16 v[82:85], v[158:161], v[198:201], v[82:85]
	v_mfma_f32_16x16x32_bf16 v[70:73], v[150:153], v[206:209], v[70:73]
	v_mfma_f32_16x16x32_bf16 v[66:69], v[158:161], v[206:209], v[66:69]
	v_mfma_f32_16x16x32_bf16 v[126:129], v[162:165], v[178:181], v[126:129]
	v_mfma_f32_16x16x32_bf16 v[122:125], v[170:173], v[178:181], v[122:125]
	v_mfma_f32_16x16x32_bf16 v[110:113], v[162:165], v[186:189], v[110:113]
	v_mfma_f32_16x16x32_bf16 v[106:109], v[170:173], v[186:189], v[106:109]
	v_mfma_f32_16x16x32_bf16 v[94:97], v[162:165], v[194:197], v[94:97]
	v_mfma_f32_16x16x32_bf16 v[90:93], v[170:173], v[194:197], v[90:93]
	v_mfma_f32_16x16x32_bf16 v[78:81], v[162:165], v[202:205], v[78:81]
	v_mfma_f32_16x16x32_bf16 v[74:77], v[170:173], v[202:205], v[74:77]
	v_mfma_f32_16x16x32_bf16 v[126:129], v[166:169], v[182:185], v[126:129]
	v_mfma_f32_16x16x32_bf16 v[122:125], v[174:177], v[182:185], v[122:125]
	v_mfma_f32_16x16x32_bf16 v[110:113], v[166:169], v[190:193], v[110:113]
	v_mfma_f32_16x16x32_bf16 v[106:109], v[174:177], v[190:193], v[106:109]
	v_mfma_f32_16x16x32_bf16 v[94:97], v[166:169], v[198:201], v[94:97]
	v_mfma_f32_16x16x32_bf16 v[90:93], v[174:177], v[198:201], v[90:93]
	v_mfma_f32_16x16x32_bf16 v[78:81], v[166:169], v[206:209], v[78:81]
	v_mfma_f32_16x16x32_bf16 v[74:77], v[174:177], v[206:209], v[74:77]
	s_barrier
	s_mov_b32 m0, s41
	v_lshl_add_u64 v[212:213], v[140:141], 0, s[36:37]
	ds_read_b128 v[178:181], v143 offset:49152
	ds_read_b128 v[182:185], v143 offset:50176
	ds_read_b128 v[186:189], v143 offset:51200
	ds_read_b128 v[190:193], v143 offset:52224
	ds_read_b128 v[194:197], v143 offset:53248
	ds_read_b128 v[198:201], v143 offset:54272
	ds_read_b128 v[202:205], v143 offset:55296
	ds_read_b128 v[206:209], v143 offset:56320
	global_load_lds_dwordx4 v[212:213], off
	v_lshl_add_u64 v[212:213], v[140:141], 0, s[38:39]
	s_mov_b32 m0, s50
	s_nop 0
	global_load_lds_dwordx4 v[212:213], off
	v_lshl_add_u64 v[212:213], v[140:141], 0, s[12:13]
	s_mov_b32 m0, s51
	v_lshl_add_u64 v[140:141], v[140:141], 0, s[14:15]
	global_load_lds_dwordx4 v[212:213], off
	s_mov_b32 m0, s33
	s_nop 0
	global_load_lds_dwordx4 v[140:141], off
	v_lshl_add_u64 v[140:141], v[210:211], 0, s[36:37]
	s_mov_b32 m0, s53
	s_nop 0
	global_load_lds_dwordx4 v[140:141], off
	v_lshl_add_u64 v[140:141], v[210:211], 0, s[38:39]
	s_mov_b32 m0, s54
	s_nop 0
	global_load_lds_dwordx4 v[140:141], off
	s_waitcnt vmcnt(8)
	s_waitcnt lgkmcnt(0)
	s_barrier
	v_mfma_f32_16x16x32_bf16 v[54:57], v[146:149], v[178:181], v[54:57]
	v_mfma_f32_16x16x32_bf16 v[50:53], v[154:157], v[178:181], v[50:53]
	v_mfma_f32_16x16x32_bf16 v[38:41], v[146:149], v[186:189], v[38:41]
	v_mfma_f32_16x16x32_bf16 v[34:37], v[154:157], v[186:189], v[34:37]
	v_mfma_f32_16x16x32_bf16 v[22:25], v[146:149], v[194:197], v[22:25]
	v_mfma_f32_16x16x32_bf16 v[18:21], v[154:157], v[194:197], v[18:21]
	v_mfma_f32_16x16x32_bf16 v[6:9], v[146:149], v[202:205], v[6:9]
	v_mfma_f32_16x16x32_bf16 v[2:5], v[154:157], v[202:205], v[2:5]
	v_mfma_f32_16x16x32_bf16 v[54:57], v[150:153], v[182:185], v[54:57]
	v_mfma_f32_16x16x32_bf16 v[50:53], v[158:161], v[182:185], v[50:53]
	v_mfma_f32_16x16x32_bf16 v[38:41], v[150:153], v[190:193], v[38:41]
	v_mfma_f32_16x16x32_bf16 v[34:37], v[158:161], v[190:193], v[34:37]
	v_mfma_f32_16x16x32_bf16 v[22:25], v[150:153], v[198:201], v[22:25]
	v_mfma_f32_16x16x32_bf16 v[18:21], v[158:161], v[198:201], v[18:21]
	v_mfma_f32_16x16x32_bf16 v[6:9], v[150:153], v[206:209], v[6:9]
	v_mfma_f32_16x16x32_bf16 v[2:5], v[158:161], v[206:209], v[2:5]
	v_mfma_f32_16x16x32_bf16 v[62:65], v[162:165], v[178:181], v[62:65]
	v_mfma_f32_16x16x32_bf16 v[58:61], v[170:173], v[178:181], v[58:61]
	v_mfma_f32_16x16x32_bf16 v[46:49], v[162:165], v[186:189], v[46:49]
	v_mfma_f32_16x16x32_bf16 v[42:45], v[170:173], v[186:189], v[42:45]
	v_mfma_f32_16x16x32_bf16 v[30:33], v[162:165], v[194:197], v[30:33]
	v_mfma_f32_16x16x32_bf16 v[26:29], v[170:173], v[194:197], v[26:29]
	v_mfma_f32_16x16x32_bf16 v[14:17], v[162:165], v[202:205], v[14:17]
	v_mfma_f32_16x16x32_bf16 v[10:13], v[170:173], v[202:205], v[10:13]
	v_mfma_f32_16x16x32_bf16 v[62:65], v[166:169], v[182:185], v[62:65]
	v_mfma_f32_16x16x32_bf16 v[58:61], v[174:177], v[182:185], v[58:61]
	v_mfma_f32_16x16x32_bf16 v[46:49], v[166:169], v[190:193], v[46:49]
	v_mfma_f32_16x16x32_bf16 v[42:45], v[174:177], v[190:193], v[42:45]
	v_mfma_f32_16x16x32_bf16 v[30:33], v[166:169], v[198:201], v[30:33]
	v_mfma_f32_16x16x32_bf16 v[26:29], v[174:177], v[198:201], v[26:29]
	v_mfma_f32_16x16x32_bf16 v[14:17], v[166:169], v[206:209], v[14:17]
	v_mfma_f32_16x16x32_bf16 v[10:13], v[174:177], v[206:209], v[10:13]
	s_barrier
	s_add_i32 s76, s76, 2
	s_add_u32 s78, s78, 0x100
	s_addc_u32 s79, s79, 0
	s_add_u32 s56, s56, 0x100
	s_addc_u32 s57, s57, 0
	s_cmp_gt_u32 s76, 29
	s_cbranch_scc0 .LBB0_767
	s_and_b64 vcc, exec, s[10:11]
	s_cbranch_vccz .LBB0_770
	s_barrier

; template <class Epi, class Sched, bool ALIGN_EPI = true, bool SP2 = true, bool FULLLINE = false, bool NOSTAGE = false, bool FP8 = false>
; __device__ __forceinline__ void gemm_phase(PG8_LAS unsigned char* lds, const Gemm g, const Sched& S, const Epi& E) {
;     ...
;         const bool has_next = S.next(ui + 1, nxt);
;         const char* nA = has_next ? PG8_ABASE(nxt) : cA; const char* nB = has_next ? PG8_BBASE(nxt) : cB;
.LBB0_869:
	ds_read_b128 v[2:5], v1
	ds_read_b128 v[6:9], v1 offset:1024
	ds_read_b128 v[10:13], v1 offset:2048
	ds_read_b128 v[14:17], v1 offset:3072
	ds_read_b128 v[18:21], v192
	ds_read_b128 v[22:25], v192 offset:1024
	ds_read_b128 v[26:29], v192 offset:2048
	ds_read_b128 v[30:33], v192 offset:3072
	v_lshl_add_u64 v[248:249], s[70:71], 0, v[170:171]
	s_add_i32 s85, s45, 0xc000
	v_lshl_add_u64 v[66:67], v[248:249], 0, s[14:15]
	s_mov_b32 m0, s85
	s_add_i32 s87, s45, 0xe000
	ds_read_b128 v[34:37], v193
	ds_read_b128 v[38:41], v193 offset:1024
	ds_read_b128 v[42:45], v193 offset:2048
	ds_read_b128 v[46:49], v193 offset:3072
	ds_read_b128 v[50:53], v193 offset:4096
	ds_read_b128 v[54:57], v193 offset:5120
	ds_read_b128 v[58:61], v193 offset:6144
	ds_read_b128 v[62:65], v193 offset:7168
	global_load_lds_dwordx4 v[66:67], off
	v_lshl_add_u64 v[66:67], v[248:249], 0, s[16:17]
	s_mov_b32 m0, s87
	s_nop 0
	global_load_lds_dwordx4 v[66:67], off
	s_waitcnt vmcnt(24)
	s_waitcnt lgkmcnt(0)
	s_barrier
	v_mfma_f32_16x16x32_bf16 v[66:69], v[2:5], v[34:37], 0
	v_mfma_f32_16x16x32_bf16 v[70:73], v[10:13], v[34:37], 0
	v_mfma_f32_16x16x32_bf16 v[78:81], v[10:13], v[42:45], 0
	v_mfma_f32_16x16x32_bf16 v[86:89], v[10:13], v[50:53], 0
	v_mfma_f32_16x16x32_bf16 v[66:69], v[6:9], v[38:41], v[66:69]
	v_mfma_f32_16x16x32_bf16 v[70:73], v[14:17], v[38:41], v[70:73]
	v_mfma_f32_16x16x32_bf16 v[74:77], v[2:5], v[42:45], 0
	v_mfma_f32_16x16x32_bf16 v[78:81], v[14:17], v[46:49], v[78:81]
	v_mfma_f32_16x16x32_bf16 v[82:85], v[2:5], v[50:53], 0
	v_mfma_f32_16x16x32_bf16 v[86:89], v[14:17], v[54:57], v[86:89]
	v_mfma_f32_16x16x32_bf16 v[90:93], v[2:5], v[58:61], 0
	v_mfma_f32_16x16x32_bf16 v[94:97], v[10:13], v[58:61], 0
	v_mfma_f32_16x16x32_bf16 v[74:77], v[6:9], v[46:49], v[74:77]
	v_mfma_f32_16x16x32_bf16 v[82:85], v[6:9], v[54:57], v[82:85]
	v_mfma_f32_16x16x32_bf16 v[90:93], v[6:9], v[62:65], v[90:93]
	v_mfma_f32_16x16x32_bf16 v[94:97], v[14:17], v[62:65], v[94:97]
	v_mfma_f32_16x16x32_bf16 v[98:101], v[18:21], v[34:37], 0
	v_mfma_f32_16x16x32_bf16 v[34:37], v[26:29], v[34:37], 0
	v_mfma_f32_16x16x32_bf16 v[98:101], v[22:25], v[38:41], v[98:101]
	v_mfma_f32_16x16x32_bf16 v[34:37], v[30:33], v[38:41], v[34:37]
	v_mfma_f32_16x16x32_bf16 v[38:41], v[18:21], v[42:45], 0
	v_mfma_f32_16x16x32_bf16 v[42:45], v[26:29], v[42:45], 0
	v_mfma_f32_16x16x32_bf16 v[38:41], v[22:25], v[46:49], v[38:41]
	v_mfma_f32_16x16x32_bf16 v[42:45], v[30:33], v[46:49], v[42:45]
	v_mfma_f32_16x16x32_bf16 v[46:49], v[18:21], v[50:53], 0
	v_mfma_f32_16x16x32_bf16 v[50:53], v[26:29], v[50:53], 0
	v_mfma_f32_16x16x32_bf16 v[46:49], v[22:25], v[54:57], v[46:49]
	v_mfma_f32_16x16x32_bf16 v[50:53], v[30:33], v[54:57], v[50:53]
	v_mfma_f32_16x16x32_bf16 v[54:57], v[18:21], v[58:61], 0
	v_mfma_f32_16x16x32_bf16 v[58:61], v[26:29], v[58:61], 0
	v_mfma_f32_16x16x32_bf16 v[54:57], v[22:25], v[62:65], v[54:57]
	v_mfma_f32_16x16x32_bf16 v[58:61], v[30:33], v[62:65], v[58:61]
	s_barrier
	v_lshl_add_u64 v[250:251], s[72:73], 0, v[172:173]
	s_add_i32 s88, s77, s44
	v_lshl_add_u64 v[130:131], v[250:251], 0, s[18:19]
	s_mov_b32 m0, s88
	s_add_i32 s89, s88, 0x2000
	ds_read_b128 v[62:65], v193 offset:16384
	ds_read_b128 v[102:105], v193 offset:17408
	ds_read_b128 v[106:109], v193 offset:18432
	ds_read_b128 v[110:113], v193 offset:19456
	ds_read_b128 v[114:117], v193 offset:20480
	ds_read_b128 v[118:121], v193 offset:21504
	ds_read_b128 v[122:125], v193 offset:22528
	ds_read_b128 v[126:129], v193 offset:23552
	global_load_lds_dwordx4 v[130:131], off
	v_lshl_add_u64 v[130:131], v[250:251], 0, s[20:21]
	s_mov_b32 m0, s89
	s_add_i32 s90, s78, s44
	global_load_lds_dwordx4 v[130:131], off
	v_lshl_add_u64 v[130:131], v[250:251], 0, s[22:23]
	s_mov_b32 m0, s90
	s_add_i32 s40, s90, 0x2000
	global_load_lds_dwordx4 v[130:131], off
	v_lshl_add_u64 v[130:131], v[250:251], 0, s[24:25]
	s_mov_b32 m0, s40
	s_nop 0
	global_load_lds_dwordx4 v[130:131], off
	v_lshl_add_u64 v[130:131], v[248:249], 0, s[18:19]
	s_mov_b32 m0, s45
	s_nop 0
	global_load_lds_dwordx4 v[130:131], off
	v_lshl_add_u64 v[130:131], v[248:249], 0, s[20:21]
	s_mov_b32 m0, s46
	s_nop 0
	global_load_lds_dwordx4 v[130:131], off
	s_waitcnt vmcnt(24)
	s_waitcnt lgkmcnt(0)
	s_barrier
	v_mfma_f32_16x16x32_bf16 v[130:133], v[2:5], v[62:65], 0
	v_mfma_f32_16x16x32_bf16 v[138:141], v[6:9], v[102:105], v[130:133]
	v_mfma_f32_16x16x32_bf16 v[130:133], v[10:13], v[62:65], 0
	v_mfma_f32_16x16x32_bf16 v[150:153], v[14:17], v[102:105], v[130:133]
	v_mfma_f32_16x16x32_bf16 v[130:133], v[2:5], v[106:109], 0
	v_mfma_f32_16x16x32_bf16 v[154:157], v[6:9], v[110:113], v[130:133]
	v_mfma_f32_16x16x32_bf16 v[130:133], v[10:13], v[106:109], 0
	v_mfma_f32_16x16x32_bf16 v[158:161], v[14:17], v[110:113], v[130:133]
	v_mfma_f32_16x16x32_bf16 v[130:133], v[2:5], v[114:117], 0
	v_mfma_f32_16x16x32_bf16 v[2:5], v[2:5], v[122:125], 0
	v_mfma_f32_16x16x32_bf16 v[162:165], v[6:9], v[118:121], v[130:133]
	v_mfma_f32_16x16x32_bf16 v[2:5], v[6:9], v[126:129], v[2:5]
	v_mfma_f32_16x16x32_bf16 v[6:9], v[10:13], v[122:125], 0
	v_mfma_f32_16x16x32_bf16 v[130:133], v[10:13], v[114:117], 0
	v_mfma_f32_16x16x32_bf16 v[6:9], v[14:17], v[126:129], v[6:9]
	v_mfma_f32_16x16x32_bf16 v[166:169], v[14:17], v[118:121], v[130:133]
	v_mfma_f32_16x16x32_bf16 v[10:13], v[18:21], v[62:65], 0
	v_mfma_f32_16x16x32_bf16 v[180:183], v[22:25], v[102:105], v[10:13]
	v_mfma_f32_16x16x32_bf16 v[10:13], v[26:29], v[62:65], 0
	v_mfma_f32_16x16x32_bf16 v[184:187], v[30:33], v[102:105], v[10:13]
	v_mfma_f32_16x16x32_bf16 v[10:13], v[18:21], v[106:109], 0
	v_mfma_f32_16x16x32_bf16 v[188:191], v[22:25], v[110:113], v[10:13]
	v_mfma_f32_16x16x32_bf16 v[10:13], v[26:29], v[106:109], 0
	v_mfma_f32_16x16x32_bf16 v[196:199], v[30:33], v[110:113], v[10:13]
	v_mfma_f32_16x16x32_bf16 v[10:13], v[18:21], v[114:117], 0
	v_mfma_f32_16x16x32_bf16 v[200:203], v[22:25], v[118:121], v[10:13]
	v_mfma_f32_16x16x32_bf16 v[10:13], v[26:29], v[114:117], 0
	v_mfma_f32_16x16x32_bf16 v[204:207], v[30:33], v[118:121], v[10:13]
	v_mfma_f32_16x16x32_bf16 v[10:13], v[18:21], v[122:125], 0
	v_mfma_f32_16x16x32_bf16 v[208:211], v[22:25], v[126:129], v[10:13]
	v_mfma_f32_16x16x32_bf16 v[10:13], v[26:29], v[122:125], 0
	v_mfma_f32_16x16x32_bf16 v[212:215], v[30:33], v[126:129], v[10:13]
	s_barrier
; #define PG8_WAIT_V(n) asm volatile("s_waitcnt vmcnt(" #n ")" ::: "memory")
; template <class Epi, class Sched, bool ALIGN_EPI = true, bool SP2 = true, bool FULLLINE = false, bool NOSTAGE = false, bool FP8 = false>
; __device__ __forceinline__ void gemm_phase(PG8_LAS unsigned char* lds, const Gemm g, const Sched& S, const Epi& E) {
;     ...
;         static_assert(SP2, "only the SP2 loop is kept");
;         { const int t = 0; if constexpr (Epi::NST == 16) PG8_ITER(PG8_WAIT_V(24)); else if constexpr (Epi::NST == 8) PG8_ITER(PG8_WAIT_V(16)); else PG8_ITER(PG8_WAIT_V(8)); }
;         for (int t = 2; t < nt; t += 2) PG8_ITER(PG8_WAIT_V(8));
	s_nop 5
	ds_read_b128 v[10:13], v194
	ds_read_b128 v[14:17], v194 offset:1024
	ds_read_b128 v[18:21], v194 offset:2048
	ds_read_b128 v[22:25], v194 offset:3072
	ds_read_b128 v[216:219], v195
	ds_read_b128 v[220:223], v195 offset:1024
	ds_read_b128 v[224:227], v195 offset:2048
	ds_read_b128 v[228:231], v195 offset:3072
	s_mov_b32 m0, s47
	v_lshl_add_u64 v[106:107], v[248:249], 0, s[22:23]
	ds_read_b128 v[26:29], v193 offset:32768
	ds_read_b128 v[30:33], v193 offset:33792
	ds_read_b128 v[62:65], v193 offset:34816
	ds_read_b128 v[102:105], v193 offset:35840
	ds_read_b128 v[232:235], v193 offset:36864
	ds_read_b128 v[236:239], v193 offset:37888
	ds_read_b128 v[240:243], v193 offset:38912
	ds_read_b128 v[244:247], v193 offset:39936
	global_load_lds_dwordx4 v[106:107], off
	v_lshl_add_u64 v[106:107], v[248:249], 0, s[24:25]
	s_mov_b32 m0, s52
	s_nop 0
	global_load_lds_dwordx4 v[106:107], off
	s_waitcnt vmcnt(8)
	s_waitcnt lgkmcnt(0)
	s_barrier
	v_mfma_f32_16x16x32_bf16 v[66:69], v[10:13], v[26:29], v[66:69]
	v_mfma_f32_16x16x32_bf16 v[146:149], v[14:17], v[30:33], v[66:69]
	v_mfma_f32_16x16x32_bf16 v[66:69], v[18:21], v[26:29], v[70:73]
	v_mfma_f32_16x16x32_bf16 v[142:145], v[22:25], v[30:33], v[66:69]
	v_mfma_f32_16x16x32_bf16 v[66:69], v[10:13], v[62:65], v[74:77]
	v_mfma_f32_16x16x32_bf16 v[126:129], v[14:17], v[102:105], v[66:69]
	v_mfma_f32_16x16x32_bf16 v[66:69], v[18:21], v[62:65], v[78:81]
	v_mfma_f32_16x16x32_bf16 v[122:125], v[22:25], v[102:105], v[66:69]
	v_mfma_f32_16x16x32_bf16 v[66:69], v[10:13], v[232:235], v[82:85]
	v_mfma_f32_16x16x32_bf16 v[110:113], v[14:17], v[236:239], v[66:69]
	v_mfma_f32_16x16x32_bf16 v[66:69], v[18:21], v[232:235], v[86:89]
	v_mfma_f32_16x16x32_bf16 v[106:109], v[22:25], v[236:239], v[66:69]
	v_mfma_f32_16x16x32_bf16 v[66:69], v[10:13], v[240:243], v[90:93]
	v_mfma_f32_16x16x32_bf16 v[86:89], v[14:17], v[244:247], v[66:69]
	v_mfma_f32_16x16x32_bf16 v[66:69], v[18:21], v[240:243], v[94:97]
	v_mfma_f32_16x16x32_bf16 v[78:81], v[22:25], v[244:247], v[66:69]
	v_mfma_f32_16x16x32_bf16 v[66:69], v[216:219], v[26:29], v[98:101]
	v_mfma_f32_16x16x32_bf16 v[26:29], v[224:227], v[26:29], v[34:37]
	v_mfma_f32_16x16x32_bf16 v[130:133], v[228:231], v[30:33], v[26:29]
	v_mfma_f32_16x16x32_bf16 v[26:29], v[216:219], v[62:65], v[38:41]
	v_mfma_f32_16x16x32_bf16 v[118:121], v[220:223], v[102:105], v[26:29]
	v_mfma_f32_16x16x32_bf16 v[26:29], v[224:227], v[62:65], v[42:45]
	v_mfma_f32_16x16x32_bf16 v[114:117], v[228:231], v[102:105], v[26:29]
	v_mfma_f32_16x16x32_bf16 v[26:29], v[216:219], v[232:235], v[46:49]
	v_mfma_f32_16x16x32_bf16 v[102:105], v[220:223], v[236:239], v[26:29]
	v_mfma_f32_16x16x32_bf16 v[26:29], v[224:227], v[232:235], v[50:53]
	v_mfma_f32_16x16x32_bf16 v[98:101], v[228:231], v[236:239], v[26:29]
	v_mfma_f32_16x16x32_bf16 v[26:29], v[216:219], v[240:243], v[54:57]
	v_mfma_f32_16x16x32_bf16 v[70:73], v[220:223], v[244:247], v[26:29]
	v_mfma_f32_16x16x32_bf16 v[26:29], v[224:227], v[240:243], v[58:61]
	v_mfma_f32_16x16x32_bf16 v[134:137], v[220:223], v[30:33], v[66:69]
	v_mfma_f32_16x16x32_bf16 v[66:69], v[228:231], v[244:247], v[26:29]
	s_barrier
	s_add_i32 s41, s79, s44
	s_nop 3
	v_lshl_add_u64 v[26:27], v[250:251], 0, s[26:27]
	s_mov_b32 m0, s41
	s_add_i32 s50, s41, 0x2000
	ds_read_b128 v[34:37], v193 offset:49152
	ds_read_b128 v[38:41], v193 offset:50176
	ds_read_b128 v[74:77], v193 offset:51200
	ds_read_b128 v[82:85], v193 offset:52224
	ds_read_b128 v[90:93], v193 offset:53248
	ds_read_b128 v[94:97], v193 offset:54272
	ds_read_b128 v[232:235], v193 offset:55296
	ds_read_b128 v[236:239], v193 offset:56320
	global_load_lds_dwordx4 v[26:27], off
	v_lshl_add_u64 v[26:27], v[250:251], 0, s[28:29]
	s_mov_b32 m0, s50
	s_mov_b64 s[56:57], 0x160180
	s_add_i32 s51, s80, s44
	global_load_lds_dwordx4 v[26:27], off
	v_lshl_add_u64 v[26:27], v[250:251], 0, s[56:57]
	s_mov_b32 m0, s51
	s_mov_b64 s[56:57], 0x210180
	s_add_i32 s33, s51, 0x2000
	global_load_lds_dwordx4 v[26:27], off
	v_lshl_add_u64 v[26:27], v[250:251], 0, s[56:57]
	s_mov_b32 m0, s33
	s_nop 0
	global_load_lds_dwordx4 v[26:27], off
	v_lshl_add_u64 v[26:27], v[248:249], 0, s[26:27]
	s_mov_b32 m0, s53
	s_nop 0
	global_load_lds_dwordx4 v[26:27], off
	v_lshl_add_u64 v[26:27], v[248:249], 0, s[28:29]
	s_mov_b32 m0, s54
	s_nop 0
	global_load_lds_dwordx4 v[26:27], off
	s_waitcnt vmcnt(8)
	s_waitcnt lgkmcnt(0)
	s_barrier
	v_mfma_f32_16x16x32_bf16 v[26:29], v[10:13], v[34:37], v[138:141]
	v_mfma_f32_16x16x32_bf16 v[62:65], v[14:17], v[38:41], v[26:29]
	v_mfma_f32_16x16x32_bf16 v[26:29], v[18:21], v[34:37], v[150:153]
	v_mfma_f32_16x16x32_bf16 v[58:61], v[22:25], v[38:41], v[26:29]
	v_mfma_f32_16x16x32_bf16 v[26:29], v[10:13], v[74:77], v[154:157]
	v_mfma_f32_16x16x32_bf16 v[46:49], v[14:17], v[82:85], v[26:29]
	v_mfma_f32_16x16x32_bf16 v[26:29], v[18:21], v[74:77], v[158:161]
	v_mfma_f32_16x16x32_bf16 v[42:45], v[22:25], v[82:85], v[26:29]
	v_mfma_f32_16x16x32_bf16 v[26:29], v[10:13], v[90:93], v[162:165]
	v_mfma_f32_16x16x32_bf16 v[2:5], v[10:13], v[232:235], v[2:5]
	v_mfma_f32_16x16x32_bf16 v[30:33], v[14:17], v[94:97], v[26:29]
	v_mfma_f32_16x16x32_bf16 v[26:29], v[18:21], v[90:93], v[166:169]
	v_mfma_f32_16x16x32_bf16 v[14:17], v[14:17], v[236:239], v[2:5]
	v_mfma_f32_16x16x32_bf16 v[2:5], v[18:21], v[232:235], v[6:9]
	v_mfma_f32_16x16x32_bf16 v[26:29], v[22:25], v[94:97], v[26:29]
	v_mfma_f32_16x16x32_bf16 v[10:13], v[22:25], v[236:239], v[2:5]
	v_mfma_f32_16x16x32_bf16 v[2:5], v[216:219], v[34:37], v[180:183]
	v_mfma_f32_16x16x32_bf16 v[54:57], v[220:223], v[38:41], v[2:5]
	v_mfma_f32_16x16x32_bf16 v[2:5], v[224:227], v[34:37], v[184:187]
	v_mfma_f32_16x16x32_bf16 v[50:53], v[228:231], v[38:41], v[2:5]
	v_mfma_f32_16x16x32_bf16 v[2:5], v[216:219], v[74:77], v[188:191]
	v_mfma_f32_16x16x32_bf16 v[38:41], v[220:223], v[82:85], v[2:5]
	v_mfma_f32_16x16x32_bf16 v[2:5], v[224:227], v[74:77], v[196:199]
	v_mfma_f32_16x16x32_bf16 v[34:37], v[228:231], v[82:85], v[2:5]
	v_mfma_f32_16x16x32_bf16 v[2:5], v[216:219], v[90:93], v[200:203]
	v_mfma_f32_16x16x32_bf16 v[22:25], v[220:223], v[94:97], v[2:5]
	v_mfma_f32_16x16x32_bf16 v[2:5], v[224:227], v[90:93], v[204:207]
	v_mfma_f32_16x16x32_bf16 v[18:21], v[228:231], v[94:97], v[2:5]
	v_mfma_f32_16x16x32_bf16 v[2:5], v[216:219], v[232:235], v[208:211]
	v_mfma_f32_16x16x32_bf16 v[6:9], v[220:223], v[236:239], v[2:5]
	v_mfma_f32_16x16x32_bf16 v[2:5], v[224:227], v[232:235], v[212:215]
	v_mfma_f32_16x16x32_bf16 v[2:5], v[228:231], v[236:239], v[2:5]
	s_barrier
	s_add_u32 s70, s70, 0x160180
	s_addc_u32 s71, s71, 0
	s_add_u32 s56, s72, 0x200
	s_addc_u32 s57, s73, 0
	s_mov_b32 s72, 0
.LBB0_870:
	ds_read_b128 v[74:77], v1
	ds_read_b128 v[82:85], v1 offset:1024
	ds_read_b128 v[90:93], v1 offset:2048
	ds_read_b128 v[94:97], v1 offset:3072
	ds_read_b128 v[138:141], v192
	ds_read_b128 v[150:153], v192 offset:1024
	ds_read_b128 v[154:157], v192 offset:2048
	ds_read_b128 v[158:161], v192 offset:3072
	s_add_u32 s0, s70, 0xffea0080
	s_addc_u32 s1, s71, -1
	s_cmpk_eq_i32 s72, 0x54
	s_cselect_b32 s93, s11, s1
	s_cselect_b32 s92, s10, s0
	s_cselect_b32 s95, s69, s57
	s_cselect_b32 s94, s68, s56
	s_mov_b32 m0, s85
	v_lshl_add_u64 v[208:209], s[70:71], 0, v[174:175]
	ds_read_b128 v[162:165], v193
	ds_read_b128 v[166:169], v193 offset:1024
	ds_read_b128 v[180:183], v193 offset:2048
	ds_read_b128 v[184:187], v193 offset:3072
	ds_read_b128 v[188:191], v193 offset:4096
	ds_read_b128 v[196:199], v193 offset:5120
	ds_read_b128 v[200:203], v193 offset:6144
	ds_read_b128 v[204:207], v193 offset:7168
	global_load_lds_dwordx4 v[208:209], off
	v_lshl_add_u64 v[208:209], v[208:209], 0, s[30:31]
	s_mov_b32 m0, s87
	s_nop 0
	global_load_lds_dwordx4 v[208:209], off
	s_waitcnt vmcnt(8)
	s_waitcnt lgkmcnt(0)
	s_barrier
	v_mfma_f32_16x16x32_bf16 v[146:149], v[74:77], v[162:165], v[146:149]
	v_mfma_f32_16x16x32_bf16 v[142:145], v[90:93], v[162:165], v[142:145]
	v_mfma_f32_16x16x32_bf16 v[126:129], v[74:77], v[180:183], v[126:129]
	v_mfma_f32_16x16x32_bf16 v[122:125], v[90:93], v[180:183], v[122:125]
	v_mfma_f32_16x16x32_bf16 v[110:113], v[74:77], v[188:191], v[110:113]
	v_mfma_f32_16x16x32_bf16 v[106:109], v[90:93], v[188:191], v[106:109]
	v_mfma_f32_16x16x32_bf16 v[86:89], v[74:77], v[200:203], v[86:89]
	v_mfma_f32_16x16x32_bf16 v[78:81], v[90:93], v[200:203], v[78:81]
	v_mfma_f32_16x16x32_bf16 v[146:149], v[82:85], v[166:169], v[146:149]
	v_mfma_f32_16x16x32_bf16 v[142:145], v[94:97], v[166:169], v[142:145]
	v_mfma_f32_16x16x32_bf16 v[126:129], v[82:85], v[184:187], v[126:129]
	v_mfma_f32_16x16x32_bf16 v[122:125], v[94:97], v[184:187], v[122:125]
	v_mfma_f32_16x16x32_bf16 v[110:113], v[82:85], v[196:199], v[110:113]
	v_mfma_f32_16x16x32_bf16 v[106:109], v[94:97], v[196:199], v[106:109]
	v_mfma_f32_16x16x32_bf16 v[86:89], v[82:85], v[204:207], v[86:89]
	v_mfma_f32_16x16x32_bf16 v[78:81], v[94:97], v[204:207], v[78:81]
	v_mfma_f32_16x16x32_bf16 v[134:137], v[138:141], v[162:165], v[134:137]
	v_mfma_f32_16x16x32_bf16 v[130:133], v[154:157], v[162:165], v[130:133]
	v_mfma_f32_16x16x32_bf16 v[118:121], v[138:141], v[180:183], v[118:121]
	v_mfma_f32_16x16x32_bf16 v[114:117], v[154:157], v[180:183], v[114:117]
	v_mfma_f32_16x16x32_bf16 v[102:105], v[138:141], v[188:191], v[102:105]
	v_mfma_f32_16x16x32_bf16 v[98:101], v[154:157], v[188:191], v[98:101]
	v_mfma_f32_16x16x32_bf16 v[70:73], v[138:141], v[200:203], v[70:73]
	v_mfma_f32_16x16x32_bf16 v[66:69], v[154:157], v[200:203], v[66:69]
	v_mfma_f32_16x16x32_bf16 v[134:137], v[150:153], v[166:169], v[134:137]
	v_mfma_f32_16x16x32_bf16 v[130:133], v[158:161], v[166:169], v[130:133]
	v_mfma_f32_16x16x32_bf16 v[118:121], v[150:153], v[184:187], v[118:121]
	v_mfma_f32_16x16x32_bf16 v[114:117], v[158:161], v[184:187], v[114:117]
	v_mfma_f32_16x16x32_bf16 v[102:105], v[150:153], v[196:199], v[102:105]
	v_mfma_f32_16x16x32_bf16 v[98:101], v[158:161], v[196:199], v[98:101]
	v_mfma_f32_16x16x32_bf16 v[70:73], v[150:153], v[204:207], v[70:73]
	v_mfma_f32_16x16x32_bf16 v[66:69], v[158:161], v[204:207], v[66:69]
	s_barrier
	s_mov_b32 m0, s88
	v_lshl_add_u64 v[208:209], s[94:95], 0, v[172:173]
	ds_read_b128 v[162:165], v193 offset:16384
	ds_read_b128 v[166:169], v193 offset:17408
	ds_read_b128 v[180:183], v193 offset:18432
	ds_read_b128 v[184:187], v193 offset:19456
	ds_read_b128 v[188:191], v193 offset:20480
	ds_read_b128 v[196:199], v193 offset:21504
	ds_read_b128 v[200:203], v193 offset:22528
	ds_read_b128 v[204:207], v193 offset:23552
	global_load_lds_dwordx4 v[208:209], off
	v_lshl_add_u64 v[210:211], v[208:209], 0, s[30:31]
	s_mov_b32 m0, s89
	s_nop 0
	global_load_lds_dwordx4 v[210:211], off
	v_lshl_add_u64 v[210:211], v[208:209], 0, s[34:35]
	s_mov_b32 m0, s90
	s_nop 0
	global_load_lds_dwordx4 v[210:211], off
	v_lshl_add_u64 v[210:211], v[208:209], 0, s[36:37]
	s_mov_b32 m0, s40
	s_nop 0
	global_load_lds_dwordx4 v[210:211], off
	v_lshl_add_u64 v[210:211], s[92:93], 0, v[170:171]
	s_mov_b32 m0, s45
	v_lshl_add_u64 v[212:213], v[210:211], 0, s[30:31]
	global_load_lds_dwordx4 v[210:211], off
	s_mov_b32 m0, s46
	s_nop 0
	global_load_lds_dwordx4 v[212:213], off
	s_waitcnt vmcnt(8)
	s_waitcnt lgkmcnt(0)
	s_barrier
	v_mfma_f32_16x16x32_bf16 v[62:65], v[74:77], v[162:165], v[62:65]
	v_mfma_f32_16x16x32_bf16 v[58:61], v[90:93], v[162:165], v[58:61]
	v_mfma_f32_16x16x32_bf16 v[46:49], v[74:77], v[180:183], v[46:49]
	v_mfma_f32_16x16x32_bf16 v[42:45], v[90:93], v[180:183], v[42:45]
	v_mfma_f32_16x16x32_bf16 v[30:33], v[74:77], v[188:191], v[30:33]
	v_mfma_f32_16x16x32_bf16 v[26:29], v[90:93], v[188:191], v[26:29]
	v_mfma_f32_16x16x32_bf16 v[14:17], v[74:77], v[200:203], v[14:17]
	v_mfma_f32_16x16x32_bf16 v[10:13], v[90:93], v[200:203], v[10:13]
	v_mfma_f32_16x16x32_bf16 v[62:65], v[82:85], v[166:169], v[62:65]
	v_mfma_f32_16x16x32_bf16 v[58:61], v[94:97], v[166:169], v[58:61]
	v_mfma_f32_16x16x32_bf16 v[46:49], v[82:85], v[184:187], v[46:49]
	v_mfma_f32_16x16x32_bf16 v[42:45], v[94:97], v[184:187], v[42:45]
	v_mfma_f32_16x16x32_bf16 v[30:33], v[82:85], v[196:199], v[30:33]
	v_mfma_f32_16x16x32_bf16 v[26:29], v[94:97], v[196:199], v[26:29]
	v_mfma_f32_16x16x32_bf16 v[14:17], v[82:85], v[204:207], v[14:17]
	v_mfma_f32_16x16x32_bf16 v[10:13], v[94:97], v[204:207], v[10:13]
	v_mfma_f32_16x16x32_bf16 v[54:57], v[138:141], v[162:165], v[54:57]
	v_mfma_f32_16x16x32_bf16 v[50:53], v[154:157], v[162:165], v[50:53]
	v_mfma_f32_16x16x32_bf16 v[38:41], v[138:141], v[180:183], v[38:41]
	v_mfma_f32_16x16x32_bf16 v[34:37], v[154:157], v[180:183], v[34:37]
	v_mfma_f32_16x16x32_bf16 v[22:25], v[138:141], v[188:191], v[22:25]
	v_mfma_f32_16x16x32_bf16 v[18:21], v[154:157], v[188:191], v[18:21]
	v_mfma_f32_16x16x32_bf16 v[6:9], v[138:141], v[200:203], v[6:9]
	v_mfma_f32_16x16x32_bf16 v[2:5], v[154:157], v[200:203], v[2:5]
	v_mfma_f32_16x16x32_bf16 v[54:57], v[150:153], v[166:169], v[54:57]
	v_mfma_f32_16x16x32_bf16 v[50:53], v[158:161], v[166:169], v[50:53]
	v_mfma_f32_16x16x32_bf16 v[38:41], v[150:153], v[184:187], v[38:41]
	v_mfma_f32_16x16x32_bf16 v[34:37], v[158:161], v[184:187], v[34:37]
	v_mfma_f32_16x16x32_bf16 v[22:25], v[150:153], v[196:199], v[22:25]
	v_mfma_f32_16x16x32_bf16 v[18:21], v[158:161], v[196:199], v[18:21]
	v_mfma_f32_16x16x32_bf16 v[6:9], v[150:153], v[204:207], v[6:9]
	v_mfma_f32_16x16x32_bf16 v[2:5], v[158:161], v[204:207], v[2:5]
	s_barrier
; #define PG8_WAIT_V(n) asm volatile("s_waitcnt vmcnt(" #n ")" ::: "memory")
; template <class Epi, class Sched, bool ALIGN_EPI = true, bool SP2 = true, bool FULLLINE = false, bool NOSTAGE = false, bool FP8 = false>
; __device__ __forceinline__ void gemm_phase(PG8_LAS unsigned char* lds, const Gemm g, const Sched& S, const Epi& E) {
;     ...
;         static_assert(SP2, "only the SP2 loop is kept");
;         { const int t = 0; if constexpr (Epi::NST == 16) PG8_ITER(PG8_WAIT_V(24)); else if constexpr (Epi::NST == 8) PG8_ITER(PG8_WAIT_V(16)); else PG8_ITER(PG8_WAIT_V(8)); }
;         for (int t = 2; t < nt; t += 2) PG8_ITER(PG8_WAIT_V(8));
	ds_read_b128 v[74:77], v194
	ds_read_b128 v[82:85], v194 offset:1024
	ds_read_b128 v[90:93], v194 offset:2048
	ds_read_b128 v[94:97], v194 offset:3072
	ds_read_b128 v[138:141], v195
	ds_read_b128 v[150:153], v195 offset:1024
	ds_read_b128 v[154:157], v195 offset:2048
	ds_read_b128 v[158:161], v195 offset:3072
	s_mov_b32 m0, s47
	v_lshl_add_u64 v[212:213], v[210:211], 0, s[34:35]
	ds_read_b128 v[162:165], v193 offset:32768
	ds_read_b128 v[166:169], v193 offset:33792
	ds_read_b128 v[180:183], v193 offset:34816
	ds_read_b128 v[184:187], v193 offset:35840
	ds_read_b128 v[188:191], v193 offset:36864
	ds_read_b128 v[196:199], v193 offset:37888
	ds_read_b128 v[200:203], v193 offset:38912
	ds_read_b128 v[204:207], v193 offset:39936
	global_load_lds_dwordx4 v[212:213], off
	v_lshl_add_u64 v[212:213], v[210:211], 0, s[36:37]
	s_mov_b32 m0, s52
	s_nop 0
	global_load_lds_dwordx4 v[212:213], off
	s_waitcnt vmcnt(8)
	s_waitcnt lgkmcnt(0)
	s_barrier
	v_mfma_f32_16x16x32_bf16 v[146:149], v[74:77], v[162:165], v[146:149]
	v_mfma_f32_16x16x32_bf16 v[142:145], v[90:93], v[162:165], v[142:145]
	v_mfma_f32_16x16x32_bf16 v[126:129], v[74:77], v[180:183], v[126:129]
	v_mfma_f32_16x16x32_bf16 v[122:125], v[90:93], v[180:183], v[122:125]
	v_mfma_f32_16x16x32_bf16 v[110:113], v[74:77], v[188:191], v[110:113]
	v_mfma_f32_16x16x32_bf16 v[106:109], v[90:93], v[188:191], v[106:109]
	v_mfma_f32_16x16x32_bf16 v[86:89], v[74:77], v[200:203], v[86:89]
	v_mfma_f32_16x16x32_bf16 v[78:81], v[90:93], v[200:203], v[78:81]
	v_mfma_f32_16x16x32_bf16 v[146:149], v[82:85], v[166:169], v[146:149]
	v_mfma_f32_16x16x32_bf16 v[142:145], v[94:97], v[166:169], v[142:145]
	v_mfma_f32_16x16x32_bf16 v[126:129], v[82:85], v[184:187], v[126:129]
	v_mfma_f32_16x16x32_bf16 v[122:125], v[94:97], v[184:187], v[122:125]
	v_mfma_f32_16x16x32_bf16 v[110:113], v[82:85], v[196:199], v[110:113]
	v_mfma_f32_16x16x32_bf16 v[106:109], v[94:97], v[196:199], v[106:109]
	v_mfma_f32_16x16x32_bf16 v[86:89], v[82:85], v[204:207], v[86:89]
	v_mfma_f32_16x16x32_bf16 v[78:81], v[94:97], v[204:207], v[78:81]
	v_mfma_f32_16x16x32_bf16 v[134:137], v[138:141], v[162:165], v[134:137]
	v_mfma_f32_16x16x32_bf16 v[130:133], v[154:157], v[162:165], v[130:133]
	v_mfma_f32_16x16x32_bf16 v[118:121], v[138:141], v[180:183], v[118:121]
	v_mfma_f32_16x16x32_bf16 v[114:117], v[154:157], v[180:183], v[114:117]
	v_mfma_f32_16x16x32_bf16 v[102:105], v[138:141], v[188:191], v[102:105]
	v_mfma_f32_16x16x32_bf16 v[98:101], v[154:157], v[188:191], v[98:101]
	v_mfma_f32_16x16x32_bf16 v[70:73], v[138:141], v[200:203], v[70:73]
	v_mfma_f32_16x16x32_bf16 v[66:69], v[154:157], v[200:203], v[66:69]
	v_mfma_f32_16x16x32_bf16 v[134:137], v[150:153], v[166:169], v[134:137]
	v_mfma_f32_16x16x32_bf16 v[130:133], v[158:161], v[166:169], v[130:133]
	v_mfma_f32_16x16x32_bf16 v[118:121], v[150:153], v[184:187], v[118:121]
	v_mfma_f32_16x16x32_bf16 v[114:117], v[158:161], v[184:187], v[114:117]
	v_mfma_f32_16x16x32_bf16 v[102:105], v[150:153], v[196:199], v[102:105]
	v_mfma_f32_16x16x32_bf16 v[98:101], v[158:161], v[196:199], v[98:101]
	v_mfma_f32_16x16x32_bf16 v[70:73], v[150:153], v[204:207], v[70:73]
	v_mfma_f32_16x16x32_bf16 v[66:69], v[158:161], v[204:207], v[66:69]
	s_barrier
	s_mov_b32 m0, s41
	v_lshl_add_u64 v[212:213], v[208:209], 0, s[38:39]
	ds_read_b128 v[162:165], v193 offset:49152
	ds_read_b128 v[166:169], v193 offset:50176
	ds_read_b128 v[180:183], v193 offset:51200
	ds_read_b128 v[184:187], v193 offset:52224
	ds_read_b128 v[188:191], v193 offset:53248
	ds_read_b128 v[196:199], v193 offset:54272
	ds_read_b128 v[200:203], v193 offset:55296
	ds_read_b128 v[204:207], v193 offset:56320
	global_load_lds_dwordx4 v[212:213], off
	v_lshl_add_u64 v[212:213], v[208:209], 0, s[66:67]
	s_mov_b32 m0, s50
	s_nop 0
	global_load_lds_dwordx4 v[212:213], off
	v_lshl_add_u64 v[212:213], v[208:209], 0, s[14:15]
	s_mov_b32 m0, s51
	v_lshl_add_u64 v[208:209], v[208:209], 0, s[16:17]
	global_load_lds_dwordx4 v[212:213], off
	s_mov_b32 m0, s33
	s_nop 0
	global_load_lds_dwordx4 v[208:209], off
	v_lshl_add_u64 v[208:209], v[210:211], 0, s[38:39]
	s_mov_b32 m0, s53
	s_nop 0
	global_load_lds_dwordx4 v[208:209], off
	v_lshl_add_u64 v[208:209], v[210:211], 0, s[66:67]
	s_mov_b32 m0, s54
	s_nop 0
	global_load_lds_dwordx4 v[208:209], off
	s_waitcnt vmcnt(8)
	s_waitcnt lgkmcnt(0)
	s_barrier
	v_mfma_f32_16x16x32_bf16 v[62:65], v[74:77], v[162:165], v[62:65]
	v_mfma_f32_16x16x32_bf16 v[58:61], v[90:93], v[162:165], v[58:61]
	v_mfma_f32_16x16x32_bf16 v[46:49], v[74:77], v[180:183], v[46:49]
	v_mfma_f32_16x16x32_bf16 v[42:45], v[90:93], v[180:183], v[42:45]
	v_mfma_f32_16x16x32_bf16 v[30:33], v[74:77], v[188:191], v[30:33]
	v_mfma_f32_16x16x32_bf16 v[26:29], v[90:93], v[188:191], v[26:29]
	v_mfma_f32_16x16x32_bf16 v[14:17], v[74:77], v[200:203], v[14:17]
	v_mfma_f32_16x16x32_bf16 v[10:13], v[90:93], v[200:203], v[10:13]
	v_mfma_f32_16x16x32_bf16 v[62:65], v[82:85], v[166:169], v[62:65]
	v_mfma_f32_16x16x32_bf16 v[58:61], v[94:97], v[166:169], v[58:61]
	v_mfma_f32_16x16x32_bf16 v[46:49], v[82:85], v[184:187], v[46:49]
	v_mfma_f32_16x16x32_bf16 v[42:45], v[94:97], v[184:187], v[42:45]
	v_mfma_f32_16x16x32_bf16 v[30:33], v[82:85], v[196:199], v[30:33]
	v_mfma_f32_16x16x32_bf16 v[26:29], v[94:97], v[196:199], v[26:29]
	v_mfma_f32_16x16x32_bf16 v[14:17], v[82:85], v[204:207], v[14:17]
	v_mfma_f32_16x16x32_bf16 v[10:13], v[94:97], v[204:207], v[10:13]
	v_mfma_f32_16x16x32_bf16 v[54:57], v[138:141], v[162:165], v[54:57]
	v_mfma_f32_16x16x32_bf16 v[50:53], v[154:157], v[162:165], v[50:53]
	v_mfma_f32_16x16x32_bf16 v[38:41], v[138:141], v[180:183], v[38:41]
	v_mfma_f32_16x16x32_bf16 v[34:37], v[154:157], v[180:183], v[34:37]
	v_mfma_f32_16x16x32_bf16 v[22:25], v[138:141], v[188:191], v[22:25]
	v_mfma_f32_16x16x32_bf16 v[18:21], v[154:157], v[188:191], v[18:21]
	v_mfma_f32_16x16x32_bf16 v[6:9], v[138:141], v[200:203], v[6:9]
	v_mfma_f32_16x16x32_bf16 v[2:5], v[154:157], v[200:203], v[2:5]
	v_mfma_f32_16x16x32_bf16 v[54:57], v[150:153], v[166:169], v[54:57]
	v_mfma_f32_16x16x32_bf16 v[50:53], v[158:161], v[166:169], v[50:53]
	v_mfma_f32_16x16x32_bf16 v[38:41], v[150:153], v[184:187], v[38:41]
	v_mfma_f32_16x16x32_bf16 v[34:37], v[158:161], v[184:187], v[34:37]
	v_mfma_f32_16x16x32_bf16 v[22:25], v[150:153], v[196:199], v[22:25]
	v_mfma_f32_16x16x32_bf16 v[18:21], v[158:161], v[196:199], v[18:21]
	v_mfma_f32_16x16x32_bf16 v[6:9], v[150:153], v[204:207], v[6:9]
	v_mfma_f32_16x16x32_bf16 v[2:5], v[158:161], v[204:207], v[2:5]
	s_barrier
	s_add_i32 s72, s72, 2
	s_add_u32 s70, s70, 0x100
	s_addc_u32 s71, s71, 0
	s_add_u32 s56, s56, 0x100
	s_addc_u32 s57, s57, 0
	s_cmpk_gt_u32 s72, 0x55
	s_cbranch_scc0 .LBB0_870
	s_and_b64 vcc, exec, s[12:13]
	s_cbranch_vccz .LBB0_873
	s_barrier

; template <class Epi, class Sched, bool ALIGN_EPI = true, bool SP2 = true, bool FULLLINE = false, bool NOSTAGE = false, bool FP8 = false>
; __device__ __forceinline__ void gemm_phase(PG8_LAS unsigned char* lds, const Gemm g, const Sched& S, const Epi& E) {
;     ...
;         const bool has_next = S.next(ui + 1, nxt);
;         const char* nA = has_next ? PG8_ABASE(nxt) : cA; const char* nB = has_next ? PG8_BBASE(nxt) : cB;
.LBB0_1024:
	s_ashr_i32 s75, s74, 31
	s_lshl_b64 s[40:41], s[74:75], 20
	s_add_u32 s76, s58, s40
	ds_read_b128 v[2:5], v1
	ds_read_b128 v[6:9], v1 offset:1024
	ds_read_b128 v[10:13], v1 offset:2048
	ds_read_b128 v[14:17], v1 offset:3072
	ds_read_b128 v[18:21], v152
	ds_read_b128 v[22:25], v152 offset:1024
	ds_read_b128 v[26:29], v152 offset:2048
	ds_read_b128 v[30:33], v152 offset:3072
	s_addc_u32 s77, s59, s41
	s_ashr_i32 s73, s72, 31
	s_lshl_b64 s[40:41], s[72:73], 20
	s_add_u32 s78, s3, s40
	s_addc_u32 s79, s42, s41
	s_and_b64 s[40:41], s[8:9], exec
	s_cselect_b32 s73, s77, s83
	s_cselect_b32 s75, s76, s82
	s_cselect_b32 s96, s79, s81
	s_cselect_b32 s97, s78, s80
	v_lshl_add_u64 v[244:245], s[82:83], 0, v[132:133]
	s_mov_b32 m0, s87
	v_lshl_add_u64 v[66:67], v[244:245], 0, s[18:19]
	ds_read_b128 v[34:37], v153
	ds_read_b128 v[38:41], v153 offset:1024
	ds_read_b128 v[42:45], v153 offset:2048
	ds_read_b128 v[46:49], v153 offset:3072
	ds_read_b128 v[50:53], v153 offset:4096
	ds_read_b128 v[54:57], v153 offset:5120
	ds_read_b128 v[58:61], v153 offset:6144
	ds_read_b128 v[62:65], v153 offset:7168
	global_load_lds_dwordx4 v[66:67], off
	v_lshl_add_u64 v[66:67], v[244:245], 0, s[20:21]
	s_mov_b32 m0, s88
	s_nop 0
	global_load_lds_dwordx4 v[66:67], off
	s_waitcnt vmcnt(16)
	s_waitcnt lgkmcnt(0)
	s_barrier
	v_mfma_f32_16x16x32_bf16 v[90:93], v[2:5], v[58:61], 0
	v_mfma_f32_16x16x32_bf16 v[66:69], v[2:5], v[34:37], 0
	v_mfma_f32_16x16x32_bf16 v[70:73], v[10:13], v[34:37], 0
	v_mfma_f32_16x16x32_bf16 v[74:77], v[2:5], v[42:45], 0
	v_mfma_f32_16x16x32_bf16 v[78:81], v[10:13], v[42:45], 0
	v_mfma_f32_16x16x32_bf16 v[82:85], v[2:5], v[50:53], 0
	v_mfma_f32_16x16x32_bf16 v[86:89], v[10:13], v[50:53], 0
	v_mfma_f32_16x16x32_bf16 v[94:97], v[6:9], v[62:65], v[90:93]
	v_mfma_f32_16x16x32_bf16 v[90:93], v[10:13], v[58:61], 0
	v_mfma_f32_16x16x32_bf16 v[66:69], v[6:9], v[38:41], v[66:69]
	v_mfma_f32_16x16x32_bf16 v[70:73], v[14:17], v[38:41], v[70:73]
	v_mfma_f32_16x16x32_bf16 v[74:77], v[6:9], v[46:49], v[74:77]
	v_mfma_f32_16x16x32_bf16 v[78:81], v[14:17], v[46:49], v[78:81]
	v_mfma_f32_16x16x32_bf16 v[82:85], v[6:9], v[54:57], v[82:85]
	v_mfma_f32_16x16x32_bf16 v[86:89], v[14:17], v[54:57], v[86:89]
	v_mfma_f32_16x16x32_bf16 v[102:105], v[14:17], v[62:65], v[90:93]
	v_mfma_f32_16x16x32_bf16 v[90:93], v[18:21], v[34:37], 0
	v_mfma_f32_16x16x32_bf16 v[34:37], v[26:29], v[34:37], 0
	v_mfma_f32_16x16x32_bf16 v[110:113], v[22:25], v[38:41], v[90:93]
	v_mfma_f32_16x16x32_bf16 v[34:37], v[30:33], v[38:41], v[34:37]
	v_mfma_f32_16x16x32_bf16 v[38:41], v[18:21], v[42:45], 0
	v_mfma_f32_16x16x32_bf16 v[42:45], v[26:29], v[42:45], 0
	v_mfma_f32_16x16x32_bf16 v[38:41], v[22:25], v[46:49], v[38:41]
	v_mfma_f32_16x16x32_bf16 v[42:45], v[30:33], v[46:49], v[42:45]
	v_mfma_f32_16x16x32_bf16 v[46:49], v[18:21], v[50:53], 0
	v_mfma_f32_16x16x32_bf16 v[50:53], v[26:29], v[50:53], 0
	v_mfma_f32_16x16x32_bf16 v[46:49], v[22:25], v[54:57], v[46:49]
	v_mfma_f32_16x16x32_bf16 v[54:57], v[30:33], v[54:57], v[50:53]
	v_mfma_f32_16x16x32_bf16 v[50:53], v[18:21], v[58:61], 0
	v_mfma_f32_16x16x32_bf16 v[140:143], v[22:25], v[62:65], v[50:53]
	v_mfma_f32_16x16x32_bf16 v[50:53], v[26:29], v[58:61], 0
	v_mfma_f32_16x16x32_bf16 v[144:147], v[30:33], v[62:65], v[50:53]
	s_barrier
	v_lshl_add_u64 v[246:247], s[80:81], 0, v[130:131]
	s_add_i32 vcc_lo, s84, s43
	v_lshl_add_u64 v[122:123], v[246:247], 0, s[22:23]
	s_mov_b32 m0, vcc_lo
	s_add_i32 vcc_hi, vcc_lo, 0x2000
	s_nop 0
	ds_read_b128 v[50:53], v153 offset:16384
	ds_read_b128 v[58:61], v153 offset:17408
	ds_read_b128 v[62:65], v153 offset:18432
	ds_read_b128 v[90:93], v153 offset:19456
	ds_read_b128 v[98:101], v153 offset:20480
	ds_read_b128 v[106:109], v153 offset:21504
	ds_read_b128 v[114:117], v153 offset:22528
	ds_read_b128 v[118:121], v153 offset:23552
	global_load_lds_dwordx4 v[122:123], off
	v_lshl_add_u64 v[122:123], v[246:247], 0, s[24:25]
	s_mov_b32 m0, vcc_hi
	s_add_i32 s40, s85, s43
	global_load_lds_dwordx4 v[122:123], off
	v_lshl_add_u64 v[122:123], v[246:247], 0, s[26:27]
	s_mov_b32 m0, s40
	s_add_i32 s41, s40, 0x2000
	global_load_lds_dwordx4 v[122:123], off
	v_lshl_add_u64 v[122:123], v[246:247], 0, s[28:29]
	s_mov_b32 m0, s41
	s_nop 0
	global_load_lds_dwordx4 v[122:123], off
	v_lshl_add_u64 v[122:123], v[244:245], 0, s[22:23]
	s_mov_b32 m0, s45
	s_nop 0
	global_load_lds_dwordx4 v[122:123], off
	v_lshl_add_u64 v[122:123], v[244:245], 0, s[24:25]
	s_mov_b32 m0, s46
	s_nop 0
	global_load_lds_dwordx4 v[122:123], off
	s_waitcnt vmcnt(16)
	s_waitcnt lgkmcnt(0)
	s_barrier
	v_mfma_f32_16x16x32_bf16 v[122:125], v[2:5], v[50:53], 0
	v_mfma_f32_16x16x32_bf16 v[148:151], v[6:9], v[58:61], v[122:125]
	v_mfma_f32_16x16x32_bf16 v[122:125], v[10:13], v[50:53], 0
	v_mfma_f32_16x16x32_bf16 v[156:159], v[14:17], v[58:61], v[122:125]
	v_mfma_f32_16x16x32_bf16 v[122:125], v[2:5], v[62:65], 0
	v_mfma_f32_16x16x32_bf16 v[160:163], v[6:9], v[90:93], v[122:125]
	v_mfma_f32_16x16x32_bf16 v[122:125], v[10:13], v[62:65], 0
	v_mfma_f32_16x16x32_bf16 v[164:167], v[14:17], v[90:93], v[122:125]
	v_mfma_f32_16x16x32_bf16 v[122:125], v[2:5], v[98:101], 0
	v_mfma_f32_16x16x32_bf16 v[2:5], v[2:5], v[114:117], 0
	v_mfma_f32_16x16x32_bf16 v[168:171], v[6:9], v[106:109], v[122:125]
	v_mfma_f32_16x16x32_bf16 v[2:5], v[6:9], v[118:121], v[2:5]
	v_mfma_f32_16x16x32_bf16 v[6:9], v[10:13], v[114:117], 0
	v_mfma_f32_16x16x32_bf16 v[122:125], v[10:13], v[98:101], 0
	v_mfma_f32_16x16x32_bf16 v[6:9], v[14:17], v[118:121], v[6:9]
	v_mfma_f32_16x16x32_bf16 v[172:175], v[14:17], v[106:109], v[122:125]
	v_mfma_f32_16x16x32_bf16 v[10:13], v[18:21], v[50:53], 0
	v_mfma_f32_16x16x32_bf16 v[176:179], v[22:25], v[58:61], v[10:13]
	v_mfma_f32_16x16x32_bf16 v[10:13], v[26:29], v[50:53], 0
	v_mfma_f32_16x16x32_bf16 v[180:183], v[30:33], v[58:61], v[10:13]
	v_mfma_f32_16x16x32_bf16 v[10:13], v[18:21], v[62:65], 0
	v_mfma_f32_16x16x32_bf16 v[184:187], v[22:25], v[90:93], v[10:13]
	v_mfma_f32_16x16x32_bf16 v[10:13], v[26:29], v[62:65], 0
	v_mfma_f32_16x16x32_bf16 v[188:191], v[30:33], v[90:93], v[10:13]
	v_mfma_f32_16x16x32_bf16 v[10:13], v[18:21], v[98:101], 0
	v_mfma_f32_16x16x32_bf16 v[192:195], v[22:25], v[106:109], v[10:13]
	v_mfma_f32_16x16x32_bf16 v[10:13], v[26:29], v[98:101], 0
	v_mfma_f32_16x16x32_bf16 v[196:199], v[30:33], v[106:109], v[10:13]
	v_mfma_f32_16x16x32_bf16 v[10:13], v[18:21], v[114:117], 0
	v_mfma_f32_16x16x32_bf16 v[200:203], v[22:25], v[118:121], v[10:13]
	v_mfma_f32_16x16x32_bf16 v[10:13], v[26:29], v[114:117], 0
	v_mfma_f32_16x16x32_bf16 v[204:207], v[30:33], v[118:121], v[10:13]
	s_barrier
; #define PG8_WAIT_V(n) asm volatile("s_waitcnt vmcnt(" #n ")" ::: "memory")
; template <class Epi, class Sched, bool ALIGN_EPI = true, bool SP2 = true, bool FULLLINE = false, bool NOSTAGE = false, bool FP8 = false>
; __device__ __forceinline__ void gemm_phase(PG8_LAS unsigned char* lds, const Gemm g, const Sched& S, const Epi& E) {
;     ...
;         static_assert(SP2, "only the SP2 loop is kept");
;         { const int t = 0; if constexpr (Epi::NST == 16) PG8_ITER(PG8_WAIT_V(24)); else if constexpr (Epi::NST == 8) PG8_ITER(PG8_WAIT_V(16)); else PG8_ITER(PG8_WAIT_V(8)); }
;         for (int t = 2; t < nt; t += 2) PG8_ITER(PG8_WAIT_V(8));
	s_nop 5
	ds_read_b128 v[10:13], v154
	ds_read_b128 v[14:17], v154 offset:1024
	ds_read_b128 v[18:21], v154 offset:2048
	ds_read_b128 v[26:29], v154 offset:3072
	ds_read_b128 v[208:211], v155
	ds_read_b128 v[212:215], v155 offset:1024
	ds_read_b128 v[216:219], v155 offset:2048
	ds_read_b128 v[220:223], v155 offset:3072
	s_mov_b32 m0, s47
	v_lshl_add_u64 v[50:51], v[244:245], 0, s[26:27]
	ds_read_b128 v[22:25], v153 offset:32768
	ds_read_b128 v[30:33], v153 offset:33792
	ds_read_b128 v[62:65], v153 offset:34816
	ds_read_b128 v[224:227], v153 offset:35840
	ds_read_b128 v[228:231], v153 offset:36864
	ds_read_b128 v[232:235], v153 offset:37888
	ds_read_b128 v[236:239], v153 offset:38912
	ds_read_b128 v[240:243], v153 offset:39936
	global_load_lds_dwordx4 v[50:51], off
	v_lshl_add_u64 v[50:51], v[244:245], 0, s[28:29]
	s_mov_b32 m0, s52
	s_nop 0
	global_load_lds_dwordx4 v[50:51], off
	s_waitcnt vmcnt(8)
	s_waitcnt lgkmcnt(0)
	s_barrier
	v_mfma_f32_16x16x32_bf16 v[50:53], v[10:13], v[22:25], v[66:69]
	v_mfma_f32_16x16x32_bf16 v[122:125], v[14:17], v[30:33], v[50:53]
	v_mfma_f32_16x16x32_bf16 v[50:53], v[18:21], v[22:25], v[70:73]
	v_mfma_f32_16x16x32_bf16 v[114:117], v[26:29], v[30:33], v[50:53]
	v_mfma_f32_16x16x32_bf16 v[50:53], v[10:13], v[62:65], v[74:77]
	v_mfma_f32_16x16x32_bf16 v[106:109], v[14:17], v[224:227], v[50:53]
	v_mfma_f32_16x16x32_bf16 v[50:53], v[18:21], v[62:65], v[78:81]
	v_mfma_f32_16x16x32_bf16 v[98:101], v[26:29], v[224:227], v[50:53]
	v_mfma_f32_16x16x32_bf16 v[50:53], v[10:13], v[228:231], v[82:85]
	v_mfma_f32_16x16x32_bf16 v[90:93], v[14:17], v[232:235], v[50:53]
	v_mfma_f32_16x16x32_bf16 v[50:53], v[18:21], v[228:231], v[86:89]
	v_mfma_f32_16x16x32_bf16 v[82:85], v[26:29], v[232:235], v[50:53]
	v_mfma_f32_16x16x32_bf16 v[50:53], v[10:13], v[236:239], v[94:97]
	v_mfma_f32_16x16x32_bf16 v[58:61], v[14:17], v[240:243], v[50:53]
	v_mfma_f32_16x16x32_bf16 v[50:53], v[18:21], v[236:239], v[102:105]
	v_mfma_f32_16x16x32_bf16 v[50:53], v[26:29], v[240:243], v[50:53]
	v_mfma_f32_16x16x32_bf16 v[66:69], v[208:211], v[22:25], v[110:113]
	v_mfma_f32_16x16x32_bf16 v[22:25], v[216:219], v[22:25], v[34:37]
	v_mfma_f32_16x16x32_bf16 v[118:121], v[220:223], v[30:33], v[22:25]
	v_mfma_f32_16x16x32_bf16 v[22:25], v[208:211], v[62:65], v[38:41]
	v_mfma_f32_16x16x32_bf16 v[110:113], v[212:215], v[224:227], v[22:25]
	v_mfma_f32_16x16x32_bf16 v[22:25], v[216:219], v[62:65], v[42:45]
	v_mfma_f32_16x16x32_bf16 v[102:105], v[220:223], v[224:227], v[22:25]
	v_mfma_f32_16x16x32_bf16 v[22:25], v[208:211], v[228:231], v[46:49]
	v_mfma_f32_16x16x32_bf16 v[94:97], v[212:215], v[232:235], v[22:25]
	v_mfma_f32_16x16x32_bf16 v[22:25], v[216:219], v[228:231], v[54:57]
	v_mfma_f32_16x16x32_bf16 v[86:89], v[220:223], v[232:235], v[22:25]
	v_mfma_f32_16x16x32_bf16 v[22:25], v[208:211], v[236:239], v[140:143]
	v_mfma_f32_16x16x32_bf16 v[62:65], v[212:215], v[240:243], v[22:25]
	v_mfma_f32_16x16x32_bf16 v[22:25], v[216:219], v[236:239], v[144:147]
	v_mfma_f32_16x16x32_bf16 v[126:129], v[212:215], v[30:33], v[66:69]
	v_mfma_f32_16x16x32_bf16 v[54:57], v[220:223], v[240:243], v[22:25]
	s_barrier
	s_add_i32 s50, s89, s43
	s_nop 3
	v_lshl_add_u64 v[22:23], v[246:247], 0, s[30:31]
	s_mov_b32 m0, s50
	s_add_i32 s51, s50, 0x2000
	ds_read_b128 v[34:37], v153 offset:49152
	ds_read_b128 v[42:45], v153 offset:50176
	ds_read_b128 v[140:143], v153 offset:51200
	ds_read_b128 v[144:147], v153 offset:52224
	ds_read_b128 v[224:227], v153 offset:53248
	ds_read_b128 v[228:231], v153 offset:54272
	ds_read_b128 v[232:235], v153 offset:55296
	ds_read_b128 v[236:239], v153 offset:56320
	global_load_lds_dwordx4 v[22:23], off
	v_lshl_add_u64 v[22:23], v[246:247], 0, s[34:35]
	s_mov_b32 m0, s51
	s_mov_b64 s[56:57], 0x80180
	s_add_i32 s33, s90, s43
	global_load_lds_dwordx4 v[22:23], off
	v_lshl_add_u64 v[22:23], v[246:247], 0, s[56:57]
	s_mov_b32 m0, s33
	s_mov_b64 s[56:57], 0xc0180
	global_load_lds_dwordx4 v[22:23], off
	v_lshl_add_u64 v[22:23], v[246:247], 0, s[56:57]
	s_add_i32 s56, s33, 0x2000
	s_mov_b32 m0, s56
	s_nop 0
	global_load_lds_dwordx4 v[22:23], off
	v_lshl_add_u64 v[22:23], v[244:245], 0, s[30:31]
	s_mov_b32 m0, s53
	s_nop 0
	global_load_lds_dwordx4 v[22:23], off
	v_lshl_add_u64 v[22:23], v[244:245], 0, s[34:35]
	s_mov_b32 m0, s54
	s_nop 0
	global_load_lds_dwordx4 v[22:23], off
	s_waitcnt vmcnt(8)
	s_waitcnt lgkmcnt(0)
	s_barrier
	v_mfma_f32_16x16x32_bf16 v[22:25], v[10:13], v[34:37], v[148:151]
	v_mfma_f32_16x16x32_bf16 v[78:81], v[14:17], v[42:45], v[22:25]
	v_mfma_f32_16x16x32_bf16 v[22:25], v[18:21], v[34:37], v[156:159]
	v_mfma_f32_16x16x32_bf16 v[70:73], v[26:29], v[42:45], v[22:25]
	v_mfma_f32_16x16x32_bf16 v[22:25], v[10:13], v[140:143], v[160:163]
	v_mfma_f32_16x16x32_bf16 v[46:49], v[14:17], v[144:147], v[22:25]
	v_mfma_f32_16x16x32_bf16 v[22:25], v[18:21], v[140:143], v[164:167]
	v_mfma_f32_16x16x32_bf16 v[38:41], v[26:29], v[144:147], v[22:25]
	v_mfma_f32_16x16x32_bf16 v[22:25], v[10:13], v[224:227], v[168:171]
	v_mfma_f32_16x16x32_bf16 v[2:5], v[10:13], v[232:235], v[2:5]
	v_mfma_f32_16x16x32_bf16 v[30:33], v[14:17], v[228:231], v[22:25]
	v_mfma_f32_16x16x32_bf16 v[22:25], v[18:21], v[224:227], v[172:175]
	v_mfma_f32_16x16x32_bf16 v[14:17], v[14:17], v[236:239], v[2:5]
	v_mfma_f32_16x16x32_bf16 v[2:5], v[18:21], v[232:235], v[6:9]
	v_mfma_f32_16x16x32_bf16 v[22:25], v[26:29], v[228:231], v[22:25]
	v_mfma_f32_16x16x32_bf16 v[10:13], v[26:29], v[236:239], v[2:5]
	v_mfma_f32_16x16x32_bf16 v[2:5], v[208:211], v[34:37], v[176:179]
	v_mfma_f32_16x16x32_bf16 v[74:77], v[212:215], v[42:45], v[2:5]
	v_mfma_f32_16x16x32_bf16 v[2:5], v[216:219], v[34:37], v[180:183]
	v_mfma_f32_16x16x32_bf16 v[66:69], v[220:223], v[42:45], v[2:5]
	v_mfma_f32_16x16x32_bf16 v[2:5], v[208:211], v[140:143], v[184:187]
	v_mfma_f32_16x16x32_bf16 v[42:45], v[212:215], v[144:147], v[2:5]
	v_mfma_f32_16x16x32_bf16 v[2:5], v[216:219], v[140:143], v[188:191]
	v_mfma_f32_16x16x32_bf16 v[34:37], v[220:223], v[144:147], v[2:5]
	v_mfma_f32_16x16x32_bf16 v[2:5], v[208:211], v[224:227], v[192:195]
	v_mfma_f32_16x16x32_bf16 v[26:29], v[212:215], v[228:231], v[2:5]
	v_mfma_f32_16x16x32_bf16 v[2:5], v[216:219], v[224:227], v[196:199]
	v_mfma_f32_16x16x32_bf16 v[18:21], v[220:223], v[228:231], v[2:5]
	v_mfma_f32_16x16x32_bf16 v[2:5], v[208:211], v[232:235], v[200:203]
	v_mfma_f32_16x16x32_bf16 v[6:9], v[212:215], v[236:239], v[2:5]
	v_mfma_f32_16x16x32_bf16 v[2:5], v[216:219], v[232:235], v[204:207]
	v_mfma_f32_16x16x32_bf16 v[2:5], v[220:223], v[236:239], v[2:5]
	s_barrier
	s_add_u32 s82, s82, 0x80180
	s_addc_u32 s83, s83, 0
	s_add_u32 s57, s80, 0x200
	s_addc_u32 s80, s81, 0
	s_mov_b32 s81, 0
.LBB0_1025:
	ds_read_b128 v[140:143], v1
	ds_read_b128 v[144:147], v1 offset:1024
	ds_read_b128 v[148:151], v1 offset:2048
	ds_read_b128 v[156:159], v1 offset:3072
	ds_read_b128 v[160:163], v152
	ds_read_b128 v[164:167], v152 offset:1024
	ds_read_b128 v[168:171], v152 offset:2048
	ds_read_b128 v[172:175], v152 offset:3072
	s_add_u32 s0, s82, 0xfff80080
	s_addc_u32 s1, s83, -1
	s_cmp_eq_u32 s81, 28
	s_cselect_b32 s1, s73, s1
	s_cselect_b32 s0, s75, s0
	s_cselect_b32 s65, s96, s80
	s_cselect_b32 s64, s97, s57
	s_mov_b32 m0, s87
	v_lshl_add_u64 v[208:209], s[82:83], 0, v[134:135]
	ds_read_b128 v[176:179], v153
	ds_read_b128 v[180:183], v153 offset:1024
	ds_read_b128 v[184:187], v153 offset:2048
	ds_read_b128 v[188:191], v153 offset:3072
	ds_read_b128 v[192:195], v153 offset:4096
	ds_read_b128 v[196:199], v153 offset:5120
	ds_read_b128 v[200:203], v153 offset:6144
	ds_read_b128 v[204:207], v153 offset:7168
	global_load_lds_dwordx4 v[208:209], off
	v_lshl_add_u64 v[208:209], v[208:209], 0, s[36:37]
	s_mov_b32 m0, s88
	s_nop 0
	global_load_lds_dwordx4 v[208:209], off
	s_waitcnt vmcnt(8)
	s_waitcnt lgkmcnt(0)
	s_barrier
	v_mfma_f32_16x16x32_bf16 v[122:125], v[140:143], v[176:179], v[122:125]
	v_mfma_f32_16x16x32_bf16 v[114:117], v[148:151], v[176:179], v[114:117]
	v_mfma_f32_16x16x32_bf16 v[106:109], v[140:143], v[184:187], v[106:109]
	v_mfma_f32_16x16x32_bf16 v[98:101], v[148:151], v[184:187], v[98:101]
	v_mfma_f32_16x16x32_bf16 v[90:93], v[140:143], v[192:195], v[90:93]
	v_mfma_f32_16x16x32_bf16 v[82:85], v[148:151], v[192:195], v[82:85]
	v_mfma_f32_16x16x32_bf16 v[58:61], v[140:143], v[200:203], v[58:61]
	v_mfma_f32_16x16x32_bf16 v[50:53], v[148:151], v[200:203], v[50:53]
	v_mfma_f32_16x16x32_bf16 v[122:125], v[144:147], v[180:183], v[122:125]
	v_mfma_f32_16x16x32_bf16 v[114:117], v[156:159], v[180:183], v[114:117]
	v_mfma_f32_16x16x32_bf16 v[106:109], v[144:147], v[188:191], v[106:109]
	v_mfma_f32_16x16x32_bf16 v[98:101], v[156:159], v[188:191], v[98:101]
	v_mfma_f32_16x16x32_bf16 v[90:93], v[144:147], v[196:199], v[90:93]
	v_mfma_f32_16x16x32_bf16 v[82:85], v[156:159], v[196:199], v[82:85]
	v_mfma_f32_16x16x32_bf16 v[58:61], v[144:147], v[204:207], v[58:61]
	v_mfma_f32_16x16x32_bf16 v[50:53], v[156:159], v[204:207], v[50:53]
	v_mfma_f32_16x16x32_bf16 v[126:129], v[160:163], v[176:179], v[126:129]
	v_mfma_f32_16x16x32_bf16 v[118:121], v[168:171], v[176:179], v[118:121]
	v_mfma_f32_16x16x32_bf16 v[110:113], v[160:163], v[184:187], v[110:113]
	v_mfma_f32_16x16x32_bf16 v[102:105], v[168:171], v[184:187], v[102:105]
	v_mfma_f32_16x16x32_bf16 v[94:97], v[160:163], v[192:195], v[94:97]
	v_mfma_f32_16x16x32_bf16 v[86:89], v[168:171], v[192:195], v[86:89]
	v_mfma_f32_16x16x32_bf16 v[62:65], v[160:163], v[200:203], v[62:65]
	v_mfma_f32_16x16x32_bf16 v[54:57], v[168:171], v[200:203], v[54:57]
	v_mfma_f32_16x16x32_bf16 v[126:129], v[164:167], v[180:183], v[126:129]
	v_mfma_f32_16x16x32_bf16 v[118:121], v[172:175], v[180:183], v[118:121]
	v_mfma_f32_16x16x32_bf16 v[110:113], v[164:167], v[188:191], v[110:113]
	v_mfma_f32_16x16x32_bf16 v[102:105], v[172:175], v[188:191], v[102:105]
	v_mfma_f32_16x16x32_bf16 v[94:97], v[164:167], v[196:199], v[94:97]
	v_mfma_f32_16x16x32_bf16 v[86:89], v[172:175], v[196:199], v[86:89]
	v_mfma_f32_16x16x32_bf16 v[62:65], v[164:167], v[204:207], v[62:65]
	v_mfma_f32_16x16x32_bf16 v[54:57], v[172:175], v[204:207], v[54:57]
	s_barrier
	s_mov_b32 m0, vcc_lo
	v_lshl_add_u64 v[208:209], s[64:65], 0, v[130:131]
	ds_read_b128 v[176:179], v153 offset:16384
	ds_read_b128 v[180:183], v153 offset:17408
	ds_read_b128 v[184:187], v153 offset:18432
	ds_read_b128 v[188:191], v153 offset:19456
	ds_read_b128 v[192:195], v153 offset:20480
	ds_read_b128 v[196:199], v153 offset:21504
	ds_read_b128 v[200:203], v153 offset:22528
	ds_read_b128 v[204:207], v153 offset:23552
	global_load_lds_dwordx4 v[208:209], off
	v_lshl_add_u64 v[210:211], v[208:209], 0, s[36:37]
	s_mov_b32 m0, vcc_hi
	s_nop 0
	global_load_lds_dwordx4 v[210:211], off
	v_lshl_add_u64 v[210:211], v[208:209], 0, s[38:39]
	s_mov_b32 m0, s40
	s_nop 0
	global_load_lds_dwordx4 v[210:211], off
	v_lshl_add_u64 v[210:211], v[208:209], 0, s[66:67]
	s_mov_b32 m0, s41
	s_nop 0
	global_load_lds_dwordx4 v[210:211], off
	v_lshl_add_u64 v[210:211], s[0:1], 0, v[132:133]
	s_mov_b32 m0, s45
	v_lshl_add_u64 v[212:213], v[210:211], 0, s[36:37]
	global_load_lds_dwordx4 v[210:211], off
	s_mov_b32 m0, s46
	s_nop 0
	global_load_lds_dwordx4 v[212:213], off
	s_waitcnt vmcnt(8)
	s_waitcnt lgkmcnt(0)
	s_barrier
	v_mfma_f32_16x16x32_bf16 v[78:81], v[140:143], v[176:179], v[78:81]
	v_mfma_f32_16x16x32_bf16 v[70:73], v[148:151], v[176:179], v[70:73]
	v_mfma_f32_16x16x32_bf16 v[46:49], v[140:143], v[184:187], v[46:49]
	v_mfma_f32_16x16x32_bf16 v[38:41], v[148:151], v[184:187], v[38:41]
	v_mfma_f32_16x16x32_bf16 v[30:33], v[140:143], v[192:195], v[30:33]
	v_mfma_f32_16x16x32_bf16 v[22:25], v[148:151], v[192:195], v[22:25]
	v_mfma_f32_16x16x32_bf16 v[14:17], v[140:143], v[200:203], v[14:17]
	v_mfma_f32_16x16x32_bf16 v[10:13], v[148:151], v[200:203], v[10:13]
	v_mfma_f32_16x16x32_bf16 v[78:81], v[144:147], v[180:183], v[78:81]
	v_mfma_f32_16x16x32_bf16 v[70:73], v[156:159], v[180:183], v[70:73]
	v_mfma_f32_16x16x32_bf16 v[46:49], v[144:147], v[188:191], v[46:49]
	v_mfma_f32_16x16x32_bf16 v[38:41], v[156:159], v[188:191], v[38:41]
	v_mfma_f32_16x16x32_bf16 v[30:33], v[144:147], v[196:199], v[30:33]
	v_mfma_f32_16x16x32_bf16 v[22:25], v[156:159], v[196:199], v[22:25]
	v_mfma_f32_16x16x32_bf16 v[14:17], v[144:147], v[204:207], v[14:17]
	v_mfma_f32_16x16x32_bf16 v[10:13], v[156:159], v[204:207], v[10:13]
	v_mfma_f32_16x16x32_bf16 v[74:77], v[160:163], v[176:179], v[74:77]
	v_mfma_f32_16x16x32_bf16 v[66:69], v[168:171], v[176:179], v[66:69]
	v_mfma_f32_16x16x32_bf16 v[42:45], v[160:163], v[184:187], v[42:45]
	v_mfma_f32_16x16x32_bf16 v[34:37], v[168:171], v[184:187], v[34:37]
	v_mfma_f32_16x16x32_bf16 v[26:29], v[160:163], v[192:195], v[26:29]
	v_mfma_f32_16x16x32_bf16 v[18:21], v[168:171], v[192:195], v[18:21]
	v_mfma_f32_16x16x32_bf16 v[6:9], v[160:163], v[200:203], v[6:9]
	v_mfma_f32_16x16x32_bf16 v[2:5], v[168:171], v[200:203], v[2:5]
	v_mfma_f32_16x16x32_bf16 v[74:77], v[164:167], v[180:183], v[74:77]
	v_mfma_f32_16x16x32_bf16 v[66:69], v[172:175], v[180:183], v[66:69]
	v_mfma_f32_16x16x32_bf16 v[42:45], v[164:167], v[188:191], v[42:45]
	v_mfma_f32_16x16x32_bf16 v[34:37], v[172:175], v[188:191], v[34:37]
	v_mfma_f32_16x16x32_bf16 v[26:29], v[164:167], v[196:199], v[26:29]
	v_mfma_f32_16x16x32_bf16 v[18:21], v[172:175], v[196:199], v[18:21]
	v_mfma_f32_16x16x32_bf16 v[6:9], v[164:167], v[204:207], v[6:9]
	v_mfma_f32_16x16x32_bf16 v[2:5], v[172:175], v[204:207], v[2:5]
	s_barrier
; #define PG8_WAIT_V(n) asm volatile("s_waitcnt vmcnt(" #n ")" ::: "memory")
; template <class Epi, class Sched, bool ALIGN_EPI = true, bool SP2 = true, bool FULLLINE = false, bool NOSTAGE = false, bool FP8 = false>
; __device__ __forceinline__ void gemm_phase(PG8_LAS unsigned char* lds, const Gemm g, const Sched& S, const Epi& E) {
;     ...
;         static_assert(SP2, "only the SP2 loop is kept");
;         { const int t = 0; if constexpr (Epi::NST == 16) PG8_ITER(PG8_WAIT_V(24)); else if constexpr (Epi::NST == 8) PG8_ITER(PG8_WAIT_V(16)); else PG8_ITER(PG8_WAIT_V(8)); }
;         for (int t = 2; t < nt; t += 2) PG8_ITER(PG8_WAIT_V(8));
	ds_read_b128 v[140:143], v154
	ds_read_b128 v[144:147], v154 offset:1024
	ds_read_b128 v[148:151], v154 offset:2048
	ds_read_b128 v[156:159], v154 offset:3072
	ds_read_b128 v[160:163], v155
	ds_read_b128 v[164:167], v155 offset:1024
	ds_read_b128 v[168:171], v155 offset:2048
	ds_read_b128 v[172:175], v155 offset:3072
	s_mov_b32 m0, s47
	v_lshl_add_u64 v[212:213], v[210:211], 0, s[38:39]
	ds_read_b128 v[176:179], v153 offset:32768
	ds_read_b128 v[180:183], v153 offset:33792
	ds_read_b128 v[184:187], v153 offset:34816
	ds_read_b128 v[188:191], v153 offset:35840
	ds_read_b128 v[192:195], v153 offset:36864
	ds_read_b128 v[196:199], v153 offset:37888
	ds_read_b128 v[200:203], v153 offset:38912
	ds_read_b128 v[204:207], v153 offset:39936
	global_load_lds_dwordx4 v[212:213], off
	v_lshl_add_u64 v[212:213], v[210:211], 0, s[66:67]
	s_mov_b32 m0, s52
	s_nop 0
	global_load_lds_dwordx4 v[212:213], off
	s_waitcnt vmcnt(8)
	s_waitcnt lgkmcnt(0)
	s_barrier
	v_mfma_f32_16x16x32_bf16 v[122:125], v[140:143], v[176:179], v[122:125]
	v_mfma_f32_16x16x32_bf16 v[114:117], v[148:151], v[176:179], v[114:117]
	v_mfma_f32_16x16x32_bf16 v[106:109], v[140:143], v[184:187], v[106:109]
	v_mfma_f32_16x16x32_bf16 v[98:101], v[148:151], v[184:187], v[98:101]
	v_mfma_f32_16x16x32_bf16 v[90:93], v[140:143], v[192:195], v[90:93]
	v_mfma_f32_16x16x32_bf16 v[82:85], v[148:151], v[192:195], v[82:85]
	v_mfma_f32_16x16x32_bf16 v[58:61], v[140:143], v[200:203], v[58:61]
	v_mfma_f32_16x16x32_bf16 v[50:53], v[148:151], v[200:203], v[50:53]
	v_mfma_f32_16x16x32_bf16 v[122:125], v[144:147], v[180:183], v[122:125]
	v_mfma_f32_16x16x32_bf16 v[114:117], v[156:159], v[180:183], v[114:117]
	v_mfma_f32_16x16x32_bf16 v[106:109], v[144:147], v[188:191], v[106:109]
	v_mfma_f32_16x16x32_bf16 v[98:101], v[156:159], v[188:191], v[98:101]
	v_mfma_f32_16x16x32_bf16 v[90:93], v[144:147], v[196:199], v[90:93]
	v_mfma_f32_16x16x32_bf16 v[82:85], v[156:159], v[196:199], v[82:85]
	v_mfma_f32_16x16x32_bf16 v[58:61], v[144:147], v[204:207], v[58:61]
	v_mfma_f32_16x16x32_bf16 v[50:53], v[156:159], v[204:207], v[50:53]
	v_mfma_f32_16x16x32_bf16 v[126:129], v[160:163], v[176:179], v[126:129]
	v_mfma_f32_16x16x32_bf16 v[118:121], v[168:171], v[176:179], v[118:121]
	v_mfma_f32_16x16x32_bf16 v[110:113], v[160:163], v[184:187], v[110:113]
	v_mfma_f32_16x16x32_bf16 v[102:105], v[168:171], v[184:187], v[102:105]
	v_mfma_f32_16x16x32_bf16 v[94:97], v[160:163], v[192:195], v[94:97]
	v_mfma_f32_16x16x32_bf16 v[86:89], v[168:171], v[192:195], v[86:89]
	v_mfma_f32_16x16x32_bf16 v[62:65], v[160:163], v[200:203], v[62:65]
	v_mfma_f32_16x16x32_bf16 v[54:57], v[168:171], v[200:203], v[54:57]
	v_mfma_f32_16x16x32_bf16 v[126:129], v[164:167], v[180:183], v[126:129]
	v_mfma_f32_16x16x32_bf16 v[118:121], v[172:175], v[180:183], v[118:121]
	v_mfma_f32_16x16x32_bf16 v[110:113], v[164:167], v[188:191], v[110:113]
	v_mfma_f32_16x16x32_bf16 v[102:105], v[172:175], v[188:191], v[102:105]
	v_mfma_f32_16x16x32_bf16 v[94:97], v[164:167], v[196:199], v[94:97]
	v_mfma_f32_16x16x32_bf16 v[86:89], v[172:175], v[196:199], v[86:89]
	v_mfma_f32_16x16x32_bf16 v[62:65], v[164:167], v[204:207], v[62:65]
	v_mfma_f32_16x16x32_bf16 v[54:57], v[172:175], v[204:207], v[54:57]
	s_barrier
	s_mov_b32 m0, s50
	v_lshl_add_u64 v[212:213], v[208:209], 0, s[68:69]
	ds_read_b128 v[176:179], v153 offset:49152
	ds_read_b128 v[180:183], v153 offset:50176
	ds_read_b128 v[184:187], v153 offset:51200
	ds_read_b128 v[188:191], v153 offset:52224
	ds_read_b128 v[192:195], v153 offset:53248
	ds_read_b128 v[196:199], v153 offset:54272
	ds_read_b128 v[200:203], v153 offset:55296
	ds_read_b128 v[204:207], v153 offset:56320
	global_load_lds_dwordx4 v[212:213], off
	v_lshl_add_u64 v[212:213], v[208:209], 0, s[70:71]
	s_mov_b32 m0, s51
	s_nop 0
	global_load_lds_dwordx4 v[212:213], off
	v_lshl_add_u64 v[212:213], v[208:209], 0, s[18:19]
	s_mov_b32 m0, s33
	v_lshl_add_u64 v[208:209], v[208:209], 0, s[20:21]
	global_load_lds_dwordx4 v[212:213], off
	s_mov_b32 m0, s56
	s_nop 0
	global_load_lds_dwordx4 v[208:209], off
	v_lshl_add_u64 v[208:209], v[210:211], 0, s[68:69]
	s_mov_b32 m0, s53
	s_nop 0
	global_load_lds_dwordx4 v[208:209], off
	v_lshl_add_u64 v[208:209], v[210:211], 0, s[70:71]
	s_mov_b32 m0, s54
	s_nop 0
	global_load_lds_dwordx4 v[208:209], off
	s_waitcnt vmcnt(8)
	s_waitcnt lgkmcnt(0)
	s_barrier
	v_mfma_f32_16x16x32_bf16 v[78:81], v[140:143], v[176:179], v[78:81]
	v_mfma_f32_16x16x32_bf16 v[70:73], v[148:151], v[176:179], v[70:73]
	v_mfma_f32_16x16x32_bf16 v[46:49], v[140:143], v[184:187], v[46:49]
	v_mfma_f32_16x16x32_bf16 v[38:41], v[148:151], v[184:187], v[38:41]
	v_mfma_f32_16x16x32_bf16 v[30:33], v[140:143], v[192:195], v[30:33]
	v_mfma_f32_16x16x32_bf16 v[22:25], v[148:151], v[192:195], v[22:25]
	v_mfma_f32_16x16x32_bf16 v[14:17], v[140:143], v[200:203], v[14:17]
	v_mfma_f32_16x16x32_bf16 v[10:13], v[148:151], v[200:203], v[10:13]
	v_mfma_f32_16x16x32_bf16 v[78:81], v[144:147], v[180:183], v[78:81]
	v_mfma_f32_16x16x32_bf16 v[70:73], v[156:159], v[180:183], v[70:73]
	v_mfma_f32_16x16x32_bf16 v[46:49], v[144:147], v[188:191], v[46:49]
	v_mfma_f32_16x16x32_bf16 v[38:41], v[156:159], v[188:191], v[38:41]
	v_mfma_f32_16x16x32_bf16 v[30:33], v[144:147], v[196:199], v[30:33]
	v_mfma_f32_16x16x32_bf16 v[22:25], v[156:159], v[196:199], v[22:25]
	v_mfma_f32_16x16x32_bf16 v[14:17], v[144:147], v[204:207], v[14:17]
	v_mfma_f32_16x16x32_bf16 v[10:13], v[156:159], v[204:207], v[10:13]
	v_mfma_f32_16x16x32_bf16 v[74:77], v[160:163], v[176:179], v[74:77]
	v_mfma_f32_16x16x32_bf16 v[66:69], v[168:171], v[176:179], v[66:69]
	v_mfma_f32_16x16x32_bf16 v[42:45], v[160:163], v[184:187], v[42:45]
	v_mfma_f32_16x16x32_bf16 v[34:37], v[168:171], v[184:187], v[34:37]
	v_mfma_f32_16x16x32_bf16 v[26:29], v[160:163], v[192:195], v[26:29]
	v_mfma_f32_16x16x32_bf16 v[18:21], v[168:171], v[192:195], v[18:21]
	v_mfma_f32_16x16x32_bf16 v[6:9], v[160:163], v[200:203], v[6:9]
	v_mfma_f32_16x16x32_bf16 v[2:5], v[168:171], v[200:203], v[2:5]
	v_mfma_f32_16x16x32_bf16 v[74:77], v[164:167], v[180:183], v[74:77]
	v_mfma_f32_16x16x32_bf16 v[66:69], v[172:175], v[180:183], v[66:69]
	v_mfma_f32_16x16x32_bf16 v[42:45], v[164:167], v[188:191], v[42:45]
	v_mfma_f32_16x16x32_bf16 v[34:37], v[172:175], v[188:191], v[34:37]
	v_mfma_f32_16x16x32_bf16 v[26:29], v[164:167], v[196:199], v[26:29]
	v_mfma_f32_16x16x32_bf16 v[18:21], v[172:175], v[196:199], v[18:21]
	v_mfma_f32_16x16x32_bf16 v[6:9], v[164:167], v[204:207], v[6:9]
	v_mfma_f32_16x16x32_bf16 v[2:5], v[172:175], v[204:207], v[2:5]
	s_barrier
	s_add_i32 s81, s81, 2
	s_add_u32 s82, s82, 0x100
	s_addc_u32 s83, s83, 0
	s_add_u32 s57, s57, 0x100
	s_addc_u32 s80, s80, 0
	s_cmp_gt_u32 s81, 29
	s_cbranch_scc0 .LBB0_1025
	s_and_b64 vcc, exec, s[14:15]
	s_cbranch_vccz .LBB0_1028
	s_barrier

; #define PG8_WAIT_V(n) asm volatile("s_waitcnt vmcnt(" #n ")" ::: "memory")
; template <class Epi, class Sched, bool ALIGN_EPI = true, bool SP2 = true, bool FULLLINE = false, bool NOSTAGE = false, bool FP8 = false>
; __device__ __forceinline__ void gemm_phase(PG8_LAS unsigned char* lds, const Gemm g, const Sched& S, const Epi& E) {
;     ...
;         static_assert(SP2, "only the SP2 loop is kept");
;         { const int t = 0; if constexpr (Epi::NST == 16) PG8_ITER(PG8_WAIT_V(24)); else if constexpr (Epi::NST == 8) PG8_ITER(PG8_WAIT_V(16)); else PG8_ITER(PG8_WAIT_V(8)); }
.LBB0_1207:
	s_ashr_i32 s69, s68, 31
	ds_read_b128 v[2:5], v1
	ds_read_b128 v[6:9], v1 offset:1024
	ds_read_b128 v[10:13], v1 offset:2048
	ds_read_b128 v[14:17], v1 offset:3072
	ds_read_b128 v[18:21], v192
	ds_read_b128 v[22:25], v192 offset:1024
	ds_read_b128 v[26:29], v192 offset:2048
	ds_read_b128 v[30:33], v192 offset:3072
	s_lshl_b64 s[0:1], s[68:69], 20
	s_add_u32 s70, s42, s0
	s_addc_u32 s71, s43, s1
	s_and_b64 s[0:1], s[8:9], exec
	s_cselect_b32 s69, s71, s77
	s_cselect_b32 s92, s70, s76
	s_ashr_i32 s67, s66, 31
	s_lshl_b64 s[0:1], s[66:67], 20
	s_add_u32 s72, s44, s0
	s_addc_u32 s73, s45, s1
	s_and_b64 s[0:1], s[8:9], exec
	s_cselect_b32 s67, s73, s79
	s_cselect_b32 s93, s72, s78
	v_lshl_add_u64 v[248:249], s[76:77], 0, v[170:171]
	s_mov_b32 m0, s88
	v_lshl_add_u64 v[66:67], v[248:249], 0, s[12:13]
	ds_read_b128 v[34:37], v193
	ds_read_b128 v[38:41], v193 offset:1024
	ds_read_b128 v[42:45], v193 offset:2048
	ds_read_b128 v[46:49], v193 offset:3072
	ds_read_b128 v[50:53], v193 offset:4096
	ds_read_b128 v[54:57], v193 offset:5120
	ds_read_b128 v[58:61], v193 offset:6144
	ds_read_b128 v[62:65], v193 offset:7168
	global_load_lds_dwordx4 v[66:67], off
	v_lshl_add_u64 v[66:67], v[248:249], 0, s[14:15]
	s_mov_b32 m0, s89
	s_nop 0
	global_load_lds_dwordx4 v[66:67], off
	s_waitcnt vmcnt(24)
	s_waitcnt lgkmcnt(0)
	s_barrier
	v_mfma_f32_16x16x32_bf16 v[66:69], v[2:5], v[34:37], 0
	v_mfma_f32_16x16x32_bf16 v[70:73], v[10:13], v[34:37], 0
	v_mfma_f32_16x16x32_bf16 v[78:81], v[10:13], v[42:45], 0
	v_mfma_f32_16x16x32_bf16 v[86:89], v[10:13], v[50:53], 0
	v_mfma_f32_16x16x32_bf16 v[66:69], v[6:9], v[38:41], v[66:69]
	v_mfma_f32_16x16x32_bf16 v[70:73], v[14:17], v[38:41], v[70:73]
	v_mfma_f32_16x16x32_bf16 v[74:77], v[2:5], v[42:45], 0
	v_mfma_f32_16x16x32_bf16 v[78:81], v[14:17], v[46:49], v[78:81]
	v_mfma_f32_16x16x32_bf16 v[82:85], v[2:5], v[50:53], 0
	v_mfma_f32_16x16x32_bf16 v[86:89], v[14:17], v[54:57], v[86:89]
	v_mfma_f32_16x16x32_bf16 v[90:93], v[2:5], v[58:61], 0
	v_mfma_f32_16x16x32_bf16 v[94:97], v[10:13], v[58:61], 0
	v_mfma_f32_16x16x32_bf16 v[74:77], v[6:9], v[46:49], v[74:77]
	v_mfma_f32_16x16x32_bf16 v[82:85], v[6:9], v[54:57], v[82:85]
	v_mfma_f32_16x16x32_bf16 v[90:93], v[6:9], v[62:65], v[90:93]
	v_mfma_f32_16x16x32_bf16 v[94:97], v[14:17], v[62:65], v[94:97]
	v_mfma_f32_16x16x32_bf16 v[98:101], v[18:21], v[34:37], 0
	v_mfma_f32_16x16x32_bf16 v[34:37], v[26:29], v[34:37], 0
	v_mfma_f32_16x16x32_bf16 v[98:101], v[22:25], v[38:41], v[98:101]
	v_mfma_f32_16x16x32_bf16 v[34:37], v[30:33], v[38:41], v[34:37]
	v_mfma_f32_16x16x32_bf16 v[38:41], v[18:21], v[42:45], 0
	v_mfma_f32_16x16x32_bf16 v[42:45], v[26:29], v[42:45], 0
	v_mfma_f32_16x16x32_bf16 v[38:41], v[22:25], v[46:49], v[38:41]
	v_mfma_f32_16x16x32_bf16 v[42:45], v[30:33], v[46:49], v[42:45]
	v_mfma_f32_16x16x32_bf16 v[46:49], v[18:21], v[50:53], 0
	v_mfma_f32_16x16x32_bf16 v[50:53], v[26:29], v[50:53], 0
	v_mfma_f32_16x16x32_bf16 v[46:49], v[22:25], v[54:57], v[46:49]
	v_mfma_f32_16x16x32_bf16 v[50:53], v[30:33], v[54:57], v[50:53]
	v_mfma_f32_16x16x32_bf16 v[54:57], v[18:21], v[58:61], 0
	v_mfma_f32_16x16x32_bf16 v[58:61], v[26:29], v[58:61], 0
	v_mfma_f32_16x16x32_bf16 v[54:57], v[22:25], v[62:65], v[54:57]
	v_mfma_f32_16x16x32_bf16 v[58:61], v[30:33], v[62:65], v[58:61]
	s_barrier
	v_lshl_add_u64 v[250:251], s[78:79], 0, v[172:173]
	s_add_i32 s94, s85, s46
	v_lshl_add_u64 v[130:131], v[250:251], 0, s[16:17]
	s_mov_b32 m0, s94
	s_add_i32 s95, s94, 0x2000
	ds_read_b128 v[62:65], v193 offset:16384
	ds_read_b128 v[102:105], v193 offset:17408
	ds_read_b128 v[106:109], v193 offset:18432
	ds_read_b128 v[110:113], v193 offset:19456
	ds_read_b128 v[114:117], v193 offset:20480
	ds_read_b128 v[118:121], v193 offset:21504
	ds_read_b128 v[122:125], v193 offset:22528
	ds_read_b128 v[126:129], v193 offset:23552
	global_load_lds_dwordx4 v[130:131], off
	v_lshl_add_u64 v[130:131], v[250:251], 0, s[18:19]
	s_mov_b32 m0, s95
	s_add_i32 s40, s87, s46
	global_load_lds_dwordx4 v[130:131], off
	v_lshl_add_u64 v[130:131], v[250:251], 0, s[20:21]
	s_mov_b32 m0, s40
	s_add_i32 s41, s40, 0x2000
	global_load_lds_dwordx4 v[130:131], off
	v_lshl_add_u64 v[130:131], v[250:251], 0, s[22:23]
	s_mov_b32 m0, s41
	s_nop 0
	global_load_lds_dwordx4 v[130:131], off
	v_lshl_add_u64 v[130:131], v[248:249], 0, s[16:17]
	s_mov_b32 m0, s47
	s_nop 0
	global_load_lds_dwordx4 v[130:131], off
	v_lshl_add_u64 v[130:131], v[248:249], 0, s[18:19]
	s_mov_b32 m0, s52
	s_nop 0
	global_load_lds_dwordx4 v[130:131], off
	s_waitcnt vmcnt(24)
	s_waitcnt lgkmcnt(0)
	s_barrier
	v_mfma_f32_16x16x32_bf16 v[130:133], v[2:5], v[62:65], 0
	v_mfma_f32_16x16x32_bf16 v[138:141], v[6:9], v[102:105], v[130:133]
	v_mfma_f32_16x16x32_bf16 v[130:133], v[10:13], v[62:65], 0
	v_mfma_f32_16x16x32_bf16 v[150:153], v[14:17], v[102:105], v[130:133]
	v_mfma_f32_16x16x32_bf16 v[130:133], v[2:5], v[106:109], 0
	v_mfma_f32_16x16x32_bf16 v[154:157], v[6:9], v[110:113], v[130:133]
	v_mfma_f32_16x16x32_bf16 v[130:133], v[10:13], v[106:109], 0
	v_mfma_f32_16x16x32_bf16 v[158:161], v[14:17], v[110:113], v[130:133]
	v_mfma_f32_16x16x32_bf16 v[130:133], v[2:5], v[114:117], 0
	v_mfma_f32_16x16x32_bf16 v[2:5], v[2:5], v[122:125], 0
	v_mfma_f32_16x16x32_bf16 v[162:165], v[6:9], v[118:121], v[130:133]
	v_mfma_f32_16x16x32_bf16 v[2:5], v[6:9], v[126:129], v[2:5]
	v_mfma_f32_16x16x32_bf16 v[6:9], v[10:13], v[122:125], 0
	v_mfma_f32_16x16x32_bf16 v[130:133], v[10:13], v[114:117], 0
	v_mfma_f32_16x16x32_bf16 v[6:9], v[14:17], v[126:129], v[6:9]
	v_mfma_f32_16x16x32_bf16 v[166:169], v[14:17], v[118:121], v[130:133]
	v_mfma_f32_16x16x32_bf16 v[10:13], v[18:21], v[62:65], 0
	v_mfma_f32_16x16x32_bf16 v[180:183], v[22:25], v[102:105], v[10:13]
	v_mfma_f32_16x16x32_bf16 v[10:13], v[26:29], v[62:65], 0
	v_mfma_f32_16x16x32_bf16 v[184:187], v[30:33], v[102:105], v[10:13]
	v_mfma_f32_16x16x32_bf16 v[10:13], v[18:21], v[106:109], 0
	v_mfma_f32_16x16x32_bf16 v[188:191], v[22:25], v[110:113], v[10:13]
	v_mfma_f32_16x16x32_bf16 v[10:13], v[26:29], v[106:109], 0
	v_mfma_f32_16x16x32_bf16 v[196:199], v[30:33], v[110:113], v[10:13]
	v_mfma_f32_16x16x32_bf16 v[10:13], v[18:21], v[114:117], 0
	v_mfma_f32_16x16x32_bf16 v[200:203], v[22:25], v[118:121], v[10:13]
	v_mfma_f32_16x16x32_bf16 v[10:13], v[26:29], v[114:117], 0
	v_mfma_f32_16x16x32_bf16 v[204:207], v[30:33], v[118:121], v[10:13]
	v_mfma_f32_16x16x32_bf16 v[10:13], v[18:21], v[122:125], 0
	v_mfma_f32_16x16x32_bf16 v[208:211], v[22:25], v[126:129], v[10:13]
	v_mfma_f32_16x16x32_bf16 v[10:13], v[26:29], v[122:125], 0
	v_mfma_f32_16x16x32_bf16 v[212:215], v[30:33], v[126:129], v[10:13]
	s_barrier
; #define PG8_WAIT_V(n) asm volatile("s_waitcnt vmcnt(" #n ")" ::: "memory")
; template <class Epi, class Sched, bool ALIGN_EPI = true, bool SP2 = true, bool FULLLINE = false, bool NOSTAGE = false, bool FP8 = false>
; __device__ __forceinline__ void gemm_phase(PG8_LAS unsigned char* lds, const Gemm g, const Sched& S, const Epi& E) {
;     ...
;         static_assert(SP2, "only the SP2 loop is kept");
;         { const int t = 0; if constexpr (Epi::NST == 16) PG8_ITER(PG8_WAIT_V(24)); else if constexpr (Epi::NST == 8) PG8_ITER(PG8_WAIT_V(16)); else PG8_ITER(PG8_WAIT_V(8)); }
	s_nop 5
	ds_read_b128 v[10:13], v194
	ds_read_b128 v[14:17], v194 offset:1024
	ds_read_b128 v[18:21], v194 offset:2048
	ds_read_b128 v[22:25], v194 offset:3072
	ds_read_b128 v[216:219], v195
	ds_read_b128 v[220:223], v195 offset:1024
	ds_read_b128 v[224:227], v195 offset:2048
	ds_read_b128 v[228:231], v195 offset:3072
	s_mov_b32 m0, s53
	v_lshl_add_u64 v[106:107], v[248:249], 0, s[20:21]
	ds_read_b128 v[26:29], v193 offset:32768
	ds_read_b128 v[30:33], v193 offset:33792
	ds_read_b128 v[62:65], v193 offset:34816
	ds_read_b128 v[102:105], v193 offset:35840
	ds_read_b128 v[232:235], v193 offset:36864
	ds_read_b128 v[236:239], v193 offset:37888
	ds_read_b128 v[240:243], v193 offset:38912
	ds_read_b128 v[244:247], v193 offset:39936
	global_load_lds_dwordx4 v[106:107], off
	v_lshl_add_u64 v[106:107], v[248:249], 0, s[22:23]
	s_mov_b32 m0, s54
	s_nop 0
	global_load_lds_dwordx4 v[106:107], off
	s_waitcnt vmcnt(8)
	s_waitcnt lgkmcnt(0)
	s_barrier
	v_mfma_f32_16x16x32_bf16 v[66:69], v[10:13], v[26:29], v[66:69]
	v_mfma_f32_16x16x32_bf16 v[146:149], v[14:17], v[30:33], v[66:69]
	v_mfma_f32_16x16x32_bf16 v[66:69], v[18:21], v[26:29], v[70:73]
	v_mfma_f32_16x16x32_bf16 v[142:145], v[22:25], v[30:33], v[66:69]
	v_mfma_f32_16x16x32_bf16 v[66:69], v[10:13], v[62:65], v[74:77]
	v_mfma_f32_16x16x32_bf16 v[126:129], v[14:17], v[102:105], v[66:69]
	v_mfma_f32_16x16x32_bf16 v[66:69], v[18:21], v[62:65], v[78:81]
	v_mfma_f32_16x16x32_bf16 v[122:125], v[22:25], v[102:105], v[66:69]
	v_mfma_f32_16x16x32_bf16 v[66:69], v[10:13], v[232:235], v[82:85]
	v_mfma_f32_16x16x32_bf16 v[110:113], v[14:17], v[236:239], v[66:69]
	v_mfma_f32_16x16x32_bf16 v[66:69], v[18:21], v[232:235], v[86:89]
	v_mfma_f32_16x16x32_bf16 v[106:109], v[22:25], v[236:239], v[66:69]
	v_mfma_f32_16x16x32_bf16 v[66:69], v[10:13], v[240:243], v[90:93]
	v_mfma_f32_16x16x32_bf16 v[86:89], v[14:17], v[244:247], v[66:69]
	v_mfma_f32_16x16x32_bf16 v[66:69], v[18:21], v[240:243], v[94:97]
	v_mfma_f32_16x16x32_bf16 v[78:81], v[22:25], v[244:247], v[66:69]
	v_mfma_f32_16x16x32_bf16 v[66:69], v[216:219], v[26:29], v[98:101]
	v_mfma_f32_16x16x32_bf16 v[26:29], v[224:227], v[26:29], v[34:37]
	v_mfma_f32_16x16x32_bf16 v[130:133], v[228:231], v[30:33], v[26:29]
	v_mfma_f32_16x16x32_bf16 v[26:29], v[216:219], v[62:65], v[38:41]
	v_mfma_f32_16x16x32_bf16 v[118:121], v[220:223], v[102:105], v[26:29]
	v_mfma_f32_16x16x32_bf16 v[26:29], v[224:227], v[62:65], v[42:45]
	v_mfma_f32_16x16x32_bf16 v[114:117], v[228:231], v[102:105], v[26:29]
	v_mfma_f32_16x16x32_bf16 v[26:29], v[216:219], v[232:235], v[46:49]
	v_mfma_f32_16x16x32_bf16 v[102:105], v[220:223], v[236:239], v[26:29]
	v_mfma_f32_16x16x32_bf16 v[26:29], v[224:227], v[232:235], v[50:53]
	v_mfma_f32_16x16x32_bf16 v[98:101], v[228:231], v[236:239], v[26:29]
	v_mfma_f32_16x16x32_bf16 v[26:29], v[216:219], v[240:243], v[54:57]
	v_mfma_f32_16x16x32_bf16 v[70:73], v[220:223], v[244:247], v[26:29]
	v_mfma_f32_16x16x32_bf16 v[26:29], v[224:227], v[240:243], v[58:61]
	v_mfma_f32_16x16x32_bf16 v[134:137], v[220:223], v[30:33], v[66:69]
	v_mfma_f32_16x16x32_bf16 v[66:69], v[228:231], v[244:247], v[26:29]
	s_barrier
	s_add_i32 s50, s90, s46
	s_nop 3
	v_lshl_add_u64 v[26:27], v[250:251], 0, s[24:25]
	s_mov_b32 m0, s50
	s_add_i32 s51, s50, 0x2000
	ds_read_b128 v[34:37], v193 offset:49152
	ds_read_b128 v[38:41], v193 offset:50176
	ds_read_b128 v[74:77], v193 offset:51200
	ds_read_b128 v[82:85], v193 offset:52224
	ds_read_b128 v[90:93], v193 offset:53248
	ds_read_b128 v[94:97], v193 offset:54272
	ds_read_b128 v[232:235], v193 offset:55296
	ds_read_b128 v[236:239], v193 offset:56320
	global_load_lds_dwordx4 v[26:27], off
	v_lshl_add_u64 v[26:27], v[250:251], 0, s[26:27]
	s_mov_b32 m0, s51
	s_mov_b64 s[0:1], 0x80180
	s_add_i32 s33, s91, s46
	global_load_lds_dwordx4 v[26:27], off
	v_lshl_add_u64 v[26:27], v[250:251], 0, s[0:1]
	s_mov_b32 m0, s33
	s_mov_b64 s[0:1], 0xc0180
	s_add_i32 s56, s33, 0x2000
	global_load_lds_dwordx4 v[26:27], off
	v_lshl_add_u64 v[26:27], v[250:251], 0, s[0:1]
	s_mov_b32 m0, s56
	s_nop 0
	global_load_lds_dwordx4 v[26:27], off
	v_lshl_add_u64 v[26:27], v[248:249], 0, s[24:25]
	s_mov_b32 m0, s55
	s_nop 0
	global_load_lds_dwordx4 v[26:27], off
	v_lshl_add_u64 v[26:27], v[248:249], 0, s[26:27]
	s_mov_b32 m0, s62
	s_nop 0
	global_load_lds_dwordx4 v[26:27], off
	s_waitcnt vmcnt(8)
	s_waitcnt lgkmcnt(0)
	s_barrier
	v_mfma_f32_16x16x32_bf16 v[26:29], v[10:13], v[34:37], v[138:141]
	v_mfma_f32_16x16x32_bf16 v[62:65], v[14:17], v[38:41], v[26:29]
	v_mfma_f32_16x16x32_bf16 v[26:29], v[18:21], v[34:37], v[150:153]
	v_mfma_f32_16x16x32_bf16 v[58:61], v[22:25], v[38:41], v[26:29]
	v_mfma_f32_16x16x32_bf16 v[26:29], v[10:13], v[74:77], v[154:157]
	v_mfma_f32_16x16x32_bf16 v[46:49], v[14:17], v[82:85], v[26:29]
	v_mfma_f32_16x16x32_bf16 v[26:29], v[18:21], v[74:77], v[158:161]
	v_mfma_f32_16x16x32_bf16 v[42:45], v[22:25], v[82:85], v[26:29]
	v_mfma_f32_16x16x32_bf16 v[26:29], v[10:13], v[90:93], v[162:165]
	v_mfma_f32_16x16x32_bf16 v[2:5], v[10:13], v[232:235], v[2:5]
	v_mfma_f32_16x16x32_bf16 v[30:33], v[14:17], v[94:97], v[26:29]
	v_mfma_f32_16x16x32_bf16 v[26:29], v[18:21], v[90:93], v[166:169]
	v_mfma_f32_16x16x32_bf16 v[14:17], v[14:17], v[236:239], v[2:5]
	v_mfma_f32_16x16x32_bf16 v[2:5], v[18:21], v[232:235], v[6:9]
	v_mfma_f32_16x16x32_bf16 v[26:29], v[22:25], v[94:97], v[26:29]
	v_mfma_f32_16x16x32_bf16 v[10:13], v[22:25], v[236:239], v[2:5]
	v_mfma_f32_16x16x32_bf16 v[2:5], v[216:219], v[34:37], v[180:183]
	v_mfma_f32_16x16x32_bf16 v[54:57], v[220:223], v[38:41], v[2:5]
	v_mfma_f32_16x16x32_bf16 v[2:5], v[224:227], v[34:37], v[184:187]
	v_mfma_f32_16x16x32_bf16 v[50:53], v[228:231], v[38:41], v[2:5]
	v_mfma_f32_16x16x32_bf16 v[2:5], v[216:219], v[74:77], v[188:191]
	v_mfma_f32_16x16x32_bf16 v[38:41], v[220:223], v[82:85], v[2:5]
	v_mfma_f32_16x16x32_bf16 v[2:5], v[224:227], v[74:77], v[196:199]
	v_mfma_f32_16x16x32_bf16 v[34:37], v[228:231], v[82:85], v[2:5]
	v_mfma_f32_16x16x32_bf16 v[2:5], v[216:219], v[90:93], v[200:203]
	v_mfma_f32_16x16x32_bf16 v[22:25], v[220:223], v[94:97], v[2:5]
	v_mfma_f32_16x16x32_bf16 v[2:5], v[224:227], v[90:93], v[204:207]
	v_mfma_f32_16x16x32_bf16 v[18:21], v[228:231], v[94:97], v[2:5]
	v_mfma_f32_16x16x32_bf16 v[2:5], v[216:219], v[232:235], v[208:211]
	v_mfma_f32_16x16x32_bf16 v[6:9], v[220:223], v[236:239], v[2:5]
	v_mfma_f32_16x16x32_bf16 v[2:5], v[224:227], v[232:235], v[212:215]
	v_mfma_f32_16x16x32_bf16 v[2:5], v[228:231], v[236:239], v[2:5]
	s_barrier
	s_add_u32 s76, s76, 0x80180
	s_addc_u32 s77, s77, 0
	s_add_u32 s57, s78, 0x200
	s_addc_u32 s78, s79, 0
	s_mov_b32 s79, 0
; #define PG8_WAIT_V(n) asm volatile("s_waitcnt vmcnt(" #n ")" ::: "memory")
; template <class Epi, class Sched, bool ALIGN_EPI = true, bool SP2 = true, bool FULLLINE = false, bool NOSTAGE = false, bool FP8 = false>
; __device__ __forceinline__ void gemm_phase(PG8_LAS unsigned char* lds, const Gemm g, const Sched& S, const Epi& E) {
;     ...
;         static_assert(SP2, "only the SP2 loop is kept");
;         { const int t = 0; if constexpr (Epi::NST == 16) PG8_ITER(PG8_WAIT_V(24)); else if constexpr (Epi::NST == 8) PG8_ITER(PG8_WAIT_V(16)); else PG8_ITER(PG8_WAIT_V(8)); }
;         for (int t = 2; t < nt; t += 2) PG8_ITER(PG8_WAIT_V(8));
.LBB0_1208:
	ds_read_b128 v[74:77], v1
	ds_read_b128 v[82:85], v1 offset:1024
	ds_read_b128 v[90:93], v1 offset:2048
	ds_read_b128 v[94:97], v1 offset:3072
	ds_read_b128 v[138:141], v192
	ds_read_b128 v[150:153], v192 offset:1024
	ds_read_b128 v[154:157], v192 offset:2048
	ds_read_b128 v[158:161], v192 offset:3072
	s_add_u32 s0, s76, 0xfff80080
	s_addc_u32 s1, s77, -1
	s_cmp_eq_u32 s79, 28
	s_cselect_b32 s1, s69, s1
	s_cselect_b32 s0, s92, s0
	s_cselect_b32 s65, s67, s78
	s_cselect_b32 s64, s93, s57
	s_mov_b32 m0, s88
	v_lshl_add_u64 v[208:209], s[76:77], 0, v[174:175]
	ds_read_b128 v[162:165], v193
	ds_read_b128 v[166:169], v193 offset:1024
	ds_read_b128 v[180:183], v193 offset:2048
	ds_read_b128 v[184:187], v193 offset:3072
	ds_read_b128 v[188:191], v193 offset:4096
	ds_read_b128 v[196:199], v193 offset:5120
	ds_read_b128 v[200:203], v193 offset:6144
	ds_read_b128 v[204:207], v193 offset:7168
	global_load_lds_dwordx4 v[208:209], off
	v_lshl_add_u64 v[208:209], v[208:209], 0, s[28:29]
	s_mov_b32 m0, s89
	s_nop 0
	global_load_lds_dwordx4 v[208:209], off
	s_waitcnt vmcnt(8)
	s_waitcnt lgkmcnt(0)
	s_barrier
	v_mfma_f32_16x16x32_bf16 v[146:149], v[74:77], v[162:165], v[146:149]
	v_mfma_f32_16x16x32_bf16 v[142:145], v[90:93], v[162:165], v[142:145]
	v_mfma_f32_16x16x32_bf16 v[126:129], v[74:77], v[180:183], v[126:129]
	v_mfma_f32_16x16x32_bf16 v[122:125], v[90:93], v[180:183], v[122:125]
	v_mfma_f32_16x16x32_bf16 v[110:113], v[74:77], v[188:191], v[110:113]
	v_mfma_f32_16x16x32_bf16 v[106:109], v[90:93], v[188:191], v[106:109]
	v_mfma_f32_16x16x32_bf16 v[86:89], v[74:77], v[200:203], v[86:89]
	v_mfma_f32_16x16x32_bf16 v[78:81], v[90:93], v[200:203], v[78:81]
	v_mfma_f32_16x16x32_bf16 v[146:149], v[82:85], v[166:169], v[146:149]
	v_mfma_f32_16x16x32_bf16 v[142:145], v[94:97], v[166:169], v[142:145]
	v_mfma_f32_16x16x32_bf16 v[126:129], v[82:85], v[184:187], v[126:129]
	v_mfma_f32_16x16x32_bf16 v[122:125], v[94:97], v[184:187], v[122:125]
	v_mfma_f32_16x16x32_bf16 v[110:113], v[82:85], v[196:199], v[110:113]
	v_mfma_f32_16x16x32_bf16 v[106:109], v[94:97], v[196:199], v[106:109]
	v_mfma_f32_16x16x32_bf16 v[86:89], v[82:85], v[204:207], v[86:89]
	v_mfma_f32_16x16x32_bf16 v[78:81], v[94:97], v[204:207], v[78:81]
	v_mfma_f32_16x16x32_bf16 v[134:137], v[138:141], v[162:165], v[134:137]
	v_mfma_f32_16x16x32_bf16 v[130:133], v[154:157], v[162:165], v[130:133]
	v_mfma_f32_16x16x32_bf16 v[118:121], v[138:141], v[180:183], v[118:121]
	v_mfma_f32_16x16x32_bf16 v[114:117], v[154:157], v[180:183], v[114:117]
	v_mfma_f32_16x16x32_bf16 v[102:105], v[138:141], v[188:191], v[102:105]
	v_mfma_f32_16x16x32_bf16 v[98:101], v[154:157], v[188:191], v[98:101]
	v_mfma_f32_16x16x32_bf16 v[70:73], v[138:141], v[200:203], v[70:73]
	v_mfma_f32_16x16x32_bf16 v[66:69], v[154:157], v[200:203], v[66:69]
	v_mfma_f32_16x16x32_bf16 v[134:137], v[150:153], v[166:169], v[134:137]
	v_mfma_f32_16x16x32_bf16 v[130:133], v[158:161], v[166:169], v[130:133]
	v_mfma_f32_16x16x32_bf16 v[118:121], v[150:153], v[184:187], v[118:121]
	v_mfma_f32_16x16x32_bf16 v[114:117], v[158:161], v[184:187], v[114:117]
	v_mfma_f32_16x16x32_bf16 v[102:105], v[150:153], v[196:199], v[102:105]
	v_mfma_f32_16x16x32_bf16 v[98:101], v[158:161], v[196:199], v[98:101]
	v_mfma_f32_16x16x32_bf16 v[70:73], v[150:153], v[204:207], v[70:73]
	v_mfma_f32_16x16x32_bf16 v[66:69], v[158:161], v[204:207], v[66:69]
	s_barrier
	s_mov_b32 m0, s94
	v_lshl_add_u64 v[208:209], s[64:65], 0, v[172:173]
	ds_read_b128 v[162:165], v193 offset:16384
	ds_read_b128 v[166:169], v193 offset:17408
	ds_read_b128 v[180:183], v193 offset:18432
	ds_read_b128 v[184:187], v193 offset:19456
	ds_read_b128 v[188:191], v193 offset:20480
	ds_read_b128 v[196:199], v193 offset:21504
	ds_read_b128 v[200:203], v193 offset:22528
	ds_read_b128 v[204:207], v193 offset:23552
	global_load_lds_dwordx4 v[208:209], off
	v_lshl_add_u64 v[210:211], v[208:209], 0, s[28:29]
	s_mov_b32 m0, s95
	s_nop 0
	global_load_lds_dwordx4 v[210:211], off
	v_lshl_add_u64 v[210:211], v[208:209], 0, s[30:31]
	s_mov_b32 m0, s40
	s_nop 0
	global_load_lds_dwordx4 v[210:211], off
	v_lshl_add_u64 v[210:211], v[208:209], 0, s[34:35]
	s_mov_b32 m0, s41
	s_nop 0
	global_load_lds_dwordx4 v[210:211], off
	v_lshl_add_u64 v[210:211], s[0:1], 0, v[170:171]
	s_mov_b32 m0, s47
	v_lshl_add_u64 v[212:213], v[210:211], 0, s[28:29]
	global_load_lds_dwordx4 v[210:211], off
	s_mov_b32 m0, s52
	s_nop 0
	global_load_lds_dwordx4 v[212:213], off
	s_waitcnt vmcnt(8)
	s_waitcnt lgkmcnt(0)
	s_barrier
	v_mfma_f32_16x16x32_bf16 v[62:65], v[74:77], v[162:165], v[62:65]
	v_mfma_f32_16x16x32_bf16 v[58:61], v[90:93], v[162:165], v[58:61]
	v_mfma_f32_16x16x32_bf16 v[46:49], v[74:77], v[180:183], v[46:49]
	v_mfma_f32_16x16x32_bf16 v[42:45], v[90:93], v[180:183], v[42:45]
	v_mfma_f32_16x16x32_bf16 v[30:33], v[74:77], v[188:191], v[30:33]
	v_mfma_f32_16x16x32_bf16 v[26:29], v[90:93], v[188:191], v[26:29]
	v_mfma_f32_16x16x32_bf16 v[14:17], v[74:77], v[200:203], v[14:17]
	v_mfma_f32_16x16x32_bf16 v[10:13], v[90:93], v[200:203], v[10:13]
	v_mfma_f32_16x16x32_bf16 v[62:65], v[82:85], v[166:169], v[62:65]
	v_mfma_f32_16x16x32_bf16 v[58:61], v[94:97], v[166:169], v[58:61]
	v_mfma_f32_16x16x32_bf16 v[46:49], v[82:85], v[184:187], v[46:49]
	v_mfma_f32_16x16x32_bf16 v[42:45], v[94:97], v[184:187], v[42:45]
	v_mfma_f32_16x16x32_bf16 v[30:33], v[82:85], v[196:199], v[30:33]
	v_mfma_f32_16x16x32_bf16 v[26:29], v[94:97], v[196:199], v[26:29]
	v_mfma_f32_16x16x32_bf16 v[14:17], v[82:85], v[204:207], v[14:17]
	v_mfma_f32_16x16x32_bf16 v[10:13], v[94:97], v[204:207], v[10:13]
	v_mfma_f32_16x16x32_bf16 v[54:57], v[138:141], v[162:165], v[54:57]
	v_mfma_f32_16x16x32_bf16 v[50:53], v[154:157], v[162:165], v[50:53]
	v_mfma_f32_16x16x32_bf16 v[38:41], v[138:141], v[180:183], v[38:41]
	v_mfma_f32_16x16x32_bf16 v[34:37], v[154:157], v[180:183], v[34:37]
	v_mfma_f32_16x16x32_bf16 v[22:25], v[138:141], v[188:191], v[22:25]
	v_mfma_f32_16x16x32_bf16 v[18:21], v[154:157], v[188:191], v[18:21]
	v_mfma_f32_16x16x32_bf16 v[6:9], v[138:141], v[200:203], v[6:9]
	v_mfma_f32_16x16x32_bf16 v[2:5], v[154:157], v[200:203], v[2:5]
	v_mfma_f32_16x16x32_bf16 v[54:57], v[150:153], v[166:169], v[54:57]
	v_mfma_f32_16x16x32_bf16 v[50:53], v[158:161], v[166:169], v[50:53]
	v_mfma_f32_16x16x32_bf16 v[38:41], v[150:153], v[184:187], v[38:41]
	v_mfma_f32_16x16x32_bf16 v[34:37], v[158:161], v[184:187], v[34:37]
	v_mfma_f32_16x16x32_bf16 v[22:25], v[150:153], v[196:199], v[22:25]
	v_mfma_f32_16x16x32_bf16 v[18:21], v[158:161], v[196:199], v[18:21]
	v_mfma_f32_16x16x32_bf16 v[6:9], v[150:153], v[204:207], v[6:9]
	v_mfma_f32_16x16x32_bf16 v[2:5], v[158:161], v[204:207], v[2:5]
	s_barrier
; #define PG8_WAIT_V(n) asm volatile("s_waitcnt vmcnt(" #n ")" ::: "memory")
; #define PG8_BAR __builtin_amdgcn_s_barrier()
; template <class Epi, class Sched, bool ALIGN_EPI = true, bool SP2 = true, bool FULLLINE = false, bool NOSTAGE = false, bool FP8 = false>
; __device__ __forceinline__ void gemm_phase(PG8_LAS unsigned char* lds, const Gemm g, const Sched& S, const Epi& E) {
;     ...
;         static_assert(SP2, "only the SP2 loop is kept");
;         { const int t = 0; if constexpr (Epi::NST == 16) PG8_ITER(PG8_WAIT_V(24)); else if constexpr (Epi::NST == 8) PG8_ITER(PG8_WAIT_V(16)); else PG8_ITER(PG8_WAIT_V(8)); }
;         for (int t = 2; t < nt; t += 2) PG8_ITER(PG8_WAIT_V(8));
;     ...
;         if constexpr (ALIGN_EPI) { if (wr == 0) PG8_BAR; }
	ds_read_b128 v[74:77], v194
	ds_read_b128 v[82:85], v194 offset:1024
	ds_read_b128 v[90:93], v194 offset:2048
	ds_read_b128 v[94:97], v194 offset:3072
	ds_read_b128 v[138:141], v195
	ds_read_b128 v[150:153], v195 offset:1024
	ds_read_b128 v[154:157], v195 offset:2048
	ds_read_b128 v[158:161], v195 offset:3072
	s_mov_b32 m0, s53
	v_lshl_add_u64 v[212:213], v[210:211], 0, s[30:31]
	ds_read_b128 v[162:165], v193 offset:32768
	ds_read_b128 v[166:169], v193 offset:33792
	ds_read_b128 v[180:183], v193 offset:34816
	ds_read_b128 v[184:187], v193 offset:35840
	ds_read_b128 v[188:191], v193 offset:36864
	ds_read_b128 v[196:199], v193 offset:37888
	ds_read_b128 v[200:203], v193 offset:38912
	ds_read_b128 v[204:207], v193 offset:39936
	global_load_lds_dwordx4 v[212:213], off
	v_lshl_add_u64 v[212:213], v[210:211], 0, s[34:35]
	s_mov_b32 m0, s54
	s_nop 0
	global_load_lds_dwordx4 v[212:213], off
	s_waitcnt vmcnt(8)
	s_waitcnt lgkmcnt(0)
	s_barrier
	v_mfma_f32_16x16x32_bf16 v[146:149], v[74:77], v[162:165], v[146:149]
	v_mfma_f32_16x16x32_bf16 v[142:145], v[90:93], v[162:165], v[142:145]
	v_mfma_f32_16x16x32_bf16 v[126:129], v[74:77], v[180:183], v[126:129]
	v_mfma_f32_16x16x32_bf16 v[122:125], v[90:93], v[180:183], v[122:125]
	v_mfma_f32_16x16x32_bf16 v[110:113], v[74:77], v[188:191], v[110:113]
	v_mfma_f32_16x16x32_bf16 v[106:109], v[90:93], v[188:191], v[106:109]
	v_mfma_f32_16x16x32_bf16 v[86:89], v[74:77], v[200:203], v[86:89]
	v_mfma_f32_16x16x32_bf16 v[78:81], v[90:93], v[200:203], v[78:81]
	v_mfma_f32_16x16x32_bf16 v[146:149], v[82:85], v[166:169], v[146:149]
	v_mfma_f32_16x16x32_bf16 v[142:145], v[94:97], v[166:169], v[142:145]
	v_mfma_f32_16x16x32_bf16 v[126:129], v[82:85], v[184:187], v[126:129]
	v_mfma_f32_16x16x32_bf16 v[122:125], v[94:97], v[184:187], v[122:125]
	v_mfma_f32_16x16x32_bf16 v[110:113], v[82:85], v[196:199], v[110:113]
	v_mfma_f32_16x16x32_bf16 v[106:109], v[94:97], v[196:199], v[106:109]
	v_mfma_f32_16x16x32_bf16 v[86:89], v[82:85], v[204:207], v[86:89]
	v_mfma_f32_16x16x32_bf16 v[78:81], v[94:97], v[204:207], v[78:81]
	v_mfma_f32_16x16x32_bf16 v[134:137], v[138:141], v[162:165], v[134:137]
	v_mfma_f32_16x16x32_bf16 v[130:133], v[154:157], v[162:165], v[130:133]
	v_mfma_f32_16x16x32_bf16 v[118:121], v[138:141], v[180:183], v[118:121]
	v_mfma_f32_16x16x32_bf16 v[114:117], v[154:157], v[180:183], v[114:117]
	v_mfma_f32_16x16x32_bf16 v[102:105], v[138:141], v[188:191], v[102:105]
	v_mfma_f32_16x16x32_bf16 v[98:101], v[154:157], v[188:191], v[98:101]
	v_mfma_f32_16x16x32_bf16 v[70:73], v[138:141], v[200:203], v[70:73]
	v_mfma_f32_16x16x32_bf16 v[66:69], v[154:157], v[200:203], v[66:69]
	v_mfma_f32_16x16x32_bf16 v[134:137], v[150:153], v[166:169], v[134:137]
	v_mfma_f32_16x16x32_bf16 v[130:133], v[158:161], v[166:169], v[130:133]
	v_mfma_f32_16x16x32_bf16 v[118:121], v[150:153], v[184:187], v[118:121]
	v_mfma_f32_16x16x32_bf16 v[114:117], v[158:161], v[184:187], v[114:117]
	v_mfma_f32_16x16x32_bf16 v[102:105], v[150:153], v[196:199], v[102:105]
	v_mfma_f32_16x16x32_bf16 v[98:101], v[158:161], v[196:199], v[98:101]
	v_mfma_f32_16x16x32_bf16 v[70:73], v[150:153], v[204:207], v[70:73]
	v_mfma_f32_16x16x32_bf16 v[66:69], v[158:161], v[204:207], v[66:69]
	s_barrier
	s_mov_b32 m0, s50
	v_lshl_add_u64 v[212:213], v[208:209], 0, s[36:37]
	ds_read_b128 v[162:165], v193 offset:49152
	ds_read_b128 v[166:169], v193 offset:50176
	ds_read_b128 v[180:183], v193 offset:51200
	ds_read_b128 v[184:187], v193 offset:52224
	ds_read_b128 v[188:191], v193 offset:53248
	ds_read_b128 v[196:199], v193 offset:54272
	ds_read_b128 v[200:203], v193 offset:55296
	ds_read_b128 v[204:207], v193 offset:56320
	global_load_lds_dwordx4 v[212:213], off
	v_lshl_add_u64 v[212:213], v[208:209], 0, s[38:39]
	s_mov_b32 m0, s51
	s_nop 0
	global_load_lds_dwordx4 v[212:213], off
	v_lshl_add_u64 v[212:213], v[208:209], 0, s[12:13]
	s_mov_b32 m0, s33
	v_lshl_add_u64 v[208:209], v[208:209], 0, s[14:15]
	global_load_lds_dwordx4 v[212:213], off
	s_mov_b32 m0, s56
	s_nop 0
	global_load_lds_dwordx4 v[208:209], off
	v_lshl_add_u64 v[208:209], v[210:211], 0, s[36:37]
	s_mov_b32 m0, s55
	s_nop 0
	global_load_lds_dwordx4 v[208:209], off
	v_lshl_add_u64 v[208:209], v[210:211], 0, s[38:39]
	s_mov_b32 m0, s62
	s_nop 0
	global_load_lds_dwordx4 v[208:209], off
	s_waitcnt vmcnt(8)
	s_waitcnt lgkmcnt(0)
	s_barrier
	v_mfma_f32_16x16x32_bf16 v[62:65], v[74:77], v[162:165], v[62:65]
	v_mfma_f32_16x16x32_bf16 v[58:61], v[90:93], v[162:165], v[58:61]
	v_mfma_f32_16x16x32_bf16 v[46:49], v[74:77], v[180:183], v[46:49]
	v_mfma_f32_16x16x32_bf16 v[42:45], v[90:93], v[180:183], v[42:45]
	v_mfma_f32_16x16x32_bf16 v[30:33], v[74:77], v[188:191], v[30:33]
	v_mfma_f32_16x16x32_bf16 v[26:29], v[90:93], v[188:191], v[26:29]
	v_mfma_f32_16x16x32_bf16 v[14:17], v[74:77], v[200:203], v[14:17]
	v_mfma_f32_16x16x32_bf16 v[10:13], v[90:93], v[200:203], v[10:13]
	v_mfma_f32_16x16x32_bf16 v[62:65], v[82:85], v[166:169], v[62:65]
	v_mfma_f32_16x16x32_bf16 v[58:61], v[94:97], v[166:169], v[58:61]
	v_mfma_f32_16x16x32_bf16 v[46:49], v[82:85], v[184:187], v[46:49]
	v_mfma_f32_16x16x32_bf16 v[42:45], v[94:97], v[184:187], v[42:45]
	v_mfma_f32_16x16x32_bf16 v[30:33], v[82:85], v[196:199], v[30:33]
	v_mfma_f32_16x16x32_bf16 v[26:29], v[94:97], v[196:199], v[26:29]
	v_mfma_f32_16x16x32_bf16 v[14:17], v[82:85], v[204:207], v[14:17]
	v_mfma_f32_16x16x32_bf16 v[10:13], v[94:97], v[204:207], v[10:13]
	v_mfma_f32_16x16x32_bf16 v[54:57], v[138:141], v[162:165], v[54:57]
	v_mfma_f32_16x16x32_bf16 v[50:53], v[154:157], v[162:165], v[50:53]
	v_mfma_f32_16x16x32_bf16 v[38:41], v[138:141], v[180:183], v[38:41]
	v_mfma_f32_16x16x32_bf16 v[34:37], v[154:157], v[180:183], v[34:37]
	v_mfma_f32_16x16x32_bf16 v[22:25], v[138:141], v[188:191], v[22:25]
	v_mfma_f32_16x16x32_bf16 v[18:21], v[154:157], v[188:191], v[18:21]
	v_mfma_f32_16x16x32_bf16 v[6:9], v[138:141], v[200:203], v[6:9]
	v_mfma_f32_16x16x32_bf16 v[2:5], v[154:157], v[200:203], v[2:5]
	v_mfma_f32_16x16x32_bf16 v[54:57], v[150:153], v[166:169], v[54:57]
	v_mfma_f32_16x16x32_bf16 v[50:53], v[158:161], v[166:169], v[50:53]
	v_mfma_f32_16x16x32_bf16 v[38:41], v[150:153], v[184:187], v[38:41]
	v_mfma_f32_16x16x32_bf16 v[34:37], v[158:161], v[184:187], v[34:37]
	v_mfma_f32_16x16x32_bf16 v[22:25], v[150:153], v[196:199], v[22:25]
	v_mfma_f32_16x16x32_bf16 v[18:21], v[158:161], v[196:199], v[18:21]
	v_mfma_f32_16x16x32_bf16 v[6:9], v[150:153], v[204:207], v[6:9]
	v_mfma_f32_16x16x32_bf16 v[2:5], v[158:161], v[204:207], v[2:5]
	s_barrier
	s_add_i32 s79, s79, 2
	s_add_u32 s76, s76, 0x100
	s_addc_u32 s77, s77, 0
	s_add_u32 s57, s57, 0x100
	s_addc_u32 s78, s78, 0
	s_cmp_gt_u32 s79, 29
	s_cbranch_scc0 .LBB0_1208
	s_and_b64 vcc, exec, s[10:11]
	s_cbranch_vccz .LBB0_1211
	s_barrier

; #define PG8_WAIT_V(n) asm volatile("s_waitcnt vmcnt(" #n ")" ::: "memory")
; template <class Epi, class Sched, bool ALIGN_EPI = true, bool SP2 = true, bool FULLLINE = false, bool NOSTAGE = false, bool FP8 = false>
; __device__ __forceinline__ void gemm_phase(PG8_LAS unsigned char* lds, const Gemm g, const Sched& S, const Epi& E) {
;     ...
;         static_assert(SP2, "only the SP2 loop is kept");
;         { const int t = 0; if constexpr (Epi::NST == 16) PG8_ITER(PG8_WAIT_V(24)); else if constexpr (Epi::NST == 8) PG8_ITER(PG8_WAIT_V(16)); else PG8_ITER(PG8_WAIT_V(8)); }
.LBB0_1380:
	s_ashr_i32 s69, s68, 31
	s_lshl_b64 s[0:1], s[68:69], 20
	s_add_u32 s70, s58, s0
	ds_read_b128 v[2:5], v1
	ds_read_b128 v[6:9], v1 offset:1024
	ds_read_b128 v[10:13], v1 offset:2048
	ds_read_b128 v[14:17], v1 offset:3072
	ds_read_b128 v[18:21], v142
	ds_read_b128 v[22:25], v142 offset:1024
	ds_read_b128 v[26:29], v142 offset:2048
	ds_read_b128 v[30:33], v142 offset:3072
	s_addc_u32 s71, s59, s1
	s_ashr_i32 s67, s66, 31
	s_lshl_b64 s[0:1], s[66:67], 20
	s_add_u32 s72, s3, s0
	s_addc_u32 s73, s42, s1
	s_and_b64 s[0:1], s[8:9], exec
	s_cselect_b32 s67, s71, s79
	s_cselect_b32 s69, s70, s78
	s_cselect_b32 s89, s73, s77
	s_cselect_b32 s90, s72, s76
	v_lshl_add_u64 v[140:141], s[78:79], 0, v[132:133]
	s_mov_b32 m0, s81
	v_lshl_add_u64 v[66:67], v[140:141], 0, s[12:13]
	ds_read_b128 v[34:37], v143
	ds_read_b128 v[38:41], v143 offset:1024
	ds_read_b128 v[42:45], v143 offset:2048
	ds_read_b128 v[46:49], v143 offset:3072
	ds_read_b128 v[50:53], v143 offset:4096
	ds_read_b128 v[54:57], v143 offset:5120
	ds_read_b128 v[58:61], v143 offset:6144
	ds_read_b128 v[62:65], v143 offset:7168
	global_load_lds_dwordx4 v[66:67], off
	v_lshl_add_u64 v[66:67], v[140:141], 0, s[14:15]
	s_mov_b32 m0, s82
	s_nop 0
	global_load_lds_dwordx4 v[66:67], off
	s_waitcnt vmcnt(16)
	s_waitcnt lgkmcnt(0)
	s_barrier
	v_mfma_f32_16x16x32_bf16 v[86:89], v[10:13], v[50:53], 0
	v_mfma_f32_16x16x32_bf16 v[90:93], v[14:17], v[54:57], v[86:89]
	v_mfma_f32_16x16x32_bf16 v[86:89], v[2:5], v[58:61], 0
	v_mfma_f32_16x16x32_bf16 v[66:69], v[2:5], v[34:37], 0
	v_mfma_f32_16x16x32_bf16 v[70:73], v[10:13], v[34:37], 0
	v_mfma_f32_16x16x32_bf16 v[74:77], v[2:5], v[42:45], 0
	v_mfma_f32_16x16x32_bf16 v[78:81], v[10:13], v[42:45], 0
	v_mfma_f32_16x16x32_bf16 v[82:85], v[2:5], v[50:53], 0
	v_mfma_f32_16x16x32_bf16 v[94:97], v[6:9], v[62:65], v[86:89]
	v_mfma_f32_16x16x32_bf16 v[86:89], v[10:13], v[58:61], 0
	v_mfma_f32_16x16x32_bf16 v[66:69], v[6:9], v[38:41], v[66:69]
	v_mfma_f32_16x16x32_bf16 v[70:73], v[14:17], v[38:41], v[70:73]
	v_mfma_f32_16x16x32_bf16 v[74:77], v[6:9], v[46:49], v[74:77]
	v_mfma_f32_16x16x32_bf16 v[78:81], v[14:17], v[46:49], v[78:81]
	v_mfma_f32_16x16x32_bf16 v[82:85], v[6:9], v[54:57], v[82:85]
	v_mfma_f32_16x16x32_bf16 v[106:109], v[14:17], v[62:65], v[86:89]
	v_mfma_f32_16x16x32_bf16 v[86:89], v[18:21], v[34:37], 0
	v_mfma_f32_16x16x32_bf16 v[34:37], v[26:29], v[34:37], 0
	v_mfma_f32_16x16x32_bf16 v[110:113], v[22:25], v[38:41], v[86:89]
	v_mfma_f32_16x16x32_bf16 v[34:37], v[30:33], v[38:41], v[34:37]
	v_mfma_f32_16x16x32_bf16 v[38:41], v[18:21], v[42:45], 0
	v_mfma_f32_16x16x32_bf16 v[42:45], v[26:29], v[42:45], 0
	v_mfma_f32_16x16x32_bf16 v[38:41], v[22:25], v[46:49], v[38:41]
	v_mfma_f32_16x16x32_bf16 v[42:45], v[30:33], v[46:49], v[42:45]
	v_mfma_f32_16x16x32_bf16 v[46:49], v[18:21], v[50:53], 0
	v_mfma_f32_16x16x32_bf16 v[50:53], v[26:29], v[50:53], 0
	v_mfma_f32_16x16x32_bf16 v[46:49], v[22:25], v[54:57], v[46:49]
	v_mfma_f32_16x16x32_bf16 v[50:53], v[30:33], v[54:57], v[50:53]
	v_mfma_f32_16x16x32_bf16 v[54:57], v[18:21], v[58:61], 0
	v_mfma_f32_16x16x32_bf16 v[58:61], v[26:29], v[58:61], 0
	v_mfma_f32_16x16x32_bf16 v[54:57], v[22:25], v[62:65], v[54:57]
	v_mfma_f32_16x16x32_bf16 v[58:61], v[30:33], v[62:65], v[58:61]
	s_barrier
	v_lshl_add_u64 v[238:239], s[76:77], 0, v[130:131]
	s_mov_b32 m0, s83
	v_lshl_add_u64 v[146:147], v[238:239], 0, s[16:17]
	s_add_i32 s91, s83, 0x2000
	ds_read_b128 v[62:65], v143 offset:16384
	ds_read_b128 v[86:89], v143 offset:17408
	ds_read_b128 v[98:101], v143 offset:18432
	ds_read_b128 v[102:105], v143 offset:19456
	ds_read_b128 v[114:117], v143 offset:20480
	ds_read_b128 v[118:121], v143 offset:21504
	ds_read_b128 v[122:125], v143 offset:22528
	ds_read_b128 v[126:129], v143 offset:23552
	global_load_lds_dwordx4 v[146:147], off
	v_lshl_add_u64 v[146:147], v[238:239], 0, s[18:19]
	s_mov_b32 m0, s91
	s_add_i32 s40, s80, s43
	global_load_lds_dwordx4 v[146:147], off
	v_lshl_add_u64 v[146:147], v[238:239], 0, s[20:21]
	s_mov_b32 m0, s40
	s_add_i32 s41, s40, 0x2000
	global_load_lds_dwordx4 v[146:147], off
	v_lshl_add_u64 v[146:147], v[238:239], 0, s[22:23]
	s_mov_b32 m0, s41
	s_nop 0
	global_load_lds_dwordx4 v[146:147], off
	v_lshl_add_u64 v[146:147], v[140:141], 0, s[16:17]
	s_mov_b32 m0, s45
	s_nop 0
	global_load_lds_dwordx4 v[146:147], off
	v_lshl_add_u64 v[146:147], v[140:141], 0, s[18:19]
	s_mov_b32 m0, s46
	s_nop 0
	global_load_lds_dwordx4 v[146:147], off
	s_waitcnt vmcnt(16)
	s_waitcnt lgkmcnt(0)
	s_barrier
	v_mfma_f32_16x16x32_bf16 v[146:149], v[2:5], v[62:65], 0
	v_mfma_f32_16x16x32_bf16 v[154:157], v[2:5], v[98:101], 0
	v_mfma_f32_16x16x32_bf16 v[162:165], v[2:5], v[114:117], 0
	v_mfma_f32_16x16x32_bf16 v[2:5], v[2:5], v[122:125], 0
	v_mfma_f32_16x16x32_bf16 v[146:149], v[6:9], v[86:89], v[146:149]
	v_mfma_f32_16x16x32_bf16 v[154:157], v[6:9], v[102:105], v[154:157]
	v_mfma_f32_16x16x32_bf16 v[162:165], v[6:9], v[118:121], v[162:165]
	v_mfma_f32_16x16x32_bf16 v[2:5], v[6:9], v[126:129], v[2:5]
	v_mfma_f32_16x16x32_bf16 v[6:9], v[10:13], v[122:125], 0
	v_mfma_f32_16x16x32_bf16 v[150:153], v[10:13], v[62:65], 0
	v_mfma_f32_16x16x32_bf16 v[158:161], v[10:13], v[98:101], 0
	v_mfma_f32_16x16x32_bf16 v[166:169], v[10:13], v[114:117], 0
	v_mfma_f32_16x16x32_bf16 v[10:13], v[14:17], v[126:129], v[6:9]
	v_mfma_f32_16x16x32_bf16 v[150:153], v[14:17], v[86:89], v[150:153]
	v_mfma_f32_16x16x32_bf16 v[158:161], v[14:17], v[102:105], v[158:161]
	v_mfma_f32_16x16x32_bf16 v[166:169], v[14:17], v[118:121], v[166:169]
	v_mfma_f32_16x16x32_bf16 v[6:9], v[18:21], v[62:65], 0
	v_mfma_f32_16x16x32_bf16 v[14:17], v[22:25], v[86:89], v[6:9]
	v_mfma_f32_16x16x32_bf16 v[6:9], v[26:29], v[62:65], 0
	v_mfma_f32_16x16x32_bf16 v[170:173], v[30:33], v[86:89], v[6:9]
	v_mfma_f32_16x16x32_bf16 v[6:9], v[18:21], v[98:101], 0
	v_mfma_f32_16x16x32_bf16 v[174:177], v[22:25], v[102:105], v[6:9]
	v_mfma_f32_16x16x32_bf16 v[6:9], v[26:29], v[98:101], 0
	v_mfma_f32_16x16x32_bf16 v[178:181], v[30:33], v[102:105], v[6:9]
	v_mfma_f32_16x16x32_bf16 v[6:9], v[18:21], v[114:117], 0
	v_mfma_f32_16x16x32_bf16 v[182:185], v[22:25], v[118:121], v[6:9]
	v_mfma_f32_16x16x32_bf16 v[6:9], v[26:29], v[114:117], 0
	v_mfma_f32_16x16x32_bf16 v[186:189], v[30:33], v[118:121], v[6:9]
	v_mfma_f32_16x16x32_bf16 v[6:9], v[18:21], v[122:125], 0
	v_mfma_f32_16x16x32_bf16 v[190:193], v[22:25], v[126:129], v[6:9]
	v_mfma_f32_16x16x32_bf16 v[6:9], v[26:29], v[122:125], 0
	v_mfma_f32_16x16x32_bf16 v[194:197], v[30:33], v[126:129], v[6:9]
	s_barrier
; #define PG8_WAIT_V(n) asm volatile("s_waitcnt vmcnt(" #n ")" ::: "memory")
; template <class Epi, class Sched, bool ALIGN_EPI = true, bool SP2 = true, bool FULLLINE = false, bool NOSTAGE = false, bool FP8 = false>
; __device__ __forceinline__ void gemm_phase(PG8_LAS unsigned char* lds, const Gemm g, const Sched& S, const Epi& E) {
;     ...
;         static_assert(SP2, "only the SP2 loop is kept");
;         { const int t = 0; if constexpr (Epi::NST == 16) PG8_ITER(PG8_WAIT_V(24)); else if constexpr (Epi::NST == 8) PG8_ITER(PG8_WAIT_V(16)); else PG8_ITER(PG8_WAIT_V(8)); }
	s_nop 5
	ds_read_b128 v[6:9], v144
	ds_read_b128 v[26:29], v144 offset:1024
	ds_read_b128 v[30:33], v144 offset:2048
	ds_read_b128 v[62:65], v144 offset:3072
	ds_read_b128 v[198:201], v145
	ds_read_b128 v[202:205], v145 offset:1024
	ds_read_b128 v[206:209], v145 offset:2048
	ds_read_b128 v[210:213], v145 offset:3072
	s_mov_b32 m0, s47
	v_lshl_add_u64 v[86:87], v[140:141], 0, s[20:21]
	ds_read_b128 v[18:21], v143 offset:32768
	ds_read_b128 v[22:25], v143 offset:33792
	ds_read_b128 v[214:217], v143 offset:34816
	ds_read_b128 v[218:221], v143 offset:35840
	ds_read_b128 v[222:225], v143 offset:36864
	ds_read_b128 v[226:229], v143 offset:37888
	ds_read_b128 v[230:233], v143 offset:38912
	ds_read_b128 v[234:237], v143 offset:39936
	global_load_lds_dwordx4 v[86:87], off
	v_lshl_add_u64 v[86:87], v[140:141], 0, s[22:23]
	s_mov_b32 m0, s52
	s_nop 0
	global_load_lds_dwordx4 v[86:87], off
	s_waitcnt vmcnt(8)
	s_waitcnt lgkmcnt(0)
	s_barrier
	v_mfma_f32_16x16x32_bf16 v[66:69], v[6:9], v[18:21], v[66:69]
	v_mfma_f32_16x16x32_bf16 v[118:121], v[26:29], v[22:25], v[66:69]
	v_mfma_f32_16x16x32_bf16 v[66:69], v[30:33], v[18:21], v[70:73]
	v_mfma_f32_16x16x32_bf16 v[114:117], v[62:65], v[22:25], v[66:69]
	v_mfma_f32_16x16x32_bf16 v[66:69], v[6:9], v[214:217], v[74:77]
	v_mfma_f32_16x16x32_bf16 v[102:105], v[26:29], v[218:221], v[66:69]
	v_mfma_f32_16x16x32_bf16 v[66:69], v[30:33], v[214:217], v[78:81]
	v_mfma_f32_16x16x32_bf16 v[98:101], v[62:65], v[218:221], v[66:69]
	v_mfma_f32_16x16x32_bf16 v[66:69], v[6:9], v[222:225], v[82:85]
	v_mfma_f32_16x16x32_bf16 v[86:89], v[26:29], v[226:229], v[66:69]
	v_mfma_f32_16x16x32_bf16 v[66:69], v[30:33], v[222:225], v[90:93]
	v_mfma_f32_16x16x32_bf16 v[82:85], v[62:65], v[226:229], v[66:69]
	v_mfma_f32_16x16x32_bf16 v[66:69], v[6:9], v[230:233], v[94:97]
	v_mfma_f32_16x16x32_bf16 v[70:73], v[26:29], v[234:237], v[66:69]
	v_mfma_f32_16x16x32_bf16 v[66:69], v[30:33], v[230:233], v[106:109]
	v_mfma_f32_16x16x32_bf16 v[66:69], v[62:65], v[234:237], v[66:69]
	v_mfma_f32_16x16x32_bf16 v[74:77], v[198:201], v[18:21], v[110:113]
	v_mfma_f32_16x16x32_bf16 v[18:21], v[206:209], v[18:21], v[34:37]
	v_mfma_f32_16x16x32_bf16 v[122:125], v[210:213], v[22:25], v[18:21]
	v_mfma_f32_16x16x32_bf16 v[18:21], v[198:201], v[214:217], v[38:41]
	v_mfma_f32_16x16x32_bf16 v[110:113], v[202:205], v[218:221], v[18:21]
	v_mfma_f32_16x16x32_bf16 v[18:21], v[206:209], v[214:217], v[42:45]
	v_mfma_f32_16x16x32_bf16 v[106:109], v[210:213], v[218:221], v[18:21]
	v_mfma_f32_16x16x32_bf16 v[18:21], v[198:201], v[222:225], v[46:49]
	v_mfma_f32_16x16x32_bf16 v[94:97], v[202:205], v[226:229], v[18:21]
	v_mfma_f32_16x16x32_bf16 v[18:21], v[206:209], v[222:225], v[50:53]
	v_mfma_f32_16x16x32_bf16 v[90:93], v[210:213], v[226:229], v[18:21]
	v_mfma_f32_16x16x32_bf16 v[18:21], v[198:201], v[230:233], v[54:57]
	v_mfma_f32_16x16x32_bf16 v[78:81], v[202:205], v[234:237], v[18:21]
	v_mfma_f32_16x16x32_bf16 v[18:21], v[206:209], v[230:233], v[58:61]
	v_mfma_f32_16x16x32_bf16 v[126:129], v[202:205], v[22:25], v[74:77]
	v_mfma_f32_16x16x32_bf16 v[74:77], v[210:213], v[234:237], v[18:21]
	s_barrier
	s_add_i32 s50, s84, s43
	s_nop 3
	v_lshl_add_u64 v[18:19], v[238:239], 0, s[24:25]
	s_mov_b32 m0, s50
	s_add_i32 s51, s50, 0x2000
	ds_read_b128 v[42:45], v143 offset:49152
	ds_read_b128 v[46:49], v143 offset:50176
	ds_read_b128 v[214:217], v143 offset:51200
	ds_read_b128 v[218:221], v143 offset:52224
	ds_read_b128 v[222:225], v143 offset:53248
	ds_read_b128 v[226:229], v143 offset:54272
	ds_read_b128 v[230:233], v143 offset:55296
	ds_read_b128 v[234:237], v143 offset:56320
	global_load_lds_dwordx4 v[18:19], off
	v_lshl_add_u64 v[18:19], v[238:239], 0, s[26:27]
	s_mov_b32 m0, s51
	s_mov_b64 s[0:1], 0x80180
	s_add_i32 s33, s85, s43
	global_load_lds_dwordx4 v[18:19], off
	v_lshl_add_u64 v[18:19], v[238:239], 0, s[0:1]
	s_mov_b32 m0, s33
	s_mov_b64 s[0:1], 0xc0180
	s_add_i32 s56, s33, 0x2000
	global_load_lds_dwordx4 v[18:19], off
	v_lshl_add_u64 v[18:19], v[238:239], 0, s[0:1]
	s_mov_b32 m0, s56
	s_nop 0
	global_load_lds_dwordx4 v[18:19], off
	v_lshl_add_u64 v[18:19], v[140:141], 0, s[24:25]
	s_mov_b32 m0, s53
	s_nop 0
	global_load_lds_dwordx4 v[18:19], off
	v_lshl_add_u64 v[18:19], v[140:141], 0, s[26:27]
	s_mov_b32 m0, s54
	s_nop 0
	global_load_lds_dwordx4 v[18:19], off
	s_waitcnt vmcnt(8)
	s_waitcnt lgkmcnt(0)
	s_barrier
	v_mfma_f32_16x16x32_bf16 v[18:21], v[6:9], v[42:45], v[146:149]
	v_mfma_f32_16x16x32_bf16 v[54:57], v[26:29], v[46:49], v[18:21]
	v_mfma_f32_16x16x32_bf16 v[18:21], v[30:33], v[42:45], v[150:153]
	v_mfma_f32_16x16x32_bf16 v[50:53], v[62:65], v[46:49], v[18:21]
	v_mfma_f32_16x16x32_bf16 v[18:21], v[6:9], v[214:217], v[154:157]
	v_mfma_f32_16x16x32_bf16 v[38:41], v[26:29], v[218:221], v[18:21]
	v_mfma_f32_16x16x32_bf16 v[18:21], v[30:33], v[214:217], v[158:161]
	v_mfma_f32_16x16x32_bf16 v[34:37], v[62:65], v[218:221], v[18:21]
	v_mfma_f32_16x16x32_bf16 v[18:21], v[6:9], v[222:225], v[162:165]
	v_mfma_f32_16x16x32_bf16 v[2:5], v[6:9], v[230:233], v[2:5]
	v_mfma_f32_16x16x32_bf16 v[22:25], v[26:29], v[226:229], v[18:21]
	v_mfma_f32_16x16x32_bf16 v[18:21], v[30:33], v[222:225], v[166:169]
	v_mfma_f32_16x16x32_bf16 v[6:9], v[26:29], v[234:237], v[2:5]
	v_mfma_f32_16x16x32_bf16 v[2:5], v[30:33], v[230:233], v[10:13]
	v_mfma_f32_16x16x32_bf16 v[18:21], v[62:65], v[226:229], v[18:21]
	v_mfma_f32_16x16x32_bf16 v[2:5], v[62:65], v[234:237], v[2:5]
	v_mfma_f32_16x16x32_bf16 v[10:13], v[198:201], v[42:45], v[14:17]
	v_mfma_f32_16x16x32_bf16 v[62:65], v[202:205], v[46:49], v[10:13]
	v_mfma_f32_16x16x32_bf16 v[10:13], v[206:209], v[42:45], v[170:173]
	v_mfma_f32_16x16x32_bf16 v[58:61], v[210:213], v[46:49], v[10:13]
	v_mfma_f32_16x16x32_bf16 v[10:13], v[198:201], v[214:217], v[174:177]
	v_mfma_f32_16x16x32_bf16 v[46:49], v[202:205], v[218:221], v[10:13]
	v_mfma_f32_16x16x32_bf16 v[10:13], v[206:209], v[214:217], v[178:181]
	v_mfma_f32_16x16x32_bf16 v[42:45], v[210:213], v[218:221], v[10:13]
	v_mfma_f32_16x16x32_bf16 v[10:13], v[198:201], v[222:225], v[182:185]
	v_mfma_f32_16x16x32_bf16 v[30:33], v[202:205], v[226:229], v[10:13]
	v_mfma_f32_16x16x32_bf16 v[10:13], v[206:209], v[222:225], v[186:189]
	v_mfma_f32_16x16x32_bf16 v[26:29], v[210:213], v[226:229], v[10:13]
	v_mfma_f32_16x16x32_bf16 v[10:13], v[198:201], v[230:233], v[190:193]
	v_mfma_f32_16x16x32_bf16 v[14:17], v[202:205], v[234:237], v[10:13]
	v_mfma_f32_16x16x32_bf16 v[10:13], v[206:209], v[230:233], v[194:197]
	v_mfma_f32_16x16x32_bf16 v[10:13], v[210:213], v[234:237], v[10:13]
	s_barrier
	s_add_u32 s78, s78, 0x80180
	s_addc_u32 s79, s79, 0
	s_add_u32 s57, s76, 0x200
	s_addc_u32 s76, s77, 0
	s_mov_b32 s77, 0
; #define PG8_WAIT_V(n) asm volatile("s_waitcnt vmcnt(" #n ")" ::: "memory")
; template <class Epi, class Sched, bool ALIGN_EPI = true, bool SP2 = true, bool FULLLINE = false, bool NOSTAGE = false, bool FP8 = false>
; __device__ __forceinline__ void gemm_phase(PG8_LAS unsigned char* lds, const Gemm g, const Sched& S, const Epi& E) {
;     ...
;         static_assert(SP2, "only the SP2 loop is kept");
;         { const int t = 0; if constexpr (Epi::NST == 16) PG8_ITER(PG8_WAIT_V(24)); else if constexpr (Epi::NST == 8) PG8_ITER(PG8_WAIT_V(16)); else PG8_ITER(PG8_WAIT_V(8)); }
;         for (int t = 2; t < nt; t += 2) PG8_ITER(PG8_WAIT_V(8));
.LBB0_1381:
	ds_read_b128 v[146:149], v1
	ds_read_b128 v[150:153], v1 offset:1024
	ds_read_b128 v[154:157], v1 offset:2048
	ds_read_b128 v[158:161], v1 offset:3072
	ds_read_b128 v[162:165], v142
	ds_read_b128 v[166:169], v142 offset:1024
	ds_read_b128 v[170:173], v142 offset:2048
	ds_read_b128 v[174:177], v142 offset:3072
	s_add_u32 s0, s78, 0xfff80080
	s_addc_u32 s1, s79, -1
	s_cmp_eq_u32 s77, 28
	s_cselect_b32 s1, s67, s1
	s_cselect_b32 s0, s69, s0
	s_cselect_b32 s65, s89, s76
	s_cselect_b32 s64, s90, s57
	s_mov_b32 m0, s81
	v_lshl_add_u64 v[140:141], s[78:79], 0, v[134:135]
	ds_read_b128 v[178:181], v143
	ds_read_b128 v[182:185], v143 offset:1024
	ds_read_b128 v[186:189], v143 offset:2048
	ds_read_b128 v[190:193], v143 offset:3072
	ds_read_b128 v[194:197], v143 offset:4096
	ds_read_b128 v[198:201], v143 offset:5120
	ds_read_b128 v[202:205], v143 offset:6144
	ds_read_b128 v[206:209], v143 offset:7168
	global_load_lds_dwordx4 v[140:141], off
	v_lshl_add_u64 v[140:141], v[140:141], 0, s[28:29]
	s_mov_b32 m0, s82
	s_nop 0
	global_load_lds_dwordx4 v[140:141], off
	s_waitcnt vmcnt(8)
	s_waitcnt lgkmcnt(0)
	s_barrier
	v_mfma_f32_16x16x32_bf16 v[118:121], v[146:149], v[178:181], v[118:121]
	v_mfma_f32_16x16x32_bf16 v[114:117], v[154:157], v[178:181], v[114:117]
	v_mfma_f32_16x16x32_bf16 v[102:105], v[146:149], v[186:189], v[102:105]
	v_mfma_f32_16x16x32_bf16 v[98:101], v[154:157], v[186:189], v[98:101]
	v_mfma_f32_16x16x32_bf16 v[86:89], v[146:149], v[194:197], v[86:89]
	v_mfma_f32_16x16x32_bf16 v[82:85], v[154:157], v[194:197], v[82:85]
	v_mfma_f32_16x16x32_bf16 v[70:73], v[146:149], v[202:205], v[70:73]
	v_mfma_f32_16x16x32_bf16 v[66:69], v[154:157], v[202:205], v[66:69]
	v_mfma_f32_16x16x32_bf16 v[118:121], v[150:153], v[182:185], v[118:121]
	v_mfma_f32_16x16x32_bf16 v[114:117], v[158:161], v[182:185], v[114:117]
	v_mfma_f32_16x16x32_bf16 v[102:105], v[150:153], v[190:193], v[102:105]
	v_mfma_f32_16x16x32_bf16 v[98:101], v[158:161], v[190:193], v[98:101]
	v_mfma_f32_16x16x32_bf16 v[86:89], v[150:153], v[198:201], v[86:89]
	v_mfma_f32_16x16x32_bf16 v[82:85], v[158:161], v[198:201], v[82:85]
	v_mfma_f32_16x16x32_bf16 v[70:73], v[150:153], v[206:209], v[70:73]
	v_mfma_f32_16x16x32_bf16 v[66:69], v[158:161], v[206:209], v[66:69]
	v_mfma_f32_16x16x32_bf16 v[126:129], v[162:165], v[178:181], v[126:129]
	v_mfma_f32_16x16x32_bf16 v[122:125], v[170:173], v[178:181], v[122:125]
	v_mfma_f32_16x16x32_bf16 v[110:113], v[162:165], v[186:189], v[110:113]
	v_mfma_f32_16x16x32_bf16 v[106:109], v[170:173], v[186:189], v[106:109]
	v_mfma_f32_16x16x32_bf16 v[94:97], v[162:165], v[194:197], v[94:97]
	v_mfma_f32_16x16x32_bf16 v[90:93], v[170:173], v[194:197], v[90:93]
	v_mfma_f32_16x16x32_bf16 v[78:81], v[162:165], v[202:205], v[78:81]
	v_mfma_f32_16x16x32_bf16 v[74:77], v[170:173], v[202:205], v[74:77]
	v_mfma_f32_16x16x32_bf16 v[126:129], v[166:169], v[182:185], v[126:129]
	v_mfma_f32_16x16x32_bf16 v[122:125], v[174:177], v[182:185], v[122:125]
	v_mfma_f32_16x16x32_bf16 v[110:113], v[166:169], v[190:193], v[110:113]
	v_mfma_f32_16x16x32_bf16 v[106:109], v[174:177], v[190:193], v[106:109]
	v_mfma_f32_16x16x32_bf16 v[94:97], v[166:169], v[198:201], v[94:97]
	v_mfma_f32_16x16x32_bf16 v[90:93], v[174:177], v[198:201], v[90:93]
	v_mfma_f32_16x16x32_bf16 v[78:81], v[166:169], v[206:209], v[78:81]
	v_mfma_f32_16x16x32_bf16 v[74:77], v[174:177], v[206:209], v[74:77]
	s_barrier
	s_mov_b32 m0, s83
	v_lshl_add_u64 v[140:141], s[64:65], 0, v[130:131]
	ds_read_b128 v[178:181], v143 offset:16384
	ds_read_b128 v[182:185], v143 offset:17408
	ds_read_b128 v[186:189], v143 offset:18432
	ds_read_b128 v[190:193], v143 offset:19456
	ds_read_b128 v[194:197], v143 offset:20480
	ds_read_b128 v[198:201], v143 offset:21504
	ds_read_b128 v[202:205], v143 offset:22528
	ds_read_b128 v[206:209], v143 offset:23552
	global_load_lds_dwordx4 v[140:141], off
	v_lshl_add_u64 v[210:211], v[140:141], 0, s[28:29]
	s_mov_b32 m0, s91
	s_nop 0
	global_load_lds_dwordx4 v[210:211], off
	v_lshl_add_u64 v[210:211], v[140:141], 0, s[30:31]
	s_mov_b32 m0, s40
	s_nop 0
	global_load_lds_dwordx4 v[210:211], off
	v_lshl_add_u64 v[210:211], v[140:141], 0, s[34:35]
	s_mov_b32 m0, s41
	s_nop 0
	global_load_lds_dwordx4 v[210:211], off
	v_lshl_add_u64 v[210:211], s[0:1], 0, v[132:133]
	s_mov_b32 m0, s45
	v_lshl_add_u64 v[212:213], v[210:211], 0, s[28:29]
	global_load_lds_dwordx4 v[210:211], off
	s_mov_b32 m0, s46
	s_nop 0
	global_load_lds_dwordx4 v[212:213], off
	s_waitcnt vmcnt(8)
	s_waitcnt lgkmcnt(0)
	s_barrier
	v_mfma_f32_16x16x32_bf16 v[54:57], v[146:149], v[178:181], v[54:57]
	v_mfma_f32_16x16x32_bf16 v[50:53], v[154:157], v[178:181], v[50:53]
	v_mfma_f32_16x16x32_bf16 v[38:41], v[146:149], v[186:189], v[38:41]
	v_mfma_f32_16x16x32_bf16 v[34:37], v[154:157], v[186:189], v[34:37]
	v_mfma_f32_16x16x32_bf16 v[22:25], v[146:149], v[194:197], v[22:25]
	v_mfma_f32_16x16x32_bf16 v[18:21], v[154:157], v[194:197], v[18:21]
	v_mfma_f32_16x16x32_bf16 v[6:9], v[146:149], v[202:205], v[6:9]
	v_mfma_f32_16x16x32_bf16 v[2:5], v[154:157], v[202:205], v[2:5]
	v_mfma_f32_16x16x32_bf16 v[54:57], v[150:153], v[182:185], v[54:57]
	v_mfma_f32_16x16x32_bf16 v[50:53], v[158:161], v[182:185], v[50:53]
	v_mfma_f32_16x16x32_bf16 v[38:41], v[150:153], v[190:193], v[38:41]
	v_mfma_f32_16x16x32_bf16 v[34:37], v[158:161], v[190:193], v[34:37]
	v_mfma_f32_16x16x32_bf16 v[22:25], v[150:153], v[198:201], v[22:25]
	v_mfma_f32_16x16x32_bf16 v[18:21], v[158:161], v[198:201], v[18:21]
	v_mfma_f32_16x16x32_bf16 v[6:9], v[150:153], v[206:209], v[6:9]
	v_mfma_f32_16x16x32_bf16 v[2:5], v[158:161], v[206:209], v[2:5]
	v_mfma_f32_16x16x32_bf16 v[62:65], v[162:165], v[178:181], v[62:65]
	v_mfma_f32_16x16x32_bf16 v[58:61], v[170:173], v[178:181], v[58:61]
	v_mfma_f32_16x16x32_bf16 v[46:49], v[162:165], v[186:189], v[46:49]
	v_mfma_f32_16x16x32_bf16 v[42:45], v[170:173], v[186:189], v[42:45]
	v_mfma_f32_16x16x32_bf16 v[30:33], v[162:165], v[194:197], v[30:33]
	v_mfma_f32_16x16x32_bf16 v[26:29], v[170:173], v[194:197], v[26:29]
	v_mfma_f32_16x16x32_bf16 v[14:17], v[162:165], v[202:205], v[14:17]
	v_mfma_f32_16x16x32_bf16 v[10:13], v[170:173], v[202:205], v[10:13]
	v_mfma_f32_16x16x32_bf16 v[62:65], v[166:169], v[182:185], v[62:65]
	v_mfma_f32_16x16x32_bf16 v[58:61], v[174:177], v[182:185], v[58:61]
	v_mfma_f32_16x16x32_bf16 v[46:49], v[166:169], v[190:193], v[46:49]
	v_mfma_f32_16x16x32_bf16 v[42:45], v[174:177], v[190:193], v[42:45]
	v_mfma_f32_16x16x32_bf16 v[30:33], v[166:169], v[198:201], v[30:33]
	v_mfma_f32_16x16x32_bf16 v[26:29], v[174:177], v[198:201], v[26:29]
	v_mfma_f32_16x16x32_bf16 v[14:17], v[166:169], v[206:209], v[14:17]
	v_mfma_f32_16x16x32_bf16 v[10:13], v[174:177], v[206:209], v[10:13]
	s_barrier
; #define PG8_WAIT_V(n) asm volatile("s_waitcnt vmcnt(" #n ")" ::: "memory")
; #define PG8_BAR __builtin_amdgcn_s_barrier()
; template <class Epi, class Sched, bool ALIGN_EPI = true, bool SP2 = true, bool FULLLINE = false, bool NOSTAGE = false, bool FP8 = false>
; __device__ __forceinline__ void gemm_phase(PG8_LAS unsigned char* lds, const Gemm g, const Sched& S, const Epi& E) {
;     ...
;         static_assert(SP2, "only the SP2 loop is kept");
;         { const int t = 0; if constexpr (Epi::NST == 16) PG8_ITER(PG8_WAIT_V(24)); else if constexpr (Epi::NST == 8) PG8_ITER(PG8_WAIT_V(16)); else PG8_ITER(PG8_WAIT_V(8)); }
;         for (int t = 2; t < nt; t += 2) PG8_ITER(PG8_WAIT_V(8));
;     ...
;         if constexpr (ALIGN_EPI) { if (wr == 0) PG8_BAR; }
	ds_read_b128 v[146:149], v144
	ds_read_b128 v[150:153], v144 offset:1024
	ds_read_b128 v[154:157], v144 offset:2048
	ds_read_b128 v[158:161], v144 offset:3072
	ds_read_b128 v[162:165], v145
	ds_read_b128 v[166:169], v145 offset:1024
	ds_read_b128 v[170:173], v145 offset:2048
	ds_read_b128 v[174:177], v145 offset:3072
	s_mov_b32 m0, s47
	v_lshl_add_u64 v[212:213], v[210:211], 0, s[30:31]
	ds_read_b128 v[178:181], v143 offset:32768
	ds_read_b128 v[182:185], v143 offset:33792
	ds_read_b128 v[186:189], v143 offset:34816
	ds_read_b128 v[190:193], v143 offset:35840
	ds_read_b128 v[194:197], v143 offset:36864
	ds_read_b128 v[198:201], v143 offset:37888
	ds_read_b128 v[202:205], v143 offset:38912
	ds_read_b128 v[206:209], v143 offset:39936
	global_load_lds_dwordx4 v[212:213], off
	v_lshl_add_u64 v[212:213], v[210:211], 0, s[34:35]
	s_mov_b32 m0, s52
	s_nop 0
	global_load_lds_dwordx4 v[212:213], off
	s_waitcnt vmcnt(8)
	s_waitcnt lgkmcnt(0)
	s_barrier
	v_mfma_f32_16x16x32_bf16 v[118:121], v[146:149], v[178:181], v[118:121]
	v_mfma_f32_16x16x32_bf16 v[114:117], v[154:157], v[178:181], v[114:117]
	v_mfma_f32_16x16x32_bf16 v[102:105], v[146:149], v[186:189], v[102:105]
	v_mfma_f32_16x16x32_bf16 v[98:101], v[154:157], v[186:189], v[98:101]
	v_mfma_f32_16x16x32_bf16 v[86:89], v[146:149], v[194:197], v[86:89]
	v_mfma_f32_16x16x32_bf16 v[82:85], v[154:157], v[194:197], v[82:85]
	v_mfma_f32_16x16x32_bf16 v[70:73], v[146:149], v[202:205], v[70:73]
	v_mfma_f32_16x16x32_bf16 v[66:69], v[154:157], v[202:205], v[66:69]
	v_mfma_f32_16x16x32_bf16 v[118:121], v[150:153], v[182:185], v[118:121]
	v_mfma_f32_16x16x32_bf16 v[114:117], v[158:161], v[182:185], v[114:117]
	v_mfma_f32_16x16x32_bf16 v[102:105], v[150:153], v[190:193], v[102:105]
	v_mfma_f32_16x16x32_bf16 v[98:101], v[158:161], v[190:193], v[98:101]
	v_mfma_f32_16x16x32_bf16 v[86:89], v[150:153], v[198:201], v[86:89]
	v_mfma_f32_16x16x32_bf16 v[82:85], v[158:161], v[198:201], v[82:85]
	v_mfma_f32_16x16x32_bf16 v[70:73], v[150:153], v[206:209], v[70:73]
	v_mfma_f32_16x16x32_bf16 v[66:69], v[158:161], v[206:209], v[66:69]
	v_mfma_f32_16x16x32_bf16 v[126:129], v[162:165], v[178:181], v[126:129]
	v_mfma_f32_16x16x32_bf16 v[122:125], v[170:173], v[178:181], v[122:125]
	v_mfma_f32_16x16x32_bf16 v[110:113], v[162:165], v[186:189], v[110:113]
	v_mfma_f32_16x16x32_bf16 v[106:109], v[170:173], v[186:189], v[106:109]
	v_mfma_f32_16x16x32_bf16 v[94:97], v[162:165], v[194:197], v[94:97]
	v_mfma_f32_16x16x32_bf16 v[90:93], v[170:173], v[194:197], v[90:93]
	v_mfma_f32_16x16x32_bf16 v[78:81], v[162:165], v[202:205], v[78:81]
	v_mfma_f32_16x16x32_bf16 v[74:77], v[170:173], v[202:205], v[74:77]
	v_mfma_f32_16x16x32_bf16 v[126:129], v[166:169], v[182:185], v[126:129]
	v_mfma_f32_16x16x32_bf16 v[122:125], v[174:177], v[182:185], v[122:125]
	v_mfma_f32_16x16x32_bf16 v[110:113], v[166:169], v[190:193], v[110:113]
	v_mfma_f32_16x16x32_bf16 v[106:109], v[174:177], v[190:193], v[106:109]
	v_mfma_f32_16x16x32_bf16 v[94:97], v[166:169], v[198:201], v[94:97]
	v_mfma_f32_16x16x32_bf16 v[90:93], v[174:177], v[198:201], v[90:93]
	v_mfma_f32_16x16x32_bf16 v[78:81], v[166:169], v[206:209], v[78:81]
	v_mfma_f32_16x16x32_bf16 v[74:77], v[174:177], v[206:209], v[74:77]
	s_barrier
	s_mov_b32 m0, s50
	v_lshl_add_u64 v[212:213], v[140:141], 0, s[36:37]
	ds_read_b128 v[178:181], v143 offset:49152
	ds_read_b128 v[182:185], v143 offset:50176
	ds_read_b128 v[186:189], v143 offset:51200
	ds_read_b128 v[190:193], v143 offset:52224
	ds_read_b128 v[194:197], v143 offset:53248
	ds_read_b128 v[198:201], v143 offset:54272
	ds_read_b128 v[202:205], v143 offset:55296
	ds_read_b128 v[206:209], v143 offset:56320
	global_load_lds_dwordx4 v[212:213], off
	v_lshl_add_u64 v[212:213], v[140:141], 0, s[38:39]
	s_mov_b32 m0, s51
	s_nop 0
	global_load_lds_dwordx4 v[212:213], off
	v_lshl_add_u64 v[212:213], v[140:141], 0, s[12:13]
	s_mov_b32 m0, s33
	v_lshl_add_u64 v[140:141], v[140:141], 0, s[14:15]
	global_load_lds_dwordx4 v[212:213], off
	s_mov_b32 m0, s56
	s_nop 0
	global_load_lds_dwordx4 v[140:141], off
	v_lshl_add_u64 v[140:141], v[210:211], 0, s[36:37]
	s_mov_b32 m0, s53
	s_nop 0
	global_load_lds_dwordx4 v[140:141], off
	v_lshl_add_u64 v[140:141], v[210:211], 0, s[38:39]
	s_mov_b32 m0, s54
	s_nop 0
	global_load_lds_dwordx4 v[140:141], off
	s_waitcnt vmcnt(8)
	s_waitcnt lgkmcnt(0)
	s_barrier
	v_mfma_f32_16x16x32_bf16 v[54:57], v[146:149], v[178:181], v[54:57]
	v_mfma_f32_16x16x32_bf16 v[50:53], v[154:157], v[178:181], v[50:53]
	v_mfma_f32_16x16x32_bf16 v[38:41], v[146:149], v[186:189], v[38:41]
	v_mfma_f32_16x16x32_bf16 v[34:37], v[154:157], v[186:189], v[34:37]
	v_mfma_f32_16x16x32_bf16 v[22:25], v[146:149], v[194:197], v[22:25]
	v_mfma_f32_16x16x32_bf16 v[18:21], v[154:157], v[194:197], v[18:21]
	v_mfma_f32_16x16x32_bf16 v[6:9], v[146:149], v[202:205], v[6:9]
	v_mfma_f32_16x16x32_bf16 v[2:5], v[154:157], v[202:205], v[2:5]
	v_mfma_f32_16x16x32_bf16 v[54:57], v[150:153], v[182:185], v[54:57]
	v_mfma_f32_16x16x32_bf16 v[50:53], v[158:161], v[182:185], v[50:53]
	v_mfma_f32_16x16x32_bf16 v[38:41], v[150:153], v[190:193], v[38:41]
	v_mfma_f32_16x16x32_bf16 v[34:37], v[158:161], v[190:193], v[34:37]
	v_mfma_f32_16x16x32_bf16 v[22:25], v[150:153], v[198:201], v[22:25]
	v_mfma_f32_16x16x32_bf16 v[18:21], v[158:161], v[198:201], v[18:21]
	v_mfma_f32_16x16x32_bf16 v[6:9], v[150:153], v[206:209], v[6:9]
	v_mfma_f32_16x16x32_bf16 v[2:5], v[158:161], v[206:209], v[2:5]
	v_mfma_f32_16x16x32_bf16 v[62:65], v[162:165], v[178:181], v[62:65]
	v_mfma_f32_16x16x32_bf16 v[58:61], v[170:173], v[178:181], v[58:61]
	v_mfma_f32_16x16x32_bf16 v[46:49], v[162:165], v[186:189], v[46:49]
	v_mfma_f32_16x16x32_bf16 v[42:45], v[170:173], v[186:189], v[42:45]
	v_mfma_f32_16x16x32_bf16 v[30:33], v[162:165], v[194:197], v[30:33]
	v_mfma_f32_16x16x32_bf16 v[26:29], v[170:173], v[194:197], v[26:29]
	v_mfma_f32_16x16x32_bf16 v[14:17], v[162:165], v[202:205], v[14:17]
	v_mfma_f32_16x16x32_bf16 v[10:13], v[170:173], v[202:205], v[10:13]
	v_mfma_f32_16x16x32_bf16 v[62:65], v[166:169], v[182:185], v[62:65]
	v_mfma_f32_16x16x32_bf16 v[58:61], v[174:177], v[182:185], v[58:61]
	v_mfma_f32_16x16x32_bf16 v[46:49], v[166:169], v[190:193], v[46:49]
	v_mfma_f32_16x16x32_bf16 v[42:45], v[174:177], v[190:193], v[42:45]
	v_mfma_f32_16x16x32_bf16 v[30:33], v[166:169], v[198:201], v[30:33]
	v_mfma_f32_16x16x32_bf16 v[26:29], v[174:177], v[198:201], v[26:29]
	v_mfma_f32_16x16x32_bf16 v[14:17], v[166:169], v[206:209], v[14:17]
	v_mfma_f32_16x16x32_bf16 v[10:13], v[174:177], v[206:209], v[10:13]
	s_barrier
	s_add_i32 s77, s77, 2
	s_add_u32 s78, s78, 0x100
	s_addc_u32 s79, s79, 0
	s_add_u32 s57, s57, 0x100
	s_addc_u32 s76, s76, 0
	s_cmp_gt_u32 s77, 29
	s_cbranch_scc0 .LBB0_1381
	s_and_b64 vcc, exec, s[10:11]
	s_cbranch_vccz .LBB0_1384
	s_barrier

; #define PG8_WAIT_V(n) asm volatile("s_waitcnt vmcnt(" #n ")" ::: "memory")
; template <class Epi, class Sched, bool ALIGN_EPI = true, bool SP2 = true, bool FULLLINE = false, bool NOSTAGE = false, bool FP8 = false>
; __device__ __forceinline__ void gemm_phase(PG8_LAS unsigned char* lds, const Gemm g, const Sched& S, const Epi& E) {
;     ...
;         static_assert(SP2, "only the SP2 loop is kept");
;         { const int t = 0; if constexpr (Epi::NST == 16) PG8_ITER(PG8_WAIT_V(24)); else if constexpr (Epi::NST == 8) PG8_ITER(PG8_WAIT_V(16)); else PG8_ITER(PG8_WAIT_V(8)); }
.LBB0_1483:
	ds_read_b128 v[2:5], v1
	ds_read_b128 v[6:9], v1 offset:1024
	ds_read_b128 v[10:13], v1 offset:2048
	ds_read_b128 v[14:17], v1 offset:3072
	ds_read_b128 v[18:21], v192
	ds_read_b128 v[22:25], v192 offset:1024
	ds_read_b128 v[26:29], v192 offset:2048
	ds_read_b128 v[30:33], v192 offset:3072
	v_lshl_add_u64 v[248:249], s[70:71], 0, v[170:171]
	s_add_i32 s85, s45, 0xc000
	v_lshl_add_u64 v[66:67], v[248:249], 0, s[14:15]
	s_mov_b32 m0, s85
	s_add_i32 s87, s45, 0xe000
	ds_read_b128 v[34:37], v193
	ds_read_b128 v[38:41], v193 offset:1024
	ds_read_b128 v[42:45], v193 offset:2048
	ds_read_b128 v[46:49], v193 offset:3072
	ds_read_b128 v[50:53], v193 offset:4096
	ds_read_b128 v[54:57], v193 offset:5120
	ds_read_b128 v[58:61], v193 offset:6144
	ds_read_b128 v[62:65], v193 offset:7168
	global_load_lds_dwordx4 v[66:67], off
	v_lshl_add_u64 v[66:67], v[248:249], 0, s[16:17]
	s_mov_b32 m0, s87
	s_nop 0
	global_load_lds_dwordx4 v[66:67], off
	s_waitcnt vmcnt(24)
	s_waitcnt lgkmcnt(0)
	s_barrier
	v_mfma_f32_16x16x32_bf16 v[66:69], v[2:5], v[34:37], 0
	v_mfma_f32_16x16x32_bf16 v[70:73], v[10:13], v[34:37], 0
	v_mfma_f32_16x16x32_bf16 v[78:81], v[10:13], v[42:45], 0
	v_mfma_f32_16x16x32_bf16 v[86:89], v[10:13], v[50:53], 0
	v_mfma_f32_16x16x32_bf16 v[66:69], v[6:9], v[38:41], v[66:69]
	v_mfma_f32_16x16x32_bf16 v[70:73], v[14:17], v[38:41], v[70:73]
	v_mfma_f32_16x16x32_bf16 v[74:77], v[2:5], v[42:45], 0
	v_mfma_f32_16x16x32_bf16 v[78:81], v[14:17], v[46:49], v[78:81]
	v_mfma_f32_16x16x32_bf16 v[82:85], v[2:5], v[50:53], 0
	v_mfma_f32_16x16x32_bf16 v[86:89], v[14:17], v[54:57], v[86:89]
	v_mfma_f32_16x16x32_bf16 v[90:93], v[2:5], v[58:61], 0
	v_mfma_f32_16x16x32_bf16 v[94:97], v[10:13], v[58:61], 0
	v_mfma_f32_16x16x32_bf16 v[74:77], v[6:9], v[46:49], v[74:77]
	v_mfma_f32_16x16x32_bf16 v[82:85], v[6:9], v[54:57], v[82:85]
	v_mfma_f32_16x16x32_bf16 v[90:93], v[6:9], v[62:65], v[90:93]
	v_mfma_f32_16x16x32_bf16 v[94:97], v[14:17], v[62:65], v[94:97]
	v_mfma_f32_16x16x32_bf16 v[98:101], v[18:21], v[34:37], 0
	v_mfma_f32_16x16x32_bf16 v[34:37], v[26:29], v[34:37], 0
	v_mfma_f32_16x16x32_bf16 v[98:101], v[22:25], v[38:41], v[98:101]
	v_mfma_f32_16x16x32_bf16 v[34:37], v[30:33], v[38:41], v[34:37]
	v_mfma_f32_16x16x32_bf16 v[38:41], v[18:21], v[42:45], 0
	v_mfma_f32_16x16x32_bf16 v[42:45], v[26:29], v[42:45], 0
	v_mfma_f32_16x16x32_bf16 v[38:41], v[22:25], v[46:49], v[38:41]
	v_mfma_f32_16x16x32_bf16 v[42:45], v[30:33], v[46:49], v[42:45]
	v_mfma_f32_16x16x32_bf16 v[46:49], v[18:21], v[50:53], 0
	v_mfma_f32_16x16x32_bf16 v[50:53], v[26:29], v[50:53], 0
	v_mfma_f32_16x16x32_bf16 v[46:49], v[22:25], v[54:57], v[46:49]
	v_mfma_f32_16x16x32_bf16 v[50:53], v[30:33], v[54:57], v[50:53]
	v_mfma_f32_16x16x32_bf16 v[54:57], v[18:21], v[58:61], 0
	v_mfma_f32_16x16x32_bf16 v[58:61], v[26:29], v[58:61], 0
	v_mfma_f32_16x16x32_bf16 v[54:57], v[22:25], v[62:65], v[54:57]
	v_mfma_f32_16x16x32_bf16 v[58:61], v[30:33], v[62:65], v[58:61]
	s_barrier
	v_lshl_add_u64 v[250:251], s[72:73], 0, v[172:173]
	s_add_i32 s88, s77, s44
	v_lshl_add_u64 v[130:131], v[250:251], 0, s[18:19]
	s_mov_b32 m0, s88
	s_add_i32 s89, s88, 0x2000
	ds_read_b128 v[62:65], v193 offset:16384
	ds_read_b128 v[102:105], v193 offset:17408
	ds_read_b128 v[106:109], v193 offset:18432
	ds_read_b128 v[110:113], v193 offset:19456
	ds_read_b128 v[114:117], v193 offset:20480
	ds_read_b128 v[118:121], v193 offset:21504
	ds_read_b128 v[122:125], v193 offset:22528
	ds_read_b128 v[126:129], v193 offset:23552
	global_load_lds_dwordx4 v[130:131], off
	v_lshl_add_u64 v[130:131], v[250:251], 0, s[20:21]
	s_mov_b32 m0, s89
	s_add_i32 s40, s78, s44
	global_load_lds_dwordx4 v[130:131], off
	v_lshl_add_u64 v[130:131], v[250:251], 0, s[22:23]
	s_mov_b32 m0, s40
	s_add_i32 s41, s40, 0x2000
	global_load_lds_dwordx4 v[130:131], off
	v_lshl_add_u64 v[130:131], v[250:251], 0, s[24:25]
	s_mov_b32 m0, s41
	s_nop 0
	global_load_lds_dwordx4 v[130:131], off
	v_lshl_add_u64 v[130:131], v[248:249], 0, s[18:19]
	s_mov_b32 m0, s45
	s_nop 0
	global_load_lds_dwordx4 v[130:131], off
	v_lshl_add_u64 v[130:131], v[248:249], 0, s[20:21]
	s_mov_b32 m0, s46
	s_nop 0
	global_load_lds_dwordx4 v[130:131], off
	s_waitcnt vmcnt(24)
	s_waitcnt lgkmcnt(0)
	s_barrier
	v_mfma_f32_16x16x32_bf16 v[130:133], v[2:5], v[62:65], 0
	v_mfma_f32_16x16x32_bf16 v[138:141], v[6:9], v[102:105], v[130:133]
	v_mfma_f32_16x16x32_bf16 v[130:133], v[10:13], v[62:65], 0
	v_mfma_f32_16x16x32_bf16 v[150:153], v[14:17], v[102:105], v[130:133]
	v_mfma_f32_16x16x32_bf16 v[130:133], v[2:5], v[106:109], 0
	v_mfma_f32_16x16x32_bf16 v[154:157], v[6:9], v[110:113], v[130:133]
	v_mfma_f32_16x16x32_bf16 v[130:133], v[10:13], v[106:109], 0
	v_mfma_f32_16x16x32_bf16 v[158:161], v[14:17], v[110:113], v[130:133]
	v_mfma_f32_16x16x32_bf16 v[130:133], v[2:5], v[114:117], 0
	v_mfma_f32_16x16x32_bf16 v[2:5], v[2:5], v[122:125], 0
	v_mfma_f32_16x16x32_bf16 v[162:165], v[6:9], v[118:121], v[130:133]
	v_mfma_f32_16x16x32_bf16 v[2:5], v[6:9], v[126:129], v[2:5]
	v_mfma_f32_16x16x32_bf16 v[6:9], v[10:13], v[122:125], 0
	v_mfma_f32_16x16x32_bf16 v[130:133], v[10:13], v[114:117], 0
	v_mfma_f32_16x16x32_bf16 v[6:9], v[14:17], v[126:129], v[6:9]
	v_mfma_f32_16x16x32_bf16 v[166:169], v[14:17], v[118:121], v[130:133]
	v_mfma_f32_16x16x32_bf16 v[10:13], v[18:21], v[62:65], 0
	v_mfma_f32_16x16x32_bf16 v[180:183], v[22:25], v[102:105], v[10:13]
	v_mfma_f32_16x16x32_bf16 v[10:13], v[26:29], v[62:65], 0
	v_mfma_f32_16x16x32_bf16 v[184:187], v[30:33], v[102:105], v[10:13]
	v_mfma_f32_16x16x32_bf16 v[10:13], v[18:21], v[106:109], 0
	v_mfma_f32_16x16x32_bf16 v[188:191], v[22:25], v[110:113], v[10:13]
	v_mfma_f32_16x16x32_bf16 v[10:13], v[26:29], v[106:109], 0
	v_mfma_f32_16x16x32_bf16 v[196:199], v[30:33], v[110:113], v[10:13]
	v_mfma_f32_16x16x32_bf16 v[10:13], v[18:21], v[114:117], 0
	v_mfma_f32_16x16x32_bf16 v[200:203], v[22:25], v[118:121], v[10:13]
	v_mfma_f32_16x16x32_bf16 v[10:13], v[26:29], v[114:117], 0
	v_mfma_f32_16x16x32_bf16 v[204:207], v[30:33], v[118:121], v[10:13]
	v_mfma_f32_16x16x32_bf16 v[10:13], v[18:21], v[122:125], 0
	v_mfma_f32_16x16x32_bf16 v[208:211], v[22:25], v[126:129], v[10:13]
	v_mfma_f32_16x16x32_bf16 v[10:13], v[26:29], v[122:125], 0
	v_mfma_f32_16x16x32_bf16 v[212:215], v[30:33], v[126:129], v[10:13]
	s_barrier
; #define PG8_WAIT_V(n) asm volatile("s_waitcnt vmcnt(" #n ")" ::: "memory")
; template <class Epi, class Sched, bool ALIGN_EPI = true, bool SP2 = true, bool FULLLINE = false, bool NOSTAGE = false, bool FP8 = false>
; __device__ __forceinline__ void gemm_phase(PG8_LAS unsigned char* lds, const Gemm g, const Sched& S, const Epi& E) {
;     ...
;         static_assert(SP2, "only the SP2 loop is kept");
;         { const int t = 0; if constexpr (Epi::NST == 16) PG8_ITER(PG8_WAIT_V(24)); else if constexpr (Epi::NST == 8) PG8_ITER(PG8_WAIT_V(16)); else PG8_ITER(PG8_WAIT_V(8)); }
	s_nop 5
	ds_read_b128 v[10:13], v194
	ds_read_b128 v[14:17], v194 offset:1024
	ds_read_b128 v[18:21], v194 offset:2048
	ds_read_b128 v[22:25], v194 offset:3072
	ds_read_b128 v[216:219], v195
	ds_read_b128 v[220:223], v195 offset:1024
	ds_read_b128 v[224:227], v195 offset:2048
	ds_read_b128 v[228:231], v195 offset:3072
	s_mov_b32 m0, s47
	v_lshl_add_u64 v[106:107], v[248:249], 0, s[22:23]
	ds_read_b128 v[26:29], v193 offset:32768
	ds_read_b128 v[30:33], v193 offset:33792
	ds_read_b128 v[62:65], v193 offset:34816
	ds_read_b128 v[102:105], v193 offset:35840
	ds_read_b128 v[232:235], v193 offset:36864
	ds_read_b128 v[236:239], v193 offset:37888
	ds_read_b128 v[240:243], v193 offset:38912
	ds_read_b128 v[244:247], v193 offset:39936
	global_load_lds_dwordx4 v[106:107], off
	v_lshl_add_u64 v[106:107], v[248:249], 0, s[24:25]
	s_mov_b32 m0, s52
	s_nop 0
	global_load_lds_dwordx4 v[106:107], off
	s_waitcnt vmcnt(8)
	s_waitcnt lgkmcnt(0)
	s_barrier
	v_mfma_f32_16x16x32_bf16 v[66:69], v[10:13], v[26:29], v[66:69]
	v_mfma_f32_16x16x32_bf16 v[146:149], v[14:17], v[30:33], v[66:69]
	v_mfma_f32_16x16x32_bf16 v[66:69], v[18:21], v[26:29], v[70:73]
	v_mfma_f32_16x16x32_bf16 v[142:145], v[22:25], v[30:33], v[66:69]
	v_mfma_f32_16x16x32_bf16 v[66:69], v[10:13], v[62:65], v[74:77]
	v_mfma_f32_16x16x32_bf16 v[126:129], v[14:17], v[102:105], v[66:69]
	v_mfma_f32_16x16x32_bf16 v[66:69], v[18:21], v[62:65], v[78:81]
	v_mfma_f32_16x16x32_bf16 v[122:125], v[22:25], v[102:105], v[66:69]
	v_mfma_f32_16x16x32_bf16 v[66:69], v[10:13], v[232:235], v[82:85]
	v_mfma_f32_16x16x32_bf16 v[110:113], v[14:17], v[236:239], v[66:69]
	v_mfma_f32_16x16x32_bf16 v[66:69], v[18:21], v[232:235], v[86:89]
	v_mfma_f32_16x16x32_bf16 v[106:109], v[22:25], v[236:239], v[66:69]
	v_mfma_f32_16x16x32_bf16 v[66:69], v[10:13], v[240:243], v[90:93]
	v_mfma_f32_16x16x32_bf16 v[86:89], v[14:17], v[244:247], v[66:69]
	v_mfma_f32_16x16x32_bf16 v[66:69], v[18:21], v[240:243], v[94:97]
	v_mfma_f32_16x16x32_bf16 v[78:81], v[22:25], v[244:247], v[66:69]
	v_mfma_f32_16x16x32_bf16 v[66:69], v[216:219], v[26:29], v[98:101]
	v_mfma_f32_16x16x32_bf16 v[26:29], v[224:227], v[26:29], v[34:37]
	v_mfma_f32_16x16x32_bf16 v[130:133], v[228:231], v[30:33], v[26:29]
	v_mfma_f32_16x16x32_bf16 v[26:29], v[216:219], v[62:65], v[38:41]
	v_mfma_f32_16x16x32_bf16 v[118:121], v[220:223], v[102:105], v[26:29]
	v_mfma_f32_16x16x32_bf16 v[26:29], v[224:227], v[62:65], v[42:45]
	v_mfma_f32_16x16x32_bf16 v[114:117], v[228:231], v[102:105], v[26:29]
	v_mfma_f32_16x16x32_bf16 v[26:29], v[216:219], v[232:235], v[46:49]
	v_mfma_f32_16x16x32_bf16 v[102:105], v[220:223], v[236:239], v[26:29]
	v_mfma_f32_16x16x32_bf16 v[26:29], v[224:227], v[232:235], v[50:53]
	v_mfma_f32_16x16x32_bf16 v[98:101], v[228:231], v[236:239], v[26:29]
	v_mfma_f32_16x16x32_bf16 v[26:29], v[216:219], v[240:243], v[54:57]
	v_mfma_f32_16x16x32_bf16 v[70:73], v[220:223], v[244:247], v[26:29]
	v_mfma_f32_16x16x32_bf16 v[26:29], v[224:227], v[240:243], v[58:61]
	v_mfma_f32_16x16x32_bf16 v[134:137], v[220:223], v[30:33], v[66:69]
	v_mfma_f32_16x16x32_bf16 v[66:69], v[228:231], v[244:247], v[26:29]
	s_barrier
	s_add_i32 s50, s79, s44
	s_nop 3
	v_lshl_add_u64 v[26:27], v[250:251], 0, s[26:27]
	s_mov_b32 m0, s50
	s_add_i32 s51, s50, 0x2000
	ds_read_b128 v[34:37], v193 offset:49152
	ds_read_b128 v[38:41], v193 offset:50176
	ds_read_b128 v[74:77], v193 offset:51200
	ds_read_b128 v[82:85], v193 offset:52224
	ds_read_b128 v[90:93], v193 offset:53248
	ds_read_b128 v[94:97], v193 offset:54272
	ds_read_b128 v[232:235], v193 offset:55296
	ds_read_b128 v[236:239], v193 offset:56320
	global_load_lds_dwordx4 v[26:27], off
	v_lshl_add_u64 v[26:27], v[250:251], 0, s[28:29]
	s_mov_b32 m0, s51
	s_mov_b64 s[0:1], 0x160180
	s_add_i32 s33, s80, s44
	global_load_lds_dwordx4 v[26:27], off
	v_lshl_add_u64 v[26:27], v[250:251], 0, s[0:1]
	s_mov_b32 m0, s33
	s_mov_b64 s[0:1], 0x210180
	s_add_i32 s56, s33, 0x2000
	global_load_lds_dwordx4 v[26:27], off
	v_lshl_add_u64 v[26:27], v[250:251], 0, s[0:1]
	s_mov_b32 m0, s56
	s_nop 0
	global_load_lds_dwordx4 v[26:27], off
	v_lshl_add_u64 v[26:27], v[248:249], 0, s[26:27]
	s_mov_b32 m0, s53
	s_nop 0
	global_load_lds_dwordx4 v[26:27], off
	v_lshl_add_u64 v[26:27], v[248:249], 0, s[28:29]
	s_mov_b32 m0, s54
	s_nop 0
	global_load_lds_dwordx4 v[26:27], off
	s_waitcnt vmcnt(8)
	s_waitcnt lgkmcnt(0)
	s_barrier
	v_mfma_f32_16x16x32_bf16 v[26:29], v[10:13], v[34:37], v[138:141]
	v_mfma_f32_16x16x32_bf16 v[62:65], v[14:17], v[38:41], v[26:29]
	v_mfma_f32_16x16x32_bf16 v[26:29], v[18:21], v[34:37], v[150:153]
	v_mfma_f32_16x16x32_bf16 v[58:61], v[22:25], v[38:41], v[26:29]
	v_mfma_f32_16x16x32_bf16 v[26:29], v[10:13], v[74:77], v[154:157]
	v_mfma_f32_16x16x32_bf16 v[46:49], v[14:17], v[82:85], v[26:29]
	v_mfma_f32_16x16x32_bf16 v[26:29], v[18:21], v[74:77], v[158:161]
	v_mfma_f32_16x16x32_bf16 v[42:45], v[22:25], v[82:85], v[26:29]
	v_mfma_f32_16x16x32_bf16 v[26:29], v[10:13], v[90:93], v[162:165]
	v_mfma_f32_16x16x32_bf16 v[2:5], v[10:13], v[232:235], v[2:5]
	v_mfma_f32_16x16x32_bf16 v[30:33], v[14:17], v[94:97], v[26:29]
	v_mfma_f32_16x16x32_bf16 v[26:29], v[18:21], v[90:93], v[166:169]
	v_mfma_f32_16x16x32_bf16 v[14:17], v[14:17], v[236:239], v[2:5]
	v_mfma_f32_16x16x32_bf16 v[2:5], v[18:21], v[232:235], v[6:9]
	v_mfma_f32_16x16x32_bf16 v[26:29], v[22:25], v[94:97], v[26:29]
	v_mfma_f32_16x16x32_bf16 v[10:13], v[22:25], v[236:239], v[2:5]
	v_mfma_f32_16x16x32_bf16 v[2:5], v[216:219], v[34:37], v[180:183]
	v_mfma_f32_16x16x32_bf16 v[54:57], v[220:223], v[38:41], v[2:5]
	v_mfma_f32_16x16x32_bf16 v[2:5], v[224:227], v[34:37], v[184:187]
	v_mfma_f32_16x16x32_bf16 v[50:53], v[228:231], v[38:41], v[2:5]
	v_mfma_f32_16x16x32_bf16 v[2:5], v[216:219], v[74:77], v[188:191]
	v_mfma_f32_16x16x32_bf16 v[38:41], v[220:223], v[82:85], v[2:5]
	v_mfma_f32_16x16x32_bf16 v[2:5], v[224:227], v[74:77], v[196:199]
	v_mfma_f32_16x16x32_bf16 v[34:37], v[228:231], v[82:85], v[2:5]
	v_mfma_f32_16x16x32_bf16 v[2:5], v[216:219], v[90:93], v[200:203]
	v_mfma_f32_16x16x32_bf16 v[22:25], v[220:223], v[94:97], v[2:5]
	v_mfma_f32_16x16x32_bf16 v[2:5], v[224:227], v[90:93], v[204:207]
	v_mfma_f32_16x16x32_bf16 v[18:21], v[228:231], v[94:97], v[2:5]
	v_mfma_f32_16x16x32_bf16 v[2:5], v[216:219], v[232:235], v[208:211]
	v_mfma_f32_16x16x32_bf16 v[6:9], v[220:223], v[236:239], v[2:5]
	v_mfma_f32_16x16x32_bf16 v[2:5], v[224:227], v[232:235], v[212:215]
	v_mfma_f32_16x16x32_bf16 v[2:5], v[228:231], v[236:239], v[2:5]
	s_barrier
	s_add_u32 s70, s70, 0x160180
	s_addc_u32 s71, s71, 0
	s_add_u32 s57, s72, 0x200
	s_addc_u32 s72, s73, 0
	s_mov_b32 s73, 0
; #define PG8_WAIT_V(n) asm volatile("s_waitcnt vmcnt(" #n ")" ::: "memory")
; template <class Epi, class Sched, bool ALIGN_EPI = true, bool SP2 = true, bool FULLLINE = false, bool NOSTAGE = false, bool FP8 = false>
; __device__ __forceinline__ void gemm_phase(PG8_LAS unsigned char* lds, const Gemm g, const Sched& S, const Epi& E) {
;     ...
;         static_assert(SP2, "only the SP2 loop is kept");
;         { const int t = 0; if constexpr (Epi::NST == 16) PG8_ITER(PG8_WAIT_V(24)); else if constexpr (Epi::NST == 8) PG8_ITER(PG8_WAIT_V(16)); else PG8_ITER(PG8_WAIT_V(8)); }
;         for (int t = 2; t < nt; t += 2) PG8_ITER(PG8_WAIT_V(8));
.LBB0_1484:
	ds_read_b128 v[74:77], v1
	ds_read_b128 v[82:85], v1 offset:1024
	ds_read_b128 v[90:93], v1 offset:2048
	ds_read_b128 v[94:97], v1 offset:3072
	ds_read_b128 v[138:141], v192
	ds_read_b128 v[150:153], v192 offset:1024
	ds_read_b128 v[154:157], v192 offset:2048
	ds_read_b128 v[158:161], v192 offset:3072
	s_add_u32 s0, s70, 0xffea0080
	s_addc_u32 s1, s71, -1
	s_cmpk_eq_i32 s73, 0x54
	s_cselect_b32 s1, s11, s1
	s_cselect_b32 s0, s10, s0
	s_cselect_b32 s65, s69, s72
	s_cselect_b32 s64, s68, s57
	s_mov_b32 m0, s85
	v_lshl_add_u64 v[208:209], s[70:71], 0, v[174:175]
	ds_read_b128 v[162:165], v193
	ds_read_b128 v[166:169], v193 offset:1024
	ds_read_b128 v[180:183], v193 offset:2048
	ds_read_b128 v[184:187], v193 offset:3072
	ds_read_b128 v[188:191], v193 offset:4096
	ds_read_b128 v[196:199], v193 offset:5120
	ds_read_b128 v[200:203], v193 offset:6144
	ds_read_b128 v[204:207], v193 offset:7168
	global_load_lds_dwordx4 v[208:209], off
	v_lshl_add_u64 v[208:209], v[208:209], 0, s[30:31]
	s_mov_b32 m0, s87
	s_nop 0
	global_load_lds_dwordx4 v[208:209], off
	s_waitcnt vmcnt(8)
	s_waitcnt lgkmcnt(0)
	s_barrier
	v_mfma_f32_16x16x32_bf16 v[146:149], v[74:77], v[162:165], v[146:149]
	v_mfma_f32_16x16x32_bf16 v[142:145], v[90:93], v[162:165], v[142:145]
	v_mfma_f32_16x16x32_bf16 v[126:129], v[74:77], v[180:183], v[126:129]
	v_mfma_f32_16x16x32_bf16 v[122:125], v[90:93], v[180:183], v[122:125]
	v_mfma_f32_16x16x32_bf16 v[110:113], v[74:77], v[188:191], v[110:113]
	v_mfma_f32_16x16x32_bf16 v[106:109], v[90:93], v[188:191], v[106:109]
	v_mfma_f32_16x16x32_bf16 v[86:89], v[74:77], v[200:203], v[86:89]
	v_mfma_f32_16x16x32_bf16 v[78:81], v[90:93], v[200:203], v[78:81]
	v_mfma_f32_16x16x32_bf16 v[146:149], v[82:85], v[166:169], v[146:149]
	v_mfma_f32_16x16x32_bf16 v[142:145], v[94:97], v[166:169], v[142:145]
	v_mfma_f32_16x16x32_bf16 v[126:129], v[82:85], v[184:187], v[126:129]
	v_mfma_f32_16x16x32_bf16 v[122:125], v[94:97], v[184:187], v[122:125]
	v_mfma_f32_16x16x32_bf16 v[110:113], v[82:85], v[196:199], v[110:113]
	v_mfma_f32_16x16x32_bf16 v[106:109], v[94:97], v[196:199], v[106:109]
	v_mfma_f32_16x16x32_bf16 v[86:89], v[82:85], v[204:207], v[86:89]
	v_mfma_f32_16x16x32_bf16 v[78:81], v[94:97], v[204:207], v[78:81]
	v_mfma_f32_16x16x32_bf16 v[134:137], v[138:141], v[162:165], v[134:137]
	v_mfma_f32_16x16x32_bf16 v[130:133], v[154:157], v[162:165], v[130:133]
	v_mfma_f32_16x16x32_bf16 v[118:121], v[138:141], v[180:183], v[118:121]
	v_mfma_f32_16x16x32_bf16 v[114:117], v[154:157], v[180:183], v[114:117]
	v_mfma_f32_16x16x32_bf16 v[102:105], v[138:141], v[188:191], v[102:105]
	v_mfma_f32_16x16x32_bf16 v[98:101], v[154:157], v[188:191], v[98:101]
	v_mfma_f32_16x16x32_bf16 v[70:73], v[138:141], v[200:203], v[70:73]
	v_mfma_f32_16x16x32_bf16 v[66:69], v[154:157], v[200:203], v[66:69]
	v_mfma_f32_16x16x32_bf16 v[134:137], v[150:153], v[166:169], v[134:137]
	v_mfma_f32_16x16x32_bf16 v[130:133], v[158:161], v[166:169], v[130:133]
	v_mfma_f32_16x16x32_bf16 v[118:121], v[150:153], v[184:187], v[118:121]
	v_mfma_f32_16x16x32_bf16 v[114:117], v[158:161], v[184:187], v[114:117]
	v_mfma_f32_16x16x32_bf16 v[102:105], v[150:153], v[196:199], v[102:105]
	v_mfma_f32_16x16x32_bf16 v[98:101], v[158:161], v[196:199], v[98:101]
	v_mfma_f32_16x16x32_bf16 v[70:73], v[150:153], v[204:207], v[70:73]
	v_mfma_f32_16x16x32_bf16 v[66:69], v[158:161], v[204:207], v[66:69]
	s_barrier
	s_mov_b32 m0, s88
	v_lshl_add_u64 v[208:209], s[64:65], 0, v[172:173]
	ds_read_b128 v[162:165], v193 offset:16384
	ds_read_b128 v[166:169], v193 offset:17408
	ds_read_b128 v[180:183], v193 offset:18432
	ds_read_b128 v[184:187], v193 offset:19456
	ds_read_b128 v[188:191], v193 offset:20480
	ds_read_b128 v[196:199], v193 offset:21504
	ds_read_b128 v[200:203], v193 offset:22528
	ds_read_b128 v[204:207], v193 offset:23552
	global_load_lds_dwordx4 v[208:209], off
	v_lshl_add_u64 v[210:211], v[208:209], 0, s[30:31]
	s_mov_b32 m0, s89
	s_nop 0
	global_load_lds_dwordx4 v[210:211], off
	v_lshl_add_u64 v[210:211], v[208:209], 0, s[34:35]
	s_mov_b32 m0, s40
	s_nop 0
	global_load_lds_dwordx4 v[210:211], off
	v_lshl_add_u64 v[210:211], v[208:209], 0, s[36:37]
	s_mov_b32 m0, s41
	s_nop 0
	global_load_lds_dwordx4 v[210:211], off
	v_lshl_add_u64 v[210:211], s[0:1], 0, v[170:171]
	s_mov_b32 m0, s45
	v_lshl_add_u64 v[212:213], v[210:211], 0, s[30:31]
	global_load_lds_dwordx4 v[210:211], off
	s_mov_b32 m0, s46
	s_nop 0
	global_load_lds_dwordx4 v[212:213], off
	s_waitcnt vmcnt(8)
	s_waitcnt lgkmcnt(0)
	s_barrier
	v_mfma_f32_16x16x32_bf16 v[62:65], v[74:77], v[162:165], v[62:65]
	v_mfma_f32_16x16x32_bf16 v[58:61], v[90:93], v[162:165], v[58:61]
	v_mfma_f32_16x16x32_bf16 v[46:49], v[74:77], v[180:183], v[46:49]
	v_mfma_f32_16x16x32_bf16 v[42:45], v[90:93], v[180:183], v[42:45]
	v_mfma_f32_16x16x32_bf16 v[30:33], v[74:77], v[188:191], v[30:33]
	v_mfma_f32_16x16x32_bf16 v[26:29], v[90:93], v[188:191], v[26:29]
	v_mfma_f32_16x16x32_bf16 v[14:17], v[74:77], v[200:203], v[14:17]
	v_mfma_f32_16x16x32_bf16 v[10:13], v[90:93], v[200:203], v[10:13]
	v_mfma_f32_16x16x32_bf16 v[62:65], v[82:85], v[166:169], v[62:65]
	v_mfma_f32_16x16x32_bf16 v[58:61], v[94:97], v[166:169], v[58:61]
	v_mfma_f32_16x16x32_bf16 v[46:49], v[82:85], v[184:187], v[46:49]
	v_mfma_f32_16x16x32_bf16 v[42:45], v[94:97], v[184:187], v[42:45]
	v_mfma_f32_16x16x32_bf16 v[30:33], v[82:85], v[196:199], v[30:33]
	v_mfma_f32_16x16x32_bf16 v[26:29], v[94:97], v[196:199], v[26:29]
	v_mfma_f32_16x16x32_bf16 v[14:17], v[82:85], v[204:207], v[14:17]
	v_mfma_f32_16x16x32_bf16 v[10:13], v[94:97], v[204:207], v[10:13]
	v_mfma_f32_16x16x32_bf16 v[54:57], v[138:141], v[162:165], v[54:57]
	v_mfma_f32_16x16x32_bf16 v[50:53], v[154:157], v[162:165], v[50:53]
	v_mfma_f32_16x16x32_bf16 v[38:41], v[138:141], v[180:183], v[38:41]
	v_mfma_f32_16x16x32_bf16 v[34:37], v[154:157], v[180:183], v[34:37]
	v_mfma_f32_16x16x32_bf16 v[22:25], v[138:141], v[188:191], v[22:25]
	v_mfma_f32_16x16x32_bf16 v[18:21], v[154:157], v[188:191], v[18:21]
	v_mfma_f32_16x16x32_bf16 v[6:9], v[138:141], v[200:203], v[6:9]
	v_mfma_f32_16x16x32_bf16 v[2:5], v[154:157], v[200:203], v[2:5]
	v_mfma_f32_16x16x32_bf16 v[54:57], v[150:153], v[166:169], v[54:57]
	v_mfma_f32_16x16x32_bf16 v[50:53], v[158:161], v[166:169], v[50:53]
	v_mfma_f32_16x16x32_bf16 v[38:41], v[150:153], v[184:187], v[38:41]
	v_mfma_f32_16x16x32_bf16 v[34:37], v[158:161], v[184:187], v[34:37]
	v_mfma_f32_16x16x32_bf16 v[22:25], v[150:153], v[196:199], v[22:25]
	v_mfma_f32_16x16x32_bf16 v[18:21], v[158:161], v[196:199], v[18:21]
	v_mfma_f32_16x16x32_bf16 v[6:9], v[150:153], v[204:207], v[6:9]
	v_mfma_f32_16x16x32_bf16 v[2:5], v[158:161], v[204:207], v[2:5]
	s_barrier
; #define PG8_WAIT_V(n) asm volatile("s_waitcnt vmcnt(" #n ")" ::: "memory")
; #define PG8_BAR __builtin_amdgcn_s_barrier()
; template <class Epi, class Sched, bool ALIGN_EPI = true, bool SP2 = true, bool FULLLINE = false, bool NOSTAGE = false, bool FP8 = false>
; __device__ __forceinline__ void gemm_phase(PG8_LAS unsigned char* lds, const Gemm g, const Sched& S, const Epi& E) {
;     ...
;         static_assert(SP2, "only the SP2 loop is kept");
;         { const int t = 0; if constexpr (Epi::NST == 16) PG8_ITER(PG8_WAIT_V(24)); else if constexpr (Epi::NST == 8) PG8_ITER(PG8_WAIT_V(16)); else PG8_ITER(PG8_WAIT_V(8)); }
;         for (int t = 2; t < nt; t += 2) PG8_ITER(PG8_WAIT_V(8));
;     ...
;         if constexpr (ALIGN_EPI) { if (wr == 0) PG8_BAR; }
	ds_read_b128 v[74:77], v194
	ds_read_b128 v[82:85], v194 offset:1024
	ds_read_b128 v[90:93], v194 offset:2048
	ds_read_b128 v[94:97], v194 offset:3072
	ds_read_b128 v[138:141], v195
	ds_read_b128 v[150:153], v195 offset:1024
	ds_read_b128 v[154:157], v195 offset:2048
	ds_read_b128 v[158:161], v195 offset:3072
	s_mov_b32 m0, s47
	v_lshl_add_u64 v[212:213], v[210:211], 0, s[34:35]
	ds_read_b128 v[162:165], v193 offset:32768
	ds_read_b128 v[166:169], v193 offset:33792
	ds_read_b128 v[180:183], v193 offset:34816
	ds_read_b128 v[184:187], v193 offset:35840
	ds_read_b128 v[188:191], v193 offset:36864
	ds_read_b128 v[196:199], v193 offset:37888
	ds_read_b128 v[200:203], v193 offset:38912
	ds_read_b128 v[204:207], v193 offset:39936
	global_load_lds_dwordx4 v[212:213], off
	v_lshl_add_u64 v[212:213], v[210:211], 0, s[36:37]
	s_mov_b32 m0, s52
	s_nop 0
	global_load_lds_dwordx4 v[212:213], off
	s_waitcnt vmcnt(8)
	s_waitcnt lgkmcnt(0)
	s_barrier
	v_mfma_f32_16x16x32_bf16 v[146:149], v[74:77], v[162:165], v[146:149]
	v_mfma_f32_16x16x32_bf16 v[142:145], v[90:93], v[162:165], v[142:145]
	v_mfma_f32_16x16x32_bf16 v[126:129], v[74:77], v[180:183], v[126:129]
	v_mfma_f32_16x16x32_bf16 v[122:125], v[90:93], v[180:183], v[122:125]
	v_mfma_f32_16x16x32_bf16 v[110:113], v[74:77], v[188:191], v[110:113]
	v_mfma_f32_16x16x32_bf16 v[106:109], v[90:93], v[188:191], v[106:109]
	v_mfma_f32_16x16x32_bf16 v[86:89], v[74:77], v[200:203], v[86:89]
	v_mfma_f32_16x16x32_bf16 v[78:81], v[90:93], v[200:203], v[78:81]
	v_mfma_f32_16x16x32_bf16 v[146:149], v[82:85], v[166:169], v[146:149]
	v_mfma_f32_16x16x32_bf16 v[142:145], v[94:97], v[166:169], v[142:145]
	v_mfma_f32_16x16x32_bf16 v[126:129], v[82:85], v[184:187], v[126:129]
	v_mfma_f32_16x16x32_bf16 v[122:125], v[94:97], v[184:187], v[122:125]
	v_mfma_f32_16x16x32_bf16 v[110:113], v[82:85], v[196:199], v[110:113]
	v_mfma_f32_16x16x32_bf16 v[106:109], v[94:97], v[196:199], v[106:109]
	v_mfma_f32_16x16x32_bf16 v[86:89], v[82:85], v[204:207], v[86:89]
	v_mfma_f32_16x16x32_bf16 v[78:81], v[94:97], v[204:207], v[78:81]
	v_mfma_f32_16x16x32_bf16 v[134:137], v[138:141], v[162:165], v[134:137]
	v_mfma_f32_16x16x32_bf16 v[130:133], v[154:157], v[162:165], v[130:133]
	v_mfma_f32_16x16x32_bf16 v[118:121], v[138:141], v[180:183], v[118:121]
	v_mfma_f32_16x16x32_bf16 v[114:117], v[154:157], v[180:183], v[114:117]
	v_mfma_f32_16x16x32_bf16 v[102:105], v[138:141], v[188:191], v[102:105]
	v_mfma_f32_16x16x32_bf16 v[98:101], v[154:157], v[188:191], v[98:101]
	v_mfma_f32_16x16x32_bf16 v[70:73], v[138:141], v[200:203], v[70:73]
	v_mfma_f32_16x16x32_bf16 v[66:69], v[154:157], v[200:203], v[66:69]
	v_mfma_f32_16x16x32_bf16 v[134:137], v[150:153], v[166:169], v[134:137]
	v_mfma_f32_16x16x32_bf16 v[130:133], v[158:161], v[166:169], v[130:133]
	v_mfma_f32_16x16x32_bf16 v[118:121], v[150:153], v[184:187], v[118:121]
	v_mfma_f32_16x16x32_bf16 v[114:117], v[158:161], v[184:187], v[114:117]
	v_mfma_f32_16x16x32_bf16 v[102:105], v[150:153], v[196:199], v[102:105]
	v_mfma_f32_16x16x32_bf16 v[98:101], v[158:161], v[196:199], v[98:101]
	v_mfma_f32_16x16x32_bf16 v[70:73], v[150:153], v[204:207], v[70:73]
	v_mfma_f32_16x16x32_bf16 v[66:69], v[158:161], v[204:207], v[66:69]
	s_barrier
	s_mov_b32 m0, s50
	v_lshl_add_u64 v[212:213], v[208:209], 0, s[38:39]
	ds_read_b128 v[162:165], v193 offset:49152
	ds_read_b128 v[166:169], v193 offset:50176
	ds_read_b128 v[180:183], v193 offset:51200
	ds_read_b128 v[184:187], v193 offset:52224
	ds_read_b128 v[188:191], v193 offset:53248
	ds_read_b128 v[196:199], v193 offset:54272
	ds_read_b128 v[200:203], v193 offset:55296
	ds_read_b128 v[204:207], v193 offset:56320
	global_load_lds_dwordx4 v[212:213], off
	v_lshl_add_u64 v[212:213], v[208:209], 0, s[66:67]
	s_mov_b32 m0, s51
	s_nop 0
	global_load_lds_dwordx4 v[212:213], off
	v_lshl_add_u64 v[212:213], v[208:209], 0, s[14:15]
	s_mov_b32 m0, s33
	v_lshl_add_u64 v[208:209], v[208:209], 0, s[16:17]
	global_load_lds_dwordx4 v[212:213], off
	s_mov_b32 m0, s56
	s_nop 0
	global_load_lds_dwordx4 v[208:209], off
	v_lshl_add_u64 v[208:209], v[210:211], 0, s[38:39]
	s_mov_b32 m0, s53
	s_nop 0
	global_load_lds_dwordx4 v[208:209], off
	v_lshl_add_u64 v[208:209], v[210:211], 0, s[66:67]
	s_mov_b32 m0, s54
	s_nop 0
	global_load_lds_dwordx4 v[208:209], off
	s_waitcnt vmcnt(8)
	s_waitcnt lgkmcnt(0)
	s_barrier
	v_mfma_f32_16x16x32_bf16 v[62:65], v[74:77], v[162:165], v[62:65]
	v_mfma_f32_16x16x32_bf16 v[58:61], v[90:93], v[162:165], v[58:61]
	v_mfma_f32_16x16x32_bf16 v[46:49], v[74:77], v[180:183], v[46:49]
	v_mfma_f32_16x16x32_bf16 v[42:45], v[90:93], v[180:183], v[42:45]
	v_mfma_f32_16x16x32_bf16 v[30:33], v[74:77], v[188:191], v[30:33]
	v_mfma_f32_16x16x32_bf16 v[26:29], v[90:93], v[188:191], v[26:29]
	v_mfma_f32_16x16x32_bf16 v[14:17], v[74:77], v[200:203], v[14:17]
	v_mfma_f32_16x16x32_bf16 v[10:13], v[90:93], v[200:203], v[10:13]
	v_mfma_f32_16x16x32_bf16 v[62:65], v[82:85], v[166:169], v[62:65]
	v_mfma_f32_16x16x32_bf16 v[58:61], v[94:97], v[166:169], v[58:61]
	v_mfma_f32_16x16x32_bf16 v[46:49], v[82:85], v[184:187], v[46:49]
	v_mfma_f32_16x16x32_bf16 v[42:45], v[94:97], v[184:187], v[42:45]
	v_mfma_f32_16x16x32_bf16 v[30:33], v[82:85], v[196:199], v[30:33]
	v_mfma_f32_16x16x32_bf16 v[26:29], v[94:97], v[196:199], v[26:29]
	v_mfma_f32_16x16x32_bf16 v[14:17], v[82:85], v[204:207], v[14:17]
	v_mfma_f32_16x16x32_bf16 v[10:13], v[94:97], v[204:207], v[10:13]
	v_mfma_f32_16x16x32_bf16 v[54:57], v[138:141], v[162:165], v[54:57]
	v_mfma_f32_16x16x32_bf16 v[50:53], v[154:157], v[162:165], v[50:53]
	v_mfma_f32_16x16x32_bf16 v[38:41], v[138:141], v[180:183], v[38:41]
	v_mfma_f32_16x16x32_bf16 v[34:37], v[154:157], v[180:183], v[34:37]
	v_mfma_f32_16x16x32_bf16 v[22:25], v[138:141], v[188:191], v[22:25]
	v_mfma_f32_16x16x32_bf16 v[18:21], v[154:157], v[188:191], v[18:21]
	v_mfma_f32_16x16x32_bf16 v[6:9], v[138:141], v[200:203], v[6:9]
	v_mfma_f32_16x16x32_bf16 v[2:5], v[154:157], v[200:203], v[2:5]
	v_mfma_f32_16x16x32_bf16 v[54:57], v[150:153], v[166:169], v[54:57]
	v_mfma_f32_16x16x32_bf16 v[50:53], v[158:161], v[166:169], v[50:53]
	v_mfma_f32_16x16x32_bf16 v[38:41], v[150:153], v[184:187], v[38:41]
	v_mfma_f32_16x16x32_bf16 v[34:37], v[158:161], v[184:187], v[34:37]
	v_mfma_f32_16x16x32_bf16 v[22:25], v[150:153], v[196:199], v[22:25]
	v_mfma_f32_16x16x32_bf16 v[18:21], v[158:161], v[196:199], v[18:21]
	v_mfma_f32_16x16x32_bf16 v[6:9], v[150:153], v[204:207], v[6:9]
	v_mfma_f32_16x16x32_bf16 v[2:5], v[158:161], v[204:207], v[2:5]
	s_barrier
	s_add_i32 s73, s73, 2
	s_add_u32 s70, s70, 0x100
	s_addc_u32 s71, s71, 0
	s_add_u32 s57, s57, 0x100
	s_addc_u32 s72, s72, 0
	s_cmpk_gt_u32 s73, 0x55
	s_cbranch_scc0 .LBB0_1484
	s_and_b64 vcc, exec, s[12:13]
	s_cbranch_vccz .LBB0_1487
	s_barrier

; #define PG8_WAIT_V(n) asm volatile("s_waitcnt vmcnt(" #n ")" ::: "memory")
; template <class Epi, class Sched, bool ALIGN_EPI = true, bool SP2 = true, bool FULLLINE = false, bool NOSTAGE = false, bool FP8 = false>
; __device__ __forceinline__ void gemm_phase(PG8_LAS unsigned char* lds, const Gemm g, const Sched& S, const Epi& E) {
;     ...
;         static_assert(SP2, "only the SP2 loop is kept");
;         { const int t = 0; if constexpr (Epi::NST == 16) PG8_ITER(PG8_WAIT_V(24)); else if constexpr (Epi::NST == 8) PG8_ITER(PG8_WAIT_V(16)); else PG8_ITER(PG8_WAIT_V(8)); }
.LBB0_1645:
	s_ashr_i32 s71, s70, 31
	s_lshl_b64 s[0:1], s[70:71], 20
	s_add_u32 s72, s58, s0
	ds_read_b128 v[2:5], v144
	ds_read_b128 v[6:9], v144 offset:1024
	ds_read_b128 v[10:13], v144 offset:2048
	ds_read_b128 v[14:17], v144 offset:3072
	ds_read_b128 v[18:21], v145
	ds_read_b128 v[22:25], v145 offset:1024
	ds_read_b128 v[26:29], v145 offset:2048
	ds_read_b128 v[30:33], v145 offset:3072
	s_addc_u32 s73, s59, s1
	s_ashr_i32 s69, s68, 31
	s_lshl_b64 s[0:1], s[68:69], 20
	s_add_u32 s74, s44, s0
	s_addc_u32 s75, s45, s1
	s_and_b64 s[0:1], s[8:9], exec
	s_cselect_b32 s11, s73, s79
	s_cselect_b32 s14, s72, s78
	s_cselect_b32 s69, s75, s77
	s_cselect_b32 s71, s74, s76
	v_lshl_add_u64 v[242:243], s[78:79], 0, v[130:131]
	s_mov_b32 m0, s97
	v_lshl_add_u64 v[66:67], v[242:243], 0, s[16:17]
	ds_read_b128 v[34:37], v146
	ds_read_b128 v[38:41], v146 offset:1024
	ds_read_b128 v[42:45], v146 offset:2048
	ds_read_b128 v[46:49], v146 offset:3072
	ds_read_b128 v[50:53], v146 offset:4096
	ds_read_b128 v[54:57], v146 offset:5120
	ds_read_b128 v[58:61], v146 offset:6144
	ds_read_b128 v[62:65], v146 offset:7168
	global_load_lds_dwordx4 v[66:67], off
	v_lshl_add_u64 v[66:67], v[242:243], 0, s[18:19]
	s_mov_b32 m0, s47
	s_nop 0
	global_load_lds_dwordx4 v[66:67], off
	s_waitcnt vmcnt(24)
	s_waitcnt lgkmcnt(0)
	s_barrier
	v_mfma_f32_16x16x32_bf16 v[90:93], v[2:5], v[58:61], 0
	v_mfma_f32_16x16x32_bf16 v[66:69], v[2:5], v[34:37], 0
	v_mfma_f32_16x16x32_bf16 v[70:73], v[10:13], v[34:37], 0
	v_mfma_f32_16x16x32_bf16 v[74:77], v[2:5], v[42:45], 0
	v_mfma_f32_16x16x32_bf16 v[78:81], v[10:13], v[42:45], 0
	v_mfma_f32_16x16x32_bf16 v[82:85], v[2:5], v[50:53], 0
	v_mfma_f32_16x16x32_bf16 v[86:89], v[10:13], v[50:53], 0
	v_mfma_f32_16x16x32_bf16 v[98:101], v[6:9], v[62:65], v[90:93]
	v_mfma_f32_16x16x32_bf16 v[90:93], v[10:13], v[58:61], 0
	v_mfma_f32_16x16x32_bf16 v[66:69], v[6:9], v[38:41], v[66:69]
	v_mfma_f32_16x16x32_bf16 v[70:73], v[14:17], v[38:41], v[70:73]
	v_mfma_f32_16x16x32_bf16 v[74:77], v[6:9], v[46:49], v[74:77]
	v_mfma_f32_16x16x32_bf16 v[78:81], v[14:17], v[46:49], v[78:81]
	v_mfma_f32_16x16x32_bf16 v[82:85], v[6:9], v[54:57], v[82:85]
	v_mfma_f32_16x16x32_bf16 v[86:89], v[14:17], v[54:57], v[86:89]
	v_mfma_f32_16x16x32_bf16 v[102:105], v[14:17], v[62:65], v[90:93]
	v_mfma_f32_16x16x32_bf16 v[90:93], v[18:21], v[34:37], 0
	v_mfma_f32_16x16x32_bf16 v[34:37], v[26:29], v[34:37], 0
	v_mfma_f32_16x16x32_bf16 v[114:117], v[22:25], v[38:41], v[90:93]
	v_mfma_f32_16x16x32_bf16 v[34:37], v[30:33], v[38:41], v[34:37]
	v_mfma_f32_16x16x32_bf16 v[38:41], v[18:21], v[42:45], 0
	v_mfma_f32_16x16x32_bf16 v[42:45], v[26:29], v[42:45], 0
	v_mfma_f32_16x16x32_bf16 v[38:41], v[22:25], v[46:49], v[38:41]
	v_mfma_f32_16x16x32_bf16 v[42:45], v[30:33], v[46:49], v[42:45]
	v_mfma_f32_16x16x32_bf16 v[46:49], v[18:21], v[50:53], 0
	v_mfma_f32_16x16x32_bf16 v[50:53], v[26:29], v[50:53], 0
	v_mfma_f32_16x16x32_bf16 v[46:49], v[22:25], v[54:57], v[46:49]
	v_mfma_f32_16x16x32_bf16 v[50:53], v[30:33], v[54:57], v[50:53]
	v_mfma_f32_16x16x32_bf16 v[54:57], v[18:21], v[58:61], 0
	v_mfma_f32_16x16x32_bf16 v[58:61], v[26:29], v[58:61], 0
	v_mfma_f32_16x16x32_bf16 v[54:57], v[22:25], v[62:65], v[54:57]
	v_mfma_f32_16x16x32_bf16 v[58:61], v[30:33], v[62:65], v[58:61]
	s_barrier
	v_lshl_add_u64 v[244:245], s[76:77], 0, v[132:133]
	s_add_i32 s81, s95, s46
	v_lshl_add_u64 v[140:141], v[244:245], 0, s[20:21]
	s_mov_b32 m0, s81
	s_add_i32 s82, s81, 0x2000
	ds_read_b128 v[62:65], v146 offset:16384
	ds_read_b128 v[90:93], v146 offset:17408
	ds_read_b128 v[94:97], v146 offset:18432
	ds_read_b128 v[106:109], v146 offset:19456
	ds_read_b128 v[110:113], v146 offset:20480
	ds_read_b128 v[118:121], v146 offset:21504
	ds_read_b128 v[122:125], v146 offset:22528
	ds_read_b128 v[126:129], v146 offset:23552
	global_load_lds_dwordx4 v[140:141], off
	v_lshl_add_u64 v[140:141], v[244:245], 0, s[22:23]
	s_mov_b32 m0, s82
	s_add_i32 s83, s96, s46
	global_load_lds_dwordx4 v[140:141], off
	v_lshl_add_u64 v[140:141], v[244:245], 0, s[24:25]
	s_mov_b32 m0, s83
	s_add_i32 s84, s83, 0x2000
	global_load_lds_dwordx4 v[140:141], off
	v_lshl_add_u64 v[140:141], v[244:245], 0, s[26:27]
	s_mov_b32 m0, s84
	s_nop 0
	global_load_lds_dwordx4 v[140:141], off
	v_lshl_add_u64 v[140:141], v[242:243], 0, s[20:21]
	s_mov_b32 m0, s87
	s_nop 0
	global_load_lds_dwordx4 v[140:141], off
	v_lshl_add_u64 v[140:141], v[242:243], 0, s[22:23]
	s_mov_b32 m0, s52
	s_nop 0
	global_load_lds_dwordx4 v[140:141], off
	s_waitcnt vmcnt(24)
	s_waitcnt lgkmcnt(0)
	s_barrier
	v_mfma_f32_16x16x32_bf16 v[140:143], v[2:5], v[62:65], 0
	v_mfma_f32_16x16x32_bf16 v[154:157], v[2:5], v[94:97], 0
	v_mfma_f32_16x16x32_bf16 v[162:165], v[2:5], v[110:113], 0
	v_mfma_f32_16x16x32_bf16 v[2:5], v[2:5], v[122:125], 0
	v_mfma_f32_16x16x32_bf16 v[140:143], v[6:9], v[90:93], v[140:143]
	v_mfma_f32_16x16x32_bf16 v[154:157], v[6:9], v[106:109], v[154:157]
	v_mfma_f32_16x16x32_bf16 v[162:165], v[6:9], v[118:121], v[162:165]
	v_mfma_f32_16x16x32_bf16 v[2:5], v[6:9], v[126:129], v[2:5]
	v_mfma_f32_16x16x32_bf16 v[6:9], v[10:13], v[122:125], 0
	v_mfma_f32_16x16x32_bf16 v[150:153], v[10:13], v[62:65], 0
	v_mfma_f32_16x16x32_bf16 v[158:161], v[10:13], v[94:97], 0
	v_mfma_f32_16x16x32_bf16 v[166:169], v[10:13], v[110:113], 0
	v_mfma_f32_16x16x32_bf16 v[6:9], v[14:17], v[126:129], v[6:9]
	v_mfma_f32_16x16x32_bf16 v[150:153], v[14:17], v[90:93], v[150:153]
	v_mfma_f32_16x16x32_bf16 v[158:161], v[14:17], v[106:109], v[158:161]
	v_mfma_f32_16x16x32_bf16 v[166:169], v[14:17], v[118:121], v[166:169]
	v_mfma_f32_16x16x32_bf16 v[10:13], v[18:21], v[62:65], 0
	v_mfma_f32_16x16x32_bf16 v[170:173], v[22:25], v[90:93], v[10:13]
	v_mfma_f32_16x16x32_bf16 v[10:13], v[26:29], v[62:65], 0
	v_mfma_f32_16x16x32_bf16 v[174:177], v[30:33], v[90:93], v[10:13]
	v_mfma_f32_16x16x32_bf16 v[10:13], v[18:21], v[94:97], 0
	v_mfma_f32_16x16x32_bf16 v[178:181], v[22:25], v[106:109], v[10:13]
	v_mfma_f32_16x16x32_bf16 v[10:13], v[26:29], v[94:97], 0
	v_mfma_f32_16x16x32_bf16 v[182:185], v[30:33], v[106:109], v[10:13]
	v_mfma_f32_16x16x32_bf16 v[10:13], v[18:21], v[110:113], 0
	v_mfma_f32_16x16x32_bf16 v[186:189], v[22:25], v[118:121], v[10:13]
	v_mfma_f32_16x16x32_bf16 v[10:13], v[26:29], v[110:113], 0
	v_mfma_f32_16x16x32_bf16 v[190:193], v[30:33], v[118:121], v[10:13]
	v_mfma_f32_16x16x32_bf16 v[10:13], v[18:21], v[122:125], 0
	v_mfma_f32_16x16x32_bf16 v[194:197], v[22:25], v[126:129], v[10:13]
	v_mfma_f32_16x16x32_bf16 v[10:13], v[26:29], v[122:125], 0
	v_mfma_f32_16x16x32_bf16 v[198:201], v[30:33], v[126:129], v[10:13]
	s_barrier
; #define PG8_WAIT_V(n) asm volatile("s_waitcnt vmcnt(" #n ")" ::: "memory")
; template <class Epi, class Sched, bool ALIGN_EPI = true, bool SP2 = true, bool FULLLINE = false, bool NOSTAGE = false, bool FP8 = false>
; __device__ __forceinline__ void gemm_phase(PG8_LAS unsigned char* lds, const Gemm g, const Sched& S, const Epi& E) {
;     ...
;         static_assert(SP2, "only the SP2 loop is kept");
;         { const int t = 0; if constexpr (Epi::NST == 16) PG8_ITER(PG8_WAIT_V(24)); else if constexpr (Epi::NST == 8) PG8_ITER(PG8_WAIT_V(16)); else PG8_ITER(PG8_WAIT_V(8)); }
	s_nop 5
	ds_read_b128 v[10:13], v147
	ds_read_b128 v[14:17], v147 offset:1024
	ds_read_b128 v[18:21], v147 offset:2048
	ds_read_b128 v[22:25], v147 offset:3072
	ds_read_b128 v[202:205], v148
	ds_read_b128 v[206:209], v148 offset:1024
	ds_read_b128 v[210:213], v148 offset:2048
	ds_read_b128 v[214:217], v148 offset:3072
	s_mov_b32 m0, s53
	v_lshl_add_u64 v[90:91], v[242:243], 0, s[24:25]
	ds_read_b128 v[26:29], v146 offset:32768
	ds_read_b128 v[30:33], v146 offset:33792
	ds_read_b128 v[62:65], v146 offset:34816
	ds_read_b128 v[218:221], v146 offset:35840
	ds_read_b128 v[222:225], v146 offset:36864
	ds_read_b128 v[226:229], v146 offset:37888
	ds_read_b128 v[230:233], v146 offset:38912
	ds_read_b128 v[234:237], v146 offset:39936
	global_load_lds_dwordx4 v[90:91], off
	v_lshl_add_u64 v[90:91], v[242:243], 0, s[26:27]
	s_mov_b32 m0, s54
	s_nop 0
	global_load_lds_dwordx4 v[90:91], off
	s_waitcnt vmcnt(8)
	s_waitcnt lgkmcnt(0)
	s_barrier
	v_mfma_f32_16x16x32_bf16 v[66:69], v[10:13], v[26:29], v[66:69]
	v_mfma_f32_16x16x32_bf16 v[126:129], v[14:17], v[30:33], v[66:69]
	v_mfma_f32_16x16x32_bf16 v[66:69], v[18:21], v[26:29], v[70:73]
	v_mfma_f32_16x16x32_bf16 v[122:125], v[22:25], v[30:33], v[66:69]
	v_mfma_f32_16x16x32_bf16 v[66:69], v[10:13], v[62:65], v[74:77]
	v_mfma_f32_16x16x32_bf16 v[110:113], v[14:17], v[218:221], v[66:69]
	v_mfma_f32_16x16x32_bf16 v[66:69], v[18:21], v[62:65], v[78:81]
	v_mfma_f32_16x16x32_bf16 v[106:109], v[22:25], v[218:221], v[66:69]
	v_mfma_f32_16x16x32_bf16 v[66:69], v[10:13], v[222:225], v[82:85]
	v_mfma_f32_16x16x32_bf16 v[94:97], v[14:17], v[226:229], v[66:69]
	v_mfma_f32_16x16x32_bf16 v[66:69], v[18:21], v[222:225], v[86:89]
	v_mfma_f32_16x16x32_bf16 v[90:93], v[22:25], v[226:229], v[66:69]
	v_mfma_f32_16x16x32_bf16 v[66:69], v[10:13], v[230:233], v[98:101]
	v_mfma_f32_16x16x32_bf16 v[78:81], v[14:17], v[234:237], v[66:69]
	v_mfma_f32_16x16x32_bf16 v[66:69], v[18:21], v[230:233], v[102:105]
	v_mfma_f32_16x16x32_bf16 v[74:77], v[22:25], v[234:237], v[66:69]
	v_mfma_f32_16x16x32_bf16 v[66:69], v[202:205], v[26:29], v[114:117]
	v_mfma_f32_16x16x32_bf16 v[26:29], v[210:213], v[26:29], v[34:37]
	v_mfma_f32_16x16x32_bf16 v[114:117], v[214:217], v[30:33], v[26:29]
	v_mfma_f32_16x16x32_bf16 v[26:29], v[202:205], v[62:65], v[38:41]
	v_mfma_f32_16x16x32_bf16 v[102:105], v[206:209], v[218:221], v[26:29]
	v_mfma_f32_16x16x32_bf16 v[26:29], v[210:213], v[62:65], v[42:45]
	v_mfma_f32_16x16x32_bf16 v[98:101], v[214:217], v[218:221], v[26:29]
	v_mfma_f32_16x16x32_bf16 v[26:29], v[202:205], v[222:225], v[46:49]
	v_mfma_f32_16x16x32_bf16 v[86:89], v[206:209], v[226:229], v[26:29]
	v_mfma_f32_16x16x32_bf16 v[26:29], v[210:213], v[222:225], v[50:53]
	v_mfma_f32_16x16x32_bf16 v[82:85], v[214:217], v[226:229], v[26:29]
	v_mfma_f32_16x16x32_bf16 v[26:29], v[202:205], v[230:233], v[54:57]
	v_mfma_f32_16x16x32_bf16 v[70:73], v[206:209], v[234:237], v[26:29]
	v_mfma_f32_16x16x32_bf16 v[26:29], v[210:213], v[230:233], v[58:61]
	v_mfma_f32_16x16x32_bf16 v[118:121], v[206:209], v[30:33], v[66:69]
	v_mfma_f32_16x16x32_bf16 v[66:69], v[214:217], v[234:237], v[26:29]
	s_barrier
	s_add_i32 s50, s3, s46
	s_nop 3
	v_lshl_add_u64 v[26:27], v[244:245], 0, s[28:29]
	s_mov_b32 m0, s50
	s_add_i32 s51, s50, 0x2000
	ds_read_b128 v[34:37], v146 offset:49152
	ds_read_b128 v[38:41], v146 offset:50176
	ds_read_b128 v[218:221], v146 offset:51200
	ds_read_b128 v[222:225], v146 offset:52224
	ds_read_b128 v[226:229], v146 offset:53248
	ds_read_b128 v[230:233], v146 offset:54272
	ds_read_b128 v[234:237], v146 offset:55296
	ds_read_b128 v[238:241], v146 offset:56320
	global_load_lds_dwordx4 v[26:27], off
	v_lshl_add_u64 v[26:27], v[244:245], 0, s[30:31]
	s_mov_b32 m0, s51
	s_mov_b64 s[0:1], 0x80180
	s_add_i32 s33, s42, s46
	global_load_lds_dwordx4 v[26:27], off
	v_lshl_add_u64 v[26:27], v[244:245], 0, s[0:1]
	s_mov_b32 m0, s33
	s_mov_b64 s[0:1], 0xc0180
	s_add_i32 s56, s33, 0x2000
	global_load_lds_dwordx4 v[26:27], off
	v_lshl_add_u64 v[26:27], v[244:245], 0, s[0:1]
	s_mov_b32 m0, s56
	s_nop 0
	global_load_lds_dwordx4 v[26:27], off
	v_lshl_add_u64 v[26:27], v[242:243], 0, s[28:29]
	s_mov_b32 m0, s55
	s_nop 0
	global_load_lds_dwordx4 v[26:27], off
	v_lshl_add_u64 v[26:27], v[242:243], 0, s[30:31]
	s_mov_b32 m0, s62
	s_nop 0
	global_load_lds_dwordx4 v[26:27], off
	s_waitcnt vmcnt(8)
	s_waitcnt lgkmcnt(0)
	s_barrier
	v_mfma_f32_16x16x32_bf16 v[26:29], v[10:13], v[34:37], v[140:143]
	v_mfma_f32_16x16x32_bf16 v[62:65], v[14:17], v[38:41], v[26:29]
	v_mfma_f32_16x16x32_bf16 v[26:29], v[18:21], v[34:37], v[150:153]
	v_mfma_f32_16x16x32_bf16 v[58:61], v[22:25], v[38:41], v[26:29]
	v_mfma_f32_16x16x32_bf16 v[26:29], v[10:13], v[218:221], v[154:157]
	v_mfma_f32_16x16x32_bf16 v[46:49], v[14:17], v[222:225], v[26:29]
	v_mfma_f32_16x16x32_bf16 v[26:29], v[18:21], v[218:221], v[158:161]
	v_mfma_f32_16x16x32_bf16 v[42:45], v[22:25], v[222:225], v[26:29]
	v_mfma_f32_16x16x32_bf16 v[26:29], v[10:13], v[226:229], v[162:165]
	v_mfma_f32_16x16x32_bf16 v[2:5], v[10:13], v[234:237], v[2:5]
	v_mfma_f32_16x16x32_bf16 v[30:33], v[14:17], v[230:233], v[26:29]
	v_mfma_f32_16x16x32_bf16 v[26:29], v[18:21], v[226:229], v[166:169]
	v_mfma_f32_16x16x32_bf16 v[14:17], v[14:17], v[238:241], v[2:5]
	v_mfma_f32_16x16x32_bf16 v[2:5], v[18:21], v[234:237], v[6:9]
	v_mfma_f32_16x16x32_bf16 v[26:29], v[22:25], v[230:233], v[26:29]
	v_mfma_f32_16x16x32_bf16 v[10:13], v[22:25], v[238:241], v[2:5]
	v_mfma_f32_16x16x32_bf16 v[2:5], v[202:205], v[34:37], v[170:173]
	v_mfma_f32_16x16x32_bf16 v[54:57], v[206:209], v[38:41], v[2:5]
	v_mfma_f32_16x16x32_bf16 v[2:5], v[210:213], v[34:37], v[174:177]
	v_mfma_f32_16x16x32_bf16 v[50:53], v[214:217], v[38:41], v[2:5]
	v_mfma_f32_16x16x32_bf16 v[2:5], v[202:205], v[218:221], v[178:181]
	v_mfma_f32_16x16x32_bf16 v[38:41], v[206:209], v[222:225], v[2:5]
	v_mfma_f32_16x16x32_bf16 v[2:5], v[210:213], v[218:221], v[182:185]
	v_mfma_f32_16x16x32_bf16 v[34:37], v[214:217], v[222:225], v[2:5]
	v_mfma_f32_16x16x32_bf16 v[2:5], v[202:205], v[226:229], v[186:189]
	v_mfma_f32_16x16x32_bf16 v[22:25], v[206:209], v[230:233], v[2:5]
	v_mfma_f32_16x16x32_bf16 v[2:5], v[210:213], v[226:229], v[190:193]
	v_mfma_f32_16x16x32_bf16 v[18:21], v[214:217], v[230:233], v[2:5]
	v_mfma_f32_16x16x32_bf16 v[2:5], v[202:205], v[234:237], v[194:197]
	v_mfma_f32_16x16x32_bf16 v[6:9], v[206:209], v[238:241], v[2:5]
	v_mfma_f32_16x16x32_bf16 v[2:5], v[210:213], v[234:237], v[198:201]
	v_mfma_f32_16x16x32_bf16 v[2:5], v[214:217], v[238:241], v[2:5]
	s_barrier
	s_add_u32 s78, s78, 0x80180
	s_addc_u32 s79, s79, 0
	s_add_u32 s57, s76, 0x200
	s_addc_u32 s76, s77, 0
	s_mov_b32 s77, 0
; #define PG8_WAIT_V(n) asm volatile("s_waitcnt vmcnt(" #n ")" ::: "memory")
; template <class Epi, class Sched, bool ALIGN_EPI = true, bool SP2 = true, bool FULLLINE = false, bool NOSTAGE = false, bool FP8 = false>
; __device__ __forceinline__ void gemm_phase(PG8_LAS unsigned char* lds, const Gemm g, const Sched& S, const Epi& E) {
;     ...
;         static_assert(SP2, "only the SP2 loop is kept");
;         { const int t = 0; if constexpr (Epi::NST == 16) PG8_ITER(PG8_WAIT_V(24)); else if constexpr (Epi::NST == 8) PG8_ITER(PG8_WAIT_V(16)); else PG8_ITER(PG8_WAIT_V(8)); }
;         for (int t = 2; t < nt; t += 2) PG8_ITER(PG8_WAIT_V(8));
.LBB0_1646:
	ds_read_b128 v[140:143], v144
	ds_read_b128 v[150:153], v144 offset:1024
	ds_read_b128 v[154:157], v144 offset:2048
	ds_read_b128 v[158:161], v144 offset:3072
	ds_read_b128 v[162:165], v145
	ds_read_b128 v[166:169], v145 offset:1024
	ds_read_b128 v[170:173], v145 offset:2048
	ds_read_b128 v[174:177], v145 offset:3072
	s_add_u32 s0, s78, 0xfff80080
	s_addc_u32 s1, s79, -1
	s_cmp_eq_u32 s77, 28
	s_cselect_b32 s1, s11, s1
	s_cselect_b32 s0, s14, s0
	s_cselect_b32 s65, s69, s76
	s_cselect_b32 s64, s71, s57
	s_mov_b32 m0, s97
	v_lshl_add_u64 v[210:211], s[78:79], 0, v[134:135]
	ds_read_b128 v[178:181], v146
	ds_read_b128 v[182:185], v146 offset:1024
	ds_read_b128 v[186:189], v146 offset:2048
	ds_read_b128 v[190:193], v146 offset:3072
	ds_read_b128 v[194:197], v146 offset:4096
	ds_read_b128 v[198:201], v146 offset:5120
	ds_read_b128 v[202:205], v146 offset:6144
	ds_read_b128 v[206:209], v146 offset:7168
	global_load_lds_dwordx4 v[210:211], off
	v_lshl_add_u64 v[210:211], v[210:211], 0, s[34:35]
	s_mov_b32 m0, s47
	s_nop 0
	global_load_lds_dwordx4 v[210:211], off
	s_waitcnt vmcnt(8)
	s_waitcnt lgkmcnt(0)
	s_barrier
	v_mfma_f32_16x16x32_bf16 v[126:129], v[140:143], v[178:181], v[126:129]
	v_mfma_f32_16x16x32_bf16 v[122:125], v[154:157], v[178:181], v[122:125]
	v_mfma_f32_16x16x32_bf16 v[110:113], v[140:143], v[186:189], v[110:113]
	v_mfma_f32_16x16x32_bf16 v[106:109], v[154:157], v[186:189], v[106:109]
	v_mfma_f32_16x16x32_bf16 v[94:97], v[140:143], v[194:197], v[94:97]
	v_mfma_f32_16x16x32_bf16 v[90:93], v[154:157], v[194:197], v[90:93]
	v_mfma_f32_16x16x32_bf16 v[78:81], v[140:143], v[202:205], v[78:81]
	v_mfma_f32_16x16x32_bf16 v[74:77], v[154:157], v[202:205], v[74:77]
	v_mfma_f32_16x16x32_bf16 v[126:129], v[150:153], v[182:185], v[126:129]
	v_mfma_f32_16x16x32_bf16 v[122:125], v[158:161], v[182:185], v[122:125]
	v_mfma_f32_16x16x32_bf16 v[110:113], v[150:153], v[190:193], v[110:113]
	v_mfma_f32_16x16x32_bf16 v[106:109], v[158:161], v[190:193], v[106:109]
	v_mfma_f32_16x16x32_bf16 v[94:97], v[150:153], v[198:201], v[94:97]
	v_mfma_f32_16x16x32_bf16 v[90:93], v[158:161], v[198:201], v[90:93]
	v_mfma_f32_16x16x32_bf16 v[78:81], v[150:153], v[206:209], v[78:81]
	v_mfma_f32_16x16x32_bf16 v[74:77], v[158:161], v[206:209], v[74:77]
	v_mfma_f32_16x16x32_bf16 v[118:121], v[162:165], v[178:181], v[118:121]
	v_mfma_f32_16x16x32_bf16 v[114:117], v[170:173], v[178:181], v[114:117]
	v_mfma_f32_16x16x32_bf16 v[102:105], v[162:165], v[186:189], v[102:105]
	v_mfma_f32_16x16x32_bf16 v[98:101], v[170:173], v[186:189], v[98:101]
	v_mfma_f32_16x16x32_bf16 v[86:89], v[162:165], v[194:197], v[86:89]
	v_mfma_f32_16x16x32_bf16 v[82:85], v[170:173], v[194:197], v[82:85]
	v_mfma_f32_16x16x32_bf16 v[70:73], v[162:165], v[202:205], v[70:73]
	v_mfma_f32_16x16x32_bf16 v[66:69], v[170:173], v[202:205], v[66:69]
	v_mfma_f32_16x16x32_bf16 v[118:121], v[166:169], v[182:185], v[118:121]
	v_mfma_f32_16x16x32_bf16 v[114:117], v[174:177], v[182:185], v[114:117]
	v_mfma_f32_16x16x32_bf16 v[102:105], v[166:169], v[190:193], v[102:105]
	v_mfma_f32_16x16x32_bf16 v[98:101], v[174:177], v[190:193], v[98:101]
	v_mfma_f32_16x16x32_bf16 v[86:89], v[166:169], v[198:201], v[86:89]
	v_mfma_f32_16x16x32_bf16 v[82:85], v[174:177], v[198:201], v[82:85]
	v_mfma_f32_16x16x32_bf16 v[70:73], v[166:169], v[206:209], v[70:73]
	v_mfma_f32_16x16x32_bf16 v[66:69], v[174:177], v[206:209], v[66:69]
	s_barrier
	s_mov_b32 m0, s81
	v_lshl_add_u64 v[210:211], s[64:65], 0, v[132:133]
	ds_read_b128 v[178:181], v146 offset:16384
	ds_read_b128 v[182:185], v146 offset:17408
	ds_read_b128 v[186:189], v146 offset:18432
	ds_read_b128 v[190:193], v146 offset:19456
	ds_read_b128 v[194:197], v146 offset:20480
	ds_read_b128 v[198:201], v146 offset:21504
	ds_read_b128 v[202:205], v146 offset:22528
	ds_read_b128 v[206:209], v146 offset:23552
	global_load_lds_dwordx4 v[210:211], off
	v_lshl_add_u64 v[212:213], v[210:211], 0, s[34:35]
	s_mov_b32 m0, s82
	s_nop 0
	global_load_lds_dwordx4 v[212:213], off
	v_lshl_add_u64 v[212:213], v[210:211], 0, s[36:37]
	s_mov_b32 m0, s83
	s_nop 0
	global_load_lds_dwordx4 v[212:213], off
	v_lshl_add_u64 v[212:213], v[210:211], 0, s[38:39]
	s_mov_b32 m0, s84
	s_nop 0
	global_load_lds_dwordx4 v[212:213], off
	v_lshl_add_u64 v[212:213], s[0:1], 0, v[130:131]
	s_mov_b32 m0, s87
	v_lshl_add_u64 v[214:215], v[212:213], 0, s[34:35]
	global_load_lds_dwordx4 v[212:213], off
	s_mov_b32 m0, s52
	s_nop 0
	global_load_lds_dwordx4 v[214:215], off
	s_waitcnt vmcnt(8)
	s_waitcnt lgkmcnt(0)
	s_barrier
	v_mfma_f32_16x16x32_bf16 v[62:65], v[140:143], v[178:181], v[62:65]
	v_mfma_f32_16x16x32_bf16 v[58:61], v[154:157], v[178:181], v[58:61]
	v_mfma_f32_16x16x32_bf16 v[46:49], v[140:143], v[186:189], v[46:49]
	v_mfma_f32_16x16x32_bf16 v[42:45], v[154:157], v[186:189], v[42:45]
	v_mfma_f32_16x16x32_bf16 v[30:33], v[140:143], v[194:197], v[30:33]
	v_mfma_f32_16x16x32_bf16 v[26:29], v[154:157], v[194:197], v[26:29]
	v_mfma_f32_16x16x32_bf16 v[14:17], v[140:143], v[202:205], v[14:17]
	v_mfma_f32_16x16x32_bf16 v[10:13], v[154:157], v[202:205], v[10:13]
	v_mfma_f32_16x16x32_bf16 v[62:65], v[150:153], v[182:185], v[62:65]
	v_mfma_f32_16x16x32_bf16 v[58:61], v[158:161], v[182:185], v[58:61]
	v_mfma_f32_16x16x32_bf16 v[46:49], v[150:153], v[190:193], v[46:49]
	v_mfma_f32_16x16x32_bf16 v[42:45], v[158:161], v[190:193], v[42:45]
	v_mfma_f32_16x16x32_bf16 v[30:33], v[150:153], v[198:201], v[30:33]
	v_mfma_f32_16x16x32_bf16 v[26:29], v[158:161], v[198:201], v[26:29]
	v_mfma_f32_16x16x32_bf16 v[14:17], v[150:153], v[206:209], v[14:17]
	v_mfma_f32_16x16x32_bf16 v[10:13], v[158:161], v[206:209], v[10:13]
	v_mfma_f32_16x16x32_bf16 v[54:57], v[162:165], v[178:181], v[54:57]
	v_mfma_f32_16x16x32_bf16 v[50:53], v[170:173], v[178:181], v[50:53]
	v_mfma_f32_16x16x32_bf16 v[38:41], v[162:165], v[186:189], v[38:41]
	v_mfma_f32_16x16x32_bf16 v[34:37], v[170:173], v[186:189], v[34:37]
	v_mfma_f32_16x16x32_bf16 v[22:25], v[162:165], v[194:197], v[22:25]
	v_mfma_f32_16x16x32_bf16 v[18:21], v[170:173], v[194:197], v[18:21]
	v_mfma_f32_16x16x32_bf16 v[6:9], v[162:165], v[202:205], v[6:9]
	v_mfma_f32_16x16x32_bf16 v[2:5], v[170:173], v[202:205], v[2:5]
	v_mfma_f32_16x16x32_bf16 v[54:57], v[166:169], v[182:185], v[54:57]
	v_mfma_f32_16x16x32_bf16 v[50:53], v[174:177], v[182:185], v[50:53]
	v_mfma_f32_16x16x32_bf16 v[38:41], v[166:169], v[190:193], v[38:41]
	v_mfma_f32_16x16x32_bf16 v[34:37], v[174:177], v[190:193], v[34:37]
	v_mfma_f32_16x16x32_bf16 v[22:25], v[166:169], v[198:201], v[22:25]
	v_mfma_f32_16x16x32_bf16 v[18:21], v[174:177], v[198:201], v[18:21]
	v_mfma_f32_16x16x32_bf16 v[6:9], v[166:169], v[206:209], v[6:9]
	v_mfma_f32_16x16x32_bf16 v[2:5], v[174:177], v[206:209], v[2:5]
	s_barrier
; #define PG8_WAIT_V(n) asm volatile("s_waitcnt vmcnt(" #n ")" ::: "memory")
; #define PG8_BAR __builtin_amdgcn_s_barrier()
; template <class Epi, class Sched, bool ALIGN_EPI = true, bool SP2 = true, bool FULLLINE = false, bool NOSTAGE = false, bool FP8 = false>
; __device__ __forceinline__ void gemm_phase(PG8_LAS unsigned char* lds, const Gemm g, const Sched& S, const Epi& E) {
;     ...
;         static_assert(SP2, "only the SP2 loop is kept");
;         { const int t = 0; if constexpr (Epi::NST == 16) PG8_ITER(PG8_WAIT_V(24)); else if constexpr (Epi::NST == 8) PG8_ITER(PG8_WAIT_V(16)); else PG8_ITER(PG8_WAIT_V(8)); }
;         for (int t = 2; t < nt; t += 2) PG8_ITER(PG8_WAIT_V(8));
;     ...
;         if constexpr (ALIGN_EPI) { if (wr == 0) PG8_BAR; }
	ds_read_b128 v[140:143], v147
	ds_read_b128 v[150:153], v147 offset:1024
	ds_read_b128 v[154:157], v147 offset:2048
	ds_read_b128 v[158:161], v147 offset:3072
	ds_read_b128 v[162:165], v148
	ds_read_b128 v[166:169], v148 offset:1024
	ds_read_b128 v[170:173], v148 offset:2048
	ds_read_b128 v[174:177], v148 offset:3072
	s_mov_b32 m0, s53
	v_lshl_add_u64 v[214:215], v[212:213], 0, s[36:37]
	ds_read_b128 v[178:181], v146 offset:32768
	ds_read_b128 v[182:185], v146 offset:33792
	ds_read_b128 v[186:189], v146 offset:34816
	ds_read_b128 v[190:193], v146 offset:35840
	ds_read_b128 v[194:197], v146 offset:36864
	ds_read_b128 v[198:201], v146 offset:37888
	ds_read_b128 v[202:205], v146 offset:38912
	ds_read_b128 v[206:209], v146 offset:39936
	global_load_lds_dwordx4 v[214:215], off
	v_lshl_add_u64 v[214:215], v[212:213], 0, s[38:39]
	s_mov_b32 m0, s54
	s_nop 0
	global_load_lds_dwordx4 v[214:215], off
	s_waitcnt vmcnt(8)
	s_waitcnt lgkmcnt(0)
	s_barrier
	v_mfma_f32_16x16x32_bf16 v[126:129], v[140:143], v[178:181], v[126:129]
	v_mfma_f32_16x16x32_bf16 v[122:125], v[154:157], v[178:181], v[122:125]
	v_mfma_f32_16x16x32_bf16 v[110:113], v[140:143], v[186:189], v[110:113]
	v_mfma_f32_16x16x32_bf16 v[106:109], v[154:157], v[186:189], v[106:109]
	v_mfma_f32_16x16x32_bf16 v[94:97], v[140:143], v[194:197], v[94:97]
	v_mfma_f32_16x16x32_bf16 v[90:93], v[154:157], v[194:197], v[90:93]
	v_mfma_f32_16x16x32_bf16 v[78:81], v[140:143], v[202:205], v[78:81]
	v_mfma_f32_16x16x32_bf16 v[74:77], v[154:157], v[202:205], v[74:77]
	v_mfma_f32_16x16x32_bf16 v[126:129], v[150:153], v[182:185], v[126:129]
	v_mfma_f32_16x16x32_bf16 v[122:125], v[158:161], v[182:185], v[122:125]
	v_mfma_f32_16x16x32_bf16 v[110:113], v[150:153], v[190:193], v[110:113]
	v_mfma_f32_16x16x32_bf16 v[106:109], v[158:161], v[190:193], v[106:109]
	v_mfma_f32_16x16x32_bf16 v[94:97], v[150:153], v[198:201], v[94:97]
	v_mfma_f32_16x16x32_bf16 v[90:93], v[158:161], v[198:201], v[90:93]
	v_mfma_f32_16x16x32_bf16 v[78:81], v[150:153], v[206:209], v[78:81]
	v_mfma_f32_16x16x32_bf16 v[74:77], v[158:161], v[206:209], v[74:77]
	v_mfma_f32_16x16x32_bf16 v[118:121], v[162:165], v[178:181], v[118:121]
	v_mfma_f32_16x16x32_bf16 v[114:117], v[170:173], v[178:181], v[114:117]
	v_mfma_f32_16x16x32_bf16 v[102:105], v[162:165], v[186:189], v[102:105]
	v_mfma_f32_16x16x32_bf16 v[98:101], v[170:173], v[186:189], v[98:101]
	v_mfma_f32_16x16x32_bf16 v[86:89], v[162:165], v[194:197], v[86:89]
	v_mfma_f32_16x16x32_bf16 v[82:85], v[170:173], v[194:197], v[82:85]
	v_mfma_f32_16x16x32_bf16 v[70:73], v[162:165], v[202:205], v[70:73]
	v_mfma_f32_16x16x32_bf16 v[66:69], v[170:173], v[202:205], v[66:69]
	v_mfma_f32_16x16x32_bf16 v[118:121], v[166:169], v[182:185], v[118:121]
	v_mfma_f32_16x16x32_bf16 v[114:117], v[174:177], v[182:185], v[114:117]
	v_mfma_f32_16x16x32_bf16 v[102:105], v[166:169], v[190:193], v[102:105]
	v_mfma_f32_16x16x32_bf16 v[98:101], v[174:177], v[190:193], v[98:101]
	v_mfma_f32_16x16x32_bf16 v[86:89], v[166:169], v[198:201], v[86:89]
	v_mfma_f32_16x16x32_bf16 v[82:85], v[174:177], v[198:201], v[82:85]
	v_mfma_f32_16x16x32_bf16 v[70:73], v[166:169], v[206:209], v[70:73]
	v_mfma_f32_16x16x32_bf16 v[66:69], v[174:177], v[206:209], v[66:69]
	s_barrier
	s_mov_b32 m0, s50
	v_lshl_add_u64 v[214:215], v[210:211], 0, s[40:41]
	ds_read_b128 v[178:181], v146 offset:49152
	ds_read_b128 v[182:185], v146 offset:50176
	ds_read_b128 v[186:189], v146 offset:51200
	ds_read_b128 v[190:193], v146 offset:52224
	ds_read_b128 v[194:197], v146 offset:53248
	ds_read_b128 v[198:201], v146 offset:54272
	ds_read_b128 v[202:205], v146 offset:55296
	ds_read_b128 v[206:209], v146 offset:56320
	global_load_lds_dwordx4 v[214:215], off
	v_lshl_add_u64 v[214:215], v[210:211], 0, s[66:67]
	s_mov_b32 m0, s51
	s_nop 0
	global_load_lds_dwordx4 v[214:215], off
	v_lshl_add_u64 v[214:215], v[210:211], 0, s[16:17]
	s_mov_b32 m0, s33
	v_lshl_add_u64 v[210:211], v[210:211], 0, s[18:19]
	global_load_lds_dwordx4 v[214:215], off
	s_mov_b32 m0, s56
	s_nop 0
	global_load_lds_dwordx4 v[210:211], off
	v_lshl_add_u64 v[210:211], v[212:213], 0, s[40:41]
	s_mov_b32 m0, s55
	s_nop 0
	global_load_lds_dwordx4 v[210:211], off
	v_lshl_add_u64 v[210:211], v[212:213], 0, s[66:67]
	s_mov_b32 m0, s62
	s_nop 0
	global_load_lds_dwordx4 v[210:211], off
	s_waitcnt vmcnt(8)
	s_waitcnt lgkmcnt(0)
	s_barrier
	v_mfma_f32_16x16x32_bf16 v[62:65], v[140:143], v[178:181], v[62:65]
	v_mfma_f32_16x16x32_bf16 v[58:61], v[154:157], v[178:181], v[58:61]
	v_mfma_f32_16x16x32_bf16 v[46:49], v[140:143], v[186:189], v[46:49]
	v_mfma_f32_16x16x32_bf16 v[42:45], v[154:157], v[186:189], v[42:45]
	v_mfma_f32_16x16x32_bf16 v[30:33], v[140:143], v[194:197], v[30:33]
	v_mfma_f32_16x16x32_bf16 v[26:29], v[154:157], v[194:197], v[26:29]
	v_mfma_f32_16x16x32_bf16 v[14:17], v[140:143], v[202:205], v[14:17]
	v_mfma_f32_16x16x32_bf16 v[10:13], v[154:157], v[202:205], v[10:13]
	v_mfma_f32_16x16x32_bf16 v[62:65], v[150:153], v[182:185], v[62:65]
	v_mfma_f32_16x16x32_bf16 v[58:61], v[158:161], v[182:185], v[58:61]
	v_mfma_f32_16x16x32_bf16 v[46:49], v[150:153], v[190:193], v[46:49]
	v_mfma_f32_16x16x32_bf16 v[42:45], v[158:161], v[190:193], v[42:45]
	v_mfma_f32_16x16x32_bf16 v[30:33], v[150:153], v[198:201], v[30:33]
	v_mfma_f32_16x16x32_bf16 v[26:29], v[158:161], v[198:201], v[26:29]
	v_mfma_f32_16x16x32_bf16 v[14:17], v[150:153], v[206:209], v[14:17]
	v_mfma_f32_16x16x32_bf16 v[10:13], v[158:161], v[206:209], v[10:13]
	v_mfma_f32_16x16x32_bf16 v[54:57], v[162:165], v[178:181], v[54:57]
	v_mfma_f32_16x16x32_bf16 v[50:53], v[170:173], v[178:181], v[50:53]
	v_mfma_f32_16x16x32_bf16 v[38:41], v[162:165], v[186:189], v[38:41]
	v_mfma_f32_16x16x32_bf16 v[34:37], v[170:173], v[186:189], v[34:37]
	v_mfma_f32_16x16x32_bf16 v[22:25], v[162:165], v[194:197], v[22:25]
	v_mfma_f32_16x16x32_bf16 v[18:21], v[170:173], v[194:197], v[18:21]
	v_mfma_f32_16x16x32_bf16 v[6:9], v[162:165], v[202:205], v[6:9]
	v_mfma_f32_16x16x32_bf16 v[2:5], v[170:173], v[202:205], v[2:5]
	v_mfma_f32_16x16x32_bf16 v[54:57], v[166:169], v[182:185], v[54:57]
	v_mfma_f32_16x16x32_bf16 v[50:53], v[174:177], v[182:185], v[50:53]
	v_mfma_f32_16x16x32_bf16 v[38:41], v[166:169], v[190:193], v[38:41]
	v_mfma_f32_16x16x32_bf16 v[34:37], v[174:177], v[190:193], v[34:37]
	v_mfma_f32_16x16x32_bf16 v[22:25], v[166:169], v[198:201], v[22:25]
	v_mfma_f32_16x16x32_bf16 v[18:21], v[174:177], v[198:201], v[18:21]
	v_mfma_f32_16x16x32_bf16 v[6:9], v[166:169], v[206:209], v[6:9]
	v_mfma_f32_16x16x32_bf16 v[2:5], v[174:177], v[206:209], v[2:5]
	s_barrier
	s_add_i32 s77, s77, 2
	s_add_u32 s78, s78, 0x100
	s_addc_u32 s79, s79, 0
	s_add_u32 s57, s57, 0x100
	s_addc_u32 s76, s76, 0
	s_cmp_gt_u32 s77, 29
	s_cbranch_scc0 .LBB0_1646
	s_and_b64 vcc, exec, s[12:13]
	s_cbranch_vccz .LBB0_1649
	s_barrier

; #define PG8_WAIT_V(n) asm volatile("s_waitcnt vmcnt(" #n ")" ::: "memory")
; template <class Epi, class Sched, bool ALIGN_EPI = true, bool SP2 = true, bool FULLLINE = false, bool NOSTAGE = false, bool FP8 = false>
; __device__ __forceinline__ void gemm_phase(PG8_LAS unsigned char* lds, const Gemm g, const Sched& S, const Epi& E) {
;     ...
;         static_assert(SP2, "only the SP2 loop is kept");
;         { const int t = 0; if constexpr (Epi::NST == 16) PG8_ITER(PG8_WAIT_V(24)); else if constexpr (Epi::NST == 8) PG8_ITER(PG8_WAIT_V(16)); else PG8_ITER(PG8_WAIT_V(8)); }
.LBB0_2096:
	s_ashr_i32 s67, s66, 31
	ds_read_b128 v[2:5], v1
	ds_read_b128 v[6:9], v1 offset:1024
	ds_read_b128 v[10:13], v1 offset:2048
	ds_read_b128 v[14:17], v1 offset:3072
	ds_read_b128 v[18:21], v192
	ds_read_b128 v[22:25], v192 offset:1024
	ds_read_b128 v[26:29], v192 offset:2048
	ds_read_b128 v[30:33], v192 offset:3072
	s_lshl_b64 s[0:1], s[66:67], 20
	s_add_u32 s68, s42, s0
	s_addc_u32 s69, s43, s1
	s_and_b64 s[0:1], s[8:9], exec
	s_cselect_b32 s67, s69, s75
	s_cselect_b32 s90, s68, s74
	s_ashr_i32 s41, s40, 31
	s_lshl_b64 s[0:1], s[40:41], 20
	s_add_u32 s70, s44, s0
	s_addc_u32 s71, s45, s1
	s_and_b64 s[0:1], s[8:9], exec
	s_cselect_b32 s41, s71, s77
	s_cselect_b32 s91, s70, s76
	v_lshl_add_u64 v[248:249], s[74:75], 0, v[170:171]
	s_mov_b32 m0, s85
	v_lshl_add_u64 v[66:67], v[248:249], 0, s[12:13]
	ds_read_b128 v[34:37], v193
	ds_read_b128 v[38:41], v193 offset:1024
	ds_read_b128 v[42:45], v193 offset:2048
	ds_read_b128 v[46:49], v193 offset:3072
	ds_read_b128 v[50:53], v193 offset:4096
	ds_read_b128 v[54:57], v193 offset:5120
	ds_read_b128 v[58:61], v193 offset:6144
	ds_read_b128 v[62:65], v193 offset:7168
	global_load_lds_dwordx4 v[66:67], off
	v_lshl_add_u64 v[66:67], v[248:249], 0, s[14:15]
	s_mov_b32 m0, s87
	s_nop 0
	global_load_lds_dwordx4 v[66:67], off
	s_waitcnt vmcnt(24)
	s_waitcnt lgkmcnt(0)
	s_barrier
	v_mfma_f32_16x16x32_bf16 v[66:69], v[2:5], v[34:37], 0
	v_mfma_f32_16x16x32_bf16 v[70:73], v[10:13], v[34:37], 0
	v_mfma_f32_16x16x32_bf16 v[78:81], v[10:13], v[42:45], 0
	v_mfma_f32_16x16x32_bf16 v[86:89], v[10:13], v[50:53], 0
	v_mfma_f32_16x16x32_bf16 v[66:69], v[6:9], v[38:41], v[66:69]
	v_mfma_f32_16x16x32_bf16 v[70:73], v[14:17], v[38:41], v[70:73]
	v_mfma_f32_16x16x32_bf16 v[74:77], v[2:5], v[42:45], 0
	v_mfma_f32_16x16x32_bf16 v[78:81], v[14:17], v[46:49], v[78:81]
	v_mfma_f32_16x16x32_bf16 v[82:85], v[2:5], v[50:53], 0
	v_mfma_f32_16x16x32_bf16 v[86:89], v[14:17], v[54:57], v[86:89]
	v_mfma_f32_16x16x32_bf16 v[90:93], v[2:5], v[58:61], 0
	v_mfma_f32_16x16x32_bf16 v[94:97], v[10:13], v[58:61], 0
	v_mfma_f32_16x16x32_bf16 v[74:77], v[6:9], v[46:49], v[74:77]
	v_mfma_f32_16x16x32_bf16 v[82:85], v[6:9], v[54:57], v[82:85]
	v_mfma_f32_16x16x32_bf16 v[90:93], v[6:9], v[62:65], v[90:93]
	v_mfma_f32_16x16x32_bf16 v[94:97], v[14:17], v[62:65], v[94:97]
	v_mfma_f32_16x16x32_bf16 v[98:101], v[18:21], v[34:37], 0
	v_mfma_f32_16x16x32_bf16 v[34:37], v[26:29], v[34:37], 0
	v_mfma_f32_16x16x32_bf16 v[98:101], v[22:25], v[38:41], v[98:101]
	v_mfma_f32_16x16x32_bf16 v[34:37], v[30:33], v[38:41], v[34:37]
	v_mfma_f32_16x16x32_bf16 v[38:41], v[18:21], v[42:45], 0
	v_mfma_f32_16x16x32_bf16 v[42:45], v[26:29], v[42:45], 0
	v_mfma_f32_16x16x32_bf16 v[38:41], v[22:25], v[46:49], v[38:41]
	v_mfma_f32_16x16x32_bf16 v[42:45], v[30:33], v[46:49], v[42:45]
	v_mfma_f32_16x16x32_bf16 v[46:49], v[18:21], v[50:53], 0
	v_mfma_f32_16x16x32_bf16 v[50:53], v[26:29], v[50:53], 0
	v_mfma_f32_16x16x32_bf16 v[46:49], v[22:25], v[54:57], v[46:49]
	v_mfma_f32_16x16x32_bf16 v[50:53], v[30:33], v[54:57], v[50:53]
	v_mfma_f32_16x16x32_bf16 v[54:57], v[18:21], v[58:61], 0
	v_mfma_f32_16x16x32_bf16 v[58:61], v[26:29], v[58:61], 0
	v_mfma_f32_16x16x32_bf16 v[54:57], v[22:25], v[62:65], v[54:57]
	v_mfma_f32_16x16x32_bf16 v[58:61], v[30:33], v[62:65], v[58:61]
	s_barrier
	v_lshl_add_u64 v[250:251], s[76:77], 0, v[172:173]
	s_add_i32 s92, s83, s46
	v_lshl_add_u64 v[130:131], v[250:251], 0, s[16:17]
	s_mov_b32 m0, s92
	s_add_i32 s93, s92, 0x2000
	ds_read_b128 v[62:65], v193 offset:16384
	ds_read_b128 v[102:105], v193 offset:17408
	ds_read_b128 v[106:109], v193 offset:18432
	ds_read_b128 v[110:113], v193 offset:19456
	ds_read_b128 v[114:117], v193 offset:20480
	ds_read_b128 v[118:121], v193 offset:21504
	ds_read_b128 v[122:125], v193 offset:22528
	ds_read_b128 v[126:129], v193 offset:23552
	global_load_lds_dwordx4 v[130:131], off
	v_lshl_add_u64 v[130:131], v[250:251], 0, s[18:19]
	s_mov_b32 m0, s93
	s_add_i32 s94, s84, s46
	global_load_lds_dwordx4 v[130:131], off
	v_lshl_add_u64 v[130:131], v[250:251], 0, s[20:21]
	s_mov_b32 m0, s94
	s_add_i32 s95, s94, 0x2000
	global_load_lds_dwordx4 v[130:131], off
	v_lshl_add_u64 v[130:131], v[250:251], 0, s[22:23]
	s_mov_b32 m0, s95
	s_nop 0
	global_load_lds_dwordx4 v[130:131], off
	v_lshl_add_u64 v[130:131], v[248:249], 0, s[16:17]
	s_mov_b32 m0, s47
	s_nop 0
	global_load_lds_dwordx4 v[130:131], off
	v_lshl_add_u64 v[130:131], v[248:249], 0, s[18:19]
	s_mov_b32 m0, s52
	s_nop 0
	global_load_lds_dwordx4 v[130:131], off
	s_waitcnt vmcnt(24)
	s_waitcnt lgkmcnt(0)
	s_barrier
	v_mfma_f32_16x16x32_bf16 v[130:133], v[2:5], v[62:65], 0
	v_mfma_f32_16x16x32_bf16 v[138:141], v[6:9], v[102:105], v[130:133]
	v_mfma_f32_16x16x32_bf16 v[130:133], v[10:13], v[62:65], 0
	v_mfma_f32_16x16x32_bf16 v[150:153], v[14:17], v[102:105], v[130:133]
	v_mfma_f32_16x16x32_bf16 v[130:133], v[2:5], v[106:109], 0
	v_mfma_f32_16x16x32_bf16 v[154:157], v[6:9], v[110:113], v[130:133]
	v_mfma_f32_16x16x32_bf16 v[130:133], v[10:13], v[106:109], 0
	v_mfma_f32_16x16x32_bf16 v[158:161], v[14:17], v[110:113], v[130:133]
	v_mfma_f32_16x16x32_bf16 v[130:133], v[2:5], v[114:117], 0
	v_mfma_f32_16x16x32_bf16 v[2:5], v[2:5], v[122:125], 0
	v_mfma_f32_16x16x32_bf16 v[162:165], v[6:9], v[118:121], v[130:133]
	v_mfma_f32_16x16x32_bf16 v[2:5], v[6:9], v[126:129], v[2:5]
	v_mfma_f32_16x16x32_bf16 v[6:9], v[10:13], v[122:125], 0
	v_mfma_f32_16x16x32_bf16 v[130:133], v[10:13], v[114:117], 0
	v_mfma_f32_16x16x32_bf16 v[6:9], v[14:17], v[126:129], v[6:9]
	v_mfma_f32_16x16x32_bf16 v[166:169], v[14:17], v[118:121], v[130:133]
	v_mfma_f32_16x16x32_bf16 v[10:13], v[18:21], v[62:65], 0
	v_mfma_f32_16x16x32_bf16 v[180:183], v[22:25], v[102:105], v[10:13]
	v_mfma_f32_16x16x32_bf16 v[10:13], v[26:29], v[62:65], 0
	v_mfma_f32_16x16x32_bf16 v[184:187], v[30:33], v[102:105], v[10:13]
	v_mfma_f32_16x16x32_bf16 v[10:13], v[18:21], v[106:109], 0
	v_mfma_f32_16x16x32_bf16 v[188:191], v[22:25], v[110:113], v[10:13]
	v_mfma_f32_16x16x32_bf16 v[10:13], v[26:29], v[106:109], 0
	v_mfma_f32_16x16x32_bf16 v[196:199], v[30:33], v[110:113], v[10:13]
	v_mfma_f32_16x16x32_bf16 v[10:13], v[18:21], v[114:117], 0
	v_mfma_f32_16x16x32_bf16 v[200:203], v[22:25], v[118:121], v[10:13]
	v_mfma_f32_16x16x32_bf16 v[10:13], v[26:29], v[114:117], 0
	v_mfma_f32_16x16x32_bf16 v[204:207], v[30:33], v[118:121], v[10:13]
	v_mfma_f32_16x16x32_bf16 v[10:13], v[18:21], v[122:125], 0
	v_mfma_f32_16x16x32_bf16 v[208:211], v[22:25], v[126:129], v[10:13]
	v_mfma_f32_16x16x32_bf16 v[10:13], v[26:29], v[122:125], 0
	v_mfma_f32_16x16x32_bf16 v[212:215], v[30:33], v[126:129], v[10:13]
	s_barrier
; #define PG8_WAIT_V(n) asm volatile("s_waitcnt vmcnt(" #n ")" ::: "memory")
; template <class Epi, class Sched, bool ALIGN_EPI = true, bool SP2 = true, bool FULLLINE = false, bool NOSTAGE = false, bool FP8 = false>
; __device__ __forceinline__ void gemm_phase(PG8_LAS unsigned char* lds, const Gemm g, const Sched& S, const Epi& E) {
;     ...
;         static_assert(SP2, "only the SP2 loop is kept");
;         { const int t = 0; if constexpr (Epi::NST == 16) PG8_ITER(PG8_WAIT_V(24)); else if constexpr (Epi::NST == 8) PG8_ITER(PG8_WAIT_V(16)); else PG8_ITER(PG8_WAIT_V(8)); }
	s_nop 5
	ds_read_b128 v[10:13], v194
	ds_read_b128 v[14:17], v194 offset:1024
	ds_read_b128 v[18:21], v194 offset:2048
	ds_read_b128 v[22:25], v194 offset:3072
	ds_read_b128 v[216:219], v195
	ds_read_b128 v[220:223], v195 offset:1024
	ds_read_b128 v[224:227], v195 offset:2048
	ds_read_b128 v[228:231], v195 offset:3072
	s_mov_b32 m0, s53
	v_lshl_add_u64 v[106:107], v[248:249], 0, s[20:21]
	ds_read_b128 v[26:29], v193 offset:32768
	ds_read_b128 v[30:33], v193 offset:33792
	ds_read_b128 v[62:65], v193 offset:34816
	ds_read_b128 v[102:105], v193 offset:35840
	ds_read_b128 v[232:235], v193 offset:36864
	ds_read_b128 v[236:239], v193 offset:37888
	ds_read_b128 v[240:243], v193 offset:38912
	ds_read_b128 v[244:247], v193 offset:39936
	global_load_lds_dwordx4 v[106:107], off
	v_lshl_add_u64 v[106:107], v[248:249], 0, s[22:23]
	s_mov_b32 m0, s54
	s_nop 0
	global_load_lds_dwordx4 v[106:107], off
	s_waitcnt vmcnt(8)
	s_waitcnt lgkmcnt(0)
	s_barrier
	v_mfma_f32_16x16x32_bf16 v[66:69], v[10:13], v[26:29], v[66:69]
	v_mfma_f32_16x16x32_bf16 v[146:149], v[14:17], v[30:33], v[66:69]
	v_mfma_f32_16x16x32_bf16 v[66:69], v[18:21], v[26:29], v[70:73]
	v_mfma_f32_16x16x32_bf16 v[142:145], v[22:25], v[30:33], v[66:69]
	v_mfma_f32_16x16x32_bf16 v[66:69], v[10:13], v[62:65], v[74:77]
	v_mfma_f32_16x16x32_bf16 v[126:129], v[14:17], v[102:105], v[66:69]
	v_mfma_f32_16x16x32_bf16 v[66:69], v[18:21], v[62:65], v[78:81]
	v_mfma_f32_16x16x32_bf16 v[122:125], v[22:25], v[102:105], v[66:69]
	v_mfma_f32_16x16x32_bf16 v[66:69], v[10:13], v[232:235], v[82:85]
	v_mfma_f32_16x16x32_bf16 v[110:113], v[14:17], v[236:239], v[66:69]
	v_mfma_f32_16x16x32_bf16 v[66:69], v[18:21], v[232:235], v[86:89]
	v_mfma_f32_16x16x32_bf16 v[106:109], v[22:25], v[236:239], v[66:69]
	v_mfma_f32_16x16x32_bf16 v[66:69], v[10:13], v[240:243], v[90:93]
	v_mfma_f32_16x16x32_bf16 v[86:89], v[14:17], v[244:247], v[66:69]
	v_mfma_f32_16x16x32_bf16 v[66:69], v[18:21], v[240:243], v[94:97]
	v_mfma_f32_16x16x32_bf16 v[78:81], v[22:25], v[244:247], v[66:69]
	v_mfma_f32_16x16x32_bf16 v[66:69], v[216:219], v[26:29], v[98:101]
	v_mfma_f32_16x16x32_bf16 v[26:29], v[224:227], v[26:29], v[34:37]
	v_mfma_f32_16x16x32_bf16 v[130:133], v[228:231], v[30:33], v[26:29]
	v_mfma_f32_16x16x32_bf16 v[26:29], v[216:219], v[62:65], v[38:41]
	v_mfma_f32_16x16x32_bf16 v[118:121], v[220:223], v[102:105], v[26:29]
	v_mfma_f32_16x16x32_bf16 v[26:29], v[224:227], v[62:65], v[42:45]
	v_mfma_f32_16x16x32_bf16 v[114:117], v[228:231], v[102:105], v[26:29]
	v_mfma_f32_16x16x32_bf16 v[26:29], v[216:219], v[232:235], v[46:49]
	v_mfma_f32_16x16x32_bf16 v[102:105], v[220:223], v[236:239], v[26:29]
	v_mfma_f32_16x16x32_bf16 v[26:29], v[224:227], v[232:235], v[50:53]
	v_mfma_f32_16x16x32_bf16 v[98:101], v[228:231], v[236:239], v[26:29]
	v_mfma_f32_16x16x32_bf16 v[26:29], v[216:219], v[240:243], v[54:57]
	v_mfma_f32_16x16x32_bf16 v[70:73], v[220:223], v[244:247], v[26:29]
	v_mfma_f32_16x16x32_bf16 v[26:29], v[224:227], v[240:243], v[58:61]
	v_mfma_f32_16x16x32_bf16 v[134:137], v[220:223], v[30:33], v[66:69]
	v_mfma_f32_16x16x32_bf16 v[66:69], v[228:231], v[244:247], v[26:29]
	s_barrier
	s_add_i32 s50, s88, s46
	s_nop 3
	v_lshl_add_u64 v[26:27], v[250:251], 0, s[24:25]
	s_mov_b32 m0, s50
	s_add_i32 s51, s50, 0x2000
	ds_read_b128 v[34:37], v193 offset:49152
	ds_read_b128 v[38:41], v193 offset:50176
	ds_read_b128 v[74:77], v193 offset:51200
	ds_read_b128 v[82:85], v193 offset:52224
	ds_read_b128 v[90:93], v193 offset:53248
	ds_read_b128 v[94:97], v193 offset:54272
	ds_read_b128 v[232:235], v193 offset:55296
	ds_read_b128 v[236:239], v193 offset:56320
	global_load_lds_dwordx4 v[26:27], off
	v_lshl_add_u64 v[26:27], v[250:251], 0, s[26:27]
	s_mov_b32 m0, s51
	s_mov_b64 s[0:1], 0x80180
	s_add_i32 s33, s89, s46
	global_load_lds_dwordx4 v[26:27], off
	v_lshl_add_u64 v[26:27], v[250:251], 0, s[0:1]
	s_mov_b32 m0, s33
	s_mov_b64 s[0:1], 0xc0180
	s_add_i32 s56, s33, 0x2000
	global_load_lds_dwordx4 v[26:27], off
	v_lshl_add_u64 v[26:27], v[250:251], 0, s[0:1]
	s_mov_b32 m0, s56
	s_nop 0
	global_load_lds_dwordx4 v[26:27], off
	v_lshl_add_u64 v[26:27], v[248:249], 0, s[24:25]
	s_mov_b32 m0, s55
	s_nop 0
	global_load_lds_dwordx4 v[26:27], off
	v_lshl_add_u64 v[26:27], v[248:249], 0, s[26:27]
	s_mov_b32 m0, s62
	s_nop 0
	global_load_lds_dwordx4 v[26:27], off
	s_waitcnt vmcnt(8)
	s_waitcnt lgkmcnt(0)
	s_barrier
	v_mfma_f32_16x16x32_bf16 v[26:29], v[10:13], v[34:37], v[138:141]
	v_mfma_f32_16x16x32_bf16 v[62:65], v[14:17], v[38:41], v[26:29]
	v_mfma_f32_16x16x32_bf16 v[26:29], v[18:21], v[34:37], v[150:153]
	v_mfma_f32_16x16x32_bf16 v[58:61], v[22:25], v[38:41], v[26:29]
	v_mfma_f32_16x16x32_bf16 v[26:29], v[10:13], v[74:77], v[154:157]
	v_mfma_f32_16x16x32_bf16 v[46:49], v[14:17], v[82:85], v[26:29]
	v_mfma_f32_16x16x32_bf16 v[26:29], v[18:21], v[74:77], v[158:161]
	v_mfma_f32_16x16x32_bf16 v[42:45], v[22:25], v[82:85], v[26:29]
	v_mfma_f32_16x16x32_bf16 v[26:29], v[10:13], v[90:93], v[162:165]
	v_mfma_f32_16x16x32_bf16 v[2:5], v[10:13], v[232:235], v[2:5]
	v_mfma_f32_16x16x32_bf16 v[30:33], v[14:17], v[94:97], v[26:29]
	v_mfma_f32_16x16x32_bf16 v[26:29], v[18:21], v[90:93], v[166:169]
	v_mfma_f32_16x16x32_bf16 v[14:17], v[14:17], v[236:239], v[2:5]
	v_mfma_f32_16x16x32_bf16 v[2:5], v[18:21], v[232:235], v[6:9]
	v_mfma_f32_16x16x32_bf16 v[26:29], v[22:25], v[94:97], v[26:29]
	v_mfma_f32_16x16x32_bf16 v[10:13], v[22:25], v[236:239], v[2:5]
	v_mfma_f32_16x16x32_bf16 v[2:5], v[216:219], v[34:37], v[180:183]
	v_mfma_f32_16x16x32_bf16 v[54:57], v[220:223], v[38:41], v[2:5]
	v_mfma_f32_16x16x32_bf16 v[2:5], v[224:227], v[34:37], v[184:187]
	v_mfma_f32_16x16x32_bf16 v[50:53], v[228:231], v[38:41], v[2:5]
	v_mfma_f32_16x16x32_bf16 v[2:5], v[216:219], v[74:77], v[188:191]
	v_mfma_f32_16x16x32_bf16 v[38:41], v[220:223], v[82:85], v[2:5]
	v_mfma_f32_16x16x32_bf16 v[2:5], v[224:227], v[74:77], v[196:199]
	v_mfma_f32_16x16x32_bf16 v[34:37], v[228:231], v[82:85], v[2:5]
	v_mfma_f32_16x16x32_bf16 v[2:5], v[216:219], v[90:93], v[200:203]
	v_mfma_f32_16x16x32_bf16 v[22:25], v[220:223], v[94:97], v[2:5]
	v_mfma_f32_16x16x32_bf16 v[2:5], v[224:227], v[90:93], v[204:207]
	v_mfma_f32_16x16x32_bf16 v[18:21], v[228:231], v[94:97], v[2:5]
	v_mfma_f32_16x16x32_bf16 v[2:5], v[216:219], v[232:235], v[208:211]
	v_mfma_f32_16x16x32_bf16 v[6:9], v[220:223], v[236:239], v[2:5]
	v_mfma_f32_16x16x32_bf16 v[2:5], v[224:227], v[232:235], v[212:215]
	v_mfma_f32_16x16x32_bf16 v[2:5], v[228:231], v[236:239], v[2:5]
	s_barrier
	s_add_u32 s74, s74, 0x80180
	s_addc_u32 s75, s75, 0
	s_add_u32 s57, s76, 0x200
	s_addc_u32 s76, s77, 0
	s_mov_b32 s77, 0
.LBB0_2097:
	ds_read_b128 v[74:77], v1
	ds_read_b128 v[82:85], v1 offset:1024
	ds_read_b128 v[90:93], v1 offset:2048
	ds_read_b128 v[94:97], v1 offset:3072
	ds_read_b128 v[138:141], v192
	ds_read_b128 v[150:153], v192 offset:1024
	ds_read_b128 v[154:157], v192 offset:2048
	ds_read_b128 v[158:161], v192 offset:3072
	s_add_u32 s0, s74, 0xfff80080
	s_addc_u32 s1, s75, -1
	s_cmp_eq_u32 s77, 28
	s_cselect_b32 s1, s67, s1
	s_cselect_b32 s0, s90, s0
	s_cselect_b32 s65, s41, s76
	s_cselect_b32 s64, s91, s57
	s_mov_b32 m0, s85
	v_lshl_add_u64 v[208:209], s[74:75], 0, v[174:175]
	ds_read_b128 v[162:165], v193
	ds_read_b128 v[166:169], v193 offset:1024
	ds_read_b128 v[180:183], v193 offset:2048
	ds_read_b128 v[184:187], v193 offset:3072
	ds_read_b128 v[188:191], v193 offset:4096
	ds_read_b128 v[196:199], v193 offset:5120
	ds_read_b128 v[200:203], v193 offset:6144
	ds_read_b128 v[204:207], v193 offset:7168
	global_load_lds_dwordx4 v[208:209], off
	v_lshl_add_u64 v[208:209], v[208:209], 0, s[28:29]
	s_mov_b32 m0, s87
	s_nop 0
	global_load_lds_dwordx4 v[208:209], off
	s_waitcnt vmcnt(8)
	s_waitcnt lgkmcnt(0)
	s_barrier
	v_mfma_f32_16x16x32_bf16 v[146:149], v[74:77], v[162:165], v[146:149]
	v_mfma_f32_16x16x32_bf16 v[142:145], v[90:93], v[162:165], v[142:145]
	v_mfma_f32_16x16x32_bf16 v[126:129], v[74:77], v[180:183], v[126:129]
	v_mfma_f32_16x16x32_bf16 v[122:125], v[90:93], v[180:183], v[122:125]
	v_mfma_f32_16x16x32_bf16 v[110:113], v[74:77], v[188:191], v[110:113]
	v_mfma_f32_16x16x32_bf16 v[106:109], v[90:93], v[188:191], v[106:109]
	v_mfma_f32_16x16x32_bf16 v[86:89], v[74:77], v[200:203], v[86:89]
	v_mfma_f32_16x16x32_bf16 v[78:81], v[90:93], v[200:203], v[78:81]
	v_mfma_f32_16x16x32_bf16 v[146:149], v[82:85], v[166:169], v[146:149]
	v_mfma_f32_16x16x32_bf16 v[142:145], v[94:97], v[166:169], v[142:145]
	v_mfma_f32_16x16x32_bf16 v[126:129], v[82:85], v[184:187], v[126:129]
	v_mfma_f32_16x16x32_bf16 v[122:125], v[94:97], v[184:187], v[122:125]
	v_mfma_f32_16x16x32_bf16 v[110:113], v[82:85], v[196:199], v[110:113]
	v_mfma_f32_16x16x32_bf16 v[106:109], v[94:97], v[196:199], v[106:109]
	v_mfma_f32_16x16x32_bf16 v[86:89], v[82:85], v[204:207], v[86:89]
	v_mfma_f32_16x16x32_bf16 v[78:81], v[94:97], v[204:207], v[78:81]
	v_mfma_f32_16x16x32_bf16 v[134:137], v[138:141], v[162:165], v[134:137]
	v_mfma_f32_16x16x32_bf16 v[130:133], v[154:157], v[162:165], v[130:133]
	v_mfma_f32_16x16x32_bf16 v[118:121], v[138:141], v[180:183], v[118:121]
	v_mfma_f32_16x16x32_bf16 v[114:117], v[154:157], v[180:183], v[114:117]
	v_mfma_f32_16x16x32_bf16 v[102:105], v[138:141], v[188:191], v[102:105]
	v_mfma_f32_16x16x32_bf16 v[98:101], v[154:157], v[188:191], v[98:101]
	v_mfma_f32_16x16x32_bf16 v[70:73], v[138:141], v[200:203], v[70:73]
	v_mfma_f32_16x16x32_bf16 v[66:69], v[154:157], v[200:203], v[66:69]
	v_mfma_f32_16x16x32_bf16 v[134:137], v[150:153], v[166:169], v[134:137]
	v_mfma_f32_16x16x32_bf16 v[130:133], v[158:161], v[166:169], v[130:133]
	v_mfma_f32_16x16x32_bf16 v[118:121], v[150:153], v[184:187], v[118:121]
	v_mfma_f32_16x16x32_bf16 v[114:117], v[158:161], v[184:187], v[114:117]
	v_mfma_f32_16x16x32_bf16 v[102:105], v[150:153], v[196:199], v[102:105]
	v_mfma_f32_16x16x32_bf16 v[98:101], v[158:161], v[196:199], v[98:101]
	v_mfma_f32_16x16x32_bf16 v[70:73], v[150:153], v[204:207], v[70:73]
	v_mfma_f32_16x16x32_bf16 v[66:69], v[158:161], v[204:207], v[66:69]
	s_barrier
	s_mov_b32 m0, s92
	v_lshl_add_u64 v[208:209], s[64:65], 0, v[172:173]
	ds_read_b128 v[162:165], v193 offset:16384
	ds_read_b128 v[166:169], v193 offset:17408
	ds_read_b128 v[180:183], v193 offset:18432
	ds_read_b128 v[184:187], v193 offset:19456
	ds_read_b128 v[188:191], v193 offset:20480
	ds_read_b128 v[196:199], v193 offset:21504
	ds_read_b128 v[200:203], v193 offset:22528
	ds_read_b128 v[204:207], v193 offset:23552
	global_load_lds_dwordx4 v[208:209], off
	v_lshl_add_u64 v[210:211], v[208:209], 0, s[28:29]
	s_mov_b32 m0, s93
	s_nop 0
	global_load_lds_dwordx4 v[210:211], off
	v_lshl_add_u64 v[210:211], v[208:209], 0, s[30:31]
	s_mov_b32 m0, s94
	s_nop 0
	global_load_lds_dwordx4 v[210:211], off
	v_lshl_add_u64 v[210:211], v[208:209], 0, s[34:35]
	s_mov_b32 m0, s95
	s_nop 0
	global_load_lds_dwordx4 v[210:211], off
	v_lshl_add_u64 v[210:211], s[0:1], 0, v[170:171]
	s_mov_b32 m0, s47
	v_lshl_add_u64 v[212:213], v[210:211], 0, s[28:29]
	global_load_lds_dwordx4 v[210:211], off
	s_mov_b32 m0, s52
	s_nop 0
	global_load_lds_dwordx4 v[212:213], off
	s_waitcnt vmcnt(8)
	s_waitcnt lgkmcnt(0)
	s_barrier
	v_mfma_f32_16x16x32_bf16 v[62:65], v[74:77], v[162:165], v[62:65]
	v_mfma_f32_16x16x32_bf16 v[58:61], v[90:93], v[162:165], v[58:61]
	v_mfma_f32_16x16x32_bf16 v[46:49], v[74:77], v[180:183], v[46:49]
	v_mfma_f32_16x16x32_bf16 v[42:45], v[90:93], v[180:183], v[42:45]
	v_mfma_f32_16x16x32_bf16 v[30:33], v[74:77], v[188:191], v[30:33]
	v_mfma_f32_16x16x32_bf16 v[26:29], v[90:93], v[188:191], v[26:29]
	v_mfma_f32_16x16x32_bf16 v[14:17], v[74:77], v[200:203], v[14:17]
	v_mfma_f32_16x16x32_bf16 v[10:13], v[90:93], v[200:203], v[10:13]
	v_mfma_f32_16x16x32_bf16 v[62:65], v[82:85], v[166:169], v[62:65]
	v_mfma_f32_16x16x32_bf16 v[58:61], v[94:97], v[166:169], v[58:61]
	v_mfma_f32_16x16x32_bf16 v[46:49], v[82:85], v[184:187], v[46:49]
	v_mfma_f32_16x16x32_bf16 v[42:45], v[94:97], v[184:187], v[42:45]
	v_mfma_f32_16x16x32_bf16 v[30:33], v[82:85], v[196:199], v[30:33]
	v_mfma_f32_16x16x32_bf16 v[26:29], v[94:97], v[196:199], v[26:29]
	v_mfma_f32_16x16x32_bf16 v[14:17], v[82:85], v[204:207], v[14:17]
	v_mfma_f32_16x16x32_bf16 v[10:13], v[94:97], v[204:207], v[10:13]
	v_mfma_f32_16x16x32_bf16 v[54:57], v[138:141], v[162:165], v[54:57]
	v_mfma_f32_16x16x32_bf16 v[50:53], v[154:157], v[162:165], v[50:53]
	v_mfma_f32_16x16x32_bf16 v[38:41], v[138:141], v[180:183], v[38:41]
	v_mfma_f32_16x16x32_bf16 v[34:37], v[154:157], v[180:183], v[34:37]
	v_mfma_f32_16x16x32_bf16 v[22:25], v[138:141], v[188:191], v[22:25]
	v_mfma_f32_16x16x32_bf16 v[18:21], v[154:157], v[188:191], v[18:21]
	v_mfma_f32_16x16x32_bf16 v[6:9], v[138:141], v[200:203], v[6:9]
	v_mfma_f32_16x16x32_bf16 v[2:5], v[154:157], v[200:203], v[2:5]
	v_mfma_f32_16x16x32_bf16 v[54:57], v[150:153], v[166:169], v[54:57]
	v_mfma_f32_16x16x32_bf16 v[50:53], v[158:161], v[166:169], v[50:53]
	v_mfma_f32_16x16x32_bf16 v[38:41], v[150:153], v[184:187], v[38:41]
	v_mfma_f32_16x16x32_bf16 v[34:37], v[158:161], v[184:187], v[34:37]
	v_mfma_f32_16x16x32_bf16 v[22:25], v[150:153], v[196:199], v[22:25]
	v_mfma_f32_16x16x32_bf16 v[18:21], v[158:161], v[196:199], v[18:21]
	v_mfma_f32_16x16x32_bf16 v[6:9], v[150:153], v[204:207], v[6:9]
	v_mfma_f32_16x16x32_bf16 v[2:5], v[158:161], v[204:207], v[2:5]
	s_barrier
; #define PG8_WAIT_V(n) asm volatile("s_waitcnt vmcnt(" #n ")" ::: "memory")
; #define PG8_BAR __builtin_amdgcn_s_barrier()
; template <class Epi, class Sched, bool ALIGN_EPI = true, bool SP2 = true, bool FULLLINE = false, bool NOSTAGE = false, bool FP8 = false>
; __device__ __forceinline__ void gemm_phase(PG8_LAS unsigned char* lds, const Gemm g, const Sched& S, const Epi& E) {
;     ...
;         static_assert(SP2, "only the SP2 loop is kept");
;         { const int t = 0; if constexpr (Epi::NST == 16) PG8_ITER(PG8_WAIT_V(24)); else if constexpr (Epi::NST == 8) PG8_ITER(PG8_WAIT_V(16)); else PG8_ITER(PG8_WAIT_V(8)); }
;         for (int t = 2; t < nt; t += 2) PG8_ITER(PG8_WAIT_V(8));
;     ...
;         if constexpr (ALIGN_EPI) { if (wr == 0) PG8_BAR; }
;         { int ln_ = lane; asm volatile("" : "+v"(ln_));
;           E(acc, cur, wr, wc, ln_ & 15, ln_ >> 4); } S.done(cur);
;         if (!has_next) break;
	ds_read_b128 v[74:77], v194
	ds_read_b128 v[82:85], v194 offset:1024
	ds_read_b128 v[90:93], v194 offset:2048
	ds_read_b128 v[94:97], v194 offset:3072
	ds_read_b128 v[138:141], v195
	ds_read_b128 v[150:153], v195 offset:1024
	ds_read_b128 v[154:157], v195 offset:2048
	ds_read_b128 v[158:161], v195 offset:3072
	s_mov_b32 m0, s53
	v_lshl_add_u64 v[212:213], v[210:211], 0, s[30:31]
	ds_read_b128 v[162:165], v193 offset:32768
	ds_read_b128 v[166:169], v193 offset:33792
	ds_read_b128 v[180:183], v193 offset:34816
	ds_read_b128 v[184:187], v193 offset:35840
	ds_read_b128 v[188:191], v193 offset:36864
	ds_read_b128 v[196:199], v193 offset:37888
	ds_read_b128 v[200:203], v193 offset:38912
	ds_read_b128 v[204:207], v193 offset:39936
	global_load_lds_dwordx4 v[212:213], off
	v_lshl_add_u64 v[212:213], v[210:211], 0, s[34:35]
	s_mov_b32 m0, s54
	s_nop 0
	global_load_lds_dwordx4 v[212:213], off
	s_waitcnt vmcnt(8)
	s_waitcnt lgkmcnt(0)
	s_barrier
	v_mfma_f32_16x16x32_bf16 v[146:149], v[74:77], v[162:165], v[146:149]
	v_mfma_f32_16x16x32_bf16 v[142:145], v[90:93], v[162:165], v[142:145]
	v_mfma_f32_16x16x32_bf16 v[126:129], v[74:77], v[180:183], v[126:129]
	v_mfma_f32_16x16x32_bf16 v[122:125], v[90:93], v[180:183], v[122:125]
	v_mfma_f32_16x16x32_bf16 v[110:113], v[74:77], v[188:191], v[110:113]
	v_mfma_f32_16x16x32_bf16 v[106:109], v[90:93], v[188:191], v[106:109]
	v_mfma_f32_16x16x32_bf16 v[86:89], v[74:77], v[200:203], v[86:89]
	v_mfma_f32_16x16x32_bf16 v[78:81], v[90:93], v[200:203], v[78:81]
	v_mfma_f32_16x16x32_bf16 v[146:149], v[82:85], v[166:169], v[146:149]
	v_mfma_f32_16x16x32_bf16 v[142:145], v[94:97], v[166:169], v[142:145]
	v_mfma_f32_16x16x32_bf16 v[126:129], v[82:85], v[184:187], v[126:129]
	v_mfma_f32_16x16x32_bf16 v[122:125], v[94:97], v[184:187], v[122:125]
	v_mfma_f32_16x16x32_bf16 v[110:113], v[82:85], v[196:199], v[110:113]
	v_mfma_f32_16x16x32_bf16 v[106:109], v[94:97], v[196:199], v[106:109]
	v_mfma_f32_16x16x32_bf16 v[86:89], v[82:85], v[204:207], v[86:89]
	v_mfma_f32_16x16x32_bf16 v[78:81], v[94:97], v[204:207], v[78:81]
	v_mfma_f32_16x16x32_bf16 v[134:137], v[138:141], v[162:165], v[134:137]
	v_mfma_f32_16x16x32_bf16 v[130:133], v[154:157], v[162:165], v[130:133]
	v_mfma_f32_16x16x32_bf16 v[118:121], v[138:141], v[180:183], v[118:121]
	v_mfma_f32_16x16x32_bf16 v[114:117], v[154:157], v[180:183], v[114:117]
	v_mfma_f32_16x16x32_bf16 v[102:105], v[138:141], v[188:191], v[102:105]
	v_mfma_f32_16x16x32_bf16 v[98:101], v[154:157], v[188:191], v[98:101]
	v_mfma_f32_16x16x32_bf16 v[70:73], v[138:141], v[200:203], v[70:73]
	v_mfma_f32_16x16x32_bf16 v[66:69], v[154:157], v[200:203], v[66:69]
	v_mfma_f32_16x16x32_bf16 v[134:137], v[150:153], v[166:169], v[134:137]
	v_mfma_f32_16x16x32_bf16 v[130:133], v[158:161], v[166:169], v[130:133]
	v_mfma_f32_16x16x32_bf16 v[118:121], v[150:153], v[184:187], v[118:121]
	v_mfma_f32_16x16x32_bf16 v[114:117], v[158:161], v[184:187], v[114:117]
	v_mfma_f32_16x16x32_bf16 v[102:105], v[150:153], v[196:199], v[102:105]
	v_mfma_f32_16x16x32_bf16 v[98:101], v[158:161], v[196:199], v[98:101]
	v_mfma_f32_16x16x32_bf16 v[70:73], v[150:153], v[204:207], v[70:73]
	v_mfma_f32_16x16x32_bf16 v[66:69], v[158:161], v[204:207], v[66:69]
	s_barrier
	s_mov_b32 m0, s50
	v_lshl_add_u64 v[212:213], v[208:209], 0, s[36:37]
	ds_read_b128 v[162:165], v193 offset:49152
	ds_read_b128 v[166:169], v193 offset:50176
	ds_read_b128 v[180:183], v193 offset:51200
	ds_read_b128 v[184:187], v193 offset:52224
	ds_read_b128 v[188:191], v193 offset:53248
	ds_read_b128 v[196:199], v193 offset:54272
	ds_read_b128 v[200:203], v193 offset:55296
	ds_read_b128 v[204:207], v193 offset:56320
	global_load_lds_dwordx4 v[212:213], off
	v_lshl_add_u64 v[212:213], v[208:209], 0, s[38:39]
	s_mov_b32 m0, s51
	s_nop 0
	global_load_lds_dwordx4 v[212:213], off
	v_lshl_add_u64 v[212:213], v[208:209], 0, s[12:13]
	s_mov_b32 m0, s33
	v_lshl_add_u64 v[208:209], v[208:209], 0, s[14:15]
	global_load_lds_dwordx4 v[212:213], off
	s_mov_b32 m0, s56
	s_nop 0
	global_load_lds_dwordx4 v[208:209], off
	v_lshl_add_u64 v[208:209], v[210:211], 0, s[36:37]
	s_mov_b32 m0, s55
	s_nop 0
	global_load_lds_dwordx4 v[208:209], off
	v_lshl_add_u64 v[208:209], v[210:211], 0, s[38:39]
	s_mov_b32 m0, s62
	s_nop 0
	global_load_lds_dwordx4 v[208:209], off
	s_waitcnt vmcnt(8)
	s_waitcnt lgkmcnt(0)
	s_barrier
	v_mfma_f32_16x16x32_bf16 v[62:65], v[74:77], v[162:165], v[62:65]
	v_mfma_f32_16x16x32_bf16 v[58:61], v[90:93], v[162:165], v[58:61]
	v_mfma_f32_16x16x32_bf16 v[46:49], v[74:77], v[180:183], v[46:49]
	v_mfma_f32_16x16x32_bf16 v[42:45], v[90:93], v[180:183], v[42:45]
	v_mfma_f32_16x16x32_bf16 v[30:33], v[74:77], v[188:191], v[30:33]
	v_mfma_f32_16x16x32_bf16 v[26:29], v[90:93], v[188:191], v[26:29]
	v_mfma_f32_16x16x32_bf16 v[14:17], v[74:77], v[200:203], v[14:17]
	v_mfma_f32_16x16x32_bf16 v[10:13], v[90:93], v[200:203], v[10:13]
	v_mfma_f32_16x16x32_bf16 v[62:65], v[82:85], v[166:169], v[62:65]
	v_mfma_f32_16x16x32_bf16 v[58:61], v[94:97], v[166:169], v[58:61]
	v_mfma_f32_16x16x32_bf16 v[46:49], v[82:85], v[184:187], v[46:49]
	v_mfma_f32_16x16x32_bf16 v[42:45], v[94:97], v[184:187], v[42:45]
	v_mfma_f32_16x16x32_bf16 v[30:33], v[82:85], v[196:199], v[30:33]
	v_mfma_f32_16x16x32_bf16 v[26:29], v[94:97], v[196:199], v[26:29]
	v_mfma_f32_16x16x32_bf16 v[14:17], v[82:85], v[204:207], v[14:17]
	v_mfma_f32_16x16x32_bf16 v[10:13], v[94:97], v[204:207], v[10:13]
	v_mfma_f32_16x16x32_bf16 v[54:57], v[138:141], v[162:165], v[54:57]
	v_mfma_f32_16x16x32_bf16 v[50:53], v[154:157], v[162:165], v[50:53]
	v_mfma_f32_16x16x32_bf16 v[38:41], v[138:141], v[180:183], v[38:41]
	v_mfma_f32_16x16x32_bf16 v[34:37], v[154:157], v[180:183], v[34:37]
	v_mfma_f32_16x16x32_bf16 v[22:25], v[138:141], v[188:191], v[22:25]
	v_mfma_f32_16x16x32_bf16 v[18:21], v[154:157], v[188:191], v[18:21]
	v_mfma_f32_16x16x32_bf16 v[6:9], v[138:141], v[200:203], v[6:9]
	v_mfma_f32_16x16x32_bf16 v[2:5], v[154:157], v[200:203], v[2:5]
	v_mfma_f32_16x16x32_bf16 v[54:57], v[150:153], v[166:169], v[54:57]
	v_mfma_f32_16x16x32_bf16 v[50:53], v[158:161], v[166:169], v[50:53]
	v_mfma_f32_16x16x32_bf16 v[38:41], v[150:153], v[184:187], v[38:41]
	v_mfma_f32_16x16x32_bf16 v[34:37], v[158:161], v[184:187], v[34:37]
	v_mfma_f32_16x16x32_bf16 v[22:25], v[150:153], v[196:199], v[22:25]
	v_mfma_f32_16x16x32_bf16 v[18:21], v[158:161], v[196:199], v[18:21]
	v_mfma_f32_16x16x32_bf16 v[6:9], v[150:153], v[204:207], v[6:9]
	v_mfma_f32_16x16x32_bf16 v[2:5], v[158:161], v[204:207], v[2:5]
	s_barrier
	s_add_i32 s77, s77, 2
	s_add_u32 s74, s74, 0x100
	s_addc_u32 s75, s75, 0
	s_add_u32 s57, s57, 0x100
	s_addc_u32 s76, s76, 0
	s_cmp_gt_u32 s77, 29
	s_cbranch_scc0 .LBB0_2097
	s_and_b64 vcc, exec, s[10:11]
	s_cbranch_vccz .LBB0_2100
	s_barrier

; template <class Epi, class Sched, bool ALIGN_EPI = true, bool SP2 = true, bool FULLLINE = false, bool NOSTAGE = false, bool FP8 = false>
; __device__ __forceinline__ void gemm_phase(PG8_LAS unsigned char* lds, const Gemm g, const Sched& S, const Epi& E) {
;     ...
;         const bool has_next = S.next(ui + 1, nxt);
;         const char* nA = has_next ? PG8_ABASE(nxt) : cA; const char* nB = has_next ? PG8_BBASE(nxt) : cB;
.LBB0_2286:
	s_ashr_i32 s63, s62, 31
	s_lshl_b64 s[0:1], s[62:63], 20
	s_add_u32 s66, s58, s0
	ds_read_b128 v[2:5], v1
	ds_read_b128 v[6:9], v1 offset:1024
	ds_read_b128 v[10:13], v1 offset:2048
	ds_read_b128 v[14:17], v1 offset:3072
	ds_read_b128 v[18:21], v142
	ds_read_b128 v[22:25], v142 offset:1024
	ds_read_b128 v[26:29], v142 offset:2048
	ds_read_b128 v[30:33], v142 offset:3072
	s_addc_u32 s67, s59, s1
	s_ashr_i32 s41, s40, 31
	s_lshl_b64 s[0:1], s[40:41], 20
	s_add_u32 s68, s3, s0
	s_addc_u32 s69, s42, s1
	s_and_b64 s[0:1], s[8:9], exec
	s_cselect_b32 s41, s67, s75
	s_cselect_b32 s63, s66, s74
	s_cselect_b32 s87, s69, s73
	s_cselect_b32 s88, s68, s72
	v_lshl_add_u64 v[140:141], s[74:75], 0, v[132:133]
	s_mov_b32 m0, s79
	v_lshl_add_u64 v[66:67], v[140:141], 0, s[12:13]
	ds_read_b128 v[34:37], v143
	ds_read_b128 v[38:41], v143 offset:1024
	ds_read_b128 v[42:45], v143 offset:2048
	ds_read_b128 v[46:49], v143 offset:3072
	ds_read_b128 v[50:53], v143 offset:4096
	ds_read_b128 v[54:57], v143 offset:5120
	ds_read_b128 v[58:61], v143 offset:6144
	ds_read_b128 v[62:65], v143 offset:7168
	global_load_lds_dwordx4 v[66:67], off
	v_lshl_add_u64 v[66:67], v[140:141], 0, s[14:15]
	s_mov_b32 m0, s80
	s_nop 0
	global_load_lds_dwordx4 v[66:67], off
	s_waitcnt vmcnt(16)
	s_waitcnt lgkmcnt(0)
	s_barrier
	v_mfma_f32_16x16x32_bf16 v[86:89], v[10:13], v[50:53], 0
	v_mfma_f32_16x16x32_bf16 v[90:93], v[14:17], v[54:57], v[86:89]
	v_mfma_f32_16x16x32_bf16 v[86:89], v[2:5], v[58:61], 0
	v_mfma_f32_16x16x32_bf16 v[66:69], v[2:5], v[34:37], 0
	v_mfma_f32_16x16x32_bf16 v[70:73], v[10:13], v[34:37], 0
	v_mfma_f32_16x16x32_bf16 v[74:77], v[2:5], v[42:45], 0
	v_mfma_f32_16x16x32_bf16 v[78:81], v[10:13], v[42:45], 0
	v_mfma_f32_16x16x32_bf16 v[82:85], v[2:5], v[50:53], 0
	v_mfma_f32_16x16x32_bf16 v[94:97], v[6:9], v[62:65], v[86:89]
	v_mfma_f32_16x16x32_bf16 v[86:89], v[10:13], v[58:61], 0
	v_mfma_f32_16x16x32_bf16 v[66:69], v[6:9], v[38:41], v[66:69]
	v_mfma_f32_16x16x32_bf16 v[70:73], v[14:17], v[38:41], v[70:73]
	v_mfma_f32_16x16x32_bf16 v[74:77], v[6:9], v[46:49], v[74:77]
	v_mfma_f32_16x16x32_bf16 v[78:81], v[14:17], v[46:49], v[78:81]
	v_mfma_f32_16x16x32_bf16 v[82:85], v[6:9], v[54:57], v[82:85]
	v_mfma_f32_16x16x32_bf16 v[106:109], v[14:17], v[62:65], v[86:89]
	v_mfma_f32_16x16x32_bf16 v[86:89], v[18:21], v[34:37], 0
	v_mfma_f32_16x16x32_bf16 v[34:37], v[26:29], v[34:37], 0
	v_mfma_f32_16x16x32_bf16 v[110:113], v[22:25], v[38:41], v[86:89]
	v_mfma_f32_16x16x32_bf16 v[34:37], v[30:33], v[38:41], v[34:37]
	v_mfma_f32_16x16x32_bf16 v[38:41], v[18:21], v[42:45], 0
	v_mfma_f32_16x16x32_bf16 v[42:45], v[26:29], v[42:45], 0
	v_mfma_f32_16x16x32_bf16 v[38:41], v[22:25], v[46:49], v[38:41]
	v_mfma_f32_16x16x32_bf16 v[42:45], v[30:33], v[46:49], v[42:45]
	v_mfma_f32_16x16x32_bf16 v[46:49], v[18:21], v[50:53], 0
	v_mfma_f32_16x16x32_bf16 v[50:53], v[26:29], v[50:53], 0
	v_mfma_f32_16x16x32_bf16 v[46:49], v[22:25], v[54:57], v[46:49]
	v_mfma_f32_16x16x32_bf16 v[50:53], v[30:33], v[54:57], v[50:53]
	v_mfma_f32_16x16x32_bf16 v[54:57], v[18:21], v[58:61], 0
	v_mfma_f32_16x16x32_bf16 v[58:61], v[26:29], v[58:61], 0
	v_mfma_f32_16x16x32_bf16 v[54:57], v[22:25], v[62:65], v[54:57]
	v_mfma_f32_16x16x32_bf16 v[58:61], v[30:33], v[62:65], v[58:61]
	s_barrier
	v_lshl_add_u64 v[238:239], s[72:73], 0, v[130:131]
	s_mov_b32 m0, s81
	v_lshl_add_u64 v[146:147], v[238:239], 0, s[16:17]
	s_add_i32 s89, s81, 0x2000
	ds_read_b128 v[62:65], v143 offset:16384
	ds_read_b128 v[86:89], v143 offset:17408
	ds_read_b128 v[98:101], v143 offset:18432
	ds_read_b128 v[102:105], v143 offset:19456
	ds_read_b128 v[114:117], v143 offset:20480
	ds_read_b128 v[118:121], v143 offset:21504
	ds_read_b128 v[122:125], v143 offset:22528
	ds_read_b128 v[126:129], v143 offset:23552
	global_load_lds_dwordx4 v[146:147], off
	v_lshl_add_u64 v[146:147], v[238:239], 0, s[18:19]
	s_mov_b32 m0, s89
	s_add_i32 s90, s78, s43
	global_load_lds_dwordx4 v[146:147], off
	v_lshl_add_u64 v[146:147], v[238:239], 0, s[20:21]
	s_mov_b32 m0, s90
	s_add_i32 s91, s90, 0x2000
	global_load_lds_dwordx4 v[146:147], off
	v_lshl_add_u64 v[146:147], v[238:239], 0, s[22:23]
	s_mov_b32 m0, s91
	s_nop 0
	global_load_lds_dwordx4 v[146:147], off
	v_lshl_add_u64 v[146:147], v[140:141], 0, s[16:17]
	s_mov_b32 m0, s45
	s_nop 0
	global_load_lds_dwordx4 v[146:147], off
	v_lshl_add_u64 v[146:147], v[140:141], 0, s[18:19]
	s_mov_b32 m0, s46
	s_nop 0
	global_load_lds_dwordx4 v[146:147], off
	s_waitcnt vmcnt(16)
	s_waitcnt lgkmcnt(0)
	s_barrier
	v_mfma_f32_16x16x32_bf16 v[146:149], v[2:5], v[62:65], 0
	v_mfma_f32_16x16x32_bf16 v[154:157], v[2:5], v[98:101], 0
	v_mfma_f32_16x16x32_bf16 v[162:165], v[2:5], v[114:117], 0
	v_mfma_f32_16x16x32_bf16 v[2:5], v[2:5], v[122:125], 0
	v_mfma_f32_16x16x32_bf16 v[146:149], v[6:9], v[86:89], v[146:149]
	v_mfma_f32_16x16x32_bf16 v[154:157], v[6:9], v[102:105], v[154:157]
	v_mfma_f32_16x16x32_bf16 v[162:165], v[6:9], v[118:121], v[162:165]
	v_mfma_f32_16x16x32_bf16 v[2:5], v[6:9], v[126:129], v[2:5]
	v_mfma_f32_16x16x32_bf16 v[6:9], v[10:13], v[122:125], 0
	v_mfma_f32_16x16x32_bf16 v[150:153], v[10:13], v[62:65], 0
	v_mfma_f32_16x16x32_bf16 v[158:161], v[10:13], v[98:101], 0
	v_mfma_f32_16x16x32_bf16 v[166:169], v[10:13], v[114:117], 0
	v_mfma_f32_16x16x32_bf16 v[10:13], v[14:17], v[126:129], v[6:9]
	v_mfma_f32_16x16x32_bf16 v[150:153], v[14:17], v[86:89], v[150:153]
	v_mfma_f32_16x16x32_bf16 v[158:161], v[14:17], v[102:105], v[158:161]
	v_mfma_f32_16x16x32_bf16 v[166:169], v[14:17], v[118:121], v[166:169]
	v_mfma_f32_16x16x32_bf16 v[6:9], v[18:21], v[62:65], 0
	v_mfma_f32_16x16x32_bf16 v[14:17], v[22:25], v[86:89], v[6:9]
	v_mfma_f32_16x16x32_bf16 v[6:9], v[26:29], v[62:65], 0
	v_mfma_f32_16x16x32_bf16 v[170:173], v[30:33], v[86:89], v[6:9]
	v_mfma_f32_16x16x32_bf16 v[6:9], v[18:21], v[98:101], 0
	v_mfma_f32_16x16x32_bf16 v[174:177], v[22:25], v[102:105], v[6:9]
	v_mfma_f32_16x16x32_bf16 v[6:9], v[26:29], v[98:101], 0
	v_mfma_f32_16x16x32_bf16 v[178:181], v[30:33], v[102:105], v[6:9]
	v_mfma_f32_16x16x32_bf16 v[6:9], v[18:21], v[114:117], 0
	v_mfma_f32_16x16x32_bf16 v[182:185], v[22:25], v[118:121], v[6:9]
	v_mfma_f32_16x16x32_bf16 v[6:9], v[26:29], v[114:117], 0
	v_mfma_f32_16x16x32_bf16 v[186:189], v[30:33], v[118:121], v[6:9]
	v_mfma_f32_16x16x32_bf16 v[6:9], v[18:21], v[122:125], 0
	v_mfma_f32_16x16x32_bf16 v[190:193], v[22:25], v[126:129], v[6:9]
	v_mfma_f32_16x16x32_bf16 v[6:9], v[26:29], v[122:125], 0
	v_mfma_f32_16x16x32_bf16 v[194:197], v[30:33], v[126:129], v[6:9]
	s_barrier
; #define PG8_WAIT_V(n) asm volatile("s_waitcnt vmcnt(" #n ")" ::: "memory")
; template <class Epi, class Sched, bool ALIGN_EPI = true, bool SP2 = true, bool FULLLINE = false, bool NOSTAGE = false, bool FP8 = false>
; __device__ __forceinline__ void gemm_phase(PG8_LAS unsigned char* lds, const Gemm g, const Sched& S, const Epi& E) {
;     ...
;         static_assert(SP2, "only the SP2 loop is kept");
;         { const int t = 0; if constexpr (Epi::NST == 16) PG8_ITER(PG8_WAIT_V(24)); else if constexpr (Epi::NST == 8) PG8_ITER(PG8_WAIT_V(16)); else PG8_ITER(PG8_WAIT_V(8)); }
;         for (int t = 2; t < nt; t += 2) PG8_ITER(PG8_WAIT_V(8));
	s_nop 5
	ds_read_b128 v[6:9], v144
	ds_read_b128 v[26:29], v144 offset:1024
	ds_read_b128 v[30:33], v144 offset:2048
	ds_read_b128 v[62:65], v144 offset:3072
	ds_read_b128 v[198:201], v145
	ds_read_b128 v[202:205], v145 offset:1024
	ds_read_b128 v[206:209], v145 offset:2048
	ds_read_b128 v[210:213], v145 offset:3072
	s_mov_b32 m0, s47
	v_lshl_add_u64 v[86:87], v[140:141], 0, s[20:21]
	ds_read_b128 v[18:21], v143 offset:32768
	ds_read_b128 v[22:25], v143 offset:33792
	ds_read_b128 v[214:217], v143 offset:34816
	ds_read_b128 v[218:221], v143 offset:35840
	ds_read_b128 v[222:225], v143 offset:36864
	ds_read_b128 v[226:229], v143 offset:37888
	ds_read_b128 v[230:233], v143 offset:38912
	ds_read_b128 v[234:237], v143 offset:39936
	global_load_lds_dwordx4 v[86:87], off
	v_lshl_add_u64 v[86:87], v[140:141], 0, s[22:23]
	s_mov_b32 m0, s52
	s_nop 0
	global_load_lds_dwordx4 v[86:87], off
	s_waitcnt vmcnt(8)
	s_waitcnt lgkmcnt(0)
	s_barrier
	v_mfma_f32_16x16x32_bf16 v[66:69], v[6:9], v[18:21], v[66:69]
	v_mfma_f32_16x16x32_bf16 v[118:121], v[26:29], v[22:25], v[66:69]
	v_mfma_f32_16x16x32_bf16 v[66:69], v[30:33], v[18:21], v[70:73]
	v_mfma_f32_16x16x32_bf16 v[114:117], v[62:65], v[22:25], v[66:69]
	v_mfma_f32_16x16x32_bf16 v[66:69], v[6:9], v[214:217], v[74:77]
	v_mfma_f32_16x16x32_bf16 v[102:105], v[26:29], v[218:221], v[66:69]
	v_mfma_f32_16x16x32_bf16 v[66:69], v[30:33], v[214:217], v[78:81]
	v_mfma_f32_16x16x32_bf16 v[98:101], v[62:65], v[218:221], v[66:69]
	v_mfma_f32_16x16x32_bf16 v[66:69], v[6:9], v[222:225], v[82:85]
	v_mfma_f32_16x16x32_bf16 v[86:89], v[26:29], v[226:229], v[66:69]
	v_mfma_f32_16x16x32_bf16 v[66:69], v[30:33], v[222:225], v[90:93]
	v_mfma_f32_16x16x32_bf16 v[82:85], v[62:65], v[226:229], v[66:69]
	v_mfma_f32_16x16x32_bf16 v[66:69], v[6:9], v[230:233], v[94:97]
	v_mfma_f32_16x16x32_bf16 v[70:73], v[26:29], v[234:237], v[66:69]
	v_mfma_f32_16x16x32_bf16 v[66:69], v[30:33], v[230:233], v[106:109]
	v_mfma_f32_16x16x32_bf16 v[66:69], v[62:65], v[234:237], v[66:69]
	v_mfma_f32_16x16x32_bf16 v[74:77], v[198:201], v[18:21], v[110:113]
	v_mfma_f32_16x16x32_bf16 v[18:21], v[206:209], v[18:21], v[34:37]
	v_mfma_f32_16x16x32_bf16 v[122:125], v[210:213], v[22:25], v[18:21]
	v_mfma_f32_16x16x32_bf16 v[18:21], v[198:201], v[214:217], v[38:41]
	v_mfma_f32_16x16x32_bf16 v[110:113], v[202:205], v[218:221], v[18:21]
	v_mfma_f32_16x16x32_bf16 v[18:21], v[206:209], v[214:217], v[42:45]
	v_mfma_f32_16x16x32_bf16 v[106:109], v[210:213], v[218:221], v[18:21]
	v_mfma_f32_16x16x32_bf16 v[18:21], v[198:201], v[222:225], v[46:49]
	v_mfma_f32_16x16x32_bf16 v[94:97], v[202:205], v[226:229], v[18:21]
	v_mfma_f32_16x16x32_bf16 v[18:21], v[206:209], v[222:225], v[50:53]
	v_mfma_f32_16x16x32_bf16 v[90:93], v[210:213], v[226:229], v[18:21]
	v_mfma_f32_16x16x32_bf16 v[18:21], v[198:201], v[230:233], v[54:57]
	v_mfma_f32_16x16x32_bf16 v[78:81], v[202:205], v[234:237], v[18:21]
	v_mfma_f32_16x16x32_bf16 v[18:21], v[206:209], v[230:233], v[58:61]
	v_mfma_f32_16x16x32_bf16 v[126:129], v[202:205], v[22:25], v[74:77]
	v_mfma_f32_16x16x32_bf16 v[74:77], v[210:213], v[234:237], v[18:21]
	s_barrier
	s_add_i32 s50, s82, s43
	s_nop 3
	v_lshl_add_u64 v[18:19], v[238:239], 0, s[24:25]
	s_mov_b32 m0, s50
	s_add_i32 s51, s50, 0x2000
	ds_read_b128 v[42:45], v143 offset:49152
	ds_read_b128 v[46:49], v143 offset:50176
	ds_read_b128 v[214:217], v143 offset:51200
	ds_read_b128 v[218:221], v143 offset:52224
	ds_read_b128 v[222:225], v143 offset:53248
	ds_read_b128 v[226:229], v143 offset:54272
	ds_read_b128 v[230:233], v143 offset:55296
	ds_read_b128 v[234:237], v143 offset:56320
	global_load_lds_dwordx4 v[18:19], off
	v_lshl_add_u64 v[18:19], v[238:239], 0, s[26:27]
	s_mov_b32 m0, s51
	s_mov_b64 s[0:1], 0x80180
	s_add_i32 s33, s83, s43
	global_load_lds_dwordx4 v[18:19], off
	v_lshl_add_u64 v[18:19], v[238:239], 0, s[0:1]
	s_mov_b32 m0, s33
	s_mov_b64 s[0:1], 0xc0180
	s_add_i32 s56, s33, 0x2000
	global_load_lds_dwordx4 v[18:19], off
	v_lshl_add_u64 v[18:19], v[238:239], 0, s[0:1]
	s_mov_b32 m0, s56
	s_nop 0
	global_load_lds_dwordx4 v[18:19], off
	v_lshl_add_u64 v[18:19], v[140:141], 0, s[24:25]
	s_mov_b32 m0, s53
	s_nop 0
	global_load_lds_dwordx4 v[18:19], off
	v_lshl_add_u64 v[18:19], v[140:141], 0, s[26:27]
	s_mov_b32 m0, s54
	s_nop 0
	global_load_lds_dwordx4 v[18:19], off
	s_waitcnt vmcnt(8)
	s_waitcnt lgkmcnt(0)
	s_barrier
	v_mfma_f32_16x16x32_bf16 v[18:21], v[6:9], v[42:45], v[146:149]
	v_mfma_f32_16x16x32_bf16 v[54:57], v[26:29], v[46:49], v[18:21]
	v_mfma_f32_16x16x32_bf16 v[18:21], v[30:33], v[42:45], v[150:153]
	v_mfma_f32_16x16x32_bf16 v[50:53], v[62:65], v[46:49], v[18:21]
	v_mfma_f32_16x16x32_bf16 v[18:21], v[6:9], v[214:217], v[154:157]
	v_mfma_f32_16x16x32_bf16 v[38:41], v[26:29], v[218:221], v[18:21]
	v_mfma_f32_16x16x32_bf16 v[18:21], v[30:33], v[214:217], v[158:161]
	v_mfma_f32_16x16x32_bf16 v[34:37], v[62:65], v[218:221], v[18:21]
	v_mfma_f32_16x16x32_bf16 v[18:21], v[6:9], v[222:225], v[162:165]
	v_mfma_f32_16x16x32_bf16 v[2:5], v[6:9], v[230:233], v[2:5]
	v_mfma_f32_16x16x32_bf16 v[22:25], v[26:29], v[226:229], v[18:21]
	v_mfma_f32_16x16x32_bf16 v[18:21], v[30:33], v[222:225], v[166:169]
	v_mfma_f32_16x16x32_bf16 v[6:9], v[26:29], v[234:237], v[2:5]
	v_mfma_f32_16x16x32_bf16 v[2:5], v[30:33], v[230:233], v[10:13]
	v_mfma_f32_16x16x32_bf16 v[18:21], v[62:65], v[226:229], v[18:21]
	v_mfma_f32_16x16x32_bf16 v[2:5], v[62:65], v[234:237], v[2:5]
	v_mfma_f32_16x16x32_bf16 v[10:13], v[198:201], v[42:45], v[14:17]
	v_mfma_f32_16x16x32_bf16 v[62:65], v[202:205], v[46:49], v[10:13]
	v_mfma_f32_16x16x32_bf16 v[10:13], v[206:209], v[42:45], v[170:173]
	v_mfma_f32_16x16x32_bf16 v[58:61], v[210:213], v[46:49], v[10:13]
	v_mfma_f32_16x16x32_bf16 v[10:13], v[198:201], v[214:217], v[174:177]
	v_mfma_f32_16x16x32_bf16 v[46:49], v[202:205], v[218:221], v[10:13]
	v_mfma_f32_16x16x32_bf16 v[10:13], v[206:209], v[214:217], v[178:181]
	v_mfma_f32_16x16x32_bf16 v[42:45], v[210:213], v[218:221], v[10:13]
	v_mfma_f32_16x16x32_bf16 v[10:13], v[198:201], v[222:225], v[182:185]
	v_mfma_f32_16x16x32_bf16 v[30:33], v[202:205], v[226:229], v[10:13]
	v_mfma_f32_16x16x32_bf16 v[10:13], v[206:209], v[222:225], v[186:189]
	v_mfma_f32_16x16x32_bf16 v[26:29], v[210:213], v[226:229], v[10:13]
	v_mfma_f32_16x16x32_bf16 v[10:13], v[198:201], v[230:233], v[190:193]
	v_mfma_f32_16x16x32_bf16 v[14:17], v[202:205], v[234:237], v[10:13]
	v_mfma_f32_16x16x32_bf16 v[10:13], v[206:209], v[230:233], v[194:197]
	v_mfma_f32_16x16x32_bf16 v[10:13], v[210:213], v[234:237], v[10:13]
	s_barrier
	s_add_u32 s74, s74, 0x80180
	s_addc_u32 s75, s75, 0
	s_add_u32 s57, s72, 0x200
	s_addc_u32 s72, s73, 0
	s_mov_b32 s73, 0
.LBB0_2287:
	ds_read_b128 v[146:149], v1
	ds_read_b128 v[150:153], v1 offset:1024
	ds_read_b128 v[154:157], v1 offset:2048
	ds_read_b128 v[158:161], v1 offset:3072
	ds_read_b128 v[162:165], v142
	ds_read_b128 v[166:169], v142 offset:1024
	ds_read_b128 v[170:173], v142 offset:2048
	ds_read_b128 v[174:177], v142 offset:3072
	s_add_u32 s0, s74, 0xfff80080
	s_addc_u32 s1, s75, -1
	s_cmp_eq_u32 s73, 28
	s_cselect_b32 s1, s41, s1
	s_cselect_b32 s0, s63, s0
	s_cselect_b32 s65, s87, s72
	s_cselect_b32 s64, s88, s57
	s_mov_b32 m0, s79
	v_lshl_add_u64 v[140:141], s[74:75], 0, v[134:135]
	ds_read_b128 v[178:181], v143
	ds_read_b128 v[182:185], v143 offset:1024
	ds_read_b128 v[186:189], v143 offset:2048
	ds_read_b128 v[190:193], v143 offset:3072
	ds_read_b128 v[194:197], v143 offset:4096
	ds_read_b128 v[198:201], v143 offset:5120
	ds_read_b128 v[202:205], v143 offset:6144
	ds_read_b128 v[206:209], v143 offset:7168
	global_load_lds_dwordx4 v[140:141], off
	v_lshl_add_u64 v[140:141], v[140:141], 0, s[28:29]
	s_mov_b32 m0, s80
	s_nop 0
	global_load_lds_dwordx4 v[140:141], off
	s_waitcnt vmcnt(8)
	s_waitcnt lgkmcnt(0)
	s_barrier
	v_mfma_f32_16x16x32_bf16 v[118:121], v[146:149], v[178:181], v[118:121]
	v_mfma_f32_16x16x32_bf16 v[114:117], v[154:157], v[178:181], v[114:117]
	v_mfma_f32_16x16x32_bf16 v[102:105], v[146:149], v[186:189], v[102:105]
	v_mfma_f32_16x16x32_bf16 v[98:101], v[154:157], v[186:189], v[98:101]
	v_mfma_f32_16x16x32_bf16 v[86:89], v[146:149], v[194:197], v[86:89]
	v_mfma_f32_16x16x32_bf16 v[82:85], v[154:157], v[194:197], v[82:85]
	v_mfma_f32_16x16x32_bf16 v[70:73], v[146:149], v[202:205], v[70:73]
	v_mfma_f32_16x16x32_bf16 v[66:69], v[154:157], v[202:205], v[66:69]
	v_mfma_f32_16x16x32_bf16 v[118:121], v[150:153], v[182:185], v[118:121]
	v_mfma_f32_16x16x32_bf16 v[114:117], v[158:161], v[182:185], v[114:117]
	v_mfma_f32_16x16x32_bf16 v[102:105], v[150:153], v[190:193], v[102:105]
	v_mfma_f32_16x16x32_bf16 v[98:101], v[158:161], v[190:193], v[98:101]
	v_mfma_f32_16x16x32_bf16 v[86:89], v[150:153], v[198:201], v[86:89]
	v_mfma_f32_16x16x32_bf16 v[82:85], v[158:161], v[198:201], v[82:85]
	v_mfma_f32_16x16x32_bf16 v[70:73], v[150:153], v[206:209], v[70:73]
	v_mfma_f32_16x16x32_bf16 v[66:69], v[158:161], v[206:209], v[66:69]
	v_mfma_f32_16x16x32_bf16 v[126:129], v[162:165], v[178:181], v[126:129]
	v_mfma_f32_16x16x32_bf16 v[122:125], v[170:173], v[178:181], v[122:125]
	v_mfma_f32_16x16x32_bf16 v[110:113], v[162:165], v[186:189], v[110:113]
	v_mfma_f32_16x16x32_bf16 v[106:109], v[170:173], v[186:189], v[106:109]
	v_mfma_f32_16x16x32_bf16 v[94:97], v[162:165], v[194:197], v[94:97]
	v_mfma_f32_16x16x32_bf16 v[90:93], v[170:173], v[194:197], v[90:93]
	v_mfma_f32_16x16x32_bf16 v[78:81], v[162:165], v[202:205], v[78:81]
	v_mfma_f32_16x16x32_bf16 v[74:77], v[170:173], v[202:205], v[74:77]
	v_mfma_f32_16x16x32_bf16 v[126:129], v[166:169], v[182:185], v[126:129]
	v_mfma_f32_16x16x32_bf16 v[122:125], v[174:177], v[182:185], v[122:125]
	v_mfma_f32_16x16x32_bf16 v[110:113], v[166:169], v[190:193], v[110:113]
	v_mfma_f32_16x16x32_bf16 v[106:109], v[174:177], v[190:193], v[106:109]
	v_mfma_f32_16x16x32_bf16 v[94:97], v[166:169], v[198:201], v[94:97]
	v_mfma_f32_16x16x32_bf16 v[90:93], v[174:177], v[198:201], v[90:93]
	v_mfma_f32_16x16x32_bf16 v[78:81], v[166:169], v[206:209], v[78:81]
	v_mfma_f32_16x16x32_bf16 v[74:77], v[174:177], v[206:209], v[74:77]
	s_barrier
	s_mov_b32 m0, s81
	v_lshl_add_u64 v[140:141], s[64:65], 0, v[130:131]
	ds_read_b128 v[178:181], v143 offset:16384
	ds_read_b128 v[182:185], v143 offset:17408
	ds_read_b128 v[186:189], v143 offset:18432
	ds_read_b128 v[190:193], v143 offset:19456
	ds_read_b128 v[194:197], v143 offset:20480
	ds_read_b128 v[198:201], v143 offset:21504
	ds_read_b128 v[202:205], v143 offset:22528
	ds_read_b128 v[206:209], v143 offset:23552
	global_load_lds_dwordx4 v[140:141], off
	v_lshl_add_u64 v[210:211], v[140:141], 0, s[28:29]
	s_mov_b32 m0, s89
	s_nop 0
	global_load_lds_dwordx4 v[210:211], off
	v_lshl_add_u64 v[210:211], v[140:141], 0, s[30:31]
	s_mov_b32 m0, s90
	s_nop 0
	global_load_lds_dwordx4 v[210:211], off
	v_lshl_add_u64 v[210:211], v[140:141], 0, s[34:35]
	s_mov_b32 m0, s91
	s_nop 0
	global_load_lds_dwordx4 v[210:211], off
	v_lshl_add_u64 v[210:211], s[0:1], 0, v[132:133]
	s_mov_b32 m0, s45
	v_lshl_add_u64 v[212:213], v[210:211], 0, s[28:29]
	global_load_lds_dwordx4 v[210:211], off
	s_mov_b32 m0, s46
	s_nop 0
	global_load_lds_dwordx4 v[212:213], off
	s_waitcnt vmcnt(8)
	s_waitcnt lgkmcnt(0)
	s_barrier
	v_mfma_f32_16x16x32_bf16 v[54:57], v[146:149], v[178:181], v[54:57]
	v_mfma_f32_16x16x32_bf16 v[50:53], v[154:157], v[178:181], v[50:53]
	v_mfma_f32_16x16x32_bf16 v[38:41], v[146:149], v[186:189], v[38:41]
	v_mfma_f32_16x16x32_bf16 v[34:37], v[154:157], v[186:189], v[34:37]
	v_mfma_f32_16x16x32_bf16 v[22:25], v[146:149], v[194:197], v[22:25]
	v_mfma_f32_16x16x32_bf16 v[18:21], v[154:157], v[194:197], v[18:21]
	v_mfma_f32_16x16x32_bf16 v[6:9], v[146:149], v[202:205], v[6:9]
	v_mfma_f32_16x16x32_bf16 v[2:5], v[154:157], v[202:205], v[2:5]
	v_mfma_f32_16x16x32_bf16 v[54:57], v[150:153], v[182:185], v[54:57]
	v_mfma_f32_16x16x32_bf16 v[50:53], v[158:161], v[182:185], v[50:53]
	v_mfma_f32_16x16x32_bf16 v[38:41], v[150:153], v[190:193], v[38:41]
	v_mfma_f32_16x16x32_bf16 v[34:37], v[158:161], v[190:193], v[34:37]
	v_mfma_f32_16x16x32_bf16 v[22:25], v[150:153], v[198:201], v[22:25]
	v_mfma_f32_16x16x32_bf16 v[18:21], v[158:161], v[198:201], v[18:21]
	v_mfma_f32_16x16x32_bf16 v[6:9], v[150:153], v[206:209], v[6:9]
	v_mfma_f32_16x16x32_bf16 v[2:5], v[158:161], v[206:209], v[2:5]
	v_mfma_f32_16x16x32_bf16 v[62:65], v[162:165], v[178:181], v[62:65]
	v_mfma_f32_16x16x32_bf16 v[58:61], v[170:173], v[178:181], v[58:61]
	v_mfma_f32_16x16x32_bf16 v[46:49], v[162:165], v[186:189], v[46:49]
	v_mfma_f32_16x16x32_bf16 v[42:45], v[170:173], v[186:189], v[42:45]
	v_mfma_f32_16x16x32_bf16 v[30:33], v[162:165], v[194:197], v[30:33]
	v_mfma_f32_16x16x32_bf16 v[26:29], v[170:173], v[194:197], v[26:29]
	v_mfma_f32_16x16x32_bf16 v[14:17], v[162:165], v[202:205], v[14:17]
	v_mfma_f32_16x16x32_bf16 v[10:13], v[170:173], v[202:205], v[10:13]
	v_mfma_f32_16x16x32_bf16 v[62:65], v[166:169], v[182:185], v[62:65]
	v_mfma_f32_16x16x32_bf16 v[58:61], v[174:177], v[182:185], v[58:61]
	v_mfma_f32_16x16x32_bf16 v[46:49], v[166:169], v[190:193], v[46:49]
	v_mfma_f32_16x16x32_bf16 v[42:45], v[174:177], v[190:193], v[42:45]
	v_mfma_f32_16x16x32_bf16 v[30:33], v[166:169], v[198:201], v[30:33]
	v_mfma_f32_16x16x32_bf16 v[26:29], v[174:177], v[198:201], v[26:29]
	v_mfma_f32_16x16x32_bf16 v[14:17], v[166:169], v[206:209], v[14:17]
	v_mfma_f32_16x16x32_bf16 v[10:13], v[174:177], v[206:209], v[10:13]
	s_barrier
; #define PG8_WAIT_V(n) asm volatile("s_waitcnt vmcnt(" #n ")" ::: "memory")
; #define PG8_BAR __builtin_amdgcn_s_barrier()
; template <class Epi, class Sched, bool ALIGN_EPI = true, bool SP2 = true, bool FULLLINE = false, bool NOSTAGE = false, bool FP8 = false>
; __device__ __forceinline__ void gemm_phase(PG8_LAS unsigned char* lds, const Gemm g, const Sched& S, const Epi& E) {
;     ...
;         static_assert(SP2, "only the SP2 loop is kept");
;         { const int t = 0; if constexpr (Epi::NST == 16) PG8_ITER(PG8_WAIT_V(24)); else if constexpr (Epi::NST == 8) PG8_ITER(PG8_WAIT_V(16)); else PG8_ITER(PG8_WAIT_V(8)); }
;         for (int t = 2; t < nt; t += 2) PG8_ITER(PG8_WAIT_V(8));
;     ...
;         if constexpr (ALIGN_EPI) { if (wr == 0) PG8_BAR; }
;         { int ln_ = lane; asm volatile("" : "+v"(ln_));
;           E(acc, cur, wr, wc, ln_ & 15, ln_ >> 4); } S.done(cur);
;         if (!has_next) break;
	ds_read_b128 v[146:149], v144
	ds_read_b128 v[150:153], v144 offset:1024
	ds_read_b128 v[154:157], v144 offset:2048
	ds_read_b128 v[158:161], v144 offset:3072
	ds_read_b128 v[162:165], v145
	ds_read_b128 v[166:169], v145 offset:1024
	ds_read_b128 v[170:173], v145 offset:2048
	ds_read_b128 v[174:177], v145 offset:3072
	s_mov_b32 m0, s47
	v_lshl_add_u64 v[212:213], v[210:211], 0, s[30:31]
	ds_read_b128 v[178:181], v143 offset:32768
	ds_read_b128 v[182:185], v143 offset:33792
	ds_read_b128 v[186:189], v143 offset:34816
	ds_read_b128 v[190:193], v143 offset:35840
	ds_read_b128 v[194:197], v143 offset:36864
	ds_read_b128 v[198:201], v143 offset:37888
	ds_read_b128 v[202:205], v143 offset:38912
	ds_read_b128 v[206:209], v143 offset:39936
	global_load_lds_dwordx4 v[212:213], off
	v_lshl_add_u64 v[212:213], v[210:211], 0, s[34:35]
	s_mov_b32 m0, s52
	s_nop 0
	global_load_lds_dwordx4 v[212:213], off
	s_waitcnt vmcnt(8)
	s_waitcnt lgkmcnt(0)
	s_barrier
	v_mfma_f32_16x16x32_bf16 v[118:121], v[146:149], v[178:181], v[118:121]
	v_mfma_f32_16x16x32_bf16 v[114:117], v[154:157], v[178:181], v[114:117]
	v_mfma_f32_16x16x32_bf16 v[102:105], v[146:149], v[186:189], v[102:105]
	v_mfma_f32_16x16x32_bf16 v[98:101], v[154:157], v[186:189], v[98:101]
	v_mfma_f32_16x16x32_bf16 v[86:89], v[146:149], v[194:197], v[86:89]
	v_mfma_f32_16x16x32_bf16 v[82:85], v[154:157], v[194:197], v[82:85]
	v_mfma_f32_16x16x32_bf16 v[70:73], v[146:149], v[202:205], v[70:73]
	v_mfma_f32_16x16x32_bf16 v[66:69], v[154:157], v[202:205], v[66:69]
	v_mfma_f32_16x16x32_bf16 v[118:121], v[150:153], v[182:185], v[118:121]
	v_mfma_f32_16x16x32_bf16 v[114:117], v[158:161], v[182:185], v[114:117]
	v_mfma_f32_16x16x32_bf16 v[102:105], v[150:153], v[190:193], v[102:105]
	v_mfma_f32_16x16x32_bf16 v[98:101], v[158:161], v[190:193], v[98:101]
	v_mfma_f32_16x16x32_bf16 v[86:89], v[150:153], v[198:201], v[86:89]
	v_mfma_f32_16x16x32_bf16 v[82:85], v[158:161], v[198:201], v[82:85]
	v_mfma_f32_16x16x32_bf16 v[70:73], v[150:153], v[206:209], v[70:73]
	v_mfma_f32_16x16x32_bf16 v[66:69], v[158:161], v[206:209], v[66:69]
	v_mfma_f32_16x16x32_bf16 v[126:129], v[162:165], v[178:181], v[126:129]
	v_mfma_f32_16x16x32_bf16 v[122:125], v[170:173], v[178:181], v[122:125]
	v_mfma_f32_16x16x32_bf16 v[110:113], v[162:165], v[186:189], v[110:113]
	v_mfma_f32_16x16x32_bf16 v[106:109], v[170:173], v[186:189], v[106:109]
	v_mfma_f32_16x16x32_bf16 v[94:97], v[162:165], v[194:197], v[94:97]
	v_mfma_f32_16x16x32_bf16 v[90:93], v[170:173], v[194:197], v[90:93]
	v_mfma_f32_16x16x32_bf16 v[78:81], v[162:165], v[202:205], v[78:81]
	v_mfma_f32_16x16x32_bf16 v[74:77], v[170:173], v[202:205], v[74:77]
	v_mfma_f32_16x16x32_bf16 v[126:129], v[166:169], v[182:185], v[126:129]
	v_mfma_f32_16x16x32_bf16 v[122:125], v[174:177], v[182:185], v[122:125]
	v_mfma_f32_16x16x32_bf16 v[110:113], v[166:169], v[190:193], v[110:113]
	v_mfma_f32_16x16x32_bf16 v[106:109], v[174:177], v[190:193], v[106:109]
	v_mfma_f32_16x16x32_bf16 v[94:97], v[166:169], v[198:201], v[94:97]
	v_mfma_f32_16x16x32_bf16 v[90:93], v[174:177], v[198:201], v[90:93]
	v_mfma_f32_16x16x32_bf16 v[78:81], v[166:169], v[206:209], v[78:81]
	v_mfma_f32_16x16x32_bf16 v[74:77], v[174:177], v[206:209], v[74:77]
	s_barrier
	s_mov_b32 m0, s50
	v_lshl_add_u64 v[212:213], v[140:141], 0, s[36:37]
	ds_read_b128 v[178:181], v143 offset:49152
	ds_read_b128 v[182:185], v143 offset:50176
	ds_read_b128 v[186:189], v143 offset:51200
	ds_read_b128 v[190:193], v143 offset:52224
	ds_read_b128 v[194:197], v143 offset:53248
	ds_read_b128 v[198:201], v143 offset:54272
	ds_read_b128 v[202:205], v143 offset:55296
	ds_read_b128 v[206:209], v143 offset:56320
	global_load_lds_dwordx4 v[212:213], off
	v_lshl_add_u64 v[212:213], v[140:141], 0, s[38:39]
	s_mov_b32 m0, s51
	s_nop 0
	global_load_lds_dwordx4 v[212:213], off
	v_lshl_add_u64 v[212:213], v[140:141], 0, s[12:13]
	s_mov_b32 m0, s33
	v_lshl_add_u64 v[140:141], v[140:141], 0, s[14:15]
	global_load_lds_dwordx4 v[212:213], off
	s_mov_b32 m0, s56
	s_nop 0
	global_load_lds_dwordx4 v[140:141], off
	v_lshl_add_u64 v[140:141], v[210:211], 0, s[36:37]
	s_mov_b32 m0, s53
	s_nop 0
	global_load_lds_dwordx4 v[140:141], off
	v_lshl_add_u64 v[140:141], v[210:211], 0, s[38:39]
	s_mov_b32 m0, s54
	s_nop 0
	global_load_lds_dwordx4 v[140:141], off
	s_waitcnt vmcnt(8)
	s_waitcnt lgkmcnt(0)
	s_barrier
	v_mfma_f32_16x16x32_bf16 v[54:57], v[146:149], v[178:181], v[54:57]
	v_mfma_f32_16x16x32_bf16 v[50:53], v[154:157], v[178:181], v[50:53]
	v_mfma_f32_16x16x32_bf16 v[38:41], v[146:149], v[186:189], v[38:41]
	v_mfma_f32_16x16x32_bf16 v[34:37], v[154:157], v[186:189], v[34:37]
	v_mfma_f32_16x16x32_bf16 v[22:25], v[146:149], v[194:197], v[22:25]
	v_mfma_f32_16x16x32_bf16 v[18:21], v[154:157], v[194:197], v[18:21]
	v_mfma_f32_16x16x32_bf16 v[6:9], v[146:149], v[202:205], v[6:9]
	v_mfma_f32_16x16x32_bf16 v[2:5], v[154:157], v[202:205], v[2:5]
	v_mfma_f32_16x16x32_bf16 v[54:57], v[150:153], v[182:185], v[54:57]
	v_mfma_f32_16x16x32_bf16 v[50:53], v[158:161], v[182:185], v[50:53]
	v_mfma_f32_16x16x32_bf16 v[38:41], v[150:153], v[190:193], v[38:41]
	v_mfma_f32_16x16x32_bf16 v[34:37], v[158:161], v[190:193], v[34:37]
	v_mfma_f32_16x16x32_bf16 v[22:25], v[150:153], v[198:201], v[22:25]
	v_mfma_f32_16x16x32_bf16 v[18:21], v[158:161], v[198:201], v[18:21]
	v_mfma_f32_16x16x32_bf16 v[6:9], v[150:153], v[206:209], v[6:9]
	v_mfma_f32_16x16x32_bf16 v[2:5], v[158:161], v[206:209], v[2:5]
	v_mfma_f32_16x16x32_bf16 v[62:65], v[162:165], v[178:181], v[62:65]
	v_mfma_f32_16x16x32_bf16 v[58:61], v[170:173], v[178:181], v[58:61]
	v_mfma_f32_16x16x32_bf16 v[46:49], v[162:165], v[186:189], v[46:49]
	v_mfma_f32_16x16x32_bf16 v[42:45], v[170:173], v[186:189], v[42:45]
	v_mfma_f32_16x16x32_bf16 v[30:33], v[162:165], v[194:197], v[30:33]
	v_mfma_f32_16x16x32_bf16 v[26:29], v[170:173], v[194:197], v[26:29]
	v_mfma_f32_16x16x32_bf16 v[14:17], v[162:165], v[202:205], v[14:17]
	v_mfma_f32_16x16x32_bf16 v[10:13], v[170:173], v[202:205], v[10:13]
	v_mfma_f32_16x16x32_bf16 v[62:65], v[166:169], v[182:185], v[62:65]
	v_mfma_f32_16x16x32_bf16 v[58:61], v[174:177], v[182:185], v[58:61]
	v_mfma_f32_16x16x32_bf16 v[46:49], v[166:169], v[190:193], v[46:49]
	v_mfma_f32_16x16x32_bf16 v[42:45], v[174:177], v[190:193], v[42:45]
	v_mfma_f32_16x16x32_bf16 v[30:33], v[166:169], v[198:201], v[30:33]
	v_mfma_f32_16x16x32_bf16 v[26:29], v[174:177], v[198:201], v[26:29]
	v_mfma_f32_16x16x32_bf16 v[14:17], v[166:169], v[206:209], v[14:17]
	v_mfma_f32_16x16x32_bf16 v[10:13], v[174:177], v[206:209], v[10:13]
	s_barrier
	s_add_i32 s73, s73, 2
	s_add_u32 s74, s74, 0x100
	s_addc_u32 s75, s75, 0
	s_add_u32 s57, s57, 0x100
	s_addc_u32 s72, s72, 0
	s_cmp_gt_u32 s73, 29
	s_cbranch_scc0 .LBB0_2287
	s_and_b64 vcc, exec, s[10:11]
	s_cbranch_vccz .LBB0_2290
	s_barrier

; template <class Epi, class Sched, bool ALIGN_EPI = true, bool SP2 = true, bool FULLLINE = false, bool NOSTAGE = false, bool FP8 = false>
; __device__ __forceinline__ void gemm_phase(PG8_LAS unsigned char* lds, const Gemm g, const Sched& S, const Epi& E) {
;     ...
;         const bool has_next = S.next(ui + 1, nxt);
;         const char* nA = has_next ? PG8_ABASE(nxt) : cA; const char* nB = has_next ? PG8_BBASE(nxt) : cB;
.LBB0_2389:
	ds_read_b128 v[2:5], v1
	ds_read_b128 v[6:9], v1 offset:1024
	ds_read_b128 v[10:13], v1 offset:2048
	ds_read_b128 v[14:17], v1 offset:3072
	ds_read_b128 v[18:21], v192
	ds_read_b128 v[22:25], v192 offset:1024
	ds_read_b128 v[26:29], v192 offset:2048
	ds_read_b128 v[30:33], v192 offset:3072
	v_lshl_add_u64 v[244:245], s[66:67], 0, v[170:171]
	s_add_i32 s83, s45, 0xc000
	v_lshl_add_u64 v[66:67], v[244:245], 0, s[14:15]
	s_mov_b32 m0, s83
	s_add_i32 s84, s45, 0xe000
	ds_read_b128 v[34:37], v193
	ds_read_b128 v[38:41], v193 offset:1024
	ds_read_b128 v[42:45], v193 offset:2048
	ds_read_b128 v[46:49], v193 offset:3072
	ds_read_b128 v[50:53], v193 offset:4096
	ds_read_b128 v[54:57], v193 offset:5120
	ds_read_b128 v[58:61], v193 offset:6144
	ds_read_b128 v[62:65], v193 offset:7168
	global_load_lds_dwordx4 v[66:67], off
	v_lshl_add_u64 v[66:67], v[244:245], 0, s[16:17]
	s_mov_b32 m0, s84
	s_nop 0
	global_load_lds_dwordx4 v[66:67], off
	s_waitcnt vmcnt(24)
	s_waitcnt lgkmcnt(0)
	s_barrier
	v_mfma_f32_16x16x32_bf16 v[66:69], v[2:5], v[34:37], 0
	v_mfma_f32_16x16x32_bf16 v[70:73], v[10:13], v[34:37], 0
	v_mfma_f32_16x16x32_bf16 v[74:77], v[2:5], v[42:45], 0
	v_mfma_f32_16x16x32_bf16 v[78:81], v[10:13], v[42:45], 0
	v_mfma_f32_16x16x32_bf16 v[90:93], v[2:5], v[58:61], 0
	v_mfma_f32_16x16x32_bf16 v[94:97], v[10:13], v[58:61], 0
	v_mfma_f32_16x16x32_bf16 v[66:69], v[6:9], v[38:41], v[66:69]
	v_mfma_f32_16x16x32_bf16 v[70:73], v[14:17], v[38:41], v[70:73]
	v_mfma_f32_16x16x32_bf16 v[74:77], v[6:9], v[46:49], v[74:77]
	v_mfma_f32_16x16x32_bf16 v[78:81], v[14:17], v[46:49], v[78:81]
	v_mfma_f32_16x16x32_bf16 v[82:85], v[2:5], v[50:53], 0
	v_mfma_f32_16x16x32_bf16 v[86:89], v[10:13], v[50:53], 0
	v_mfma_f32_16x16x32_bf16 v[90:93], v[6:9], v[62:65], v[90:93]
	v_mfma_f32_16x16x32_bf16 v[94:97], v[14:17], v[62:65], v[94:97]
	v_mfma_f32_16x16x32_bf16 v[82:85], v[6:9], v[54:57], v[82:85]
	v_mfma_f32_16x16x32_bf16 v[86:89], v[14:17], v[54:57], v[86:89]
	v_mfma_f32_16x16x32_bf16 v[98:101], v[18:21], v[34:37], 0
	v_mfma_f32_16x16x32_bf16 v[34:37], v[26:29], v[34:37], 0
	v_mfma_f32_16x16x32_bf16 v[98:101], v[22:25], v[38:41], v[98:101]
	v_mfma_f32_16x16x32_bf16 v[34:37], v[30:33], v[38:41], v[34:37]
	v_mfma_f32_16x16x32_bf16 v[38:41], v[18:21], v[42:45], 0
	v_mfma_f32_16x16x32_bf16 v[42:45], v[26:29], v[42:45], 0
	v_mfma_f32_16x16x32_bf16 v[38:41], v[22:25], v[46:49], v[38:41]
	v_mfma_f32_16x16x32_bf16 v[42:45], v[30:33], v[46:49], v[42:45]
	v_mfma_f32_16x16x32_bf16 v[46:49], v[18:21], v[50:53], 0
	v_mfma_f32_16x16x32_bf16 v[50:53], v[26:29], v[50:53], 0
	v_mfma_f32_16x16x32_bf16 v[46:49], v[22:25], v[54:57], v[46:49]
	v_mfma_f32_16x16x32_bf16 v[50:53], v[30:33], v[54:57], v[50:53]
	v_mfma_f32_16x16x32_bf16 v[54:57], v[18:21], v[58:61], 0
	v_mfma_f32_16x16x32_bf16 v[58:61], v[26:29], v[58:61], 0
	v_mfma_f32_16x16x32_bf16 v[54:57], v[22:25], v[62:65], v[54:57]
	v_mfma_f32_16x16x32_bf16 v[58:61], v[30:33], v[62:65], v[58:61]
	s_barrier
	v_lshl_add_u64 v[246:247], s[68:69], 0, v[172:173]
	s_add_i32 s85, s75, s44
	v_lshl_add_u64 v[130:131], v[246:247], 0, s[18:19]
	s_mov_b32 m0, s85
	s_add_i32 s87, s85, 0x2000
	ds_read_b128 v[62:65], v193 offset:16384
	ds_read_b128 v[102:105], v193 offset:17408
	ds_read_b128 v[106:109], v193 offset:18432
	ds_read_b128 v[110:113], v193 offset:19456
	ds_read_b128 v[114:117], v193 offset:20480
	ds_read_b128 v[118:121], v193 offset:21504
	ds_read_b128 v[122:125], v193 offset:22528
	ds_read_b128 v[126:129], v193 offset:23552
	global_load_lds_dwordx4 v[130:131], off
	v_lshl_add_u64 v[130:131], v[246:247], 0, s[20:21]
	s_mov_b32 m0, s87
	s_add_i32 s88, s76, s44
	global_load_lds_dwordx4 v[130:131], off
	v_lshl_add_u64 v[130:131], v[246:247], 0, s[22:23]
	s_mov_b32 m0, s88
	s_add_i32 s89, s88, 0x2000
	global_load_lds_dwordx4 v[130:131], off
	v_lshl_add_u64 v[130:131], v[246:247], 0, s[24:25]
	s_mov_b32 m0, s89
	s_nop 0
	global_load_lds_dwordx4 v[130:131], off
	v_lshl_add_u64 v[130:131], v[244:245], 0, s[18:19]
	s_mov_b32 m0, s45
	s_nop 0
	global_load_lds_dwordx4 v[130:131], off
	v_lshl_add_u64 v[130:131], v[244:245], 0, s[20:21]
	s_mov_b32 m0, s46
	s_nop 0
	global_load_lds_dwordx4 v[130:131], off
	s_waitcnt vmcnt(24)
	s_waitcnt lgkmcnt(0)
	s_barrier
	v_mfma_f32_16x16x32_bf16 v[130:133], v[2:5], v[62:65], 0
	v_mfma_f32_16x16x32_bf16 v[146:149], v[6:9], v[102:105], v[130:133]
	v_mfma_f32_16x16x32_bf16 v[130:133], v[10:13], v[62:65], 0
	v_mfma_f32_16x16x32_bf16 v[150:153], v[14:17], v[102:105], v[130:133]
	v_mfma_f32_16x16x32_bf16 v[130:133], v[2:5], v[106:109], 0
	v_mfma_f32_16x16x32_bf16 v[154:157], v[6:9], v[110:113], v[130:133]
	v_mfma_f32_16x16x32_bf16 v[130:133], v[10:13], v[106:109], 0
	v_mfma_f32_16x16x32_bf16 v[158:161], v[14:17], v[110:113], v[130:133]
	v_mfma_f32_16x16x32_bf16 v[130:133], v[2:5], v[114:117], 0
	v_mfma_f32_16x16x32_bf16 v[2:5], v[2:5], v[122:125], 0
	v_mfma_f32_16x16x32_bf16 v[162:165], v[6:9], v[118:121], v[130:133]
	v_mfma_f32_16x16x32_bf16 v[2:5], v[6:9], v[126:129], v[2:5]
	v_mfma_f32_16x16x32_bf16 v[6:9], v[10:13], v[122:125], 0
	v_mfma_f32_16x16x32_bf16 v[130:133], v[10:13], v[114:117], 0
	v_mfma_f32_16x16x32_bf16 v[6:9], v[14:17], v[126:129], v[6:9]
	v_mfma_f32_16x16x32_bf16 v[166:169], v[14:17], v[118:121], v[130:133]
	v_mfma_f32_16x16x32_bf16 v[10:13], v[18:21], v[62:65], 0
	v_mfma_f32_16x16x32_bf16 v[180:183], v[22:25], v[102:105], v[10:13]
	v_mfma_f32_16x16x32_bf16 v[10:13], v[26:29], v[62:65], 0
	v_mfma_f32_16x16x32_bf16 v[102:105], v[30:33], v[102:105], v[10:13]
	v_mfma_f32_16x16x32_bf16 v[10:13], v[18:21], v[106:109], 0
	v_mfma_f32_16x16x32_bf16 v[184:187], v[22:25], v[110:113], v[10:13]
	v_mfma_f32_16x16x32_bf16 v[10:13], v[26:29], v[106:109], 0
	v_mfma_f32_16x16x32_bf16 v[188:191], v[30:33], v[110:113], v[10:13]
	v_mfma_f32_16x16x32_bf16 v[10:13], v[18:21], v[114:117], 0
	v_mfma_f32_16x16x32_bf16 v[196:199], v[22:25], v[118:121], v[10:13]
	v_mfma_f32_16x16x32_bf16 v[10:13], v[26:29], v[114:117], 0
	v_mfma_f32_16x16x32_bf16 v[200:203], v[30:33], v[118:121], v[10:13]
	v_mfma_f32_16x16x32_bf16 v[10:13], v[18:21], v[122:125], 0
	v_mfma_f32_16x16x32_bf16 v[204:207], v[22:25], v[126:129], v[10:13]
	v_mfma_f32_16x16x32_bf16 v[10:13], v[26:29], v[122:125], 0
	v_mfma_f32_16x16x32_bf16 v[208:211], v[30:33], v[126:129], v[10:13]
	s_barrier
; #define PG8_WAIT_V(n) asm volatile("s_waitcnt vmcnt(" #n ")" ::: "memory")
; template <class Epi, class Sched, bool ALIGN_EPI = true, bool SP2 = true, bool FULLLINE = false, bool NOSTAGE = false, bool FP8 = false>
; __device__ __forceinline__ void gemm_phase(PG8_LAS unsigned char* lds, const Gemm g, const Sched& S, const Epi& E) {
;     ...
;         static_assert(SP2, "only the SP2 loop is kept");
;         { const int t = 0; if constexpr (Epi::NST == 16) PG8_ITER(PG8_WAIT_V(24)); else if constexpr (Epi::NST == 8) PG8_ITER(PG8_WAIT_V(16)); else PG8_ITER(PG8_WAIT_V(8)); }
;         for (int t = 2; t < nt; t += 2) PG8_ITER(PG8_WAIT_V(8));
	s_nop 5
	ds_read_b128 v[10:13], v194
	ds_read_b128 v[14:17], v194 offset:1024
	ds_read_b128 v[18:21], v194 offset:2048
	ds_read_b128 v[22:25], v194 offset:3072
	ds_read_b128 v[212:215], v195
	ds_read_b128 v[216:219], v195 offset:1024
	ds_read_b128 v[220:223], v195 offset:2048
	ds_read_b128 v[224:227], v195 offset:3072
	s_mov_b32 m0, s47
	v_lshl_add_u64 v[106:107], v[244:245], 0, s[22:23]
	ds_read_b128 v[26:29], v193 offset:32768
	ds_read_b128 v[30:33], v193 offset:33792
	ds_read_b128 v[62:65], v193 offset:34816
	ds_read_b128 v[114:117], v193 offset:35840
	ds_read_b128 v[228:231], v193 offset:36864
	ds_read_b128 v[232:235], v193 offset:37888
	ds_read_b128 v[236:239], v193 offset:38912
	ds_read_b128 v[240:243], v193 offset:39936
	global_load_lds_dwordx4 v[106:107], off
	v_lshl_add_u64 v[106:107], v[244:245], 0, s[24:25]
	s_mov_b32 m0, s52
	s_nop 0
	global_load_lds_dwordx4 v[106:107], off
	s_waitcnt vmcnt(8)
	s_waitcnt lgkmcnt(0)
	s_barrier
	v_mfma_f32_16x16x32_bf16 v[66:69], v[10:13], v[26:29], v[66:69]
	v_mfma_f32_16x16x32_bf16 v[142:145], v[14:17], v[30:33], v[66:69]
	v_mfma_f32_16x16x32_bf16 v[66:69], v[18:21], v[26:29], v[70:73]
	v_mfma_f32_16x16x32_bf16 v[138:141], v[22:25], v[30:33], v[66:69]
	v_mfma_f32_16x16x32_bf16 v[66:69], v[10:13], v[62:65], v[74:77]
	v_mfma_f32_16x16x32_bf16 v[126:129], v[14:17], v[114:117], v[66:69]
	v_mfma_f32_16x16x32_bf16 v[66:69], v[18:21], v[62:65], v[78:81]
	v_mfma_f32_16x16x32_bf16 v[122:125], v[22:25], v[114:117], v[66:69]
	v_mfma_f32_16x16x32_bf16 v[66:69], v[10:13], v[228:231], v[82:85]
	v_mfma_f32_16x16x32_bf16 v[110:113], v[14:17], v[232:235], v[66:69]
	v_mfma_f32_16x16x32_bf16 v[66:69], v[18:21], v[228:231], v[86:89]
	v_mfma_f32_16x16x32_bf16 v[106:109], v[22:25], v[232:235], v[66:69]
	v_mfma_f32_16x16x32_bf16 v[66:69], v[10:13], v[236:239], v[90:93]
	v_mfma_f32_16x16x32_bf16 v[78:81], v[14:17], v[240:243], v[66:69]
	v_mfma_f32_16x16x32_bf16 v[66:69], v[18:21], v[236:239], v[94:97]
	v_mfma_f32_16x16x32_bf16 v[74:77], v[22:25], v[240:243], v[66:69]
	v_mfma_f32_16x16x32_bf16 v[66:69], v[212:215], v[26:29], v[98:101]
	v_mfma_f32_16x16x32_bf16 v[26:29], v[220:223], v[26:29], v[34:37]
	v_mfma_f32_16x16x32_bf16 v[130:133], v[224:227], v[30:33], v[26:29]
	v_mfma_f32_16x16x32_bf16 v[26:29], v[212:215], v[62:65], v[38:41]
	v_mfma_f32_16x16x32_bf16 v[118:121], v[216:219], v[114:117], v[26:29]
	v_mfma_f32_16x16x32_bf16 v[26:29], v[220:223], v[62:65], v[42:45]
	v_mfma_f32_16x16x32_bf16 v[114:117], v[224:227], v[114:117], v[26:29]
	v_mfma_f32_16x16x32_bf16 v[26:29], v[212:215], v[228:231], v[46:49]
	v_mfma_f32_16x16x32_bf16 v[94:97], v[216:219], v[232:235], v[26:29]
	v_mfma_f32_16x16x32_bf16 v[26:29], v[220:223], v[228:231], v[50:53]
	v_mfma_f32_16x16x32_bf16 v[90:93], v[224:227], v[232:235], v[26:29]
	v_mfma_f32_16x16x32_bf16 v[26:29], v[212:215], v[236:239], v[54:57]
	v_mfma_f32_16x16x32_bf16 v[70:73], v[216:219], v[240:243], v[26:29]
	v_mfma_f32_16x16x32_bf16 v[26:29], v[220:223], v[236:239], v[58:61]
	v_mfma_f32_16x16x32_bf16 v[134:137], v[216:219], v[30:33], v[66:69]
	v_mfma_f32_16x16x32_bf16 v[66:69], v[224:227], v[240:243], v[26:29]
	s_barrier
	s_add_i32 s50, s77, s44
	s_nop 3
	v_lshl_add_u64 v[26:27], v[246:247], 0, s[26:27]
	s_mov_b32 m0, s50
	s_add_i32 s51, s50, 0x2000
	ds_read_b128 v[34:37], v193 offset:49152
	ds_read_b128 v[38:41], v193 offset:50176
	ds_read_b128 v[82:85], v193 offset:51200
	ds_read_b128 v[86:89], v193 offset:52224
	ds_read_b128 v[98:101], v193 offset:53248
	ds_read_b128 v[228:231], v193 offset:54272
	ds_read_b128 v[232:235], v193 offset:55296
	ds_read_b128 v[236:239], v193 offset:56320
	global_load_lds_dwordx4 v[26:27], off
	v_lshl_add_u64 v[26:27], v[246:247], 0, s[28:29]
	s_mov_b32 m0, s51
	s_mov_b64 s[0:1], 0x160180
	s_add_i32 s33, s78, s44
	global_load_lds_dwordx4 v[26:27], off
	v_lshl_add_u64 v[26:27], v[246:247], 0, s[0:1]
	s_mov_b32 m0, s33
	s_mov_b64 s[0:1], 0x210180
	s_add_i32 s56, s33, 0x2000
	global_load_lds_dwordx4 v[26:27], off
	v_lshl_add_u64 v[26:27], v[246:247], 0, s[0:1]
	s_mov_b32 m0, s56
	s_nop 0
	global_load_lds_dwordx4 v[26:27], off
	v_lshl_add_u64 v[26:27], v[244:245], 0, s[26:27]
	s_mov_b32 m0, s53
	s_nop 0
	global_load_lds_dwordx4 v[26:27], off
	v_lshl_add_u64 v[26:27], v[244:245], 0, s[28:29]
	s_mov_b32 m0, s54
	s_nop 0
	global_load_lds_dwordx4 v[26:27], off
	s_waitcnt vmcnt(8)
	s_waitcnt lgkmcnt(0)
	s_barrier
	v_mfma_f32_16x16x32_bf16 v[26:29], v[10:13], v[34:37], v[146:149]
	v_mfma_f32_16x16x32_bf16 v[62:65], v[14:17], v[38:41], v[26:29]
	v_mfma_f32_16x16x32_bf16 v[26:29], v[18:21], v[34:37], v[150:153]
	v_mfma_f32_16x16x32_bf16 v[58:61], v[22:25], v[38:41], v[26:29]
	v_mfma_f32_16x16x32_bf16 v[26:29], v[10:13], v[82:85], v[154:157]
	v_mfma_f32_16x16x32_bf16 v[46:49], v[14:17], v[86:89], v[26:29]
	v_mfma_f32_16x16x32_bf16 v[26:29], v[18:21], v[82:85], v[158:161]
	v_mfma_f32_16x16x32_bf16 v[42:45], v[22:25], v[86:89], v[26:29]
	v_mfma_f32_16x16x32_bf16 v[26:29], v[10:13], v[98:101], v[162:165]
	v_mfma_f32_16x16x32_bf16 v[2:5], v[10:13], v[232:235], v[2:5]
	v_mfma_f32_16x16x32_bf16 v[30:33], v[14:17], v[228:231], v[26:29]
	v_mfma_f32_16x16x32_bf16 v[26:29], v[18:21], v[98:101], v[166:169]
	v_mfma_f32_16x16x32_bf16 v[14:17], v[14:17], v[236:239], v[2:5]
	v_mfma_f32_16x16x32_bf16 v[2:5], v[18:21], v[232:235], v[6:9]
	v_mfma_f32_16x16x32_bf16 v[26:29], v[22:25], v[228:231], v[26:29]
	v_mfma_f32_16x16x32_bf16 v[10:13], v[22:25], v[236:239], v[2:5]
	v_mfma_f32_16x16x32_bf16 v[2:5], v[212:215], v[34:37], v[180:183]
	v_mfma_f32_16x16x32_bf16 v[54:57], v[216:219], v[38:41], v[2:5]
	v_mfma_f32_16x16x32_bf16 v[2:5], v[220:223], v[34:37], v[102:105]
	v_mfma_f32_16x16x32_bf16 v[50:53], v[224:227], v[38:41], v[2:5]
	v_mfma_f32_16x16x32_bf16 v[2:5], v[212:215], v[82:85], v[184:187]
	v_mfma_f32_16x16x32_bf16 v[38:41], v[216:219], v[86:89], v[2:5]
	v_mfma_f32_16x16x32_bf16 v[2:5], v[220:223], v[82:85], v[188:191]
	v_mfma_f32_16x16x32_bf16 v[34:37], v[224:227], v[86:89], v[2:5]
	v_mfma_f32_16x16x32_bf16 v[2:5], v[212:215], v[98:101], v[196:199]
	v_mfma_f32_16x16x32_bf16 v[22:25], v[216:219], v[228:231], v[2:5]
	v_mfma_f32_16x16x32_bf16 v[2:5], v[220:223], v[98:101], v[200:203]
	v_mfma_f32_16x16x32_bf16 v[18:21], v[224:227], v[228:231], v[2:5]
	v_mfma_f32_16x16x32_bf16 v[2:5], v[212:215], v[232:235], v[204:207]
	v_mfma_f32_16x16x32_bf16 v[6:9], v[216:219], v[236:239], v[2:5]
	v_mfma_f32_16x16x32_bf16 v[2:5], v[220:223], v[232:235], v[208:211]
	v_mfma_f32_16x16x32_bf16 v[2:5], v[224:227], v[236:239], v[2:5]
	s_barrier
	s_add_u32 s66, s66, 0x160180
	s_addc_u32 s67, s67, 0
	s_add_u32 s57, s68, 0x200
	s_addc_u32 s68, s69, 0
	s_mov_b32 s69, 0
.LBB0_2390:
	ds_read_b128 v[82:85], v1
	ds_read_b128 v[86:89], v1 offset:1024
	ds_read_b128 v[98:101], v1 offset:2048
	ds_read_b128 v[102:105], v1 offset:3072
	ds_read_b128 v[146:149], v192
	ds_read_b128 v[150:153], v192 offset:1024
	ds_read_b128 v[154:157], v192 offset:2048
	ds_read_b128 v[158:161], v192 offset:3072
	s_add_u32 s0, s66, 0xffea0080
	s_addc_u32 s1, s67, -1
	s_cmpk_eq_i32 s69, 0x54
	s_cselect_b32 s1, s11, s1
	s_cselect_b32 s0, s10, s0
	s_cselect_b32 s65, s63, s68
	s_cselect_b32 s64, s62, s57
	s_mov_b32 m0, s83
	v_lshl_add_u64 v[208:209], s[66:67], 0, v[174:175]
	ds_read_b128 v[162:165], v193
	ds_read_b128 v[166:169], v193 offset:1024
	ds_read_b128 v[180:183], v193 offset:2048
	ds_read_b128 v[184:187], v193 offset:3072
	ds_read_b128 v[188:191], v193 offset:4096
	ds_read_b128 v[196:199], v193 offset:5120
	ds_read_b128 v[200:203], v193 offset:6144
	ds_read_b128 v[204:207], v193 offset:7168
	global_load_lds_dwordx4 v[208:209], off
	v_lshl_add_u64 v[208:209], v[208:209], 0, s[30:31]
	s_mov_b32 m0, s84
	s_nop 0
	global_load_lds_dwordx4 v[208:209], off
	s_waitcnt vmcnt(8)
	s_waitcnt lgkmcnt(0)
	s_barrier
	v_mfma_f32_16x16x32_bf16 v[142:145], v[82:85], v[162:165], v[142:145]
	v_mfma_f32_16x16x32_bf16 v[138:141], v[98:101], v[162:165], v[138:141]
	v_mfma_f32_16x16x32_bf16 v[126:129], v[82:85], v[180:183], v[126:129]
	v_mfma_f32_16x16x32_bf16 v[122:125], v[98:101], v[180:183], v[122:125]
	v_mfma_f32_16x16x32_bf16 v[110:113], v[82:85], v[188:191], v[110:113]
	v_mfma_f32_16x16x32_bf16 v[106:109], v[98:101], v[188:191], v[106:109]
	v_mfma_f32_16x16x32_bf16 v[78:81], v[82:85], v[200:203], v[78:81]
	v_mfma_f32_16x16x32_bf16 v[74:77], v[98:101], v[200:203], v[74:77]
	v_mfma_f32_16x16x32_bf16 v[142:145], v[86:89], v[166:169], v[142:145]
	v_mfma_f32_16x16x32_bf16 v[138:141], v[102:105], v[166:169], v[138:141]
	v_mfma_f32_16x16x32_bf16 v[126:129], v[86:89], v[184:187], v[126:129]
	v_mfma_f32_16x16x32_bf16 v[122:125], v[102:105], v[184:187], v[122:125]
	v_mfma_f32_16x16x32_bf16 v[110:113], v[86:89], v[196:199], v[110:113]
	v_mfma_f32_16x16x32_bf16 v[106:109], v[102:105], v[196:199], v[106:109]
	v_mfma_f32_16x16x32_bf16 v[78:81], v[86:89], v[204:207], v[78:81]
	v_mfma_f32_16x16x32_bf16 v[74:77], v[102:105], v[204:207], v[74:77]
	v_mfma_f32_16x16x32_bf16 v[134:137], v[146:149], v[162:165], v[134:137]
	v_mfma_f32_16x16x32_bf16 v[130:133], v[154:157], v[162:165], v[130:133]
	v_mfma_f32_16x16x32_bf16 v[118:121], v[146:149], v[180:183], v[118:121]
	v_mfma_f32_16x16x32_bf16 v[114:117], v[154:157], v[180:183], v[114:117]
	v_mfma_f32_16x16x32_bf16 v[94:97], v[146:149], v[188:191], v[94:97]
	v_mfma_f32_16x16x32_bf16 v[90:93], v[154:157], v[188:191], v[90:93]
	v_mfma_f32_16x16x32_bf16 v[70:73], v[146:149], v[200:203], v[70:73]
	v_mfma_f32_16x16x32_bf16 v[66:69], v[154:157], v[200:203], v[66:69]
	v_mfma_f32_16x16x32_bf16 v[134:137], v[150:153], v[166:169], v[134:137]
	v_mfma_f32_16x16x32_bf16 v[130:133], v[158:161], v[166:169], v[130:133]
	v_mfma_f32_16x16x32_bf16 v[118:121], v[150:153], v[184:187], v[118:121]
	v_mfma_f32_16x16x32_bf16 v[114:117], v[158:161], v[184:187], v[114:117]
	v_mfma_f32_16x16x32_bf16 v[94:97], v[150:153], v[196:199], v[94:97]
	v_mfma_f32_16x16x32_bf16 v[90:93], v[158:161], v[196:199], v[90:93]
	v_mfma_f32_16x16x32_bf16 v[70:73], v[150:153], v[204:207], v[70:73]
	v_mfma_f32_16x16x32_bf16 v[66:69], v[158:161], v[204:207], v[66:69]
	s_barrier
	s_mov_b32 m0, s85
	v_lshl_add_u64 v[208:209], s[64:65], 0, v[172:173]
	ds_read_b128 v[162:165], v193 offset:16384
	ds_read_b128 v[166:169], v193 offset:17408
	ds_read_b128 v[180:183], v193 offset:18432
	ds_read_b128 v[184:187], v193 offset:19456
	ds_read_b128 v[188:191], v193 offset:20480
	ds_read_b128 v[196:199], v193 offset:21504
	ds_read_b128 v[200:203], v193 offset:22528
	ds_read_b128 v[204:207], v193 offset:23552
	global_load_lds_dwordx4 v[208:209], off
	v_lshl_add_u64 v[210:211], v[208:209], 0, s[30:31]
	s_mov_b32 m0, s87
	s_nop 0
	global_load_lds_dwordx4 v[210:211], off
	v_lshl_add_u64 v[210:211], v[208:209], 0, s[34:35]
	s_mov_b32 m0, s88
	s_nop 0
	global_load_lds_dwordx4 v[210:211], off
	v_lshl_add_u64 v[210:211], v[208:209], 0, s[36:37]
	s_mov_b32 m0, s89
	s_nop 0
	global_load_lds_dwordx4 v[210:211], off
	v_lshl_add_u64 v[210:211], s[0:1], 0, v[170:171]
	s_mov_b32 m0, s45
	v_lshl_add_u64 v[212:213], v[210:211], 0, s[30:31]
	global_load_lds_dwordx4 v[210:211], off
	s_mov_b32 m0, s46
	s_nop 0
	global_load_lds_dwordx4 v[212:213], off
	s_waitcnt vmcnt(8)
	s_waitcnt lgkmcnt(0)
	s_barrier
	v_mfma_f32_16x16x32_bf16 v[62:65], v[82:85], v[162:165], v[62:65]
	v_mfma_f32_16x16x32_bf16 v[58:61], v[98:101], v[162:165], v[58:61]
	v_mfma_f32_16x16x32_bf16 v[46:49], v[82:85], v[180:183], v[46:49]
	v_mfma_f32_16x16x32_bf16 v[42:45], v[98:101], v[180:183], v[42:45]
	v_mfma_f32_16x16x32_bf16 v[30:33], v[82:85], v[188:191], v[30:33]
	v_mfma_f32_16x16x32_bf16 v[26:29], v[98:101], v[188:191], v[26:29]
	v_mfma_f32_16x16x32_bf16 v[14:17], v[82:85], v[200:203], v[14:17]
	v_mfma_f32_16x16x32_bf16 v[10:13], v[98:101], v[200:203], v[10:13]
	v_mfma_f32_16x16x32_bf16 v[62:65], v[86:89], v[166:169], v[62:65]
	v_mfma_f32_16x16x32_bf16 v[58:61], v[102:105], v[166:169], v[58:61]
	v_mfma_f32_16x16x32_bf16 v[46:49], v[86:89], v[184:187], v[46:49]
	v_mfma_f32_16x16x32_bf16 v[42:45], v[102:105], v[184:187], v[42:45]
	v_mfma_f32_16x16x32_bf16 v[30:33], v[86:89], v[196:199], v[30:33]
	v_mfma_f32_16x16x32_bf16 v[26:29], v[102:105], v[196:199], v[26:29]
	v_mfma_f32_16x16x32_bf16 v[14:17], v[86:89], v[204:207], v[14:17]
	v_mfma_f32_16x16x32_bf16 v[10:13], v[102:105], v[204:207], v[10:13]
	v_mfma_f32_16x16x32_bf16 v[54:57], v[146:149], v[162:165], v[54:57]
	v_mfma_f32_16x16x32_bf16 v[50:53], v[154:157], v[162:165], v[50:53]
	v_mfma_f32_16x16x32_bf16 v[38:41], v[146:149], v[180:183], v[38:41]
	v_mfma_f32_16x16x32_bf16 v[34:37], v[154:157], v[180:183], v[34:37]
	v_mfma_f32_16x16x32_bf16 v[22:25], v[146:149], v[188:191], v[22:25]
	v_mfma_f32_16x16x32_bf16 v[18:21], v[154:157], v[188:191], v[18:21]
	v_mfma_f32_16x16x32_bf16 v[6:9], v[146:149], v[200:203], v[6:9]
	v_mfma_f32_16x16x32_bf16 v[2:5], v[154:157], v[200:203], v[2:5]
	v_mfma_f32_16x16x32_bf16 v[54:57], v[150:153], v[166:169], v[54:57]
	v_mfma_f32_16x16x32_bf16 v[50:53], v[158:161], v[166:169], v[50:53]
	v_mfma_f32_16x16x32_bf16 v[38:41], v[150:153], v[184:187], v[38:41]
	v_mfma_f32_16x16x32_bf16 v[34:37], v[158:161], v[184:187], v[34:37]
	v_mfma_f32_16x16x32_bf16 v[22:25], v[150:153], v[196:199], v[22:25]
	v_mfma_f32_16x16x32_bf16 v[18:21], v[158:161], v[196:199], v[18:21]
	v_mfma_f32_16x16x32_bf16 v[6:9], v[150:153], v[204:207], v[6:9]
	v_mfma_f32_16x16x32_bf16 v[2:5], v[158:161], v[204:207], v[2:5]
	s_barrier
; #define PG8_WAIT_V(n) asm volatile("s_waitcnt vmcnt(" #n ")" ::: "memory")
; #define PG8_BAR __builtin_amdgcn_s_barrier()
; template <class Epi, class Sched, bool ALIGN_EPI = true, bool SP2 = true, bool FULLLINE = false, bool NOSTAGE = false, bool FP8 = false>
; __device__ __forceinline__ void gemm_phase(PG8_LAS unsigned char* lds, const Gemm g, const Sched& S, const Epi& E) {
;     ...
;         static_assert(SP2, "only the SP2 loop is kept");
;         { const int t = 0; if constexpr (Epi::NST == 16) PG8_ITER(PG8_WAIT_V(24)); else if constexpr (Epi::NST == 8) PG8_ITER(PG8_WAIT_V(16)); else PG8_ITER(PG8_WAIT_V(8)); }
;         for (int t = 2; t < nt; t += 2) PG8_ITER(PG8_WAIT_V(8));
;     ...
;         if constexpr (ALIGN_EPI) { if (wr == 0) PG8_BAR; }
;         { int ln_ = lane; asm volatile("" : "+v"(ln_));
;           E(acc, cur, wr, wc, ln_ & 15, ln_ >> 4); } S.done(cur);
;         if (!has_next) break;
	ds_read_b128 v[82:85], v194
	ds_read_b128 v[86:89], v194 offset:1024
	ds_read_b128 v[98:101], v194 offset:2048
	ds_read_b128 v[102:105], v194 offset:3072
	ds_read_b128 v[146:149], v195
	ds_read_b128 v[150:153], v195 offset:1024
	ds_read_b128 v[154:157], v195 offset:2048
	ds_read_b128 v[158:161], v195 offset:3072
	s_mov_b32 m0, s47
	v_lshl_add_u64 v[212:213], v[210:211], 0, s[34:35]
	ds_read_b128 v[162:165], v193 offset:32768
	ds_read_b128 v[166:169], v193 offset:33792
	ds_read_b128 v[180:183], v193 offset:34816
	ds_read_b128 v[184:187], v193 offset:35840
	ds_read_b128 v[188:191], v193 offset:36864
	ds_read_b128 v[196:199], v193 offset:37888
	ds_read_b128 v[200:203], v193 offset:38912
	ds_read_b128 v[204:207], v193 offset:39936
	global_load_lds_dwordx4 v[212:213], off
	v_lshl_add_u64 v[212:213], v[210:211], 0, s[36:37]
	s_mov_b32 m0, s52
	s_nop 0
	global_load_lds_dwordx4 v[212:213], off
	s_waitcnt vmcnt(8)
	s_waitcnt lgkmcnt(0)
	s_barrier
	v_mfma_f32_16x16x32_bf16 v[142:145], v[82:85], v[162:165], v[142:145]
	v_mfma_f32_16x16x32_bf16 v[138:141], v[98:101], v[162:165], v[138:141]
	v_mfma_f32_16x16x32_bf16 v[126:129], v[82:85], v[180:183], v[126:129]
	v_mfma_f32_16x16x32_bf16 v[122:125], v[98:101], v[180:183], v[122:125]
	v_mfma_f32_16x16x32_bf16 v[110:113], v[82:85], v[188:191], v[110:113]
	v_mfma_f32_16x16x32_bf16 v[106:109], v[98:101], v[188:191], v[106:109]
	v_mfma_f32_16x16x32_bf16 v[78:81], v[82:85], v[200:203], v[78:81]
	v_mfma_f32_16x16x32_bf16 v[74:77], v[98:101], v[200:203], v[74:77]
	v_mfma_f32_16x16x32_bf16 v[142:145], v[86:89], v[166:169], v[142:145]
	v_mfma_f32_16x16x32_bf16 v[138:141], v[102:105], v[166:169], v[138:141]
	v_mfma_f32_16x16x32_bf16 v[126:129], v[86:89], v[184:187], v[126:129]
	v_mfma_f32_16x16x32_bf16 v[122:125], v[102:105], v[184:187], v[122:125]
	v_mfma_f32_16x16x32_bf16 v[110:113], v[86:89], v[196:199], v[110:113]
	v_mfma_f32_16x16x32_bf16 v[106:109], v[102:105], v[196:199], v[106:109]
	v_mfma_f32_16x16x32_bf16 v[78:81], v[86:89], v[204:207], v[78:81]
	v_mfma_f32_16x16x32_bf16 v[74:77], v[102:105], v[204:207], v[74:77]
	v_mfma_f32_16x16x32_bf16 v[134:137], v[146:149], v[162:165], v[134:137]
	v_mfma_f32_16x16x32_bf16 v[130:133], v[154:157], v[162:165], v[130:133]
	v_mfma_f32_16x16x32_bf16 v[118:121], v[146:149], v[180:183], v[118:121]
	v_mfma_f32_16x16x32_bf16 v[114:117], v[154:157], v[180:183], v[114:117]
	v_mfma_f32_16x16x32_bf16 v[94:97], v[146:149], v[188:191], v[94:97]
	v_mfma_f32_16x16x32_bf16 v[90:93], v[154:157], v[188:191], v[90:93]
	v_mfma_f32_16x16x32_bf16 v[70:73], v[146:149], v[200:203], v[70:73]
	v_mfma_f32_16x16x32_bf16 v[66:69], v[154:157], v[200:203], v[66:69]
	v_mfma_f32_16x16x32_bf16 v[134:137], v[150:153], v[166:169], v[134:137]
	v_mfma_f32_16x16x32_bf16 v[130:133], v[158:161], v[166:169], v[130:133]
	v_mfma_f32_16x16x32_bf16 v[118:121], v[150:153], v[184:187], v[118:121]
	v_mfma_f32_16x16x32_bf16 v[114:117], v[158:161], v[184:187], v[114:117]
	v_mfma_f32_16x16x32_bf16 v[94:97], v[150:153], v[196:199], v[94:97]
	v_mfma_f32_16x16x32_bf16 v[90:93], v[158:161], v[196:199], v[90:93]
	v_mfma_f32_16x16x32_bf16 v[70:73], v[150:153], v[204:207], v[70:73]
	v_mfma_f32_16x16x32_bf16 v[66:69], v[158:161], v[204:207], v[66:69]
	s_barrier
	s_mov_b32 m0, s50
	v_lshl_add_u64 v[212:213], v[208:209], 0, s[38:39]
	ds_read_b128 v[162:165], v193 offset:49152
	ds_read_b128 v[166:169], v193 offset:50176
	ds_read_b128 v[180:183], v193 offset:51200
	ds_read_b128 v[184:187], v193 offset:52224
	ds_read_b128 v[188:191], v193 offset:53248
	ds_read_b128 v[196:199], v193 offset:54272
	ds_read_b128 v[200:203], v193 offset:55296
	ds_read_b128 v[204:207], v193 offset:56320
	global_load_lds_dwordx4 v[212:213], off
	v_lshl_add_u64 v[212:213], v[208:209], 0, s[40:41]
	s_mov_b32 m0, s51
	s_nop 0
	global_load_lds_dwordx4 v[212:213], off
	v_lshl_add_u64 v[212:213], v[208:209], 0, s[14:15]
	s_mov_b32 m0, s33
	v_lshl_add_u64 v[208:209], v[208:209], 0, s[16:17]
	global_load_lds_dwordx4 v[212:213], off
	s_mov_b32 m0, s56
	s_nop 0
	global_load_lds_dwordx4 v[208:209], off
	v_lshl_add_u64 v[208:209], v[210:211], 0, s[38:39]
	s_mov_b32 m0, s53
	s_nop 0
	global_load_lds_dwordx4 v[208:209], off
	v_lshl_add_u64 v[208:209], v[210:211], 0, s[40:41]
	s_mov_b32 m0, s54
	s_nop 0
	global_load_lds_dwordx4 v[208:209], off
	s_waitcnt vmcnt(8)
	s_waitcnt lgkmcnt(0)
	s_barrier
	v_mfma_f32_16x16x32_bf16 v[62:65], v[82:85], v[162:165], v[62:65]
	v_mfma_f32_16x16x32_bf16 v[58:61], v[98:101], v[162:165], v[58:61]
	v_mfma_f32_16x16x32_bf16 v[46:49], v[82:85], v[180:183], v[46:49]
	v_mfma_f32_16x16x32_bf16 v[42:45], v[98:101], v[180:183], v[42:45]
	v_mfma_f32_16x16x32_bf16 v[30:33], v[82:85], v[188:191], v[30:33]
	v_mfma_f32_16x16x32_bf16 v[26:29], v[98:101], v[188:191], v[26:29]
	v_mfma_f32_16x16x32_bf16 v[14:17], v[82:85], v[200:203], v[14:17]
	v_mfma_f32_16x16x32_bf16 v[10:13], v[98:101], v[200:203], v[10:13]
	v_mfma_f32_16x16x32_bf16 v[62:65], v[86:89], v[166:169], v[62:65]
	v_mfma_f32_16x16x32_bf16 v[58:61], v[102:105], v[166:169], v[58:61]
	v_mfma_f32_16x16x32_bf16 v[46:49], v[86:89], v[184:187], v[46:49]
	v_mfma_f32_16x16x32_bf16 v[42:45], v[102:105], v[184:187], v[42:45]
	v_mfma_f32_16x16x32_bf16 v[30:33], v[86:89], v[196:199], v[30:33]
	v_mfma_f32_16x16x32_bf16 v[26:29], v[102:105], v[196:199], v[26:29]
	v_mfma_f32_16x16x32_bf16 v[14:17], v[86:89], v[204:207], v[14:17]
	v_mfma_f32_16x16x32_bf16 v[10:13], v[102:105], v[204:207], v[10:13]
	v_mfma_f32_16x16x32_bf16 v[54:57], v[146:149], v[162:165], v[54:57]
	v_mfma_f32_16x16x32_bf16 v[50:53], v[154:157], v[162:165], v[50:53]
	v_mfma_f32_16x16x32_bf16 v[38:41], v[146:149], v[180:183], v[38:41]
	v_mfma_f32_16x16x32_bf16 v[34:37], v[154:157], v[180:183], v[34:37]
	v_mfma_f32_16x16x32_bf16 v[22:25], v[146:149], v[188:191], v[22:25]
	v_mfma_f32_16x16x32_bf16 v[18:21], v[154:157], v[188:191], v[18:21]
	v_mfma_f32_16x16x32_bf16 v[6:9], v[146:149], v[200:203], v[6:9]
	v_mfma_f32_16x16x32_bf16 v[2:5], v[154:157], v[200:203], v[2:5]
	v_mfma_f32_16x16x32_bf16 v[54:57], v[150:153], v[166:169], v[54:57]
	v_mfma_f32_16x16x32_bf16 v[50:53], v[158:161], v[166:169], v[50:53]
	v_mfma_f32_16x16x32_bf16 v[38:41], v[150:153], v[184:187], v[38:41]
	v_mfma_f32_16x16x32_bf16 v[34:37], v[158:161], v[184:187], v[34:37]
	v_mfma_f32_16x16x32_bf16 v[22:25], v[150:153], v[196:199], v[22:25]
	v_mfma_f32_16x16x32_bf16 v[18:21], v[158:161], v[196:199], v[18:21]
	v_mfma_f32_16x16x32_bf16 v[6:9], v[150:153], v[204:207], v[6:9]
	v_mfma_f32_16x16x32_bf16 v[2:5], v[158:161], v[204:207], v[2:5]
	s_barrier
	s_add_i32 s69, s69, 2
	s_add_u32 s66, s66, 0x100
	s_addc_u32 s67, s67, 0
	s_add_u32 s57, s57, 0x100
	s_addc_u32 s68, s68, 0
	s_cmpk_gt_u32 s69, 0x55
	s_cbranch_scc0 .LBB0_2390
	s_and_b64 vcc, exec, s[12:13]
	s_cbranch_vccz .LBB0_2393
	s_barrier

; template <class Epi, class Sched, bool ALIGN_EPI = true, bool SP2 = true, bool FULLLINE = false, bool NOSTAGE = false, bool FP8 = false>
; __device__ __forceinline__ void gemm_phase(PG8_LAS unsigned char* lds, const Gemm g, const Sched& S, const Epi& E) {
;     ...
;         const bool has_next = S.next(ui + 1, nxt);
;         const char* nA = has_next ? PG8_ABASE(nxt) : cA; const char* nB = has_next ? PG8_BBASE(nxt) : cB;
.LBB0_2681:
	ds_read_b128 v[2:5], v1
	ds_read_b128 v[6:9], v1 offset:1024
	ds_read_b128 v[10:13], v1 offset:2048
	ds_read_b128 v[14:17], v1 offset:3072
	ds_read_b128 v[18:21], v200
	ds_read_b128 v[22:25], v200 offset:1024
	ds_read_b128 v[26:29], v200 offset:2048
	ds_read_b128 v[30:33], v200 offset:3072
	s_ashr_i32 s31, s30, 31
	s_lshl_b64 s[0:1], s[30:31], 18
	s_add_u32 s38, s43, s0
	s_addc_u32 s39, s46, s1
	s_and_b64 s[0:1], s[10:11], exec
	s_cselect_b32 s31, s39, s63
	s_cselect_b32 s35, s38, s62
	v_lshl_add_u64 v[244:245], s[66:67], 0, v[178:179]
	s_mov_b64 s[0:1], 0x80080
	s_add_i32 s79, s41, 0xc000
	v_lshl_add_u64 v[66:67], v[244:245], 0, s[0:1]
	s_mov_b32 m0, s79
	s_mov_b64 s[0:1], 0xc0080
	s_add_i32 s80, s41, 0xe000
	ds_read_b128 v[34:37], v201
	ds_read_b128 v[38:41], v201 offset:1024
	ds_read_b128 v[42:45], v201 offset:2048
	ds_read_b128 v[46:49], v201 offset:3072
	ds_read_b128 v[50:53], v201 offset:4096
	ds_read_b128 v[54:57], v201 offset:5120
	ds_read_b128 v[58:61], v201 offset:6144
	ds_read_b128 v[62:65], v201 offset:7168
	global_load_lds_dwordx4 v[66:67], off
	v_lshl_add_u64 v[66:67], v[244:245], 0, s[0:1]
	s_mov_b32 m0, s80
	s_nop 0
	global_load_lds_dwordx4 v[66:67], off
	s_waitcnt vmcnt(24)
	s_waitcnt lgkmcnt(0)
	s_barrier
	v_mfma_f32_16x16x32_bf16 v[66:69], v[2:5], v[34:37], 0
	v_mfma_f32_16x16x32_bf16 v[70:73], v[10:13], v[34:37], 0
	v_mfma_f32_16x16x32_bf16 v[74:77], v[2:5], v[42:45], 0
	v_mfma_f32_16x16x32_bf16 v[78:81], v[10:13], v[42:45], 0
	v_mfma_f32_16x16x32_bf16 v[82:85], v[2:5], v[50:53], 0
	v_mfma_f32_16x16x32_bf16 v[90:93], v[2:5], v[58:61], 0
	v_mfma_f32_16x16x32_bf16 v[66:69], v[6:9], v[38:41], v[66:69]
	v_mfma_f32_16x16x32_bf16 v[70:73], v[14:17], v[38:41], v[70:73]
	v_mfma_f32_16x16x32_bf16 v[74:77], v[6:9], v[46:49], v[74:77]
	v_mfma_f32_16x16x32_bf16 v[78:81], v[14:17], v[46:49], v[78:81]
	v_mfma_f32_16x16x32_bf16 v[82:85], v[6:9], v[54:57], v[82:85]
	v_mfma_f32_16x16x32_bf16 v[86:89], v[10:13], v[50:53], 0
	v_mfma_f32_16x16x32_bf16 v[90:93], v[6:9], v[62:65], v[90:93]
	v_mfma_f32_16x16x32_bf16 v[94:97], v[10:13], v[58:61], 0
	v_mfma_f32_16x16x32_bf16 v[86:89], v[14:17], v[54:57], v[86:89]
	v_mfma_f32_16x16x32_bf16 v[94:97], v[14:17], v[62:65], v[94:97]
	v_mfma_f32_16x16x32_bf16 v[98:101], v[18:21], v[34:37], 0
	v_mfma_f32_16x16x32_bf16 v[34:37], v[26:29], v[34:37], 0
	v_mfma_f32_16x16x32_bf16 v[102:105], v[22:25], v[38:41], v[98:101]
	v_mfma_f32_16x16x32_bf16 v[34:37], v[30:33], v[38:41], v[34:37]
	v_mfma_f32_16x16x32_bf16 v[38:41], v[18:21], v[42:45], 0
	v_mfma_f32_16x16x32_bf16 v[42:45], v[26:29], v[42:45], 0
	v_mfma_f32_16x16x32_bf16 v[38:41], v[22:25], v[46:49], v[38:41]
	v_mfma_f32_16x16x32_bf16 v[42:45], v[30:33], v[46:49], v[42:45]
	v_mfma_f32_16x16x32_bf16 v[46:49], v[18:21], v[50:53], 0
	v_mfma_f32_16x16x32_bf16 v[50:53], v[26:29], v[50:53], 0
	v_mfma_f32_16x16x32_bf16 v[46:49], v[22:25], v[54:57], v[46:49]
	v_mfma_f32_16x16x32_bf16 v[50:53], v[30:33], v[54:57], v[50:53]
	v_mfma_f32_16x16x32_bf16 v[54:57], v[18:21], v[58:61], 0
	v_mfma_f32_16x16x32_bf16 v[58:61], v[26:29], v[58:61], 0
	v_mfma_f32_16x16x32_bf16 v[54:57], v[22:25], v[62:65], v[54:57]
	v_mfma_f32_16x16x32_bf16 v[58:61], v[30:33], v[62:65], v[58:61]
	s_barrier
	v_lshl_add_u64 v[246:247], s[62:63], 0, v[180:181]
	s_add_i32 s81, s75, s47
	v_lshl_add_u64 v[130:131], v[246:247], 0, s[18:19]
	s_mov_b32 m0, s81
	s_mov_b64 s[0:1], 0x10100
	s_add_i32 s82, s81, 0x2000
	ds_read_b128 v[62:65], v201 offset:16384
	ds_read_b128 v[98:101], v201 offset:17408
	ds_read_b128 v[106:109], v201 offset:18432
	ds_read_b128 v[110:113], v201 offset:19456
	ds_read_b128 v[114:117], v201 offset:20480
	ds_read_b128 v[118:121], v201 offset:21504
	ds_read_b128 v[122:125], v201 offset:22528
	ds_read_b128 v[126:129], v201 offset:23552
	global_load_lds_dwordx4 v[130:131], off
	v_lshl_add_u64 v[130:131], v[246:247], 0, s[0:1]
	s_mov_b32 m0, s82
	s_mov_b64 s[0:1], 0x20100
	s_add_i32 s83, s76, s47
	global_load_lds_dwordx4 v[130:131], off
	v_lshl_add_u64 v[130:131], v[246:247], 0, s[0:1]
	s_mov_b32 m0, s83
	s_mov_b64 s[0:1], 0x30100
	s_add_i32 s84, s83, 0x2000
	global_load_lds_dwordx4 v[130:131], off
	v_lshl_add_u64 v[130:131], v[246:247], 0, s[0:1]
	s_mov_b32 m0, s84
	s_mov_b64 s[0:1], 0x40100
	global_load_lds_dwordx4 v[130:131], off
	v_lshl_add_u64 v[130:131], v[244:245], 0, s[18:19]
	s_mov_b32 m0, s41
	s_nop 0
	global_load_lds_dwordx4 v[130:131], off
	v_lshl_add_u64 v[130:131], v[244:245], 0, s[0:1]
	s_mov_b32 m0, s45
	s_nop 0
	global_load_lds_dwordx4 v[130:131], off
	s_waitcnt vmcnt(24)
	s_waitcnt lgkmcnt(0)
	s_barrier
	v_mfma_f32_16x16x32_bf16 v[130:133], v[2:5], v[62:65], 0
	v_mfma_f32_16x16x32_bf16 v[146:149], v[6:9], v[98:101], v[130:133]
	v_mfma_f32_16x16x32_bf16 v[130:133], v[10:13], v[62:65], 0
	v_mfma_f32_16x16x32_bf16 v[150:153], v[14:17], v[98:101], v[130:133]
	v_mfma_f32_16x16x32_bf16 v[130:133], v[2:5], v[106:109], 0
	v_mfma_f32_16x16x32_bf16 v[154:157], v[6:9], v[110:113], v[130:133]
	v_mfma_f32_16x16x32_bf16 v[130:133], v[10:13], v[106:109], 0
	v_mfma_f32_16x16x32_bf16 v[158:161], v[14:17], v[110:113], v[130:133]
	v_mfma_f32_16x16x32_bf16 v[130:133], v[2:5], v[114:117], 0
	v_mfma_f32_16x16x32_bf16 v[2:5], v[2:5], v[122:125], 0
	v_mfma_f32_16x16x32_bf16 v[162:165], v[6:9], v[118:121], v[130:133]
	v_mfma_f32_16x16x32_bf16 v[2:5], v[6:9], v[126:129], v[2:5]
	v_mfma_f32_16x16x32_bf16 v[6:9], v[10:13], v[122:125], 0
	v_mfma_f32_16x16x32_bf16 v[130:133], v[10:13], v[114:117], 0
	v_mfma_f32_16x16x32_bf16 v[6:9], v[14:17], v[126:129], v[6:9]
	v_mfma_f32_16x16x32_bf16 v[166:169], v[14:17], v[118:121], v[130:133]
	v_mfma_f32_16x16x32_bf16 v[10:13], v[18:21], v[62:65], 0
	v_mfma_f32_16x16x32_bf16 v[170:173], v[22:25], v[98:101], v[10:13]
	v_mfma_f32_16x16x32_bf16 v[10:13], v[26:29], v[62:65], 0
	v_mfma_f32_16x16x32_bf16 v[174:177], v[30:33], v[98:101], v[10:13]
	v_mfma_f32_16x16x32_bf16 v[10:13], v[18:21], v[106:109], 0
	v_mfma_f32_16x16x32_bf16 v[188:191], v[22:25], v[110:113], v[10:13]
	v_mfma_f32_16x16x32_bf16 v[10:13], v[26:29], v[106:109], 0
	v_mfma_f32_16x16x32_bf16 v[106:109], v[30:33], v[110:113], v[10:13]
	v_mfma_f32_16x16x32_bf16 v[10:13], v[18:21], v[114:117], 0
	v_mfma_f32_16x16x32_bf16 v[192:195], v[22:25], v[118:121], v[10:13]
	v_mfma_f32_16x16x32_bf16 v[10:13], v[26:29], v[114:117], 0
	v_mfma_f32_16x16x32_bf16 v[196:199], v[30:33], v[118:121], v[10:13]
	v_mfma_f32_16x16x32_bf16 v[10:13], v[18:21], v[122:125], 0
	v_mfma_f32_16x16x32_bf16 v[204:207], v[22:25], v[126:129], v[10:13]
	v_mfma_f32_16x16x32_bf16 v[10:13], v[26:29], v[122:125], 0
	v_mfma_f32_16x16x32_bf16 v[208:211], v[30:33], v[126:129], v[10:13]
	s_barrier
; #define PG8_WAIT_V(n) asm volatile("s_waitcnt vmcnt(" #n ")" ::: "memory")
; template <class Epi, class Sched, bool ALIGN_EPI = true, bool SP2 = true, bool FULLLINE = false, bool NOSTAGE = false, bool FP8 = false>
; __device__ __forceinline__ void gemm_phase(PG8_LAS unsigned char* lds, const Gemm g, const Sched& S, const Epi& E) {
;     ...
;         static_assert(SP2, "only the SP2 loop is kept");
;         { const int t = 0; if constexpr (Epi::NST == 16) PG8_ITER(PG8_WAIT_V(24)); else if constexpr (Epi::NST == 8) PG8_ITER(PG8_WAIT_V(16)); else PG8_ITER(PG8_WAIT_V(8)); }
;         for (int t = 2; t < nt; t += 2) PG8_ITER(PG8_WAIT_V(8));
	s_nop 5
	ds_read_b128 v[10:13], v202
	ds_read_b128 v[14:17], v202 offset:1024
	ds_read_b128 v[18:21], v202 offset:2048
	ds_read_b128 v[22:25], v202 offset:3072
	ds_read_b128 v[212:215], v203
	ds_read_b128 v[216:219], v203 offset:1024
	ds_read_b128 v[220:223], v203 offset:2048
	ds_read_b128 v[224:227], v203 offset:3072
	s_mov_b64 s[0:1], 0x80100
	s_mov_b32 m0, s52
	v_lshl_add_u64 v[98:99], v[244:245], 0, s[0:1]
	s_mov_b64 s[0:1], 0xc0100
	ds_read_b128 v[26:29], v201 offset:32768
	ds_read_b128 v[30:33], v201 offset:33792
	ds_read_b128 v[62:65], v201 offset:34816
	ds_read_b128 v[114:117], v201 offset:35840
	ds_read_b128 v[228:231], v201 offset:36864
	ds_read_b128 v[232:235], v201 offset:37888
	ds_read_b128 v[236:239], v201 offset:38912
	ds_read_b128 v[240:243], v201 offset:39936
	global_load_lds_dwordx4 v[98:99], off
	v_lshl_add_u64 v[98:99], v[244:245], 0, s[0:1]
	s_mov_b32 m0, s53
	s_nop 0
	global_load_lds_dwordx4 v[98:99], off
	s_waitcnt vmcnt(8)
	s_waitcnt lgkmcnt(0)
	s_barrier
	v_mfma_f32_16x16x32_bf16 v[66:69], v[10:13], v[26:29], v[66:69]
	v_mfma_f32_16x16x32_bf16 v[134:137], v[14:17], v[30:33], v[66:69]
	v_mfma_f32_16x16x32_bf16 v[66:69], v[18:21], v[26:29], v[70:73]
	v_mfma_f32_16x16x32_bf16 v[130:133], v[22:25], v[30:33], v[66:69]
	v_mfma_f32_16x16x32_bf16 v[66:69], v[10:13], v[62:65], v[74:77]
	v_mfma_f32_16x16x32_bf16 v[126:129], v[14:17], v[114:117], v[66:69]
	v_mfma_f32_16x16x32_bf16 v[66:69], v[18:21], v[62:65], v[78:81]
	v_mfma_f32_16x16x32_bf16 v[122:125], v[22:25], v[114:117], v[66:69]
	v_mfma_f32_16x16x32_bf16 v[66:69], v[10:13], v[228:231], v[82:85]
	v_mfma_f32_16x16x32_bf16 v[110:113], v[14:17], v[232:235], v[66:69]
	v_mfma_f32_16x16x32_bf16 v[66:69], v[18:21], v[228:231], v[86:89]
	v_mfma_f32_16x16x32_bf16 v[98:101], v[22:25], v[232:235], v[66:69]
	v_mfma_f32_16x16x32_bf16 v[66:69], v[10:13], v[236:239], v[90:93]
	v_mfma_f32_16x16x32_bf16 v[78:81], v[14:17], v[240:243], v[66:69]
	v_mfma_f32_16x16x32_bf16 v[66:69], v[18:21], v[236:239], v[94:97]
	v_mfma_f32_16x16x32_bf16 v[74:77], v[22:25], v[240:243], v[66:69]
	v_mfma_f32_16x16x32_bf16 v[66:69], v[212:215], v[26:29], v[102:105]
	v_mfma_f32_16x16x32_bf16 v[26:29], v[220:223], v[26:29], v[34:37]
	v_mfma_f32_16x16x32_bf16 v[138:141], v[224:227], v[30:33], v[26:29]
	v_mfma_f32_16x16x32_bf16 v[26:29], v[212:215], v[62:65], v[38:41]
	v_mfma_f32_16x16x32_bf16 v[118:121], v[216:219], v[114:117], v[26:29]
	v_mfma_f32_16x16x32_bf16 v[26:29], v[220:223], v[62:65], v[42:45]
	v_mfma_f32_16x16x32_bf16 v[114:117], v[224:227], v[114:117], v[26:29]
	v_mfma_f32_16x16x32_bf16 v[26:29], v[212:215], v[228:231], v[46:49]
	v_mfma_f32_16x16x32_bf16 v[90:93], v[216:219], v[232:235], v[26:29]
	v_mfma_f32_16x16x32_bf16 v[26:29], v[220:223], v[228:231], v[50:53]
	v_mfma_f32_16x16x32_bf16 v[82:85], v[224:227], v[232:235], v[26:29]
	v_mfma_f32_16x16x32_bf16 v[26:29], v[212:215], v[236:239], v[54:57]
	v_mfma_f32_16x16x32_bf16 v[70:73], v[216:219], v[240:243], v[26:29]
	v_mfma_f32_16x16x32_bf16 v[26:29], v[220:223], v[236:239], v[58:61]
	v_mfma_f32_16x16x32_bf16 v[142:145], v[216:219], v[30:33], v[66:69]
	v_mfma_f32_16x16x32_bf16 v[66:69], v[224:227], v[240:243], v[26:29]
	s_barrier
	s_add_i32 s85, s77, s47
	s_nop 3
	v_lshl_add_u64 v[26:27], v[246:247], 0, s[20:21]
	s_mov_b32 m0, s85
	s_mov_b64 s[0:1], 0x10180
	s_add_i32 s87, s85, 0x2000
	ds_read_b128 v[34:37], v201 offset:49152
	ds_read_b128 v[38:41], v201 offset:50176
	ds_read_b128 v[86:89], v201 offset:51200
	ds_read_b128 v[94:97], v201 offset:52224
	ds_read_b128 v[102:105], v201 offset:53248
	ds_read_b128 v[228:231], v201 offset:54272
	ds_read_b128 v[232:235], v201 offset:55296
	ds_read_b128 v[236:239], v201 offset:56320
	global_load_lds_dwordx4 v[26:27], off
	v_lshl_add_u64 v[26:27], v[246:247], 0, s[0:1]
	s_mov_b32 m0, s87
	s_mov_b64 s[0:1], 0x20180
	s_add_i32 s50, s78, s47
	global_load_lds_dwordx4 v[26:27], off
	v_lshl_add_u64 v[26:27], v[246:247], 0, s[0:1]
	s_mov_b32 m0, s50
	s_mov_b64 s[0:1], 0x30180
	s_add_i32 s51, s50, 0x2000
	global_load_lds_dwordx4 v[26:27], off
	v_lshl_add_u64 v[26:27], v[246:247], 0, s[0:1]
	s_mov_b32 m0, s51
	s_mov_b64 s[0:1], 0x40180
	global_load_lds_dwordx4 v[26:27], off
	v_lshl_add_u64 v[26:27], v[244:245], 0, s[20:21]
	s_mov_b32 m0, s54
	s_nop 0
	global_load_lds_dwordx4 v[26:27], off
	v_lshl_add_u64 v[26:27], v[244:245], 0, s[0:1]
	s_mov_b32 m0, s55
	s_nop 0
	global_load_lds_dwordx4 v[26:27], off
	s_waitcnt vmcnt(8)
	s_waitcnt lgkmcnt(0)
	s_barrier
	v_mfma_f32_16x16x32_bf16 v[26:29], v[10:13], v[34:37], v[146:149]
	v_mfma_f32_16x16x32_bf16 v[62:65], v[14:17], v[38:41], v[26:29]
	v_mfma_f32_16x16x32_bf16 v[26:29], v[18:21], v[34:37], v[150:153]
	v_mfma_f32_16x16x32_bf16 v[58:61], v[22:25], v[38:41], v[26:29]
	v_mfma_f32_16x16x32_bf16 v[26:29], v[10:13], v[86:89], v[154:157]
	v_mfma_f32_16x16x32_bf16 v[46:49], v[14:17], v[94:97], v[26:29]
	v_mfma_f32_16x16x32_bf16 v[26:29], v[18:21], v[86:89], v[158:161]
	v_mfma_f32_16x16x32_bf16 v[42:45], v[22:25], v[94:97], v[26:29]
	v_mfma_f32_16x16x32_bf16 v[26:29], v[10:13], v[102:105], v[162:165]
	v_mfma_f32_16x16x32_bf16 v[2:5], v[10:13], v[232:235], v[2:5]
	v_mfma_f32_16x16x32_bf16 v[30:33], v[14:17], v[228:231], v[26:29]
	v_mfma_f32_16x16x32_bf16 v[26:29], v[18:21], v[102:105], v[166:169]
	v_mfma_f32_16x16x32_bf16 v[14:17], v[14:17], v[236:239], v[2:5]
	v_mfma_f32_16x16x32_bf16 v[2:5], v[18:21], v[232:235], v[6:9]
	v_mfma_f32_16x16x32_bf16 v[26:29], v[22:25], v[228:231], v[26:29]
	v_mfma_f32_16x16x32_bf16 v[10:13], v[22:25], v[236:239], v[2:5]
	v_mfma_f32_16x16x32_bf16 v[2:5], v[212:215], v[34:37], v[170:173]
	v_mfma_f32_16x16x32_bf16 v[54:57], v[216:219], v[38:41], v[2:5]
	v_mfma_f32_16x16x32_bf16 v[2:5], v[220:223], v[34:37], v[174:177]
	v_mfma_f32_16x16x32_bf16 v[50:53], v[224:227], v[38:41], v[2:5]
	v_mfma_f32_16x16x32_bf16 v[2:5], v[212:215], v[86:89], v[188:191]
	v_mfma_f32_16x16x32_bf16 v[38:41], v[216:219], v[94:97], v[2:5]
	v_mfma_f32_16x16x32_bf16 v[2:5], v[220:223], v[86:89], v[106:109]
	v_mfma_f32_16x16x32_bf16 v[34:37], v[224:227], v[94:97], v[2:5]
	v_mfma_f32_16x16x32_bf16 v[2:5], v[212:215], v[102:105], v[192:195]
	v_mfma_f32_16x16x32_bf16 v[22:25], v[216:219], v[228:231], v[2:5]
	v_mfma_f32_16x16x32_bf16 v[2:5], v[220:223], v[102:105], v[196:199]
	v_mfma_f32_16x16x32_bf16 v[18:21], v[224:227], v[228:231], v[2:5]
	v_mfma_f32_16x16x32_bf16 v[2:5], v[212:215], v[232:235], v[204:207]
	v_mfma_f32_16x16x32_bf16 v[6:9], v[216:219], v[236:239], v[2:5]
	v_mfma_f32_16x16x32_bf16 v[2:5], v[220:223], v[232:235], v[208:211]
	v_mfma_f32_16x16x32_bf16 v[2:5], v[224:227], v[236:239], v[2:5]
	s_barrier
	s_add_u32 s10, s66, 0x80180
	s_addc_u32 s11, s67, 0
	s_add_u32 s33, s62, 0x200
	s_addc_u32 s56, s63, 0
	s_mov_b32 s57, 0
.LBB0_2682:
	ds_read_b128 v[86:89], v1
	ds_read_b128 v[94:97], v1 offset:1024
	ds_read_b128 v[102:105], v1 offset:2048
	ds_read_b128 v[106:109], v1 offset:3072
	ds_read_b128 v[146:149], v200
	ds_read_b128 v[150:153], v200 offset:1024
	ds_read_b128 v[154:157], v200 offset:2048
	ds_read_b128 v[158:161], v200 offset:3072
	s_add_u32 s0, s10, 0xfff80080
	s_addc_u32 s1, s11, -1
	s_cmp_eq_u32 s57, 4
	s_cselect_b32 s1, s37, s1
	s_cselect_b32 s0, s36, s0
	s_cselect_b32 s63, s31, s56
	s_cselect_b32 s62, s35, s33
	s_mov_b32 m0, s79
	v_lshl_add_u64 v[208:209], s[10:11], 0, v[182:183]
	ds_read_b128 v[162:165], v201
	ds_read_b128 v[166:169], v201 offset:1024
	ds_read_b128 v[170:173], v201 offset:2048
	ds_read_b128 v[174:177], v201 offset:3072
	ds_read_b128 v[188:191], v201 offset:4096
	ds_read_b128 v[192:195], v201 offset:5120
	ds_read_b128 v[196:199], v201 offset:6144
	ds_read_b128 v[204:207], v201 offset:7168
	global_load_lds_dwordx4 v[208:209], off
	v_lshl_add_u64 v[208:209], v[208:209], 0, s[22:23]
	s_mov_b32 m0, s80
	s_nop 0
	global_load_lds_dwordx4 v[208:209], off
	s_waitcnt vmcnt(8)
	s_waitcnt lgkmcnt(0)
	s_barrier
	v_mfma_f32_16x16x32_bf16 v[134:137], v[86:89], v[162:165], v[134:137]
	v_mfma_f32_16x16x32_bf16 v[130:133], v[102:105], v[162:165], v[130:133]
	v_mfma_f32_16x16x32_bf16 v[126:129], v[86:89], v[170:173], v[126:129]
	v_mfma_f32_16x16x32_bf16 v[122:125], v[102:105], v[170:173], v[122:125]
	v_mfma_f32_16x16x32_bf16 v[110:113], v[86:89], v[188:191], v[110:113]
	v_mfma_f32_16x16x32_bf16 v[98:101], v[102:105], v[188:191], v[98:101]
	v_mfma_f32_16x16x32_bf16 v[78:81], v[86:89], v[196:199], v[78:81]
	v_mfma_f32_16x16x32_bf16 v[74:77], v[102:105], v[196:199], v[74:77]
	v_mfma_f32_16x16x32_bf16 v[134:137], v[94:97], v[166:169], v[134:137]
	v_mfma_f32_16x16x32_bf16 v[130:133], v[106:109], v[166:169], v[130:133]
	v_mfma_f32_16x16x32_bf16 v[126:129], v[94:97], v[174:177], v[126:129]
	v_mfma_f32_16x16x32_bf16 v[122:125], v[106:109], v[174:177], v[122:125]
	v_mfma_f32_16x16x32_bf16 v[110:113], v[94:97], v[192:195], v[110:113]
	v_mfma_f32_16x16x32_bf16 v[98:101], v[106:109], v[192:195], v[98:101]
	v_mfma_f32_16x16x32_bf16 v[78:81], v[94:97], v[204:207], v[78:81]
	v_mfma_f32_16x16x32_bf16 v[74:77], v[106:109], v[204:207], v[74:77]
	v_mfma_f32_16x16x32_bf16 v[142:145], v[146:149], v[162:165], v[142:145]
	v_mfma_f32_16x16x32_bf16 v[138:141], v[154:157], v[162:165], v[138:141]
	v_mfma_f32_16x16x32_bf16 v[118:121], v[146:149], v[170:173], v[118:121]
	v_mfma_f32_16x16x32_bf16 v[114:117], v[154:157], v[170:173], v[114:117]
	v_mfma_f32_16x16x32_bf16 v[90:93], v[146:149], v[188:191], v[90:93]
	v_mfma_f32_16x16x32_bf16 v[82:85], v[154:157], v[188:191], v[82:85]
	v_mfma_f32_16x16x32_bf16 v[70:73], v[146:149], v[196:199], v[70:73]
	v_mfma_f32_16x16x32_bf16 v[66:69], v[154:157], v[196:199], v[66:69]
	v_mfma_f32_16x16x32_bf16 v[142:145], v[150:153], v[166:169], v[142:145]
	v_mfma_f32_16x16x32_bf16 v[138:141], v[158:161], v[166:169], v[138:141]
	v_mfma_f32_16x16x32_bf16 v[118:121], v[150:153], v[174:177], v[118:121]
	v_mfma_f32_16x16x32_bf16 v[114:117], v[158:161], v[174:177], v[114:117]
	v_mfma_f32_16x16x32_bf16 v[90:93], v[150:153], v[192:195], v[90:93]
	v_mfma_f32_16x16x32_bf16 v[82:85], v[158:161], v[192:195], v[82:85]
	v_mfma_f32_16x16x32_bf16 v[70:73], v[150:153], v[204:207], v[70:73]
	v_mfma_f32_16x16x32_bf16 v[66:69], v[158:161], v[204:207], v[66:69]
	s_barrier
	s_mov_b32 m0, s81
	v_lshl_add_u64 v[208:209], s[62:63], 0, v[180:181]
	s_mov_b64 s[62:63], 0x10000
	ds_read_b128 v[162:165], v201 offset:16384
	ds_read_b128 v[166:169], v201 offset:17408
	ds_read_b128 v[170:173], v201 offset:18432
	ds_read_b128 v[174:177], v201 offset:19456
	ds_read_b128 v[188:191], v201 offset:20480
	ds_read_b128 v[192:195], v201 offset:21504
	ds_read_b128 v[196:199], v201 offset:22528
	ds_read_b128 v[204:207], v201 offset:23552
	global_load_lds_dwordx4 v[208:209], off
	v_lshl_add_u64 v[210:211], v[208:209], 0, s[62:63]
	s_mov_b32 m0, s82
	s_mov_b64 s[62:63], 0x20000
	global_load_lds_dwordx4 v[210:211], off
	v_lshl_add_u64 v[210:211], v[208:209], 0, s[62:63]
	s_mov_b32 m0, s83
	s_mov_b64 s[62:63], 0x30000
	global_load_lds_dwordx4 v[210:211], off
	v_lshl_add_u64 v[210:211], v[208:209], 0, s[62:63]
	s_mov_b32 m0, s84
	s_nop 0
	global_load_lds_dwordx4 v[210:211], off
	v_lshl_add_u64 v[210:211], s[0:1], 0, v[178:179]
	s_mov_b32 m0, s41
	v_lshl_add_u64 v[212:213], v[210:211], 0, s[22:23]
	global_load_lds_dwordx4 v[210:211], off
	s_mov_b32 m0, s45
	s_nop 0
	global_load_lds_dwordx4 v[212:213], off
	s_waitcnt vmcnt(8)
	s_waitcnt lgkmcnt(0)
	s_barrier
	v_mfma_f32_16x16x32_bf16 v[62:65], v[86:89], v[162:165], v[62:65]
	v_mfma_f32_16x16x32_bf16 v[58:61], v[102:105], v[162:165], v[58:61]
	v_mfma_f32_16x16x32_bf16 v[46:49], v[86:89], v[170:173], v[46:49]
	v_mfma_f32_16x16x32_bf16 v[42:45], v[102:105], v[170:173], v[42:45]
	v_mfma_f32_16x16x32_bf16 v[30:33], v[86:89], v[188:191], v[30:33]
	v_mfma_f32_16x16x32_bf16 v[26:29], v[102:105], v[188:191], v[26:29]
	v_mfma_f32_16x16x32_bf16 v[14:17], v[86:89], v[196:199], v[14:17]
	v_mfma_f32_16x16x32_bf16 v[10:13], v[102:105], v[196:199], v[10:13]
	v_mfma_f32_16x16x32_bf16 v[62:65], v[94:97], v[166:169], v[62:65]
	v_mfma_f32_16x16x32_bf16 v[58:61], v[106:109], v[166:169], v[58:61]
	v_mfma_f32_16x16x32_bf16 v[46:49], v[94:97], v[174:177], v[46:49]
	v_mfma_f32_16x16x32_bf16 v[42:45], v[106:109], v[174:177], v[42:45]
	v_mfma_f32_16x16x32_bf16 v[30:33], v[94:97], v[192:195], v[30:33]
	v_mfma_f32_16x16x32_bf16 v[26:29], v[106:109], v[192:195], v[26:29]
	v_mfma_f32_16x16x32_bf16 v[14:17], v[94:97], v[204:207], v[14:17]
	v_mfma_f32_16x16x32_bf16 v[10:13], v[106:109], v[204:207], v[10:13]
	v_mfma_f32_16x16x32_bf16 v[54:57], v[146:149], v[162:165], v[54:57]
	v_mfma_f32_16x16x32_bf16 v[50:53], v[154:157], v[162:165], v[50:53]
	v_mfma_f32_16x16x32_bf16 v[38:41], v[146:149], v[170:173], v[38:41]
	v_mfma_f32_16x16x32_bf16 v[34:37], v[154:157], v[170:173], v[34:37]
	v_mfma_f32_16x16x32_bf16 v[22:25], v[146:149], v[188:191], v[22:25]
	v_mfma_f32_16x16x32_bf16 v[18:21], v[154:157], v[188:191], v[18:21]
	v_mfma_f32_16x16x32_bf16 v[6:9], v[146:149], v[196:199], v[6:9]
	v_mfma_f32_16x16x32_bf16 v[2:5], v[154:157], v[196:199], v[2:5]
	v_mfma_f32_16x16x32_bf16 v[54:57], v[150:153], v[166:169], v[54:57]
	v_mfma_f32_16x16x32_bf16 v[50:53], v[158:161], v[166:169], v[50:53]
	v_mfma_f32_16x16x32_bf16 v[38:41], v[150:153], v[174:177], v[38:41]
	v_mfma_f32_16x16x32_bf16 v[34:37], v[158:161], v[174:177], v[34:37]
	v_mfma_f32_16x16x32_bf16 v[22:25], v[150:153], v[192:195], v[22:25]
	v_mfma_f32_16x16x32_bf16 v[18:21], v[158:161], v[192:195], v[18:21]
	v_mfma_f32_16x16x32_bf16 v[6:9], v[150:153], v[204:207], v[6:9]
	v_mfma_f32_16x16x32_bf16 v[2:5], v[158:161], v[204:207], v[2:5]
	s_barrier
	ds_read_b128 v[86:89], v202
	ds_read_b128 v[94:97], v202 offset:1024
	ds_read_b128 v[102:105], v202 offset:2048
	ds_read_b128 v[106:109], v202 offset:3072
	ds_read_b128 v[146:149], v203
	ds_read_b128 v[150:153], v203 offset:1024
	ds_read_b128 v[154:157], v203 offset:2048
	ds_read_b128 v[158:161], v203 offset:3072
	s_mov_b32 m0, s52
	v_lshl_add_u64 v[212:213], v[210:211], 0, s[24:25]
	s_mov_b64 s[0:1], 0xc0000
	ds_read_b128 v[162:165], v201 offset:32768
	ds_read_b128 v[166:169], v201 offset:33792
	ds_read_b128 v[170:173], v201 offset:34816
	ds_read_b128 v[174:177], v201 offset:35840
	ds_read_b128 v[188:191], v201 offset:36864
	ds_read_b128 v[192:195], v201 offset:37888
	ds_read_b128 v[196:199], v201 offset:38912
	ds_read_b128 v[204:207], v201 offset:39936
	global_load_lds_dwordx4 v[212:213], off
	v_lshl_add_u64 v[212:213], v[210:211], 0, s[0:1]
	s_mov_b32 m0, s53
	s_nop 0
	global_load_lds_dwordx4 v[212:213], off
	s_waitcnt vmcnt(8)
	s_waitcnt lgkmcnt(0)
	s_barrier
	v_mfma_f32_16x16x32_bf16 v[134:137], v[86:89], v[162:165], v[134:137]
	v_mfma_f32_16x16x32_bf16 v[130:133], v[102:105], v[162:165], v[130:133]
	v_mfma_f32_16x16x32_bf16 v[126:129], v[86:89], v[170:173], v[126:129]
	v_mfma_f32_16x16x32_bf16 v[122:125], v[102:105], v[170:173], v[122:125]
	v_mfma_f32_16x16x32_bf16 v[110:113], v[86:89], v[188:191], v[110:113]
	v_mfma_f32_16x16x32_bf16 v[98:101], v[102:105], v[188:191], v[98:101]
	v_mfma_f32_16x16x32_bf16 v[78:81], v[86:89], v[196:199], v[78:81]
	v_mfma_f32_16x16x32_bf16 v[74:77], v[102:105], v[196:199], v[74:77]
	v_mfma_f32_16x16x32_bf16 v[134:137], v[94:97], v[166:169], v[134:137]
	v_mfma_f32_16x16x32_bf16 v[130:133], v[106:109], v[166:169], v[130:133]
	v_mfma_f32_16x16x32_bf16 v[126:129], v[94:97], v[174:177], v[126:129]
	v_mfma_f32_16x16x32_bf16 v[122:125], v[106:109], v[174:177], v[122:125]
	v_mfma_f32_16x16x32_bf16 v[110:113], v[94:97], v[192:195], v[110:113]
	v_mfma_f32_16x16x32_bf16 v[98:101], v[106:109], v[192:195], v[98:101]
	v_mfma_f32_16x16x32_bf16 v[78:81], v[94:97], v[204:207], v[78:81]
	v_mfma_f32_16x16x32_bf16 v[74:77], v[106:109], v[204:207], v[74:77]
	v_mfma_f32_16x16x32_bf16 v[142:145], v[146:149], v[162:165], v[142:145]
	v_mfma_f32_16x16x32_bf16 v[138:141], v[154:157], v[162:165], v[138:141]
	v_mfma_f32_16x16x32_bf16 v[118:121], v[146:149], v[170:173], v[118:121]
	v_mfma_f32_16x16x32_bf16 v[114:117], v[154:157], v[170:173], v[114:117]
	v_mfma_f32_16x16x32_bf16 v[90:93], v[146:149], v[188:191], v[90:93]
	v_mfma_f32_16x16x32_bf16 v[82:85], v[154:157], v[188:191], v[82:85]
	v_mfma_f32_16x16x32_bf16 v[70:73], v[146:149], v[196:199], v[70:73]
	v_mfma_f32_16x16x32_bf16 v[66:69], v[154:157], v[196:199], v[66:69]
	v_mfma_f32_16x16x32_bf16 v[142:145], v[150:153], v[166:169], v[142:145]
	v_mfma_f32_16x16x32_bf16 v[138:141], v[158:161], v[166:169], v[138:141]
	v_mfma_f32_16x16x32_bf16 v[118:121], v[150:153], v[174:177], v[118:121]
	v_mfma_f32_16x16x32_bf16 v[114:117], v[158:161], v[174:177], v[114:117]
	v_mfma_f32_16x16x32_bf16 v[90:93], v[150:153], v[192:195], v[90:93]
	v_mfma_f32_16x16x32_bf16 v[82:85], v[158:161], v[192:195], v[82:85]
	v_mfma_f32_16x16x32_bf16 v[70:73], v[150:153], v[204:207], v[70:73]
	v_mfma_f32_16x16x32_bf16 v[66:69], v[158:161], v[204:207], v[66:69]
	s_barrier
; #define PG8_WAIT_V(n) asm volatile("s_waitcnt vmcnt(" #n ")" ::: "memory")
; #define PG8_BAR __builtin_amdgcn_s_barrier()
; template <class Epi, class Sched, bool ALIGN_EPI = true, bool SP2 = true, bool FULLLINE = false, bool NOSTAGE = false, bool FP8 = false>
; __device__ __forceinline__ void gemm_phase(PG8_LAS unsigned char* lds, const Gemm g, const Sched& S, const Epi& E) {
;     ...
;         static_assert(SP2, "only the SP2 loop is kept");
;         { const int t = 0; if constexpr (Epi::NST == 16) PG8_ITER(PG8_WAIT_V(24)); else if constexpr (Epi::NST == 8) PG8_ITER(PG8_WAIT_V(16)); else PG8_ITER(PG8_WAIT_V(8)); }
;         for (int t = 2; t < nt; t += 2) PG8_ITER(PG8_WAIT_V(8));
;     ...
;         if constexpr (ALIGN_EPI) { if (wr == 0) PG8_BAR; }
;         { int ln_ = lane; asm volatile("" : "+v"(ln_));
;           E(acc, cur, wr, wc, ln_ & 15, ln_ >> 4); } S.done(cur);
;         if (!has_next) break;
	s_mov_b32 m0, s85
	v_lshl_add_u64 v[212:213], v[208:209], 0, s[26:27]
	s_mov_b64 s[0:1], 0x10080
	ds_read_b128 v[162:165], v201 offset:49152
	ds_read_b128 v[166:169], v201 offset:50176
	ds_read_b128 v[170:173], v201 offset:51200
	ds_read_b128 v[174:177], v201 offset:52224
	ds_read_b128 v[188:191], v201 offset:53248
	ds_read_b128 v[192:195], v201 offset:54272
	ds_read_b128 v[196:199], v201 offset:55296
	ds_read_b128 v[204:207], v201 offset:56320
	global_load_lds_dwordx4 v[212:213], off
	v_lshl_add_u64 v[212:213], v[208:209], 0, s[0:1]
	s_mov_b32 m0, s87
	s_mov_b64 s[0:1], 0x20080
	global_load_lds_dwordx4 v[212:213], off
	v_lshl_add_u64 v[212:213], v[208:209], 0, s[0:1]
	s_mov_b32 m0, s50
	s_mov_b64 s[0:1], 0x30080
	global_load_lds_dwordx4 v[212:213], off
	v_lshl_add_u64 v[208:209], v[208:209], 0, s[0:1]
	s_mov_b32 m0, s51
	s_mov_b64 s[0:1], 0x40080
	global_load_lds_dwordx4 v[208:209], off
	v_lshl_add_u64 v[208:209], v[210:211], 0, s[26:27]
	s_mov_b32 m0, s54
	s_nop 0
	global_load_lds_dwordx4 v[208:209], off
	v_lshl_add_u64 v[208:209], v[210:211], 0, s[0:1]
	s_mov_b32 m0, s55
	s_nop 0
	global_load_lds_dwordx4 v[208:209], off
	s_waitcnt vmcnt(8)
	s_waitcnt lgkmcnt(0)
	s_barrier
	v_mfma_f32_16x16x32_bf16 v[62:65], v[86:89], v[162:165], v[62:65]
	v_mfma_f32_16x16x32_bf16 v[58:61], v[102:105], v[162:165], v[58:61]
	v_mfma_f32_16x16x32_bf16 v[46:49], v[86:89], v[170:173], v[46:49]
	v_mfma_f32_16x16x32_bf16 v[42:45], v[102:105], v[170:173], v[42:45]
	v_mfma_f32_16x16x32_bf16 v[30:33], v[86:89], v[188:191], v[30:33]
	v_mfma_f32_16x16x32_bf16 v[26:29], v[102:105], v[188:191], v[26:29]
	v_mfma_f32_16x16x32_bf16 v[14:17], v[86:89], v[196:199], v[14:17]
	v_mfma_f32_16x16x32_bf16 v[10:13], v[102:105], v[196:199], v[10:13]
	v_mfma_f32_16x16x32_bf16 v[62:65], v[94:97], v[166:169], v[62:65]
	v_mfma_f32_16x16x32_bf16 v[58:61], v[106:109], v[166:169], v[58:61]
	v_mfma_f32_16x16x32_bf16 v[46:49], v[94:97], v[174:177], v[46:49]
	v_mfma_f32_16x16x32_bf16 v[42:45], v[106:109], v[174:177], v[42:45]
	v_mfma_f32_16x16x32_bf16 v[30:33], v[94:97], v[192:195], v[30:33]
	v_mfma_f32_16x16x32_bf16 v[26:29], v[106:109], v[192:195], v[26:29]
	v_mfma_f32_16x16x32_bf16 v[14:17], v[94:97], v[204:207], v[14:17]
	v_mfma_f32_16x16x32_bf16 v[10:13], v[106:109], v[204:207], v[10:13]
	v_mfma_f32_16x16x32_bf16 v[54:57], v[146:149], v[162:165], v[54:57]
	v_mfma_f32_16x16x32_bf16 v[50:53], v[154:157], v[162:165], v[50:53]
	v_mfma_f32_16x16x32_bf16 v[38:41], v[146:149], v[170:173], v[38:41]
	v_mfma_f32_16x16x32_bf16 v[34:37], v[154:157], v[170:173], v[34:37]
	v_mfma_f32_16x16x32_bf16 v[22:25], v[146:149], v[188:191], v[22:25]
	v_mfma_f32_16x16x32_bf16 v[18:21], v[154:157], v[188:191], v[18:21]
	v_mfma_f32_16x16x32_bf16 v[6:9], v[146:149], v[196:199], v[6:9]
	v_mfma_f32_16x16x32_bf16 v[2:5], v[154:157], v[196:199], v[2:5]
	v_mfma_f32_16x16x32_bf16 v[54:57], v[150:153], v[166:169], v[54:57]
	v_mfma_f32_16x16x32_bf16 v[50:53], v[158:161], v[166:169], v[50:53]
	v_mfma_f32_16x16x32_bf16 v[38:41], v[150:153], v[174:177], v[38:41]
	v_mfma_f32_16x16x32_bf16 v[34:37], v[158:161], v[174:177], v[34:37]
	v_mfma_f32_16x16x32_bf16 v[22:25], v[150:153], v[192:195], v[22:25]
	v_mfma_f32_16x16x32_bf16 v[18:21], v[158:161], v[192:195], v[18:21]
	v_mfma_f32_16x16x32_bf16 v[6:9], v[150:153], v[204:207], v[6:9]
	v_mfma_f32_16x16x32_bf16 v[2:5], v[158:161], v[204:207], v[2:5]
	s_barrier
	s_add_i32 s57, s57, 2
	s_add_u32 s10, s10, 0x100
	s_addc_u32 s11, s11, 0
	s_add_u32 s33, s33, 0x100
	s_addc_u32 s56, s56, 0
	s_cmp_gt_u32 s57, 5
	s_cbranch_scc0 .LBB0_2682
	s_and_b64 vcc, exec, s[14:15]
	s_cbranch_vccz .LBB0_2685
	s_barrier

; template <class Epi, class Sched, bool ALIGN_EPI = true, bool SP2 = true, bool FULLLINE = false, bool NOSTAGE = false, bool FP8 = false>
; __device__ __forceinline__ void gemm_phase(PG8_LAS unsigned char* lds, const Gemm g, const Sched& S, const Epi& E) {
;     ...
;         const bool has_next = S.next(ui + 1, nxt);
;         const char* nA = has_next ? PG8_ABASE(nxt) : cA; const char* nB = has_next ? PG8_BBASE(nxt) : cB;
.LBB0_2861:
	s_ashr_i32 s45, s44, 31
	s_lshl_b64 s[0:1], s[44:45], 20
	s_add_u32 s46, s58, s0
	ds_read_b128 v[2:5], v1
	ds_read_b128 v[6:9], v1 offset:1024
	ds_read_b128 v[10:13], v1 offset:2048
	ds_read_b128 v[14:17], v1 offset:3072
	ds_read_b128 v[18:21], v142
	ds_read_b128 v[22:25], v142 offset:1024
	ds_read_b128 v[26:29], v142 offset:2048
	ds_read_b128 v[30:33], v142 offset:3072
	s_addc_u32 s47, s59, s1
	s_ashr_i32 s41, s40, 31
	s_lshl_b64 s[0:1], s[40:41], 20
	s_add_u32 s62, s3, s0
	s_addc_u32 s63, s42, s1
	s_and_b64 s[0:1], s[8:9], exec
	s_cselect_b32 s41, s47, s71
	s_cselect_b32 s45, s46, s70
	s_cselect_b32 s87, s63, s69
	s_cselect_b32 s88, s62, s68
	v_lshl_add_u64 v[140:141], s[70:71], 0, v[132:133]
	s_mov_b32 m0, s79
	v_lshl_add_u64 v[66:67], v[140:141], 0, s[12:13]
	ds_read_b128 v[34:37], v143
	ds_read_b128 v[38:41], v143 offset:1024
	ds_read_b128 v[42:45], v143 offset:2048
	ds_read_b128 v[46:49], v143 offset:3072
	ds_read_b128 v[50:53], v143 offset:4096
	ds_read_b128 v[54:57], v143 offset:5120
	ds_read_b128 v[58:61], v143 offset:6144
	ds_read_b128 v[62:65], v143 offset:7168
	global_load_lds_dwordx4 v[66:67], off
	v_lshl_add_u64 v[66:67], v[140:141], 0, s[14:15]
	s_mov_b32 m0, s80
	s_nop 0
	global_load_lds_dwordx4 v[66:67], off
	s_waitcnt vmcnt(16)
	s_waitcnt lgkmcnt(0)
	s_barrier
	v_mfma_f32_16x16x32_bf16 v[86:89], v[10:13], v[50:53], 0
	v_mfma_f32_16x16x32_bf16 v[90:93], v[14:17], v[54:57], v[86:89]
	v_mfma_f32_16x16x32_bf16 v[86:89], v[2:5], v[58:61], 0
	v_mfma_f32_16x16x32_bf16 v[66:69], v[2:5], v[34:37], 0
	v_mfma_f32_16x16x32_bf16 v[70:73], v[10:13], v[34:37], 0
	v_mfma_f32_16x16x32_bf16 v[74:77], v[2:5], v[42:45], 0
	v_mfma_f32_16x16x32_bf16 v[78:81], v[10:13], v[42:45], 0
	v_mfma_f32_16x16x32_bf16 v[82:85], v[2:5], v[50:53], 0
	v_mfma_f32_16x16x32_bf16 v[94:97], v[6:9], v[62:65], v[86:89]
	v_mfma_f32_16x16x32_bf16 v[86:89], v[10:13], v[58:61], 0
	v_mfma_f32_16x16x32_bf16 v[66:69], v[6:9], v[38:41], v[66:69]
	v_mfma_f32_16x16x32_bf16 v[70:73], v[14:17], v[38:41], v[70:73]
	v_mfma_f32_16x16x32_bf16 v[74:77], v[6:9], v[46:49], v[74:77]
	v_mfma_f32_16x16x32_bf16 v[78:81], v[14:17], v[46:49], v[78:81]
	v_mfma_f32_16x16x32_bf16 v[82:85], v[6:9], v[54:57], v[82:85]
	v_mfma_f32_16x16x32_bf16 v[106:109], v[14:17], v[62:65], v[86:89]
	v_mfma_f32_16x16x32_bf16 v[86:89], v[18:21], v[34:37], 0
	v_mfma_f32_16x16x32_bf16 v[34:37], v[26:29], v[34:37], 0
	v_mfma_f32_16x16x32_bf16 v[110:113], v[22:25], v[38:41], v[86:89]
	v_mfma_f32_16x16x32_bf16 v[34:37], v[30:33], v[38:41], v[34:37]
	v_mfma_f32_16x16x32_bf16 v[38:41], v[18:21], v[42:45], 0
	v_mfma_f32_16x16x32_bf16 v[42:45], v[26:29], v[42:45], 0
	v_mfma_f32_16x16x32_bf16 v[38:41], v[22:25], v[46:49], v[38:41]
	v_mfma_f32_16x16x32_bf16 v[42:45], v[30:33], v[46:49], v[42:45]
	v_mfma_f32_16x16x32_bf16 v[46:49], v[18:21], v[50:53], 0
	v_mfma_f32_16x16x32_bf16 v[50:53], v[26:29], v[50:53], 0
	v_mfma_f32_16x16x32_bf16 v[46:49], v[22:25], v[54:57], v[46:49]
	v_mfma_f32_16x16x32_bf16 v[50:53], v[30:33], v[54:57], v[50:53]
	v_mfma_f32_16x16x32_bf16 v[54:57], v[18:21], v[58:61], 0
	v_mfma_f32_16x16x32_bf16 v[58:61], v[26:29], v[58:61], 0
	v_mfma_f32_16x16x32_bf16 v[54:57], v[22:25], v[62:65], v[54:57]
	v_mfma_f32_16x16x32_bf16 v[58:61], v[30:33], v[62:65], v[58:61]
	s_barrier
	v_lshl_add_u64 v[238:239], s[68:69], 0, v[130:131]
	s_mov_b32 m0, s81
	v_lshl_add_u64 v[146:147], v[238:239], 0, s[16:17]
	s_add_i32 s89, s81, 0x2000
	ds_read_b128 v[62:65], v143 offset:16384
	ds_read_b128 v[86:89], v143 offset:17408
	ds_read_b128 v[98:101], v143 offset:18432
	ds_read_b128 v[102:105], v143 offset:19456
	ds_read_b128 v[114:117], v143 offset:20480
	ds_read_b128 v[118:121], v143 offset:21504
	ds_read_b128 v[122:125], v143 offset:22528
	ds_read_b128 v[126:129], v143 offset:23552
	global_load_lds_dwordx4 v[146:147], off
	v_lshl_add_u64 v[146:147], v[238:239], 0, s[18:19]
	s_mov_b32 m0, s89
	s_add_i32 s90, s78, s43
	global_load_lds_dwordx4 v[146:147], off
	v_lshl_add_u64 v[146:147], v[238:239], 0, s[20:21]
	s_mov_b32 m0, s90
	s_add_i32 s91, s90, 0x2000
	global_load_lds_dwordx4 v[146:147], off
	v_lshl_add_u64 v[146:147], v[238:239], 0, s[22:23]
	s_mov_b32 m0, s91
	s_nop 0
	global_load_lds_dwordx4 v[146:147], off
	v_lshl_add_u64 v[146:147], v[140:141], 0, s[16:17]
	s_mov_b32 m0, s53
	s_nop 0
	global_load_lds_dwordx4 v[146:147], off
	v_lshl_add_u64 v[146:147], v[140:141], 0, s[18:19]
	s_mov_b32 m0, s54
	s_nop 0
	global_load_lds_dwordx4 v[146:147], off
	s_waitcnt vmcnt(16)
	s_waitcnt lgkmcnt(0)
	s_barrier
	v_mfma_f32_16x16x32_bf16 v[146:149], v[2:5], v[62:65], 0
	v_mfma_f32_16x16x32_bf16 v[154:157], v[2:5], v[98:101], 0
	v_mfma_f32_16x16x32_bf16 v[162:165], v[2:5], v[114:117], 0
	v_mfma_f32_16x16x32_bf16 v[2:5], v[2:5], v[122:125], 0
	v_mfma_f32_16x16x32_bf16 v[146:149], v[6:9], v[86:89], v[146:149]
	v_mfma_f32_16x16x32_bf16 v[154:157], v[6:9], v[102:105], v[154:157]
	v_mfma_f32_16x16x32_bf16 v[162:165], v[6:9], v[118:121], v[162:165]
	v_mfma_f32_16x16x32_bf16 v[2:5], v[6:9], v[126:129], v[2:5]
	v_mfma_f32_16x16x32_bf16 v[6:9], v[10:13], v[122:125], 0
	v_mfma_f32_16x16x32_bf16 v[150:153], v[10:13], v[62:65], 0
	v_mfma_f32_16x16x32_bf16 v[158:161], v[10:13], v[98:101], 0
	v_mfma_f32_16x16x32_bf16 v[166:169], v[10:13], v[114:117], 0
	v_mfma_f32_16x16x32_bf16 v[10:13], v[14:17], v[126:129], v[6:9]
	v_mfma_f32_16x16x32_bf16 v[150:153], v[14:17], v[86:89], v[150:153]
	v_mfma_f32_16x16x32_bf16 v[158:161], v[14:17], v[102:105], v[158:161]
	v_mfma_f32_16x16x32_bf16 v[166:169], v[14:17], v[118:121], v[166:169]
	v_mfma_f32_16x16x32_bf16 v[6:9], v[18:21], v[62:65], 0
	v_mfma_f32_16x16x32_bf16 v[14:17], v[22:25], v[86:89], v[6:9]
	v_mfma_f32_16x16x32_bf16 v[6:9], v[26:29], v[62:65], 0
	v_mfma_f32_16x16x32_bf16 v[170:173], v[30:33], v[86:89], v[6:9]
	v_mfma_f32_16x16x32_bf16 v[6:9], v[18:21], v[98:101], 0
	v_mfma_f32_16x16x32_bf16 v[174:177], v[22:25], v[102:105], v[6:9]
	v_mfma_f32_16x16x32_bf16 v[6:9], v[26:29], v[98:101], 0
	v_mfma_f32_16x16x32_bf16 v[178:181], v[30:33], v[102:105], v[6:9]
	v_mfma_f32_16x16x32_bf16 v[6:9], v[18:21], v[114:117], 0
	v_mfma_f32_16x16x32_bf16 v[182:185], v[22:25], v[118:121], v[6:9]
	v_mfma_f32_16x16x32_bf16 v[6:9], v[26:29], v[114:117], 0
	v_mfma_f32_16x16x32_bf16 v[186:189], v[30:33], v[118:121], v[6:9]
	v_mfma_f32_16x16x32_bf16 v[6:9], v[18:21], v[122:125], 0
	v_mfma_f32_16x16x32_bf16 v[190:193], v[22:25], v[126:129], v[6:9]
	v_mfma_f32_16x16x32_bf16 v[6:9], v[26:29], v[122:125], 0
	v_mfma_f32_16x16x32_bf16 v[194:197], v[30:33], v[126:129], v[6:9]
	s_barrier
; #define PG8_WAIT_V(n) asm volatile("s_waitcnt vmcnt(" #n ")" ::: "memory")
; template <class Epi, class Sched, bool ALIGN_EPI = true, bool SP2 = true, bool FULLLINE = false, bool NOSTAGE = false, bool FP8 = false>
; __device__ __forceinline__ void gemm_phase(PG8_LAS unsigned char* lds, const Gemm g, const Sched& S, const Epi& E) {
;     ...
;         static_assert(SP2, "only the SP2 loop is kept");
;         { const int t = 0; if constexpr (Epi::NST == 16) PG8_ITER(PG8_WAIT_V(24)); else if constexpr (Epi::NST == 8) PG8_ITER(PG8_WAIT_V(16)); else PG8_ITER(PG8_WAIT_V(8)); }
;         for (int t = 2; t < nt; t += 2) PG8_ITER(PG8_WAIT_V(8));
	s_nop 5
	ds_read_b128 v[6:9], v144
	ds_read_b128 v[26:29], v144 offset:1024
	ds_read_b128 v[30:33], v144 offset:2048
	ds_read_b128 v[62:65], v144 offset:3072
	ds_read_b128 v[198:201], v145
	ds_read_b128 v[202:205], v145 offset:1024
	ds_read_b128 v[206:209], v145 offset:2048
	ds_read_b128 v[210:213], v145 offset:3072
	s_mov_b32 m0, s55
	v_lshl_add_u64 v[86:87], v[140:141], 0, s[20:21]
	ds_read_b128 v[18:21], v143 offset:32768
	ds_read_b128 v[22:25], v143 offset:33792
	ds_read_b128 v[214:217], v143 offset:34816
	ds_read_b128 v[218:221], v143 offset:35840
	ds_read_b128 v[222:225], v143 offset:36864
	ds_read_b128 v[226:229], v143 offset:37888
	ds_read_b128 v[230:233], v143 offset:38912
	ds_read_b128 v[234:237], v143 offset:39936
	global_load_lds_dwordx4 v[86:87], off
	v_lshl_add_u64 v[86:87], v[140:141], 0, s[22:23]
	s_mov_b32 m0, s67
	s_nop 0
	global_load_lds_dwordx4 v[86:87], off
	s_waitcnt vmcnt(8)
	s_waitcnt lgkmcnt(0)
	s_barrier
	v_mfma_f32_16x16x32_bf16 v[66:69], v[6:9], v[18:21], v[66:69]
	v_mfma_f32_16x16x32_bf16 v[118:121], v[26:29], v[22:25], v[66:69]
	v_mfma_f32_16x16x32_bf16 v[66:69], v[30:33], v[18:21], v[70:73]
	v_mfma_f32_16x16x32_bf16 v[114:117], v[62:65], v[22:25], v[66:69]
	v_mfma_f32_16x16x32_bf16 v[66:69], v[6:9], v[214:217], v[74:77]
	v_mfma_f32_16x16x32_bf16 v[102:105], v[26:29], v[218:221], v[66:69]
	v_mfma_f32_16x16x32_bf16 v[66:69], v[30:33], v[214:217], v[78:81]
	v_mfma_f32_16x16x32_bf16 v[98:101], v[62:65], v[218:221], v[66:69]
	v_mfma_f32_16x16x32_bf16 v[66:69], v[6:9], v[222:225], v[82:85]
	v_mfma_f32_16x16x32_bf16 v[86:89], v[26:29], v[226:229], v[66:69]
	v_mfma_f32_16x16x32_bf16 v[66:69], v[30:33], v[222:225], v[90:93]
	v_mfma_f32_16x16x32_bf16 v[82:85], v[62:65], v[226:229], v[66:69]
	v_mfma_f32_16x16x32_bf16 v[66:69], v[6:9], v[230:233], v[94:97]
	v_mfma_f32_16x16x32_bf16 v[70:73], v[26:29], v[234:237], v[66:69]
	v_mfma_f32_16x16x32_bf16 v[66:69], v[30:33], v[230:233], v[106:109]
	v_mfma_f32_16x16x32_bf16 v[66:69], v[62:65], v[234:237], v[66:69]
	v_mfma_f32_16x16x32_bf16 v[74:77], v[198:201], v[18:21], v[110:113]
	v_mfma_f32_16x16x32_bf16 v[18:21], v[206:209], v[18:21], v[34:37]
	v_mfma_f32_16x16x32_bf16 v[122:125], v[210:213], v[22:25], v[18:21]
	v_mfma_f32_16x16x32_bf16 v[18:21], v[198:201], v[214:217], v[38:41]
	v_mfma_f32_16x16x32_bf16 v[110:113], v[202:205], v[218:221], v[18:21]
	v_mfma_f32_16x16x32_bf16 v[18:21], v[206:209], v[214:217], v[42:45]
	v_mfma_f32_16x16x32_bf16 v[106:109], v[210:213], v[218:221], v[18:21]
	v_mfma_f32_16x16x32_bf16 v[18:21], v[198:201], v[222:225], v[46:49]
	v_mfma_f32_16x16x32_bf16 v[94:97], v[202:205], v[226:229], v[18:21]
	v_mfma_f32_16x16x32_bf16 v[18:21], v[206:209], v[222:225], v[50:53]
	v_mfma_f32_16x16x32_bf16 v[90:93], v[210:213], v[226:229], v[18:21]
	v_mfma_f32_16x16x32_bf16 v[18:21], v[198:201], v[230:233], v[54:57]
	v_mfma_f32_16x16x32_bf16 v[78:81], v[202:205], v[234:237], v[18:21]
	v_mfma_f32_16x16x32_bf16 v[18:21], v[206:209], v[230:233], v[58:61]
	v_mfma_f32_16x16x32_bf16 v[126:129], v[202:205], v[22:25], v[74:77]
	v_mfma_f32_16x16x32_bf16 v[74:77], v[210:213], v[234:237], v[18:21]
	s_barrier
	s_add_i32 s50, s82, s43
	s_nop 3
	v_lshl_add_u64 v[18:19], v[238:239], 0, s[24:25]
	s_mov_b32 m0, s50
	s_add_i32 s51, s50, 0x2000
	ds_read_b128 v[42:45], v143 offset:49152
	ds_read_b128 v[46:49], v143 offset:50176
	ds_read_b128 v[214:217], v143 offset:51200
	ds_read_b128 v[218:221], v143 offset:52224
	ds_read_b128 v[222:225], v143 offset:53248
	ds_read_b128 v[226:229], v143 offset:54272
	ds_read_b128 v[230:233], v143 offset:55296
	ds_read_b128 v[234:237], v143 offset:56320
	global_load_lds_dwordx4 v[18:19], off
	v_lshl_add_u64 v[18:19], v[238:239], 0, s[26:27]
	s_mov_b32 m0, s51
	s_mov_b64 s[0:1], 0x80180
	s_add_i32 s33, s83, s43
	global_load_lds_dwordx4 v[18:19], off
	v_lshl_add_u64 v[18:19], v[238:239], 0, s[0:1]
	s_mov_b32 m0, s33
	s_mov_b64 s[0:1], 0xc0180
	s_add_i32 s56, s33, 0x2000
	global_load_lds_dwordx4 v[18:19], off
	v_lshl_add_u64 v[18:19], v[238:239], 0, s[0:1]
	s_mov_b32 m0, s56
	s_nop 0
	global_load_lds_dwordx4 v[18:19], off
	v_lshl_add_u64 v[18:19], v[140:141], 0, s[24:25]
	s_mov_b32 m0, s72
	s_nop 0
	global_load_lds_dwordx4 v[18:19], off
	v_lshl_add_u64 v[18:19], v[140:141], 0, s[26:27]
	s_mov_b32 m0, s73
	s_nop 0
	global_load_lds_dwordx4 v[18:19], off
	s_waitcnt vmcnt(8)
	s_waitcnt lgkmcnt(0)
	s_barrier
	v_mfma_f32_16x16x32_bf16 v[18:21], v[6:9], v[42:45], v[146:149]
	v_mfma_f32_16x16x32_bf16 v[54:57], v[26:29], v[46:49], v[18:21]
	v_mfma_f32_16x16x32_bf16 v[18:21], v[30:33], v[42:45], v[150:153]
	v_mfma_f32_16x16x32_bf16 v[50:53], v[62:65], v[46:49], v[18:21]
	v_mfma_f32_16x16x32_bf16 v[18:21], v[6:9], v[214:217], v[154:157]
	v_mfma_f32_16x16x32_bf16 v[38:41], v[26:29], v[218:221], v[18:21]
	v_mfma_f32_16x16x32_bf16 v[18:21], v[30:33], v[214:217], v[158:161]
	v_mfma_f32_16x16x32_bf16 v[34:37], v[62:65], v[218:221], v[18:21]
	v_mfma_f32_16x16x32_bf16 v[18:21], v[6:9], v[222:225], v[162:165]
	v_mfma_f32_16x16x32_bf16 v[2:5], v[6:9], v[230:233], v[2:5]
	v_mfma_f32_16x16x32_bf16 v[22:25], v[26:29], v[226:229], v[18:21]
	v_mfma_f32_16x16x32_bf16 v[18:21], v[30:33], v[222:225], v[166:169]
	v_mfma_f32_16x16x32_bf16 v[6:9], v[26:29], v[234:237], v[2:5]
	v_mfma_f32_16x16x32_bf16 v[2:5], v[30:33], v[230:233], v[10:13]
	v_mfma_f32_16x16x32_bf16 v[18:21], v[62:65], v[226:229], v[18:21]
	v_mfma_f32_16x16x32_bf16 v[2:5], v[62:65], v[234:237], v[2:5]
	v_mfma_f32_16x16x32_bf16 v[10:13], v[198:201], v[42:45], v[14:17]
	v_mfma_f32_16x16x32_bf16 v[62:65], v[202:205], v[46:49], v[10:13]
	v_mfma_f32_16x16x32_bf16 v[10:13], v[206:209], v[42:45], v[170:173]
	v_mfma_f32_16x16x32_bf16 v[58:61], v[210:213], v[46:49], v[10:13]
	v_mfma_f32_16x16x32_bf16 v[10:13], v[198:201], v[214:217], v[174:177]
	v_mfma_f32_16x16x32_bf16 v[46:49], v[202:205], v[218:221], v[10:13]
	v_mfma_f32_16x16x32_bf16 v[10:13], v[206:209], v[214:217], v[178:181]
	v_mfma_f32_16x16x32_bf16 v[42:45], v[210:213], v[218:221], v[10:13]
	v_mfma_f32_16x16x32_bf16 v[10:13], v[198:201], v[222:225], v[182:185]
	v_mfma_f32_16x16x32_bf16 v[30:33], v[202:205], v[226:229], v[10:13]
	v_mfma_f32_16x16x32_bf16 v[10:13], v[206:209], v[222:225], v[186:189]
	v_mfma_f32_16x16x32_bf16 v[26:29], v[210:213], v[226:229], v[10:13]
	v_mfma_f32_16x16x32_bf16 v[10:13], v[198:201], v[230:233], v[190:193]
	v_mfma_f32_16x16x32_bf16 v[14:17], v[202:205], v[234:237], v[10:13]
	v_mfma_f32_16x16x32_bf16 v[10:13], v[206:209], v[230:233], v[194:197]
	v_mfma_f32_16x16x32_bf16 v[10:13], v[210:213], v[234:237], v[10:13]
	s_barrier
	s_add_u32 s70, s70, 0x80180
	s_addc_u32 s71, s71, 0
	s_add_u32 s57, s68, 0x200
	s_addc_u32 s68, s69, 0
	s_mov_b32 s69, 0
.LBB0_2862:
	ds_read_b128 v[146:149], v1
	ds_read_b128 v[150:153], v1 offset:1024
	ds_read_b128 v[154:157], v1 offset:2048
	ds_read_b128 v[158:161], v1 offset:3072
	ds_read_b128 v[162:165], v142
	ds_read_b128 v[166:169], v142 offset:1024
	ds_read_b128 v[170:173], v142 offset:2048
	ds_read_b128 v[174:177], v142 offset:3072
	s_add_u32 s0, s70, 0xfff80080
	s_addc_u32 s1, s71, -1
	s_cmp_eq_u32 s69, 28
	s_cselect_b32 s1, s41, s1
	s_cselect_b32 s0, s45, s0
	s_cselect_b32 s65, s87, s68
	s_cselect_b32 s64, s88, s57
	s_mov_b32 m0, s79
	v_lshl_add_u64 v[140:141], s[70:71], 0, v[134:135]
	ds_read_b128 v[178:181], v143
	ds_read_b128 v[182:185], v143 offset:1024
	ds_read_b128 v[186:189], v143 offset:2048
	ds_read_b128 v[190:193], v143 offset:3072
	ds_read_b128 v[194:197], v143 offset:4096
	ds_read_b128 v[198:201], v143 offset:5120
	ds_read_b128 v[202:205], v143 offset:6144
	ds_read_b128 v[206:209], v143 offset:7168
	global_load_lds_dwordx4 v[140:141], off
	v_lshl_add_u64 v[140:141], v[140:141], 0, s[28:29]
	s_mov_b32 m0, s80
	s_nop 0
	global_load_lds_dwordx4 v[140:141], off
	s_waitcnt vmcnt(8)
	s_waitcnt lgkmcnt(0)
	s_barrier
	v_mfma_f32_16x16x32_bf16 v[118:121], v[146:149], v[178:181], v[118:121]
	v_mfma_f32_16x16x32_bf16 v[114:117], v[154:157], v[178:181], v[114:117]
	v_mfma_f32_16x16x32_bf16 v[102:105], v[146:149], v[186:189], v[102:105]
	v_mfma_f32_16x16x32_bf16 v[98:101], v[154:157], v[186:189], v[98:101]
	v_mfma_f32_16x16x32_bf16 v[86:89], v[146:149], v[194:197], v[86:89]
	v_mfma_f32_16x16x32_bf16 v[82:85], v[154:157], v[194:197], v[82:85]
	v_mfma_f32_16x16x32_bf16 v[70:73], v[146:149], v[202:205], v[70:73]
	v_mfma_f32_16x16x32_bf16 v[66:69], v[154:157], v[202:205], v[66:69]
	v_mfma_f32_16x16x32_bf16 v[118:121], v[150:153], v[182:185], v[118:121]
	v_mfma_f32_16x16x32_bf16 v[114:117], v[158:161], v[182:185], v[114:117]
	v_mfma_f32_16x16x32_bf16 v[102:105], v[150:153], v[190:193], v[102:105]
	v_mfma_f32_16x16x32_bf16 v[98:101], v[158:161], v[190:193], v[98:101]
	v_mfma_f32_16x16x32_bf16 v[86:89], v[150:153], v[198:201], v[86:89]
	v_mfma_f32_16x16x32_bf16 v[82:85], v[158:161], v[198:201], v[82:85]
	v_mfma_f32_16x16x32_bf16 v[70:73], v[150:153], v[206:209], v[70:73]
	v_mfma_f32_16x16x32_bf16 v[66:69], v[158:161], v[206:209], v[66:69]
	v_mfma_f32_16x16x32_bf16 v[126:129], v[162:165], v[178:181], v[126:129]
	v_mfma_f32_16x16x32_bf16 v[122:125], v[170:173], v[178:181], v[122:125]
	v_mfma_f32_16x16x32_bf16 v[110:113], v[162:165], v[186:189], v[110:113]
	v_mfma_f32_16x16x32_bf16 v[106:109], v[170:173], v[186:189], v[106:109]
	v_mfma_f32_16x16x32_bf16 v[94:97], v[162:165], v[194:197], v[94:97]
	v_mfma_f32_16x16x32_bf16 v[90:93], v[170:173], v[194:197], v[90:93]
	v_mfma_f32_16x16x32_bf16 v[78:81], v[162:165], v[202:205], v[78:81]
	v_mfma_f32_16x16x32_bf16 v[74:77], v[170:173], v[202:205], v[74:77]
	v_mfma_f32_16x16x32_bf16 v[126:129], v[166:169], v[182:185], v[126:129]
	v_mfma_f32_16x16x32_bf16 v[122:125], v[174:177], v[182:185], v[122:125]
	v_mfma_f32_16x16x32_bf16 v[110:113], v[166:169], v[190:193], v[110:113]
	v_mfma_f32_16x16x32_bf16 v[106:109], v[174:177], v[190:193], v[106:109]
	v_mfma_f32_16x16x32_bf16 v[94:97], v[166:169], v[198:201], v[94:97]
	v_mfma_f32_16x16x32_bf16 v[90:93], v[174:177], v[198:201], v[90:93]
	v_mfma_f32_16x16x32_bf16 v[78:81], v[166:169], v[206:209], v[78:81]
	v_mfma_f32_16x16x32_bf16 v[74:77], v[174:177], v[206:209], v[74:77]
	s_barrier
	s_mov_b32 m0, s81
	v_lshl_add_u64 v[140:141], s[64:65], 0, v[130:131]
	ds_read_b128 v[178:181], v143 offset:16384
	ds_read_b128 v[182:185], v143 offset:17408
	ds_read_b128 v[186:189], v143 offset:18432
	ds_read_b128 v[190:193], v143 offset:19456
	ds_read_b128 v[194:197], v143 offset:20480
	ds_read_b128 v[198:201], v143 offset:21504
	ds_read_b128 v[202:205], v143 offset:22528
	ds_read_b128 v[206:209], v143 offset:23552
	global_load_lds_dwordx4 v[140:141], off
	v_lshl_add_u64 v[210:211], v[140:141], 0, s[28:29]
	s_mov_b32 m0, s89
	s_nop 0
	global_load_lds_dwordx4 v[210:211], off
	v_lshl_add_u64 v[210:211], v[140:141], 0, s[30:31]
	s_mov_b32 m0, s90
	s_nop 0
	global_load_lds_dwordx4 v[210:211], off
	v_lshl_add_u64 v[210:211], v[140:141], 0, s[34:35]
	s_mov_b32 m0, s91
	s_nop 0
	global_load_lds_dwordx4 v[210:211], off
	v_lshl_add_u64 v[210:211], s[0:1], 0, v[132:133]
	s_mov_b32 m0, s53
	v_lshl_add_u64 v[212:213], v[210:211], 0, s[28:29]
	global_load_lds_dwordx4 v[210:211], off
	s_mov_b32 m0, s54
	s_nop 0
	global_load_lds_dwordx4 v[212:213], off
	s_waitcnt vmcnt(8)
	s_waitcnt lgkmcnt(0)
	s_barrier
	v_mfma_f32_16x16x32_bf16 v[54:57], v[146:149], v[178:181], v[54:57]
	v_mfma_f32_16x16x32_bf16 v[50:53], v[154:157], v[178:181], v[50:53]
	v_mfma_f32_16x16x32_bf16 v[38:41], v[146:149], v[186:189], v[38:41]
	v_mfma_f32_16x16x32_bf16 v[34:37], v[154:157], v[186:189], v[34:37]
	v_mfma_f32_16x16x32_bf16 v[22:25], v[146:149], v[194:197], v[22:25]
	v_mfma_f32_16x16x32_bf16 v[18:21], v[154:157], v[194:197], v[18:21]
	v_mfma_f32_16x16x32_bf16 v[6:9], v[146:149], v[202:205], v[6:9]
	v_mfma_f32_16x16x32_bf16 v[2:5], v[154:157], v[202:205], v[2:5]
	v_mfma_f32_16x16x32_bf16 v[54:57], v[150:153], v[182:185], v[54:57]
	v_mfma_f32_16x16x32_bf16 v[50:53], v[158:161], v[182:185], v[50:53]
	v_mfma_f32_16x16x32_bf16 v[38:41], v[150:153], v[190:193], v[38:41]
	v_mfma_f32_16x16x32_bf16 v[34:37], v[158:161], v[190:193], v[34:37]
	v_mfma_f32_16x16x32_bf16 v[22:25], v[150:153], v[198:201], v[22:25]
	v_mfma_f32_16x16x32_bf16 v[18:21], v[158:161], v[198:201], v[18:21]
	v_mfma_f32_16x16x32_bf16 v[6:9], v[150:153], v[206:209], v[6:9]
	v_mfma_f32_16x16x32_bf16 v[2:5], v[158:161], v[206:209], v[2:5]
	v_mfma_f32_16x16x32_bf16 v[62:65], v[162:165], v[178:181], v[62:65]
	v_mfma_f32_16x16x32_bf16 v[58:61], v[170:173], v[178:181], v[58:61]
	v_mfma_f32_16x16x32_bf16 v[46:49], v[162:165], v[186:189], v[46:49]
	v_mfma_f32_16x16x32_bf16 v[42:45], v[170:173], v[186:189], v[42:45]
	v_mfma_f32_16x16x32_bf16 v[30:33], v[162:165], v[194:197], v[30:33]
	v_mfma_f32_16x16x32_bf16 v[26:29], v[170:173], v[194:197], v[26:29]
	v_mfma_f32_16x16x32_bf16 v[14:17], v[162:165], v[202:205], v[14:17]
	v_mfma_f32_16x16x32_bf16 v[10:13], v[170:173], v[202:205], v[10:13]
	v_mfma_f32_16x16x32_bf16 v[62:65], v[166:169], v[182:185], v[62:65]
	v_mfma_f32_16x16x32_bf16 v[58:61], v[174:177], v[182:185], v[58:61]
	v_mfma_f32_16x16x32_bf16 v[46:49], v[166:169], v[190:193], v[46:49]
	v_mfma_f32_16x16x32_bf16 v[42:45], v[174:177], v[190:193], v[42:45]
	v_mfma_f32_16x16x32_bf16 v[30:33], v[166:169], v[198:201], v[30:33]
	v_mfma_f32_16x16x32_bf16 v[26:29], v[174:177], v[198:201], v[26:29]
	v_mfma_f32_16x16x32_bf16 v[14:17], v[166:169], v[206:209], v[14:17]
	v_mfma_f32_16x16x32_bf16 v[10:13], v[174:177], v[206:209], v[10:13]
	s_barrier
; #define PG8_WAIT_V(n) asm volatile("s_waitcnt vmcnt(" #n ")" ::: "memory")
; #define PG8_BAR __builtin_amdgcn_s_barrier()
; template <class Epi, class Sched, bool ALIGN_EPI = true, bool SP2 = true, bool FULLLINE = false, bool NOSTAGE = false, bool FP8 = false>
; __device__ __forceinline__ void gemm_phase(PG8_LAS unsigned char* lds, const Gemm g, const Sched& S, const Epi& E) {
;     ...
;         static_assert(SP2, "only the SP2 loop is kept");
;         { const int t = 0; if constexpr (Epi::NST == 16) PG8_ITER(PG8_WAIT_V(24)); else if constexpr (Epi::NST == 8) PG8_ITER(PG8_WAIT_V(16)); else PG8_ITER(PG8_WAIT_V(8)); }
;         for (int t = 2; t < nt; t += 2) PG8_ITER(PG8_WAIT_V(8));
;     ...
;         if constexpr (ALIGN_EPI) { if (wr == 0) PG8_BAR; }
;         { int ln_ = lane; asm volatile("" : "+v"(ln_));
;           E(acc, cur, wr, wc, ln_ & 15, ln_ >> 4); } S.done(cur);
;         if (!has_next) break;
	ds_read_b128 v[146:149], v144
	ds_read_b128 v[150:153], v144 offset:1024
	ds_read_b128 v[154:157], v144 offset:2048
	ds_read_b128 v[158:161], v144 offset:3072
	ds_read_b128 v[162:165], v145
	ds_read_b128 v[166:169], v145 offset:1024
	ds_read_b128 v[170:173], v145 offset:2048
	ds_read_b128 v[174:177], v145 offset:3072
	s_mov_b32 m0, s55
	v_lshl_add_u64 v[212:213], v[210:211], 0, s[30:31]
	ds_read_b128 v[178:181], v143 offset:32768
	ds_read_b128 v[182:185], v143 offset:33792
	ds_read_b128 v[186:189], v143 offset:34816
	ds_read_b128 v[190:193], v143 offset:35840
	ds_read_b128 v[194:197], v143 offset:36864
	ds_read_b128 v[198:201], v143 offset:37888
	ds_read_b128 v[202:205], v143 offset:38912
	ds_read_b128 v[206:209], v143 offset:39936
	global_load_lds_dwordx4 v[212:213], off
	v_lshl_add_u64 v[212:213], v[210:211], 0, s[34:35]
	s_mov_b32 m0, s67
	s_nop 0
	global_load_lds_dwordx4 v[212:213], off
	s_waitcnt vmcnt(8)
	s_waitcnt lgkmcnt(0)
	s_barrier
	v_mfma_f32_16x16x32_bf16 v[118:121], v[146:149], v[178:181], v[118:121]
	v_mfma_f32_16x16x32_bf16 v[114:117], v[154:157], v[178:181], v[114:117]
	v_mfma_f32_16x16x32_bf16 v[102:105], v[146:149], v[186:189], v[102:105]
	v_mfma_f32_16x16x32_bf16 v[98:101], v[154:157], v[186:189], v[98:101]
	v_mfma_f32_16x16x32_bf16 v[86:89], v[146:149], v[194:197], v[86:89]
	v_mfma_f32_16x16x32_bf16 v[82:85], v[154:157], v[194:197], v[82:85]
	v_mfma_f32_16x16x32_bf16 v[70:73], v[146:149], v[202:205], v[70:73]
	v_mfma_f32_16x16x32_bf16 v[66:69], v[154:157], v[202:205], v[66:69]
	v_mfma_f32_16x16x32_bf16 v[118:121], v[150:153], v[182:185], v[118:121]
	v_mfma_f32_16x16x32_bf16 v[114:117], v[158:161], v[182:185], v[114:117]
	v_mfma_f32_16x16x32_bf16 v[102:105], v[150:153], v[190:193], v[102:105]
	v_mfma_f32_16x16x32_bf16 v[98:101], v[158:161], v[190:193], v[98:101]
	v_mfma_f32_16x16x32_bf16 v[86:89], v[150:153], v[198:201], v[86:89]
	v_mfma_f32_16x16x32_bf16 v[82:85], v[158:161], v[198:201], v[82:85]
	v_mfma_f32_16x16x32_bf16 v[70:73], v[150:153], v[206:209], v[70:73]
	v_mfma_f32_16x16x32_bf16 v[66:69], v[158:161], v[206:209], v[66:69]
	v_mfma_f32_16x16x32_bf16 v[126:129], v[162:165], v[178:181], v[126:129]
	v_mfma_f32_16x16x32_bf16 v[122:125], v[170:173], v[178:181], v[122:125]
	v_mfma_f32_16x16x32_bf16 v[110:113], v[162:165], v[186:189], v[110:113]
	v_mfma_f32_16x16x32_bf16 v[106:109], v[170:173], v[186:189], v[106:109]
	v_mfma_f32_16x16x32_bf16 v[94:97], v[162:165], v[194:197], v[94:97]
	v_mfma_f32_16x16x32_bf16 v[90:93], v[170:173], v[194:197], v[90:93]
	v_mfma_f32_16x16x32_bf16 v[78:81], v[162:165], v[202:205], v[78:81]
	v_mfma_f32_16x16x32_bf16 v[74:77], v[170:173], v[202:205], v[74:77]
	v_mfma_f32_16x16x32_bf16 v[126:129], v[166:169], v[182:185], v[126:129]
	v_mfma_f32_16x16x32_bf16 v[122:125], v[174:177], v[182:185], v[122:125]
	v_mfma_f32_16x16x32_bf16 v[110:113], v[166:169], v[190:193], v[110:113]
	v_mfma_f32_16x16x32_bf16 v[106:109], v[174:177], v[190:193], v[106:109]
	v_mfma_f32_16x16x32_bf16 v[94:97], v[166:169], v[198:201], v[94:97]
	v_mfma_f32_16x16x32_bf16 v[90:93], v[174:177], v[198:201], v[90:93]
	v_mfma_f32_16x16x32_bf16 v[78:81], v[166:169], v[206:209], v[78:81]
	v_mfma_f32_16x16x32_bf16 v[74:77], v[174:177], v[206:209], v[74:77]
	s_barrier
	s_mov_b32 m0, s50
	v_lshl_add_u64 v[212:213], v[140:141], 0, s[36:37]
	ds_read_b128 v[178:181], v143 offset:49152
	ds_read_b128 v[182:185], v143 offset:50176
	ds_read_b128 v[186:189], v143 offset:51200
	ds_read_b128 v[190:193], v143 offset:52224
	ds_read_b128 v[194:197], v143 offset:53248
	ds_read_b128 v[198:201], v143 offset:54272
	ds_read_b128 v[202:205], v143 offset:55296
	ds_read_b128 v[206:209], v143 offset:56320
	global_load_lds_dwordx4 v[212:213], off
	v_lshl_add_u64 v[212:213], v[140:141], 0, s[38:39]
	s_mov_b32 m0, s51
	s_nop 0
	global_load_lds_dwordx4 v[212:213], off
	v_lshl_add_u64 v[212:213], v[140:141], 0, s[12:13]
	s_mov_b32 m0, s33
	v_lshl_add_u64 v[140:141], v[140:141], 0, s[14:15]
	global_load_lds_dwordx4 v[212:213], off
	s_mov_b32 m0, s56
	s_nop 0
	global_load_lds_dwordx4 v[140:141], off
	v_lshl_add_u64 v[140:141], v[210:211], 0, s[36:37]
	s_mov_b32 m0, s72
	s_nop 0
	global_load_lds_dwordx4 v[140:141], off
	v_lshl_add_u64 v[140:141], v[210:211], 0, s[38:39]
	s_mov_b32 m0, s73
	s_nop 0
	global_load_lds_dwordx4 v[140:141], off
	s_waitcnt vmcnt(8)
	s_waitcnt lgkmcnt(0)
	s_barrier
	v_mfma_f32_16x16x32_bf16 v[54:57], v[146:149], v[178:181], v[54:57]
	v_mfma_f32_16x16x32_bf16 v[50:53], v[154:157], v[178:181], v[50:53]
	v_mfma_f32_16x16x32_bf16 v[38:41], v[146:149], v[186:189], v[38:41]
	v_mfma_f32_16x16x32_bf16 v[34:37], v[154:157], v[186:189], v[34:37]
	v_mfma_f32_16x16x32_bf16 v[22:25], v[146:149], v[194:197], v[22:25]
	v_mfma_f32_16x16x32_bf16 v[18:21], v[154:157], v[194:197], v[18:21]
	v_mfma_f32_16x16x32_bf16 v[6:9], v[146:149], v[202:205], v[6:9]
	v_mfma_f32_16x16x32_bf16 v[2:5], v[154:157], v[202:205], v[2:5]
	v_mfma_f32_16x16x32_bf16 v[54:57], v[150:153], v[182:185], v[54:57]
	v_mfma_f32_16x16x32_bf16 v[50:53], v[158:161], v[182:185], v[50:53]
	v_mfma_f32_16x16x32_bf16 v[38:41], v[150:153], v[190:193], v[38:41]
	v_mfma_f32_16x16x32_bf16 v[34:37], v[158:161], v[190:193], v[34:37]
	v_mfma_f32_16x16x32_bf16 v[22:25], v[150:153], v[198:201], v[22:25]
	v_mfma_f32_16x16x32_bf16 v[18:21], v[158:161], v[198:201], v[18:21]
	v_mfma_f32_16x16x32_bf16 v[6:9], v[150:153], v[206:209], v[6:9]
	v_mfma_f32_16x16x32_bf16 v[2:5], v[158:161], v[206:209], v[2:5]
	v_mfma_f32_16x16x32_bf16 v[62:65], v[162:165], v[178:181], v[62:65]
	v_mfma_f32_16x16x32_bf16 v[58:61], v[170:173], v[178:181], v[58:61]
	v_mfma_f32_16x16x32_bf16 v[46:49], v[162:165], v[186:189], v[46:49]
	v_mfma_f32_16x16x32_bf16 v[42:45], v[170:173], v[186:189], v[42:45]
	v_mfma_f32_16x16x32_bf16 v[30:33], v[162:165], v[194:197], v[30:33]
	v_mfma_f32_16x16x32_bf16 v[26:29], v[170:173], v[194:197], v[26:29]
	v_mfma_f32_16x16x32_bf16 v[14:17], v[162:165], v[202:205], v[14:17]
	v_mfma_f32_16x16x32_bf16 v[10:13], v[170:173], v[202:205], v[10:13]
	v_mfma_f32_16x16x32_bf16 v[62:65], v[166:169], v[182:185], v[62:65]
	v_mfma_f32_16x16x32_bf16 v[58:61], v[174:177], v[182:185], v[58:61]
	v_mfma_f32_16x16x32_bf16 v[46:49], v[166:169], v[190:193], v[46:49]
	v_mfma_f32_16x16x32_bf16 v[42:45], v[174:177], v[190:193], v[42:45]
	v_mfma_f32_16x16x32_bf16 v[30:33], v[166:169], v[198:201], v[30:33]
	v_mfma_f32_16x16x32_bf16 v[26:29], v[174:177], v[198:201], v[26:29]
	v_mfma_f32_16x16x32_bf16 v[14:17], v[166:169], v[206:209], v[14:17]
	v_mfma_f32_16x16x32_bf16 v[10:13], v[174:177], v[206:209], v[10:13]
	s_barrier
	s_add_i32 s69, s69, 2
	s_add_u32 s70, s70, 0x100
	s_addc_u32 s71, s71, 0
	s_add_u32 s57, s57, 0x100
	s_addc_u32 s68, s68, 0
	s_cmp_gt_u32 s69, 29
	s_cbranch_scc0 .LBB0_2862
	s_and_b64 vcc, exec, s[10:11]
	s_cbranch_vccz .LBB0_2865
	s_barrier

; #define PG8_WAIT_V(n) asm volatile("s_waitcnt vmcnt(" #n ")" ::: "memory")
; template <class Epi, class Sched, bool ALIGN_EPI = true, bool SP2 = true, bool FULLLINE = false, bool NOSTAGE = false, bool FP8 = false>
; __device__ __forceinline__ void gemm_phase(PG8_LAS unsigned char* lds, const Gemm g, const Sched& S, const Epi& E) {
;     ...
;         { const int t = 0; if constexpr (Epi::NST == 16) PG8_ITER(PG8_WAIT_V(24)); else if constexpr (Epi::NST == 8) PG8_ITER(PG8_WAIT_V(16)); else PG8_ITER(PG8_WAIT_V(8)); }
.LBB0_2964:
	ds_read_b128 v[2:5], v1
	ds_read_b128 v[6:9], v1 offset:1024
	ds_read_b128 v[10:13], v1 offset:2048
	ds_read_b128 v[14:17], v1 offset:3072
	ds_read_b128 v[18:21], v168
	ds_read_b128 v[22:25], v168 offset:1024
	ds_read_b128 v[26:29], v168 offset:2048
	ds_read_b128 v[30:33], v168 offset:3072
	v_lshl_add_u64 v[244:245], s[46:47], 0, v[150:151]
	s_add_i32 s81, s53, 0xc000
	v_lshl_add_u64 v[66:67], v[244:245], 0, s[14:15]
	s_mov_b32 m0, s81
	s_add_i32 s82, s53, 0xe000
	ds_read_b128 v[34:37], v169
	ds_read_b128 v[38:41], v169 offset:1024
	ds_read_b128 v[42:45], v169 offset:2048
	ds_read_b128 v[46:49], v169 offset:3072
	ds_read_b128 v[50:53], v169 offset:4096
	ds_read_b128 v[54:57], v169 offset:5120
	ds_read_b128 v[58:61], v169 offset:6144
	ds_read_b128 v[62:65], v169 offset:7168
	global_load_lds_dwordx4 v[66:67], off
	v_lshl_add_u64 v[66:67], v[244:245], 0, s[16:17]
	s_mov_b32 m0, s82
	s_nop 0
	global_load_lds_dwordx4 v[66:67], off
	s_waitcnt vmcnt(24)
	s_waitcnt lgkmcnt(0)
	s_barrier
	v_mfma_f32_16x16x32_bf16 v[66:69], v[2:5], v[34:37], 0
	v_mfma_f32_16x16x32_bf16 v[70:73], v[10:13], v[34:37], 0
	v_mfma_f32_16x16x32_bf16 v[74:77], v[2:5], v[42:45], 0
	v_mfma_f32_16x16x32_bf16 v[78:81], v[10:13], v[42:45], 0
	v_mfma_f32_16x16x32_bf16 v[90:93], v[2:5], v[58:61], 0
	v_mfma_f32_16x16x32_bf16 v[66:69], v[6:9], v[38:41], v[66:69]
	v_mfma_f32_16x16x32_bf16 v[70:73], v[14:17], v[38:41], v[70:73]
	v_mfma_f32_16x16x32_bf16 v[74:77], v[6:9], v[46:49], v[74:77]
	v_mfma_f32_16x16x32_bf16 v[78:81], v[14:17], v[46:49], v[78:81]
	v_mfma_f32_16x16x32_bf16 v[82:85], v[2:5], v[50:53], 0
	v_mfma_f32_16x16x32_bf16 v[86:89], v[10:13], v[50:53], 0
	v_mfma_f32_16x16x32_bf16 v[90:93], v[6:9], v[62:65], v[90:93]
	v_mfma_f32_16x16x32_bf16 v[94:97], v[10:13], v[58:61], 0
	v_mfma_f32_16x16x32_bf16 v[82:85], v[6:9], v[54:57], v[82:85]
	v_mfma_f32_16x16x32_bf16 v[86:89], v[14:17], v[54:57], v[86:89]
	v_mfma_f32_16x16x32_bf16 v[94:97], v[14:17], v[62:65], v[94:97]
	v_mfma_f32_16x16x32_bf16 v[98:101], v[18:21], v[34:37], 0
	v_mfma_f32_16x16x32_bf16 v[34:37], v[26:29], v[34:37], 0
	v_mfma_f32_16x16x32_bf16 v[98:101], v[22:25], v[38:41], v[98:101]
	v_mfma_f32_16x16x32_bf16 v[34:37], v[30:33], v[38:41], v[34:37]
	v_mfma_f32_16x16x32_bf16 v[38:41], v[18:21], v[42:45], 0
	v_mfma_f32_16x16x32_bf16 v[42:45], v[26:29], v[42:45], 0
	v_mfma_f32_16x16x32_bf16 v[38:41], v[22:25], v[46:49], v[38:41]
	v_mfma_f32_16x16x32_bf16 v[42:45], v[30:33], v[46:49], v[42:45]
	v_mfma_f32_16x16x32_bf16 v[46:49], v[18:21], v[50:53], 0
	v_mfma_f32_16x16x32_bf16 v[50:53], v[26:29], v[50:53], 0
	v_mfma_f32_16x16x32_bf16 v[46:49], v[22:25], v[54:57], v[46:49]
	v_mfma_f32_16x16x32_bf16 v[50:53], v[30:33], v[54:57], v[50:53]
	v_mfma_f32_16x16x32_bf16 v[54:57], v[18:21], v[58:61], 0
	v_mfma_f32_16x16x32_bf16 v[58:61], v[26:29], v[58:61], 0
	v_mfma_f32_16x16x32_bf16 v[54:57], v[22:25], v[62:65], v[54:57]
	v_mfma_f32_16x16x32_bf16 v[58:61], v[30:33], v[62:65], v[58:61]
	s_barrier
	v_lshl_add_u64 v[246:247], s[58:59], 0, v[152:153]
	s_add_i32 s83, s73, s52
	v_lshl_add_u64 v[130:131], v[246:247], 0, s[18:19]
	s_mov_b32 m0, s83
	s_add_i32 s84, s83, 0x2000
	ds_read_b128 v[62:65], v169 offset:16384
	ds_read_b128 v[102:105], v169 offset:17408
	ds_read_b128 v[106:109], v169 offset:18432
	ds_read_b128 v[110:113], v169 offset:19456
	ds_read_b128 v[114:117], v169 offset:20480
	ds_read_b128 v[118:121], v169 offset:21504
	ds_read_b128 v[122:125], v169 offset:22528
	ds_read_b128 v[126:129], v169 offset:23552
	global_load_lds_dwordx4 v[130:131], off
	v_lshl_add_u64 v[130:131], v[246:247], 0, s[20:21]
	s_mov_b32 m0, s84
	s_add_i32 s85, s74, s52
	global_load_lds_dwordx4 v[130:131], off
	v_lshl_add_u64 v[130:131], v[246:247], 0, s[22:23]
	s_mov_b32 m0, s85
	s_add_i32 s87, s85, 0x2000
	global_load_lds_dwordx4 v[130:131], off
	v_lshl_add_u64 v[130:131], v[246:247], 0, s[24:25]
	s_mov_b32 m0, s87
	s_nop 0
	global_load_lds_dwordx4 v[130:131], off
	v_lshl_add_u64 v[130:131], v[244:245], 0, s[18:19]
	s_mov_b32 m0, s53
	s_nop 0
	global_load_lds_dwordx4 v[130:131], off
	v_lshl_add_u64 v[130:131], v[244:245], 0, s[20:21]
	s_mov_b32 m0, s54
	s_nop 0
	global_load_lds_dwordx4 v[130:131], off
	s_waitcnt vmcnt(24)
	s_waitcnt lgkmcnt(0)
	s_barrier
	v_mfma_f32_16x16x32_bf16 v[130:133], v[2:5], v[62:65], 0
	v_mfma_f32_16x16x32_bf16 v[146:149], v[6:9], v[102:105], v[130:133]
	v_mfma_f32_16x16x32_bf16 v[130:133], v[10:13], v[62:65], 0
	v_mfma_f32_16x16x32_bf16 v[160:163], v[14:17], v[102:105], v[130:133]
	v_mfma_f32_16x16x32_bf16 v[130:133], v[2:5], v[106:109], 0
	v_mfma_f32_16x16x32_bf16 v[164:167], v[6:9], v[110:113], v[130:133]
	v_mfma_f32_16x16x32_bf16 v[130:133], v[10:13], v[106:109], 0
	v_mfma_f32_16x16x32_bf16 v[172:175], v[14:17], v[110:113], v[130:133]
	v_mfma_f32_16x16x32_bf16 v[130:133], v[2:5], v[114:117], 0
	v_mfma_f32_16x16x32_bf16 v[2:5], v[2:5], v[122:125], 0
	v_mfma_f32_16x16x32_bf16 v[176:179], v[6:9], v[118:121], v[130:133]
	v_mfma_f32_16x16x32_bf16 v[2:5], v[6:9], v[126:129], v[2:5]
	v_mfma_f32_16x16x32_bf16 v[6:9], v[10:13], v[122:125], 0
	v_mfma_f32_16x16x32_bf16 v[130:133], v[10:13], v[114:117], 0
	v_mfma_f32_16x16x32_bf16 v[6:9], v[14:17], v[126:129], v[6:9]
	v_mfma_f32_16x16x32_bf16 v[180:183], v[14:17], v[118:121], v[130:133]
	v_mfma_f32_16x16x32_bf16 v[10:13], v[18:21], v[62:65], 0
	v_mfma_f32_16x16x32_bf16 v[184:187], v[22:25], v[102:105], v[10:13]
	v_mfma_f32_16x16x32_bf16 v[10:13], v[26:29], v[62:65], 0
	v_mfma_f32_16x16x32_bf16 v[102:105], v[30:33], v[102:105], v[10:13]
	v_mfma_f32_16x16x32_bf16 v[10:13], v[18:21], v[106:109], 0
	v_mfma_f32_16x16x32_bf16 v[188:191], v[22:25], v[110:113], v[10:13]
	v_mfma_f32_16x16x32_bf16 v[10:13], v[26:29], v[106:109], 0
	v_mfma_f32_16x16x32_bf16 v[192:195], v[30:33], v[110:113], v[10:13]
	v_mfma_f32_16x16x32_bf16 v[10:13], v[18:21], v[114:117], 0
	v_mfma_f32_16x16x32_bf16 v[196:199], v[22:25], v[118:121], v[10:13]
	v_mfma_f32_16x16x32_bf16 v[10:13], v[26:29], v[114:117], 0
	v_mfma_f32_16x16x32_bf16 v[200:203], v[30:33], v[118:121], v[10:13]
	v_mfma_f32_16x16x32_bf16 v[10:13], v[18:21], v[122:125], 0
	v_mfma_f32_16x16x32_bf16 v[204:207], v[22:25], v[126:129], v[10:13]
	v_mfma_f32_16x16x32_bf16 v[10:13], v[26:29], v[122:125], 0
	v_mfma_f32_16x16x32_bf16 v[208:211], v[30:33], v[126:129], v[10:13]
	s_barrier
; #define PG8_WAIT_V(n) asm volatile("s_waitcnt vmcnt(" #n ")" ::: "memory")
; template <class Epi, class Sched, bool ALIGN_EPI = true, bool SP2 = true, bool FULLLINE = false, bool NOSTAGE = false, bool FP8 = false>
; __device__ __forceinline__ void gemm_phase(PG8_LAS unsigned char* lds, const Gemm g, const Sched& S, const Epi& E) {
;     ...
;         { const int t = 0; if constexpr (Epi::NST == 16) PG8_ITER(PG8_WAIT_V(24)); else if constexpr (Epi::NST == 8) PG8_ITER(PG8_WAIT_V(16)); else PG8_ITER(PG8_WAIT_V(8)); }
	s_nop 5
	ds_read_b128 v[10:13], v170
	ds_read_b128 v[14:17], v170 offset:1024
	ds_read_b128 v[18:21], v170 offset:2048
	ds_read_b128 v[22:25], v170 offset:3072
	ds_read_b128 v[212:215], v171
	ds_read_b128 v[216:219], v171 offset:1024
	ds_read_b128 v[220:223], v171 offset:2048
	ds_read_b128 v[224:227], v171 offset:3072
	s_mov_b32 m0, s55
	v_lshl_add_u64 v[106:107], v[244:245], 0, s[22:23]
	ds_read_b128 v[26:29], v169 offset:32768
	ds_read_b128 v[30:33], v169 offset:33792
	ds_read_b128 v[62:65], v169 offset:34816
	ds_read_b128 v[114:117], v169 offset:35840
	ds_read_b128 v[228:231], v169 offset:36864
	ds_read_b128 v[232:235], v169 offset:37888
	ds_read_b128 v[236:239], v169 offset:38912
	ds_read_b128 v[240:243], v169 offset:39936
	global_load_lds_dwordx4 v[106:107], off
	v_lshl_add_u64 v[106:107], v[244:245], 0, s[24:25]
	s_mov_b32 m0, s62
	s_nop 0
	global_load_lds_dwordx4 v[106:107], off
	s_waitcnt vmcnt(8)
	s_waitcnt lgkmcnt(0)
	s_barrier
	v_mfma_f32_16x16x32_bf16 v[66:69], v[10:13], v[26:29], v[66:69]
	v_mfma_f32_16x16x32_bf16 v[138:141], v[14:17], v[30:33], v[66:69]
	v_mfma_f32_16x16x32_bf16 v[66:69], v[18:21], v[26:29], v[70:73]
	v_mfma_f32_16x16x32_bf16 v[134:137], v[22:25], v[30:33], v[66:69]
	v_mfma_f32_16x16x32_bf16 v[66:69], v[10:13], v[62:65], v[74:77]
	v_mfma_f32_16x16x32_bf16 v[126:129], v[14:17], v[114:117], v[66:69]
	v_mfma_f32_16x16x32_bf16 v[66:69], v[18:21], v[62:65], v[78:81]
	v_mfma_f32_16x16x32_bf16 v[122:125], v[22:25], v[114:117], v[66:69]
	v_mfma_f32_16x16x32_bf16 v[66:69], v[10:13], v[228:231], v[82:85]
	v_mfma_f32_16x16x32_bf16 v[110:113], v[14:17], v[232:235], v[66:69]
	v_mfma_f32_16x16x32_bf16 v[66:69], v[18:21], v[228:231], v[86:89]
	v_mfma_f32_16x16x32_bf16 v[106:109], v[22:25], v[232:235], v[66:69]
	v_mfma_f32_16x16x32_bf16 v[66:69], v[10:13], v[236:239], v[90:93]
	v_mfma_f32_16x16x32_bf16 v[78:81], v[14:17], v[240:243], v[66:69]
	v_mfma_f32_16x16x32_bf16 v[66:69], v[18:21], v[236:239], v[94:97]
	v_mfma_f32_16x16x32_bf16 v[74:77], v[22:25], v[240:243], v[66:69]
	v_mfma_f32_16x16x32_bf16 v[66:69], v[212:215], v[26:29], v[98:101]
	v_mfma_f32_16x16x32_bf16 v[26:29], v[220:223], v[26:29], v[34:37]
	v_mfma_f32_16x16x32_bf16 v[130:133], v[224:227], v[30:33], v[26:29]
	v_mfma_f32_16x16x32_bf16 v[26:29], v[212:215], v[62:65], v[38:41]
	v_mfma_f32_16x16x32_bf16 v[118:121], v[216:219], v[114:117], v[26:29]
	v_mfma_f32_16x16x32_bf16 v[26:29], v[220:223], v[62:65], v[42:45]
	v_mfma_f32_16x16x32_bf16 v[114:117], v[224:227], v[114:117], v[26:29]
	v_mfma_f32_16x16x32_bf16 v[26:29], v[212:215], v[228:231], v[46:49]
	v_mfma_f32_16x16x32_bf16 v[98:101], v[216:219], v[232:235], v[26:29]
	v_mfma_f32_16x16x32_bf16 v[26:29], v[220:223], v[228:231], v[50:53]
	v_mfma_f32_16x16x32_bf16 v[90:93], v[224:227], v[232:235], v[26:29]
	v_mfma_f32_16x16x32_bf16 v[26:29], v[212:215], v[236:239], v[54:57]
	v_mfma_f32_16x16x32_bf16 v[70:73], v[216:219], v[240:243], v[26:29]
	v_mfma_f32_16x16x32_bf16 v[26:29], v[220:223], v[236:239], v[58:61]
	v_mfma_f32_16x16x32_bf16 v[142:145], v[216:219], v[30:33], v[66:69]
	v_mfma_f32_16x16x32_bf16 v[66:69], v[224:227], v[240:243], v[26:29]
	s_barrier
	s_add_i32 s50, s75, s52
	s_nop 3
	v_lshl_add_u64 v[26:27], v[246:247], 0, s[26:27]
	s_mov_b32 m0, s50
	s_add_i32 s51, s50, 0x2000
	ds_read_b128 v[34:37], v169 offset:49152
	ds_read_b128 v[38:41], v169 offset:50176
	ds_read_b128 v[82:85], v169 offset:51200
	ds_read_b128 v[86:89], v169 offset:52224
	ds_read_b128 v[94:97], v169 offset:53248
	ds_read_b128 v[228:231], v169 offset:54272
	ds_read_b128 v[232:235], v169 offset:55296
	ds_read_b128 v[236:239], v169 offset:56320
	global_load_lds_dwordx4 v[26:27], off
	v_lshl_add_u64 v[26:27], v[246:247], 0, s[28:29]
	s_mov_b32 m0, s51
	s_mov_b64 s[0:1], 0x160180
	s_add_i32 s33, s76, s52
	global_load_lds_dwordx4 v[26:27], off
	v_lshl_add_u64 v[26:27], v[246:247], 0, s[0:1]
	s_mov_b32 m0, s33
	s_mov_b64 s[0:1], 0x210180
	s_add_i32 s56, s33, 0x2000
	global_load_lds_dwordx4 v[26:27], off
	v_lshl_add_u64 v[26:27], v[246:247], 0, s[0:1]
	s_mov_b32 m0, s56
	s_nop 0
	global_load_lds_dwordx4 v[26:27], off
	v_lshl_add_u64 v[26:27], v[244:245], 0, s[26:27]
	s_mov_b32 m0, s63
	s_nop 0
	global_load_lds_dwordx4 v[26:27], off
	v_lshl_add_u64 v[26:27], v[244:245], 0, s[28:29]
	s_mov_b32 m0, s66
	s_nop 0
	global_load_lds_dwordx4 v[26:27], off
	s_waitcnt vmcnt(8)
	s_waitcnt lgkmcnt(0)
	s_barrier
	v_mfma_f32_16x16x32_bf16 v[26:29], v[10:13], v[34:37], v[146:149]
	v_mfma_f32_16x16x32_bf16 v[62:65], v[14:17], v[38:41], v[26:29]
	v_mfma_f32_16x16x32_bf16 v[26:29], v[18:21], v[34:37], v[160:163]
	v_mfma_f32_16x16x32_bf16 v[58:61], v[22:25], v[38:41], v[26:29]
	v_mfma_f32_16x16x32_bf16 v[26:29], v[10:13], v[82:85], v[164:167]
	v_mfma_f32_16x16x32_bf16 v[46:49], v[14:17], v[86:89], v[26:29]
	v_mfma_f32_16x16x32_bf16 v[26:29], v[18:21], v[82:85], v[172:175]
	v_mfma_f32_16x16x32_bf16 v[42:45], v[22:25], v[86:89], v[26:29]
	v_mfma_f32_16x16x32_bf16 v[26:29], v[10:13], v[94:97], v[176:179]
	v_mfma_f32_16x16x32_bf16 v[2:5], v[10:13], v[232:235], v[2:5]
	v_mfma_f32_16x16x32_bf16 v[30:33], v[14:17], v[228:231], v[26:29]
	v_mfma_f32_16x16x32_bf16 v[26:29], v[18:21], v[94:97], v[180:183]
	v_mfma_f32_16x16x32_bf16 v[14:17], v[14:17], v[236:239], v[2:5]
	v_mfma_f32_16x16x32_bf16 v[2:5], v[18:21], v[232:235], v[6:9]
	v_mfma_f32_16x16x32_bf16 v[26:29], v[22:25], v[228:231], v[26:29]
	v_mfma_f32_16x16x32_bf16 v[10:13], v[22:25], v[236:239], v[2:5]
	v_mfma_f32_16x16x32_bf16 v[2:5], v[212:215], v[34:37], v[184:187]
	v_mfma_f32_16x16x32_bf16 v[54:57], v[216:219], v[38:41], v[2:5]
	v_mfma_f32_16x16x32_bf16 v[2:5], v[220:223], v[34:37], v[102:105]
	v_mfma_f32_16x16x32_bf16 v[50:53], v[224:227], v[38:41], v[2:5]
	v_mfma_f32_16x16x32_bf16 v[2:5], v[212:215], v[82:85], v[188:191]
	v_mfma_f32_16x16x32_bf16 v[38:41], v[216:219], v[86:89], v[2:5]
	v_mfma_f32_16x16x32_bf16 v[2:5], v[220:223], v[82:85], v[192:195]
	v_mfma_f32_16x16x32_bf16 v[34:37], v[224:227], v[86:89], v[2:5]
	v_mfma_f32_16x16x32_bf16 v[2:5], v[212:215], v[94:97], v[196:199]
	v_mfma_f32_16x16x32_bf16 v[22:25], v[216:219], v[228:231], v[2:5]
	v_mfma_f32_16x16x32_bf16 v[2:5], v[220:223], v[94:97], v[200:203]
	v_mfma_f32_16x16x32_bf16 v[18:21], v[224:227], v[228:231], v[2:5]
	v_mfma_f32_16x16x32_bf16 v[2:5], v[212:215], v[232:235], v[204:207]
	v_mfma_f32_16x16x32_bf16 v[6:9], v[216:219], v[236:239], v[2:5]
	v_mfma_f32_16x16x32_bf16 v[2:5], v[220:223], v[232:235], v[208:211]
	v_mfma_f32_16x16x32_bf16 v[2:5], v[224:227], v[236:239], v[2:5]
	s_barrier
	s_add_u32 s46, s46, 0x160180
	s_addc_u32 s47, s47, 0
	s_add_u32 s57, s58, 0x200
	s_addc_u32 s58, s59, 0
	s_mov_b32 s59, 0
; #define PG8_WAIT_V(n) asm volatile("s_waitcnt vmcnt(" #n ")" ::: "memory")
; template <class Epi, class Sched, bool ALIGN_EPI = true, bool SP2 = true, bool FULLLINE = false, bool NOSTAGE = false, bool FP8 = false>
; __device__ __forceinline__ void gemm_phase(PG8_LAS unsigned char* lds, const Gemm g, const Sched& S, const Epi& E) {
;     ...
;         for (int t = 2; t < nt; t += 2) PG8_ITER(PG8_WAIT_V(8));
.LBB0_2965:
	ds_read_b128 v[82:85], v1
	ds_read_b128 v[86:89], v1 offset:1024
	ds_read_b128 v[94:97], v1 offset:2048
	ds_read_b128 v[102:105], v1 offset:3072
	ds_read_b128 v[146:149], v168
	ds_read_b128 v[160:163], v168 offset:1024
	ds_read_b128 v[164:167], v168 offset:2048
	ds_read_b128 v[172:175], v168 offset:3072
	s_add_u32 s0, s46, 0xffea0080
	s_addc_u32 s1, s47, -1
	s_cmpk_eq_i32 s59, 0x54
	s_cselect_b32 s1, s11, s1
	s_cselect_b32 s0, s10, s0
	s_cselect_b32 s65, s45, s58
	s_cselect_b32 s64, s44, s57
	s_mov_b32 m0, s81
	v_lshl_add_u64 v[208:209], s[46:47], 0, v[154:155]
	ds_read_b128 v[176:179], v169
	ds_read_b128 v[180:183], v169 offset:1024
	ds_read_b128 v[184:187], v169 offset:2048
	ds_read_b128 v[188:191], v169 offset:3072
	ds_read_b128 v[192:195], v169 offset:4096
	ds_read_b128 v[196:199], v169 offset:5120
	ds_read_b128 v[200:203], v169 offset:6144
	ds_read_b128 v[204:207], v169 offset:7168
	global_load_lds_dwordx4 v[208:209], off
	v_lshl_add_u64 v[208:209], v[208:209], 0, s[30:31]
	s_mov_b32 m0, s82
	s_nop 0
	global_load_lds_dwordx4 v[208:209], off
	s_waitcnt vmcnt(8)
	s_waitcnt lgkmcnt(0)
	s_barrier
	v_mfma_f32_16x16x32_bf16 v[138:141], v[82:85], v[176:179], v[138:141]
	v_mfma_f32_16x16x32_bf16 v[134:137], v[94:97], v[176:179], v[134:137]
	v_mfma_f32_16x16x32_bf16 v[126:129], v[82:85], v[184:187], v[126:129]
	v_mfma_f32_16x16x32_bf16 v[122:125], v[94:97], v[184:187], v[122:125]
	v_mfma_f32_16x16x32_bf16 v[110:113], v[82:85], v[192:195], v[110:113]
	v_mfma_f32_16x16x32_bf16 v[106:109], v[94:97], v[192:195], v[106:109]
	v_mfma_f32_16x16x32_bf16 v[78:81], v[82:85], v[200:203], v[78:81]
	v_mfma_f32_16x16x32_bf16 v[74:77], v[94:97], v[200:203], v[74:77]
	v_mfma_f32_16x16x32_bf16 v[138:141], v[86:89], v[180:183], v[138:141]
	v_mfma_f32_16x16x32_bf16 v[134:137], v[102:105], v[180:183], v[134:137]
	v_mfma_f32_16x16x32_bf16 v[126:129], v[86:89], v[188:191], v[126:129]
	v_mfma_f32_16x16x32_bf16 v[122:125], v[102:105], v[188:191], v[122:125]
	v_mfma_f32_16x16x32_bf16 v[110:113], v[86:89], v[196:199], v[110:113]
	v_mfma_f32_16x16x32_bf16 v[106:109], v[102:105], v[196:199], v[106:109]
	v_mfma_f32_16x16x32_bf16 v[78:81], v[86:89], v[204:207], v[78:81]
	v_mfma_f32_16x16x32_bf16 v[74:77], v[102:105], v[204:207], v[74:77]
	v_mfma_f32_16x16x32_bf16 v[142:145], v[146:149], v[176:179], v[142:145]
	v_mfma_f32_16x16x32_bf16 v[130:133], v[164:167], v[176:179], v[130:133]
	v_mfma_f32_16x16x32_bf16 v[118:121], v[146:149], v[184:187], v[118:121]
	v_mfma_f32_16x16x32_bf16 v[114:117], v[164:167], v[184:187], v[114:117]
	v_mfma_f32_16x16x32_bf16 v[98:101], v[146:149], v[192:195], v[98:101]
	v_mfma_f32_16x16x32_bf16 v[90:93], v[164:167], v[192:195], v[90:93]
	v_mfma_f32_16x16x32_bf16 v[70:73], v[146:149], v[200:203], v[70:73]
	v_mfma_f32_16x16x32_bf16 v[66:69], v[164:167], v[200:203], v[66:69]
	v_mfma_f32_16x16x32_bf16 v[142:145], v[160:163], v[180:183], v[142:145]
	v_mfma_f32_16x16x32_bf16 v[130:133], v[172:175], v[180:183], v[130:133]
	v_mfma_f32_16x16x32_bf16 v[118:121], v[160:163], v[188:191], v[118:121]
	v_mfma_f32_16x16x32_bf16 v[114:117], v[172:175], v[188:191], v[114:117]
	v_mfma_f32_16x16x32_bf16 v[98:101], v[160:163], v[196:199], v[98:101]
	v_mfma_f32_16x16x32_bf16 v[90:93], v[172:175], v[196:199], v[90:93]
	v_mfma_f32_16x16x32_bf16 v[70:73], v[160:163], v[204:207], v[70:73]
	v_mfma_f32_16x16x32_bf16 v[66:69], v[172:175], v[204:207], v[66:69]
	s_barrier
	s_mov_b32 m0, s83
	v_lshl_add_u64 v[208:209], s[64:65], 0, v[152:153]
	ds_read_b128 v[176:179], v169 offset:16384
	ds_read_b128 v[180:183], v169 offset:17408
	ds_read_b128 v[184:187], v169 offset:18432
	ds_read_b128 v[188:191], v169 offset:19456
	ds_read_b128 v[192:195], v169 offset:20480
	ds_read_b128 v[196:199], v169 offset:21504
	ds_read_b128 v[200:203], v169 offset:22528
	ds_read_b128 v[204:207], v169 offset:23552
	global_load_lds_dwordx4 v[208:209], off
	v_lshl_add_u64 v[210:211], v[208:209], 0, s[30:31]
	s_mov_b32 m0, s84
	s_nop 0
	global_load_lds_dwordx4 v[210:211], off
	v_lshl_add_u64 v[210:211], v[208:209], 0, s[34:35]
	s_mov_b32 m0, s85
	s_nop 0
	global_load_lds_dwordx4 v[210:211], off
	v_lshl_add_u64 v[210:211], v[208:209], 0, s[36:37]
	s_mov_b32 m0, s87
	s_nop 0
	global_load_lds_dwordx4 v[210:211], off
	v_lshl_add_u64 v[210:211], s[0:1], 0, v[150:151]
	s_mov_b32 m0, s53
	v_lshl_add_u64 v[212:213], v[210:211], 0, s[30:31]
	global_load_lds_dwordx4 v[210:211], off
	s_mov_b32 m0, s54
	s_nop 0
	global_load_lds_dwordx4 v[212:213], off
	s_waitcnt vmcnt(8)
	s_waitcnt lgkmcnt(0)
	s_barrier
	v_mfma_f32_16x16x32_bf16 v[62:65], v[82:85], v[176:179], v[62:65]
	v_mfma_f32_16x16x32_bf16 v[58:61], v[94:97], v[176:179], v[58:61]
	v_mfma_f32_16x16x32_bf16 v[46:49], v[82:85], v[184:187], v[46:49]
	v_mfma_f32_16x16x32_bf16 v[42:45], v[94:97], v[184:187], v[42:45]
	v_mfma_f32_16x16x32_bf16 v[30:33], v[82:85], v[192:195], v[30:33]
	v_mfma_f32_16x16x32_bf16 v[26:29], v[94:97], v[192:195], v[26:29]
	v_mfma_f32_16x16x32_bf16 v[14:17], v[82:85], v[200:203], v[14:17]
	v_mfma_f32_16x16x32_bf16 v[10:13], v[94:97], v[200:203], v[10:13]
	v_mfma_f32_16x16x32_bf16 v[62:65], v[86:89], v[180:183], v[62:65]
	v_mfma_f32_16x16x32_bf16 v[58:61], v[102:105], v[180:183], v[58:61]
	v_mfma_f32_16x16x32_bf16 v[46:49], v[86:89], v[188:191], v[46:49]
	v_mfma_f32_16x16x32_bf16 v[42:45], v[102:105], v[188:191], v[42:45]
	v_mfma_f32_16x16x32_bf16 v[30:33], v[86:89], v[196:199], v[30:33]
	v_mfma_f32_16x16x32_bf16 v[26:29], v[102:105], v[196:199], v[26:29]
	v_mfma_f32_16x16x32_bf16 v[14:17], v[86:89], v[204:207], v[14:17]
	v_mfma_f32_16x16x32_bf16 v[10:13], v[102:105], v[204:207], v[10:13]
	v_mfma_f32_16x16x32_bf16 v[54:57], v[146:149], v[176:179], v[54:57]
	v_mfma_f32_16x16x32_bf16 v[50:53], v[164:167], v[176:179], v[50:53]
	v_mfma_f32_16x16x32_bf16 v[38:41], v[146:149], v[184:187], v[38:41]
	v_mfma_f32_16x16x32_bf16 v[34:37], v[164:167], v[184:187], v[34:37]
	v_mfma_f32_16x16x32_bf16 v[22:25], v[146:149], v[192:195], v[22:25]
	v_mfma_f32_16x16x32_bf16 v[18:21], v[164:167], v[192:195], v[18:21]
	v_mfma_f32_16x16x32_bf16 v[6:9], v[146:149], v[200:203], v[6:9]
	v_mfma_f32_16x16x32_bf16 v[2:5], v[164:167], v[200:203], v[2:5]
	v_mfma_f32_16x16x32_bf16 v[54:57], v[160:163], v[180:183], v[54:57]
	v_mfma_f32_16x16x32_bf16 v[50:53], v[172:175], v[180:183], v[50:53]
	v_mfma_f32_16x16x32_bf16 v[38:41], v[160:163], v[188:191], v[38:41]
	v_mfma_f32_16x16x32_bf16 v[34:37], v[172:175], v[188:191], v[34:37]
	v_mfma_f32_16x16x32_bf16 v[22:25], v[160:163], v[196:199], v[22:25]
	v_mfma_f32_16x16x32_bf16 v[18:21], v[172:175], v[196:199], v[18:21]
	v_mfma_f32_16x16x32_bf16 v[6:9], v[160:163], v[204:207], v[6:9]
	v_mfma_f32_16x16x32_bf16 v[2:5], v[172:175], v[204:207], v[2:5]
	s_barrier
; #define PG8_WAIT_V(n) asm volatile("s_waitcnt vmcnt(" #n ")" ::: "memory")
; #define PG8_BAR __builtin_amdgcn_s_barrier()
; template <class Epi, class Sched, bool ALIGN_EPI = true, bool SP2 = true, bool FULLLINE = false, bool NOSTAGE = false, bool FP8 = false>
; __device__ __forceinline__ void gemm_phase(PG8_LAS unsigned char* lds, const Gemm g, const Sched& S, const Epi& E) {
;     ...
;         for (int t = 2; t < nt; t += 2) PG8_ITER(PG8_WAIT_V(8));
;     ...
;         if constexpr (ALIGN_EPI) { if (wr == 0) PG8_BAR; }
	ds_read_b128 v[82:85], v170
	ds_read_b128 v[86:89], v170 offset:1024
	ds_read_b128 v[94:97], v170 offset:2048
	ds_read_b128 v[102:105], v170 offset:3072
	ds_read_b128 v[146:149], v171
	ds_read_b128 v[160:163], v171 offset:1024
	ds_read_b128 v[164:167], v171 offset:2048
	ds_read_b128 v[172:175], v171 offset:3072
	s_mov_b32 m0, s55
	v_lshl_add_u64 v[212:213], v[210:211], 0, s[34:35]
	ds_read_b128 v[176:179], v169 offset:32768
	ds_read_b128 v[180:183], v169 offset:33792
	ds_read_b128 v[184:187], v169 offset:34816
	ds_read_b128 v[188:191], v169 offset:35840
	ds_read_b128 v[192:195], v169 offset:36864
	ds_read_b128 v[196:199], v169 offset:37888
	ds_read_b128 v[200:203], v169 offset:38912
	ds_read_b128 v[204:207], v169 offset:39936
	global_load_lds_dwordx4 v[212:213], off
	v_lshl_add_u64 v[212:213], v[210:211], 0, s[36:37]
	s_mov_b32 m0, s62
	s_nop 0
	global_load_lds_dwordx4 v[212:213], off
	s_waitcnt vmcnt(8)
	s_waitcnt lgkmcnt(0)
	s_barrier
	v_mfma_f32_16x16x32_bf16 v[138:141], v[82:85], v[176:179], v[138:141]
	v_mfma_f32_16x16x32_bf16 v[134:137], v[94:97], v[176:179], v[134:137]
	v_mfma_f32_16x16x32_bf16 v[126:129], v[82:85], v[184:187], v[126:129]
	v_mfma_f32_16x16x32_bf16 v[122:125], v[94:97], v[184:187], v[122:125]
	v_mfma_f32_16x16x32_bf16 v[110:113], v[82:85], v[192:195], v[110:113]
	v_mfma_f32_16x16x32_bf16 v[106:109], v[94:97], v[192:195], v[106:109]
	v_mfma_f32_16x16x32_bf16 v[78:81], v[82:85], v[200:203], v[78:81]
	v_mfma_f32_16x16x32_bf16 v[74:77], v[94:97], v[200:203], v[74:77]
	v_mfma_f32_16x16x32_bf16 v[138:141], v[86:89], v[180:183], v[138:141]
	v_mfma_f32_16x16x32_bf16 v[134:137], v[102:105], v[180:183], v[134:137]
	v_mfma_f32_16x16x32_bf16 v[126:129], v[86:89], v[188:191], v[126:129]
	v_mfma_f32_16x16x32_bf16 v[122:125], v[102:105], v[188:191], v[122:125]
	v_mfma_f32_16x16x32_bf16 v[110:113], v[86:89], v[196:199], v[110:113]
	v_mfma_f32_16x16x32_bf16 v[106:109], v[102:105], v[196:199], v[106:109]
	v_mfma_f32_16x16x32_bf16 v[78:81], v[86:89], v[204:207], v[78:81]
	v_mfma_f32_16x16x32_bf16 v[74:77], v[102:105], v[204:207], v[74:77]
	v_mfma_f32_16x16x32_bf16 v[142:145], v[146:149], v[176:179], v[142:145]
	v_mfma_f32_16x16x32_bf16 v[130:133], v[164:167], v[176:179], v[130:133]
	v_mfma_f32_16x16x32_bf16 v[118:121], v[146:149], v[184:187], v[118:121]
	v_mfma_f32_16x16x32_bf16 v[114:117], v[164:167], v[184:187], v[114:117]
	v_mfma_f32_16x16x32_bf16 v[98:101], v[146:149], v[192:195], v[98:101]
	v_mfma_f32_16x16x32_bf16 v[90:93], v[164:167], v[192:195], v[90:93]
	v_mfma_f32_16x16x32_bf16 v[70:73], v[146:149], v[200:203], v[70:73]
	v_mfma_f32_16x16x32_bf16 v[66:69], v[164:167], v[200:203], v[66:69]
	v_mfma_f32_16x16x32_bf16 v[142:145], v[160:163], v[180:183], v[142:145]
	v_mfma_f32_16x16x32_bf16 v[130:133], v[172:175], v[180:183], v[130:133]
	v_mfma_f32_16x16x32_bf16 v[118:121], v[160:163], v[188:191], v[118:121]
	v_mfma_f32_16x16x32_bf16 v[114:117], v[172:175], v[188:191], v[114:117]
	v_mfma_f32_16x16x32_bf16 v[98:101], v[160:163], v[196:199], v[98:101]
	v_mfma_f32_16x16x32_bf16 v[90:93], v[172:175], v[196:199], v[90:93]
	v_mfma_f32_16x16x32_bf16 v[70:73], v[160:163], v[204:207], v[70:73]
	v_mfma_f32_16x16x32_bf16 v[66:69], v[172:175], v[204:207], v[66:69]
	s_barrier
	s_mov_b32 m0, s50
	v_lshl_add_u64 v[212:213], v[208:209], 0, s[38:39]
	ds_read_b128 v[176:179], v169 offset:49152
	ds_read_b128 v[180:183], v169 offset:50176
	ds_read_b128 v[184:187], v169 offset:51200
	ds_read_b128 v[188:191], v169 offset:52224
	ds_read_b128 v[192:195], v169 offset:53248
	ds_read_b128 v[196:199], v169 offset:54272
	ds_read_b128 v[200:203], v169 offset:55296
	ds_read_b128 v[204:207], v169 offset:56320
	global_load_lds_dwordx4 v[212:213], off
	v_lshl_add_u64 v[212:213], v[208:209], 0, s[40:41]
	s_mov_b32 m0, s51
	s_nop 0
	global_load_lds_dwordx4 v[212:213], off
	v_lshl_add_u64 v[212:213], v[208:209], 0, s[14:15]
	s_mov_b32 m0, s33
	v_lshl_add_u64 v[208:209], v[208:209], 0, s[16:17]
	global_load_lds_dwordx4 v[212:213], off
	s_mov_b32 m0, s56
	s_nop 0
	global_load_lds_dwordx4 v[208:209], off
	v_lshl_add_u64 v[208:209], v[210:211], 0, s[38:39]
	s_mov_b32 m0, s63
	s_nop 0
	global_load_lds_dwordx4 v[208:209], off
	v_lshl_add_u64 v[208:209], v[210:211], 0, s[40:41]
	s_mov_b32 m0, s66
	s_nop 0
	global_load_lds_dwordx4 v[208:209], off
	s_waitcnt vmcnt(8)
	s_waitcnt lgkmcnt(0)
	s_barrier
	v_mfma_f32_16x16x32_bf16 v[62:65], v[82:85], v[176:179], v[62:65]
	v_mfma_f32_16x16x32_bf16 v[58:61], v[94:97], v[176:179], v[58:61]
	v_mfma_f32_16x16x32_bf16 v[46:49], v[82:85], v[184:187], v[46:49]
	v_mfma_f32_16x16x32_bf16 v[42:45], v[94:97], v[184:187], v[42:45]
	v_mfma_f32_16x16x32_bf16 v[30:33], v[82:85], v[192:195], v[30:33]
	v_mfma_f32_16x16x32_bf16 v[26:29], v[94:97], v[192:195], v[26:29]
	v_mfma_f32_16x16x32_bf16 v[14:17], v[82:85], v[200:203], v[14:17]
	v_mfma_f32_16x16x32_bf16 v[10:13], v[94:97], v[200:203], v[10:13]
	v_mfma_f32_16x16x32_bf16 v[62:65], v[86:89], v[180:183], v[62:65]
	v_mfma_f32_16x16x32_bf16 v[58:61], v[102:105], v[180:183], v[58:61]
	v_mfma_f32_16x16x32_bf16 v[46:49], v[86:89], v[188:191], v[46:49]
	v_mfma_f32_16x16x32_bf16 v[42:45], v[102:105], v[188:191], v[42:45]
	v_mfma_f32_16x16x32_bf16 v[30:33], v[86:89], v[196:199], v[30:33]
	v_mfma_f32_16x16x32_bf16 v[26:29], v[102:105], v[196:199], v[26:29]
	v_mfma_f32_16x16x32_bf16 v[14:17], v[86:89], v[204:207], v[14:17]
	v_mfma_f32_16x16x32_bf16 v[10:13], v[102:105], v[204:207], v[10:13]
	v_mfma_f32_16x16x32_bf16 v[54:57], v[146:149], v[176:179], v[54:57]
	v_mfma_f32_16x16x32_bf16 v[50:53], v[164:167], v[176:179], v[50:53]
	v_mfma_f32_16x16x32_bf16 v[38:41], v[146:149], v[184:187], v[38:41]
	v_mfma_f32_16x16x32_bf16 v[34:37], v[164:167], v[184:187], v[34:37]
	v_mfma_f32_16x16x32_bf16 v[22:25], v[146:149], v[192:195], v[22:25]
	v_mfma_f32_16x16x32_bf16 v[18:21], v[164:167], v[192:195], v[18:21]
	v_mfma_f32_16x16x32_bf16 v[6:9], v[146:149], v[200:203], v[6:9]
	v_mfma_f32_16x16x32_bf16 v[2:5], v[164:167], v[200:203], v[2:5]
	v_mfma_f32_16x16x32_bf16 v[54:57], v[160:163], v[180:183], v[54:57]
	v_mfma_f32_16x16x32_bf16 v[50:53], v[172:175], v[180:183], v[50:53]
	v_mfma_f32_16x16x32_bf16 v[38:41], v[160:163], v[188:191], v[38:41]
	v_mfma_f32_16x16x32_bf16 v[34:37], v[172:175], v[188:191], v[34:37]
	v_mfma_f32_16x16x32_bf16 v[22:25], v[160:163], v[196:199], v[22:25]
	v_mfma_f32_16x16x32_bf16 v[18:21], v[172:175], v[196:199], v[18:21]
	v_mfma_f32_16x16x32_bf16 v[6:9], v[160:163], v[204:207], v[6:9]
	v_mfma_f32_16x16x32_bf16 v[2:5], v[172:175], v[204:207], v[2:5]
	s_barrier
	s_add_i32 s59, s59, 2
	s_add_u32 s46, s46, 0x100
	s_addc_u32 s47, s47, 0
	s_add_u32 s57, s57, 0x100
	s_addc_u32 s58, s58, 0
	s_cmpk_gt_u32 s59, 0x55
	s_cbranch_scc0 .LBB0_2965
	s_and_b64 vcc, exec, s[12:13]
	s_cbranch_vccz .LBB0_2968
	s_barrier
